# v16 + every packed fp32 VALU op in the kernel (1827 sites incl. GEMM epilogues and P0) split into scalar pairs, bit-identical
# speedup vs baseline: 1.0022x; 1.0022x over previous
.LBB0_44:
	s_or_b64 exec, exec, s[12:13]
	s_waitcnt lgkmcnt(0)
	s_cmp_lg_u64 s[10:11], 0
	s_cbranch_scc0 .LBB0_46
	v_ashrrev_i32_e32 v163, 31, v162
	v_lshl_add_u64 v[4:5], v[162:163], 2, s[10:11]
	global_load_dword v162, v[4:5], off
	s_waitcnt vmcnt(0)
	v_mul_f32_e32 v72, v72, v162
	v_mul_f32_e32 v73, v73, v162
	v_mul_f32_e32 v70, v70, v162
	v_mul_f32_e32 v71, v71, v162
	global_load_dword v162, v[4:5], off offset:16
	s_waitcnt vmcnt(0)
	v_mul_f32_e32 v76, v76, v162
	v_mul_f32_e32 v77, v77, v162
	v_mul_f32_e32 v74, v74, v162
	v_mul_f32_e32 v75, v75, v162
	global_load_dword v162, v[4:5], off offset:32
	s_waitcnt vmcnt(0)
	v_mul_f32_e32 v80, v80, v162
	v_mul_f32_e32 v81, v81, v162
	v_mul_f32_e32 v78, v78, v162
	v_mul_f32_e32 v79, v79, v162
	global_load_dword v162, v[4:5], off offset:48
	s_waitcnt vmcnt(0)
	v_mul_f32_e32 v84, v84, v162
	v_mul_f32_e32 v85, v85, v162
	v_mul_f32_e32 v82, v82, v162
	v_mul_f32_e32 v83, v83, v162
	global_load_dword v162, v[4:5], off offset:64
	s_waitcnt vmcnt(0)
	v_mul_f32_e32 v88, v88, v162
	v_mul_f32_e32 v89, v89, v162
	v_mul_f32_e32 v86, v86, v162
	v_mul_f32_e32 v87, v87, v162
	global_load_dword v162, v[4:5], off offset:80
	s_waitcnt vmcnt(0)
	v_mul_f32_e32 v92, v92, v162
	v_mul_f32_e32 v93, v93, v162
	v_mul_f32_e32 v90, v90, v162
	v_mul_f32_e32 v91, v91, v162
	global_load_dword v162, v[4:5], off offset:96
	s_waitcnt vmcnt(0)
	v_mul_f32_e32 v96, v96, v162
	v_mul_f32_e32 v97, v97, v162
	v_mul_f32_e32 v94, v94, v162
	v_mul_f32_e32 v95, v95, v162
	global_load_dword v162, v[4:5], off offset:112
	s_waitcnt vmcnt(0)
	v_mul_f32_e32 v100, v100, v162
	v_mul_f32_e32 v101, v101, v162
	v_mul_f32_e32 v98, v98, v162
	v_mul_f32_e32 v99, v99, v162
	global_load_dword v162, v[4:5], off offset:128
	s_waitcnt vmcnt(0)
	v_mul_f32_e32 v104, v104, v162
	v_mul_f32_e32 v105, v105, v162
	v_mul_f32_e32 v102, v102, v162
	v_mul_f32_e32 v103, v103, v162
	global_load_dword v162, v[4:5], off offset:144
	s_waitcnt vmcnt(0)
	v_mul_f32_e32 v108, v108, v162
	v_mul_f32_e32 v109, v109, v162
	v_mul_f32_e32 v106, v106, v162
	v_mul_f32_e32 v107, v107, v162
	global_load_dword v162, v[4:5], off offset:160
	s_waitcnt vmcnt(0)
	v_mul_f32_e32 v112, v112, v162
	v_mul_f32_e32 v113, v113, v162
	v_mul_f32_e32 v110, v110, v162
	v_mul_f32_e32 v111, v111, v162
	global_load_dword v162, v[4:5], off offset:176
	s_waitcnt vmcnt(0)
	v_mul_f32_e32 v116, v116, v162
	v_mul_f32_e32 v117, v117, v162
	v_mul_f32_e32 v114, v114, v162
	v_mul_f32_e32 v115, v115, v162
	global_load_dword v162, v[4:5], off offset:192
	s_waitcnt vmcnt(0)
	v_mul_f32_e32 v120, v120, v162
	v_mul_f32_e32 v121, v121, v162
	v_mul_f32_e32 v118, v118, v162
	v_mul_f32_e32 v119, v119, v162
	global_load_dword v162, v[4:5], off offset:208
	s_waitcnt vmcnt(0)
	v_mul_f32_e32 v124, v124, v162
	v_mul_f32_e32 v125, v125, v162
	v_mul_f32_e32 v122, v122, v162
	v_mul_f32_e32 v123, v123, v162
	global_load_dword v162, v[4:5], off offset:224
	s_waitcnt vmcnt(0)
	v_mul_f32_e32 v128, v128, v162
	v_mul_f32_e32 v129, v129, v162
	global_load_dword v4, v[4:5], off offset:240
	v_mul_f32_e32 v126, v126, v162
	v_mul_f32_e32 v127, v127, v162
	s_waitcnt vmcnt(0)
	v_mul_f32_e32 v132, v132, v4
	v_mul_f32_e32 v133, v133, v4
	v_mul_f32_e32 v130, v130, v4
	v_mul_f32_e32 v131, v131, v4

.LBB0_79:
	s_or_b64 exec, exec, s[16:17]
	s_waitcnt lgkmcnt(0)
	s_cmp_lg_u64 s[12:13], 0
	s_cbranch_scc0 .LBB0_81
	v_ashrrev_i32_e32 v5, 31, v4
	v_lshl_add_u64 v[4:5], v[4:5], 2, s[12:13]
	global_load_dword v162, v[4:5], off
	s_waitcnt vmcnt(0)
	v_mul_f32_e32 v8, v8, v162
	v_mul_f32_e32 v9, v9, v162
	v_mul_f32_e32 v6, v6, v162
	v_mul_f32_e32 v7, v7, v162
	global_load_dword v162, v[4:5], off offset:16
	s_waitcnt vmcnt(0)
	v_mul_f32_e32 v12, v12, v162
	v_mul_f32_e32 v13, v13, v162
	v_mul_f32_e32 v10, v10, v162
	v_mul_f32_e32 v11, v11, v162
	global_load_dword v162, v[4:5], off offset:32
	s_waitcnt vmcnt(0)
	v_mul_f32_e32 v20, v20, v162
	v_mul_f32_e32 v21, v21, v162
	v_mul_f32_e32 v18, v18, v162
	v_mul_f32_e32 v19, v19, v162
	global_load_dword v162, v[4:5], off offset:48
	s_waitcnt vmcnt(0)
	v_mul_f32_e32 v16, v16, v162
	v_mul_f32_e32 v17, v17, v162
	v_mul_f32_e32 v14, v14, v162
	v_mul_f32_e32 v15, v15, v162
	global_load_dword v162, v[4:5], off offset:64
	s_waitcnt vmcnt(0)
	v_mul_f32_e32 v28, v28, v162
	v_mul_f32_e32 v29, v29, v162
	v_mul_f32_e32 v26, v26, v162
	v_mul_f32_e32 v27, v27, v162
	global_load_dword v162, v[4:5], off offset:80
	s_waitcnt vmcnt(0)
	v_mul_f32_e32 v24, v24, v162
	v_mul_f32_e32 v25, v25, v162
	v_mul_f32_e32 v22, v22, v162
	v_mul_f32_e32 v23, v23, v162
	global_load_dword v162, v[4:5], off offset:96
	s_waitcnt vmcnt(0)
	v_mul_f32_e32 v36, v36, v162
	v_mul_f32_e32 v37, v37, v162
	v_mul_f32_e32 v34, v34, v162
	v_mul_f32_e32 v35, v35, v162
	global_load_dword v162, v[4:5], off offset:112
	s_waitcnt vmcnt(0)
	v_mul_f32_e32 v32, v32, v162
	v_mul_f32_e32 v33, v33, v162
	v_mul_f32_e32 v30, v30, v162
	v_mul_f32_e32 v31, v31, v162
	global_load_dword v162, v[4:5], off offset:128
	s_waitcnt vmcnt(0)
	v_mul_f32_e32 v44, v44, v162
	v_mul_f32_e32 v45, v45, v162
	v_mul_f32_e32 v42, v42, v162
	v_mul_f32_e32 v43, v43, v162
	global_load_dword v162, v[4:5], off offset:144
	s_waitcnt vmcnt(0)
	v_mul_f32_e32 v40, v40, v162
	v_mul_f32_e32 v41, v41, v162
	v_mul_f32_e32 v38, v38, v162
	v_mul_f32_e32 v39, v39, v162
	global_load_dword v162, v[4:5], off offset:160
	s_waitcnt vmcnt(0)
	v_mul_f32_e32 v52, v52, v162
	v_mul_f32_e32 v53, v53, v162
	v_mul_f32_e32 v50, v50, v162
	v_mul_f32_e32 v51, v51, v162
	global_load_dword v162, v[4:5], off offset:176
	s_waitcnt vmcnt(0)
	v_mul_f32_e32 v48, v48, v162
	v_mul_f32_e32 v49, v49, v162
	v_mul_f32_e32 v46, v46, v162
	v_mul_f32_e32 v47, v47, v162
	global_load_dword v162, v[4:5], off offset:192
	s_waitcnt vmcnt(0)
	v_mul_f32_e32 v60, v60, v162
	v_mul_f32_e32 v61, v61, v162
	v_mul_f32_e32 v58, v58, v162
	v_mul_f32_e32 v59, v59, v162
	global_load_dword v162, v[4:5], off offset:208
	s_waitcnt vmcnt(0)
	v_mul_f32_e32 v56, v56, v162
	v_mul_f32_e32 v57, v57, v162
	v_mul_f32_e32 v54, v54, v162
	v_mul_f32_e32 v55, v55, v162
	global_load_dword v162, v[4:5], off offset:224
	s_waitcnt vmcnt(0)
	v_mul_f32_e32 v68, v68, v162
	v_mul_f32_e32 v69, v69, v162
	global_load_dword v4, v[4:5], off offset:240
	v_mul_f32_e32 v66, v66, v162
	v_mul_f32_e32 v67, v67, v162
	s_waitcnt vmcnt(0)
	v_mul_f32_e32 v64, v64, v4
	v_mul_f32_e32 v65, v65, v4
	v_mul_f32_e32 v62, v62, v4
	v_mul_f32_e32 v63, v63, v4

.LBB0_337:
	s_or_b64 exec, exec, s[10:11]
	s_waitcnt lgkmcnt(0)
	s_cmp_lg_u64 s[8:9], 0
	s_cbranch_scc0 .LBB0_339
	v_lshl_add_u64 v[4:5], v[162:163], 2, s[8:9]
	global_load_dword v162, v[4:5], off
	s_waitcnt vmcnt(0)
	v_mul_f32_e32 v72, v72, v162
	v_mul_f32_e32 v73, v73, v162
	v_mul_f32_e32 v70, v70, v162
	v_mul_f32_e32 v71, v71, v162
	global_load_dword v162, v[4:5], off offset:16
	s_waitcnt vmcnt(0)
	v_mul_f32_e32 v76, v76, v162
	v_mul_f32_e32 v77, v77, v162
	v_mul_f32_e32 v74, v74, v162
	v_mul_f32_e32 v75, v75, v162
	global_load_dword v162, v[4:5], off offset:32
	s_waitcnt vmcnt(0)
	v_mul_f32_e32 v80, v80, v162
	v_mul_f32_e32 v81, v81, v162
	v_mul_f32_e32 v78, v78, v162
	v_mul_f32_e32 v79, v79, v162
	global_load_dword v162, v[4:5], off offset:48
	s_waitcnt vmcnt(0)
	v_mul_f32_e32 v84, v84, v162
	v_mul_f32_e32 v85, v85, v162
	v_mul_f32_e32 v82, v82, v162
	v_mul_f32_e32 v83, v83, v162
	global_load_dword v162, v[4:5], off offset:64
	s_waitcnt vmcnt(0)
	v_mul_f32_e32 v88, v88, v162
	v_mul_f32_e32 v89, v89, v162
	v_mul_f32_e32 v86, v86, v162
	v_mul_f32_e32 v87, v87, v162
	global_load_dword v162, v[4:5], off offset:80
	s_waitcnt vmcnt(0)
	v_mul_f32_e32 v92, v92, v162
	v_mul_f32_e32 v93, v93, v162
	v_mul_f32_e32 v90, v90, v162
	v_mul_f32_e32 v91, v91, v162
	global_load_dword v162, v[4:5], off offset:96
	s_waitcnt vmcnt(0)
	v_mul_f32_e32 v96, v96, v162
	v_mul_f32_e32 v97, v97, v162
	v_mul_f32_e32 v94, v94, v162
	v_mul_f32_e32 v95, v95, v162
	global_load_dword v162, v[4:5], off offset:112
	s_waitcnt vmcnt(0)
	v_mul_f32_e32 v100, v100, v162
	v_mul_f32_e32 v101, v101, v162
	v_mul_f32_e32 v98, v98, v162
	v_mul_f32_e32 v99, v99, v162
	global_load_dword v162, v[4:5], off offset:128
	s_waitcnt vmcnt(0)
	v_mul_f32_e32 v104, v104, v162
	v_mul_f32_e32 v105, v105, v162
	v_mul_f32_e32 v102, v102, v162
	v_mul_f32_e32 v103, v103, v162
	global_load_dword v162, v[4:5], off offset:144
	s_waitcnt vmcnt(0)
	v_mul_f32_e32 v108, v108, v162
	v_mul_f32_e32 v109, v109, v162
	v_mul_f32_e32 v106, v106, v162
	v_mul_f32_e32 v107, v107, v162
	global_load_dword v162, v[4:5], off offset:160
	s_waitcnt vmcnt(0)
	v_mul_f32_e32 v112, v112, v162
	v_mul_f32_e32 v113, v113, v162
	v_mul_f32_e32 v110, v110, v162
	v_mul_f32_e32 v111, v111, v162
	global_load_dword v162, v[4:5], off offset:176
	s_waitcnt vmcnt(0)
	v_mul_f32_e32 v116, v116, v162
	v_mul_f32_e32 v117, v117, v162
	v_mul_f32_e32 v114, v114, v162
	v_mul_f32_e32 v115, v115, v162
	global_load_dword v162, v[4:5], off offset:192
	s_waitcnt vmcnt(0)
	v_mul_f32_e32 v120, v120, v162
	v_mul_f32_e32 v121, v121, v162
	v_mul_f32_e32 v118, v118, v162
	v_mul_f32_e32 v119, v119, v162
	global_load_dword v162, v[4:5], off offset:208
	s_waitcnt vmcnt(0)
	v_mul_f32_e32 v124, v124, v162
	v_mul_f32_e32 v125, v125, v162
	v_mul_f32_e32 v122, v122, v162
	v_mul_f32_e32 v123, v123, v162
	global_load_dword v162, v[4:5], off offset:224
	s_waitcnt vmcnt(0)
	v_mul_f32_e32 v128, v128, v162
	v_mul_f32_e32 v129, v129, v162
	global_load_dword v4, v[4:5], off offset:240
	v_mul_f32_e32 v126, v126, v162
	v_mul_f32_e32 v127, v127, v162
	s_waitcnt vmcnt(0)
	v_mul_f32_e32 v132, v132, v4
	v_mul_f32_e32 v133, v133, v4
	v_mul_f32_e32 v130, v130, v4
	v_mul_f32_e32 v131, v131, v4

.LBB0_372:
	s_or_b64 exec, exec, s[12:13]
	s_waitcnt lgkmcnt(0)
	s_cmp_lg_u64 s[10:11], 0
	s_cbranch_scc0 .LBB0_374
	v_lshl_add_u64 v[4:5], v[4:5], 2, s[10:11]
	global_load_dword v162, v[4:5], off
	s_waitcnt vmcnt(0)
	v_mul_f32_e32 v8, v8, v162
	v_mul_f32_e32 v9, v9, v162
	v_mul_f32_e32 v6, v6, v162
	v_mul_f32_e32 v7, v7, v162
	global_load_dword v162, v[4:5], off offset:16
	s_waitcnt vmcnt(0)
	v_mul_f32_e32 v12, v12, v162
	v_mul_f32_e32 v13, v13, v162
	v_mul_f32_e32 v10, v10, v162
	v_mul_f32_e32 v11, v11, v162
	global_load_dword v162, v[4:5], off offset:32
	s_waitcnt vmcnt(0)
	v_mul_f32_e32 v20, v20, v162
	v_mul_f32_e32 v21, v21, v162
	v_mul_f32_e32 v18, v18, v162
	v_mul_f32_e32 v19, v19, v162
	global_load_dword v162, v[4:5], off offset:48
	s_waitcnt vmcnt(0)
	v_mul_f32_e32 v16, v16, v162
	v_mul_f32_e32 v17, v17, v162
	v_mul_f32_e32 v14, v14, v162
	v_mul_f32_e32 v15, v15, v162
	global_load_dword v162, v[4:5], off offset:64
	s_waitcnt vmcnt(0)
	v_mul_f32_e32 v28, v28, v162
	v_mul_f32_e32 v29, v29, v162
	v_mul_f32_e32 v26, v26, v162
	v_mul_f32_e32 v27, v27, v162
	global_load_dword v162, v[4:5], off offset:80
	s_waitcnt vmcnt(0)
	v_mul_f32_e32 v24, v24, v162
	v_mul_f32_e32 v25, v25, v162
	v_mul_f32_e32 v22, v22, v162
	v_mul_f32_e32 v23, v23, v162
	global_load_dword v162, v[4:5], off offset:96
	s_waitcnt vmcnt(0)
	v_mul_f32_e32 v36, v36, v162
	v_mul_f32_e32 v37, v37, v162
	v_mul_f32_e32 v34, v34, v162
	v_mul_f32_e32 v35, v35, v162
	global_load_dword v162, v[4:5], off offset:112
	s_waitcnt vmcnt(0)
	v_mul_f32_e32 v32, v32, v162
	v_mul_f32_e32 v33, v33, v162
	v_mul_f32_e32 v30, v30, v162
	v_mul_f32_e32 v31, v31, v162
	global_load_dword v162, v[4:5], off offset:128
	s_waitcnt vmcnt(0)
	v_mul_f32_e32 v44, v44, v162
	v_mul_f32_e32 v45, v45, v162
	v_mul_f32_e32 v42, v42, v162
	v_mul_f32_e32 v43, v43, v162
	global_load_dword v162, v[4:5], off offset:144
	s_waitcnt vmcnt(0)
	v_mul_f32_e32 v40, v40, v162
	v_mul_f32_e32 v41, v41, v162
	v_mul_f32_e32 v38, v38, v162
	v_mul_f32_e32 v39, v39, v162
	global_load_dword v162, v[4:5], off offset:160
	s_waitcnt vmcnt(0)
	v_mul_f32_e32 v52, v52, v162
	v_mul_f32_e32 v53, v53, v162
	v_mul_f32_e32 v50, v50, v162
	v_mul_f32_e32 v51, v51, v162
	global_load_dword v162, v[4:5], off offset:176
	s_waitcnt vmcnt(0)
	v_mul_f32_e32 v48, v48, v162
	v_mul_f32_e32 v49, v49, v162
	v_mul_f32_e32 v46, v46, v162
	v_mul_f32_e32 v47, v47, v162
	global_load_dword v162, v[4:5], off offset:192
	s_waitcnt vmcnt(0)
	v_mul_f32_e32 v60, v60, v162
	v_mul_f32_e32 v61, v61, v162
	v_mul_f32_e32 v58, v58, v162
	v_mul_f32_e32 v59, v59, v162
	global_load_dword v162, v[4:5], off offset:208
	s_waitcnt vmcnt(0)
	v_mul_f32_e32 v56, v56, v162
	v_mul_f32_e32 v57, v57, v162
	v_mul_f32_e32 v54, v54, v162
	v_mul_f32_e32 v55, v55, v162
	global_load_dword v162, v[4:5], off offset:224
	s_waitcnt vmcnt(0)
	v_mul_f32_e32 v68, v68, v162
	v_mul_f32_e32 v69, v69, v162
	global_load_dword v4, v[4:5], off offset:240
	v_mul_f32_e32 v66, v66, v162
	v_mul_f32_e32 v67, v67, v162
	s_waitcnt vmcnt(0)
	v_mul_f32_e32 v64, v64, v4
	v_mul_f32_e32 v65, v65, v4
	v_mul_f32_e32 v62, v62, v4
	v_mul_f32_e32 v63, v63, v4

.LBB0_761:
	v_and_b32_e32 v6, 62, v3
	v_cvt_f32_ubyte0_e32 v6, v6
	v_mul_f32_e32 v6, 0x3c800000, v6
	v_cmp_eq_f32_e32 vcc, 0, v6
	s_nop 1
	v_cndmask_b32_e64 v30, v10, 1.0, vcc
	v_frexp_mant_f32_e32 v8, v30
	v_cmp_gt_f32_e32 vcc, s29, v8
	s_nop 1
	v_cndmask_b32_e64 v20, 1.0, 2.0, vcc
	v_mul_f32_e32 v8, v8, v20
	v_add_f32_e32 v20, 1.0, v8
	v_rcp_f32_e32 v28, v20
	v_add_f32_e32 v21, -1.0, v20
	v_sub_f32_e32 v23, v8, v21
	v_add_f32_e32 v21, -1.0, v8
	v_mul_f32_e32 v8, v21, v28
	v_mul_f32_e32 v22, v20, v8
	v_fma_f32 v24, v8, v20, -v22
	v_fmac_f32_e32 v24, v8, v23
	v_add_f32_e32 v20, v22, v24
	v_sub_f32_e32 v23, v21, v20
	v_sub_f32_e32 v26, v20, v22
	v_sub_f32_e32 v27, v21, v23
	v_mov_b32_e32 v25, v20
	v_sub_f32_e32 v20, v26, v24
	v_sub_f32_e32 v21, v27, v25
	s_nop 0
	v_add_f32_e32 v20, v20, v21
	v_add_f32_e32 v20, v23, v20
	v_mul_f32_e32 v21, v28, v20
	v_add_f32_e32 v20, v8, v21
	v_sub_f32_e32 v8, v20, v8
	v_sub_f32_e32 v31, v21, v8
	v_mul_f32_e32 v8, v20, v20
	v_fma_f32 v21, v20, v20, -v8
	v_add_f32_e32 v22, v31, v31
	v_fmac_f32_e32 v21, v20, v22
	v_add_f32_e32 v22, v8, v21
	v_fmamk_f32 v23, v22, 0x3e76c4e1, v11
	v_fmaak_f32 v23, v22, v23, 0x3ecccdef
	v_sub_f32_e32 v8, v22, v8
	v_sub_f32_e32 v32, v21, v8
	v_mul_f32_e32 v21, v22, v23
	v_fma_f32 v8, v22, v23, -v21
	v_fmac_f32_e32 v8, v32, v23
	v_add_f32_e32 v25, v21, v8
	v_sub_f32_e32 v24, v25, v21
	v_sub_f32_e32 v26, v8, v24
	v_sub_f32_e32 v27, v9, v25
	v_pk_add_f32 v[28:29], v[24:25], s[2:3]
	s_nop 0
	v_mov_b32_e32 v27, v29
	v_pk_add_f32 v[26:27], v[26:27], s[50:51]
	s_nop 0
	v_sub_f32_e32 v23, v25, v27
	v_mov_b32_e32 v21, v26
	v_mul_f32_e32 v24, v20, v22
	v_mul_f32_e32 v25, v21, v23
	v_add_f32_e32 v27, v26, v23
	v_add_f32_e32 v26, v26, v22
	v_fma_f32 v28, v22, v20, -v24
	v_fmac_f32_e32 v28, v22, v31
	v_mov_b32_e32 v25, v27
	v_fmac_f32_e32 v28, v32, v20
	v_add_f32_e32 v22, v24, v28
	v_add_f32_e32 v23, v25, v29
	s_nop 0
	v_sub_f32_e32 v21, v29, v23
	v_sub_f32_e32 v8, v22, v24
	v_add_f32_e32 v21, v27, v21
	v_mul_f32_e32 v24, v22, v23
	v_mul_f32_e32 v25, v23, v22
	v_cvt_f64_f32_e32 v[26:27], v30
	v_frexp_exp_i32_f64_e32 v25, v[26:27]
	v_subbrev_co_u32_e32 v25, vcc, 0, v25, vcc
	v_cvt_f32_i32_e32 v25, v25
	v_fma_f32 v26, v22, v23, -v24
	v_sub_f32_e32 v8, v28, v8
	v_fmac_f32_e32 v26, v22, v21
	v_mul_f32_e32 v22, 0x3f317218, v25
	v_fmac_f32_e32 v26, v8, v23
	v_fma_f32 v28, v25, s30, -v22
	v_fmac_f32_e32 v28, 0xb102e308, v25
	v_ldexp_f32 v29, v20, 1
	v_add_f32_e32 v23, v24, v26
	v_add_f32_e32 v20, v22, v28
	v_add_f32_e32 v21, v23, v29
	v_ldexp_f32 v8, v31, 1
	v_mov_b32_e32 v30, v23
	v_mov_b32_e32 v31, v21
	v_mov_b32_e32 v25, v29
	v_sub_f32_e32 v24, v30, v24
	v_sub_f32_e32 v25, v31, v25
	v_mov_b32_e32 v27, v23
	v_sub_f32_e32 v24, v26, v24
	v_sub_f32_e32 v25, v27, v25
	v_mov_b32_e32 v29, v20
	v_add_f32_e32 v8, v8, v24
	v_add_f32_e32 v23, v8, v25
	v_sub_f32_e32 v24, v20, v22
	v_sub_f32_e32 v25, v21, v23
	v_add_f32_e32 v26, v20, v22
	v_add_f32_e32 v27, v21, v23
	v_mov_b32_e32 v22, v23
	v_mov_b32_e32 v25, v27
	v_sub_f32_e32 v30, v28, v24
	v_sub_f32_e32 v31, v29, v25
	v_add_f32_e32 v24, v28, v24
	v_add_f32_e32 v25, v29, v25
	v_mov_b32_e32 v23, v20
	v_sub_f32_e32 v28, v25, v20
	v_sub_f32_e32 v29, v24, v21
	v_sub_f32_e32 v32, v26, v28
	v_sub_f32_e32 v33, v27, v28
	v_mov_b32_e32 v26, v27
	v_mov_b32_e32 v27, v25
	v_pk_mov_b32 v[28:29], v[20:21], v[28:29] op_sel:[1,0]
	v_mov_b32_e32 v32, v30
	v_sub_f32_e32 v26, v26, v28
	v_sub_f32_e32 v27, v27, v29
	v_mov_b32_e32 v31, v25
	v_sub_f32_e32 v20, v22, v26
	v_sub_f32_e32 v21, v23, v27
	s_nop 0
	v_add_f32_e32 v22, v32, v20
	v_add_f32_e32 v23, v33, v21
	s_nop 0
	v_add_f32_e32 v26, v22, v23
	v_add_f32_e32 v27, v23, v22
	s_nop 0
	v_pk_add_f32 v[24:25], v[24:25], v[26:27] op_sel:[1,0] op_sel_hi:[0,1]
	v_mov_b32_e32 v23, v24
	v_sub_f32_e32 v28, v22, v30
	v_sub_f32_e32 v29, v23, v31
	v_mov_b32_e32 v21, v26
	v_sub_f32_e32 v8, v22, v28
	v_sub_f32_e32 v20, v20, v28
	v_sub_f32_e32 v21, v21, v29
	v_sub_f32_e32 v8, v30, v8
	v_add_f32_e32 v8, v20, v8
	v_add_f32_e32 v8, v8, v21
	v_add_f32_e32 v20, v24, v8
	v_sub_f32_e32 v21, v20, v24
	v_sub_f32_e32 v8, v8, v21
	v_mul_f32_e32 v21, v6, v20
	v_fma_f32 v20, v6, v20, -v21
	v_fmac_f32_e32 v20, v6, v8
	v_add_f32_e32 v8, v21, v20
	v_cmp_class_f32_e64 vcc, v21, s31
	v_sub_f32_e32 v22, v8, v21
	v_sub_f32_e32 v20, v20, v22
	v_cndmask_b32_e32 v8, v8, v21, vcc
	v_cmp_eq_f32_e32 vcc, s35, v8
	s_nop 1
	v_cndmask_b32_e32 v21, 0, v12, vcc
	v_sub_f32_e32 v22, v8, v21
	v_mul_f32_e32 v23, 0x3fb8aa3b, v22
	v_fma_f32 v24, v22, s46, -v23
	v_rndne_f32_e32 v25, v23
	v_fmac_f32_e32 v24, 0x32a5705f, v22
	v_sub_f32_e32 v23, v23, v25
	v_add_f32_e32 v23, v23, v24
	v_exp_f32_e32 v23, v23
	v_cvt_i32_f32_e32 v24, v25
	v_cmp_neq_f32_e64 vcc, |v8|, s34
	s_nop 1
	v_cndmask_b32_e32 v8, 0, v20, vcc
	v_ldexp_f32 v20, v23, v24
	v_cmp_ngt_f32_e32 vcc, s47, v22
	v_add_f32_e32 v8, v21, v8
	v_ashrrev_i32_e32 v23, 5, v19
	v_cndmask_b32_e32 v20, 0, v20, vcc
	v_cmp_nlt_f32_e32 vcc, s35, v22
	s_nop 1
	v_cndmask_b32_e32 v20, v13, v20, vcc
	v_fma_f32 v8, v20, v8, v20
	v_cmp_class_f32_e64 vcc, v20, s31
	s_nop 1
	v_cndmask_b32_e32 v8, v8, v20, vcc
	v_and_b32_e32 v20, 0x7fffffff, v8
	v_div_scale_f32 v21, s[4:5], v20, v20, 1.0
	v_rcp_f32_e32 v22, v21
	v_div_scale_f32 v20, vcc, 1.0, v20, 1.0
	v_fma_f32 v24, -v21, v22, 1.0
	v_fmac_f32_e32 v22, v24, v22
	v_mul_f32_e32 v24, v20, v22
	v_fma_f32 v25, -v21, v24, v20
	v_fmac_f32_e32 v24, v25, v22
	v_fma_f32 v20, -v21, v24, v20
	v_cvt_f32_i32_e32 v21, v23
	v_div_fmas_f32 v20, v20, v22, v24
	v_div_fixup_f32 v8, v20, |v8|, 1.0
	v_cmp_neq_f32_e32 vcc, s34, v6
	s_nop 1
	v_cndmask_b32_e32 v6, 0, v8, vcc
	v_mul_f32_e32 v8, v6, v21
	v_and_b32_e32 v20, 0x7fffffff, v8
	v_lshrrev_b32_e32 v6, 23, v20
	v_and_b32_e32 v21, 0x7fffff, v20
	v_cmp_nlt_f32_e64 s[10:11], |v8|, s54
	v_add_u32_e32 v22, 0xffffff88, v6
	v_or_b32_e32 v21, 0x800000, v21
	s_and_saveexec_b64 s[4:5], s[10:11]
	s_xor_b64 s[52:53], exec, s[4:5]
	s_cbranch_execz .LBB0_763
	v_cmp_lt_u32_e32 vcc, 63, v22
	v_mad_u64_u32 v[24:25], s[8:9], v21, s55, 0
	s_nop 0
	v_cndmask_b32_e32 v6, 0, v16, vcc
	v_add_u32_e32 v6, v6, v22
	v_cmp_lt_u32_e64 s[4:5], 31, v6
	s_nop 1
	v_cndmask_b32_e64 v23, 0, v17, s[4:5]
	v_add_u32_e32 v6, v23, v6
	v_cmp_lt_u32_e64 s[6:7], 31, v6
	s_nop 1
	v_cndmask_b32_e64 v23, 0, v17, s[6:7]
	v_add_u32_e32 v23, v23, v6
	v_mov_b32_e32 v6, v25
	v_mad_u64_u32 v[26:27], s[8:9], v21, s56, v[6:7]
	v_mov_b32_e32 v6, v27
	v_mad_u64_u32 v[28:29], s[8:9], v21, s57, v[6:7]
	v_mov_b32_e32 v6, v29
	v_mad_u64_u32 v[30:31], s[8:9], v21, s58, v[6:7]
	v_mov_b32_e32 v6, v31
	v_mad_u64_u32 v[32:33], s[8:9], v21, s59, v[6:7]
	v_mov_b32_e32 v6, v33
	v_mad_u64_u32 v[34:35], s[8:9], v21, s60, v[6:7]
	v_mov_b32_e32 v6, v35
	v_mad_u64_u32 v[36:37], s[8:9], v21, s61, v[6:7]
	v_cndmask_b32_e32 v25, v34, v30, vcc
	v_cndmask_b32_e32 v6, v36, v32, vcc
	v_cndmask_b32_e32 v29, v37, v34, vcc
	v_cndmask_b32_e64 v27, v6, v25, s[4:5]
	v_cndmask_b32_e64 v6, v29, v6, s[4:5]
	v_cndmask_b32_e32 v29, v32, v28, vcc
	v_cndmask_b32_e64 v25, v25, v29, s[4:5]
	v_sub_u32_e32 v31, 32, v23
	v_cmp_eq_u32_e64 s[8:9], 0, v23
	v_cndmask_b32_e32 v23, v30, v26, vcc
	v_cndmask_b32_e64 v6, v6, v27, s[6:7]
	v_cndmask_b32_e64 v27, v27, v25, s[6:7]
	v_cndmask_b32_e64 v26, v29, v23, s[4:5]
	v_alignbit_b32 v32, v6, v27, v31
	v_cndmask_b32_e64 v25, v25, v26, s[6:7]
	v_cndmask_b32_e64 v6, v32, v6, s[8:9]
	v_alignbit_b32 v29, v27, v25, v31
	v_cndmask_b32_e32 v24, v28, v24, vcc
	v_cndmask_b32_e64 v27, v29, v27, s[8:9]
	v_bfe_u32 v32, v6, 29, 1
	v_cndmask_b32_e64 v23, v23, v24, s[4:5]
	v_alignbit_b32 v29, v6, v27, 30
	v_sub_u32_e32 v33, 0, v32
	v_cndmask_b32_e64 v23, v26, v23, s[6:7]
	v_xor_b32_e32 v29, v29, v33
	v_alignbit_b32 v24, v25, v23, v31
	v_cndmask_b32_e64 v24, v24, v25, s[8:9]
	v_ffbh_u32_e32 v26, v29
	v_alignbit_b32 v25, v27, v24, 30
	v_min_u32_e32 v26, 32, v26
	v_alignbit_b32 v23, v24, v23, 30
	v_xor_b32_e32 v25, v25, v33
	v_sub_u32_e32 v27, 31, v26
	v_xor_b32_e32 v23, v23, v33
	v_alignbit_b32 v28, v29, v25, v27
	v_alignbit_b32 v23, v25, v23, v27
	v_alignbit_b32 v24, v28, v23, 9
	v_ffbh_u32_e32 v25, v24
	v_min_u32_e32 v25, 32, v25
	v_lshrrev_b32_e32 v30, 29, v6
	v_not_b32_e32 v27, v25
	v_alignbit_b32 v23, v24, v23, v27
	v_lshlrev_b32_e32 v24, 31, v30
	v_or_b32_e32 v27, 0x33000000, v24
	v_add_lshl_u32 v25, v25, v26, 23
	v_lshrrev_b32_e32 v23, 9, v23
	v_sub_u32_e32 v25, v27, v25
	v_or_b32_e32 v24, 0.5, v24
	v_lshlrev_b32_e32 v26, 23, v26
	v_or_b32_e32 v23, v25, v23
	v_lshrrev_b32_e32 v25, 9, v28
	v_sub_u32_e32 v24, v24, v26
	v_or_b32_e32 v24, v25, v24
	v_mul_f32_e32 v25, 0x3fc90fda, v24
	v_fma_f32 v26, v24, s62, -v25
	v_fmac_f32_e32 v26, 0x33a22168, v24
	v_fmac_f32_e32 v26, 0x3fc90fda, v23
	v_lshrrev_b32_e32 v6, 30, v6
	v_add_f32_e32 v24, v25, v26
	v_add_u32_e32 v23, v32, v6

.LBB0_852:
	v_lshl_add_u32 v148, s70, 8, v150
	v_ashrrev_i32_e32 v149, 31, v148
	v_lshlrev_b64 v[146:147], 7, v[148:149]
	v_lshl_add_u64 v[146:147], s[52:53], 0, v[146:147]
	v_mov_b32_e32 v149, 0
	v_lshl_add_u64 v[146:147], v[136:137], 4, v[146:147]
	s_and_saveexec_b64 s[70:71], s[8:9]
	s_cbranch_execz .LBB0_854
	global_load_dwordx4 v[160:163], v[146:147], off
	s_waitcnt vmcnt(0)
	v_mov_b32_e32 v164, v161
	v_mov_b32_e32 v165, v162
	v_mov_b32_e32 v161, v163
	v_add_f32_e32 v160, v164, v160
	v_add_f32_e32 v161, v165, v161
	s_nop 0
	v_add_f32_e32 v149, v160, v161
	v_add_f32_e32 v149, 0, v149
.LBB0_854:
	s_or_b64 exec, exec, s[70:71]
	s_and_saveexec_b64 s[70:71], s[10:11]
	s_cbranch_execz .LBB0_856
	global_load_dwordx4 v[160:163], v[146:147], off offset:64
	s_waitcnt vmcnt(0)
	v_mov_b32_e32 v146, v161
	v_mov_b32_e32 v147, v162
	v_mov_b32_e32 v161, v163
	v_add_f32_e32 v146, v146, v160
	v_add_f32_e32 v147, v147, v161
	s_nop 0
	v_add_f32_e32 v146, v146, v147
	v_add_f32_e32 v149, v149, v146
.LBB0_856:
	s_or_b64 exec, exec, s[70:71]
	ds_bpermute_b32 v146, v153, v149
	v_mov_b64_e32 v[160:161], s[50:51]
	s_waitcnt lgkmcnt(0)
	v_add_f32_e32 v149, v149, v146
	ds_bpermute_b32 v159, v154, v149
	v_lshl_add_u32 v146, s68, 8, v152
	v_ashrrev_i32_e32 v147, 31, v146
	v_mad_i64_i32 v[160:161], s[68:69], v148, s82, v[160:161]
	s_waitcnt lgkmcnt(0)
	v_add_f32_e32 v149, v149, v159
	v_fmamk_f32 v149, v149, 0x3a000000, v158
	v_rsq_f32_e32 v162, v149
	v_lshl_add_u64 v[160:161], v[146:147], 1, v[160:161]
	v_mul_f32_e32 v126, v126, v162
	v_mul_f32_e32 v127, v127, v162
	v_mul_f32_e32 v124, v124, v162
	v_mul_f32_e32 v125, v125, v162
	v_mul_f32_e32 v164, v122, v162
	v_mul_f32_e32 v165, v123, v162
	v_mul_f32_e32 v122, v120, v162
	v_mul_f32_e32 v123, v121, v162
	v_cvt_pk_bf16_f32 v120, v124, v125
	v_cvt_pk_bf16_f32 v121, v126, v127
	v_cvt_pk_bf16_f32 v122, v122, v123
	v_cvt_pk_bf16_f32 v123, v164, v165
	global_store_dwordx4 v[160:161], v[120:123], off
	v_mul_f32_e32 v118, v118, v162
	v_mul_f32_e32 v119, v119, v162
	v_mul_f32_e32 v116, v116, v162
	v_mul_f32_e32 v117, v117, v162
	v_mul_f32_e32 v120, v114, v162
	v_mul_f32_e32 v121, v115, v162
	v_mul_f32_e32 v114, v112, v162
	v_mul_f32_e32 v115, v113, v162
	v_cvt_pk_bf16_f32 v112, v116, v117
	v_cvt_pk_bf16_f32 v113, v118, v119
	v_cvt_pk_bf16_f32 v114, v114, v115
	v_cvt_pk_bf16_f32 v115, v120, v121
	global_store_dwordx4 v[160:161], v[112:115], off offset:256
	s_nop 1
	v_or_b32_e32 v112, 16, v148
	v_ashrrev_i32_e32 v113, 31, v112
	v_lshlrev_b64 v[114:115], 7, v[112:113]
	v_lshl_add_u64 v[114:115], s[52:53], 0, v[114:115]
	v_mov_b32_e32 v113, 0
	v_lshl_add_u64 v[114:115], v[136:137], 4, v[114:115]
	s_and_saveexec_b64 s[68:69], s[8:9]
	s_cbranch_execz .LBB0_858
	global_load_dwordx4 v[116:119], v[114:115], off
	s_waitcnt vmcnt(0)
	v_mov_b32_e32 v120, v117
	v_mov_b32_e32 v121, v118
	v_mov_b32_e32 v117, v119
	v_add_f32_e32 v116, v120, v116
	v_add_f32_e32 v117, v121, v117
	s_nop 0
	v_add_f32_e32 v113, v116, v117
	v_add_f32_e32 v113, 0, v113
.LBB0_858:
	s_or_b64 exec, exec, s[68:69]
	s_and_saveexec_b64 s[68:69], s[10:11]
	s_cbranch_execz .LBB0_860
	global_load_dwordx4 v[114:117], v[114:115], off offset:64
	s_waitcnt vmcnt(0)
	v_mov_b32_e32 v118, v115
	v_mov_b32_e32 v119, v116
	v_mov_b32_e32 v115, v117
	v_add_f32_e32 v114, v118, v114
	v_add_f32_e32 v115, v119, v115
	s_nop 0
	v_add_f32_e32 v114, v114, v115
	v_add_f32_e32 v113, v113, v114
.LBB0_860:
	s_or_b64 exec, exec, s[68:69]
	ds_bpermute_b32 v114, v153, v113
	s_waitcnt lgkmcnt(0)
	v_add_f32_e32 v113, v113, v114
	ds_bpermute_b32 v116, v154, v113
	v_mov_b64_e32 v[114:115], s[50:51]
	s_waitcnt lgkmcnt(0)
	v_add_f32_e32 v113, v113, v116
	v_fmamk_f32 v113, v113, 0x3a000000, v158
	v_rsq_f32_e32 v116, v113
	v_mad_i64_i32 v[112:113], s[68:69], v112, s82, v[114:115]
	v_lshl_add_u64 v[112:113], v[146:147], 1, v[112:113]
	v_mul_f32_e32 v110, v110, v116
	v_mul_f32_e32 v111, v111, v116
	v_mul_f32_e32 v108, v108, v116
	v_mul_f32_e32 v109, v109, v116
	v_mul_f32_e32 v106, v106, v116
	v_mul_f32_e32 v107, v107, v116
	v_mul_f32_e32 v104, v104, v116
	v_mul_f32_e32 v105, v105, v116
	v_mul_f32_e32 v114, v102, v116
	v_mul_f32_e32 v115, v103, v116
	v_cvt_pk_bf16_f32 v102, v108, v109
	v_cvt_pk_bf16_f32 v103, v110, v111
	v_cvt_pk_bf16_f32 v104, v104, v105
	v_cvt_pk_bf16_f32 v105, v106, v107
	global_store_dwordx4 v[112:113], v[102:105], off
	v_mul_f32_e32 v100, v100, v116
	v_mul_f32_e32 v101, v101, v116
	s_nop 0
	v_mul_f32_e32 v102, v98, v116
	v_mul_f32_e32 v103, v99, v116
	v_mul_f32_e32 v98, v96, v116
	v_mul_f32_e32 v99, v97, v116
	v_cvt_pk_bf16_f32 v96, v100, v101
	v_cvt_pk_bf16_f32 v97, v114, v115
	v_cvt_pk_bf16_f32 v98, v98, v99
	v_cvt_pk_bf16_f32 v99, v102, v103
	global_store_dwordx4 v[112:113], v[96:99], off offset:256
	s_nop 1
	v_or_b32_e32 v96, 32, v148
	v_ashrrev_i32_e32 v97, 31, v96
	v_lshlrev_b64 v[98:99], 7, v[96:97]
	v_lshl_add_u64 v[98:99], s[52:53], 0, v[98:99]
	v_mov_b32_e32 v97, 0
	v_lshl_add_u64 v[98:99], v[136:137], 4, v[98:99]
	s_and_saveexec_b64 s[68:69], s[8:9]
	s_cbranch_execz .LBB0_862
	global_load_dwordx4 v[100:103], v[98:99], off
	s_waitcnt vmcnt(0)
	v_mov_b32_e32 v104, v101
	v_mov_b32_e32 v105, v102
	v_mov_b32_e32 v101, v103
	v_add_f32_e32 v100, v104, v100
	v_add_f32_e32 v101, v105, v101
	s_nop 0
	v_add_f32_e32 v97, v100, v101
	v_add_f32_e32 v97, 0, v97
.LBB0_862:
	s_or_b64 exec, exec, s[68:69]
	s_and_saveexec_b64 s[68:69], s[10:11]
	s_cbranch_execz .LBB0_864
	global_load_dwordx4 v[98:101], v[98:99], off offset:64
	s_waitcnt vmcnt(0)
	v_mov_b32_e32 v102, v99
	v_mov_b32_e32 v103, v100
	v_mov_b32_e32 v99, v101
	v_add_f32_e32 v98, v102, v98
	v_add_f32_e32 v99, v103, v99
	s_nop 0
	v_add_f32_e32 v98, v98, v99
	v_add_f32_e32 v97, v97, v98
.LBB0_864:
	s_or_b64 exec, exec, s[68:69]
	ds_bpermute_b32 v98, v153, v97
	s_waitcnt lgkmcnt(0)
	v_add_f32_e32 v97, v97, v98
	ds_bpermute_b32 v100, v154, v97
	v_mov_b64_e32 v[98:99], s[50:51]
	s_waitcnt lgkmcnt(0)
	v_add_f32_e32 v97, v97, v100
	v_fmamk_f32 v97, v97, 0x3a000000, v158
	v_rsq_f32_e32 v100, v97
	v_mad_i64_i32 v[96:97], s[68:69], v96, s82, v[98:99]
	v_lshl_add_u64 v[96:97], v[146:147], 1, v[96:97]
	v_mul_f32_e32 v94, v94, v100
	v_mul_f32_e32 v95, v95, v100
	v_mul_f32_e32 v92, v92, v100
	v_mul_f32_e32 v93, v93, v100
	v_mul_f32_e32 v90, v90, v100
	v_mul_f32_e32 v91, v91, v100
	v_mul_f32_e32 v88, v88, v100
	v_mul_f32_e32 v89, v89, v100
	v_mul_f32_e32 v98, v86, v100
	v_mul_f32_e32 v99, v87, v100
	v_cvt_pk_bf16_f32 v86, v92, v93
	v_cvt_pk_bf16_f32 v87, v94, v95
	v_cvt_pk_bf16_f32 v88, v88, v89
	v_cvt_pk_bf16_f32 v89, v90, v91
	global_store_dwordx4 v[96:97], v[86:89], off
	v_mul_f32_e32 v84, v84, v100
	v_mul_f32_e32 v85, v85, v100
	s_nop 0
	v_mul_f32_e32 v86, v82, v100
	v_mul_f32_e32 v87, v83, v100
	v_mul_f32_e32 v82, v80, v100
	v_mul_f32_e32 v83, v81, v100
	v_cvt_pk_bf16_f32 v80, v84, v85
	v_cvt_pk_bf16_f32 v81, v98, v99
	v_cvt_pk_bf16_f32 v82, v82, v83
	v_cvt_pk_bf16_f32 v83, v86, v87
	global_store_dwordx4 v[96:97], v[80:83], off offset:256
	s_nop 1
	v_or_b32_e32 v80, 48, v148
	v_ashrrev_i32_e32 v81, 31, v80
	v_lshlrev_b64 v[82:83], 7, v[80:81]
	v_lshl_add_u64 v[82:83], s[52:53], 0, v[82:83]
	v_mov_b32_e32 v81, 0
	v_lshl_add_u64 v[82:83], v[136:137], 4, v[82:83]
	s_and_saveexec_b64 s[68:69], s[8:9]
	s_cbranch_execz .LBB0_866
	global_load_dwordx4 v[84:87], v[82:83], off
	s_waitcnt vmcnt(0)
	v_mov_b32_e32 v88, v85
	v_mov_b32_e32 v89, v86
	v_mov_b32_e32 v85, v87
	v_add_f32_e32 v84, v88, v84
	v_add_f32_e32 v85, v89, v85
	s_nop 0
	v_add_f32_e32 v81, v84, v85
	v_add_f32_e32 v81, 0, v81
.LBB0_866:
	s_or_b64 exec, exec, s[68:69]
	s_and_saveexec_b64 s[68:69], s[10:11]
	s_cbranch_execz .LBB0_868
	global_load_dwordx4 v[82:85], v[82:83], off offset:64
	s_waitcnt vmcnt(0)
	v_mov_b32_e32 v86, v83
	v_mov_b32_e32 v87, v84
	v_mov_b32_e32 v83, v85
	v_add_f32_e32 v82, v86, v82
	v_add_f32_e32 v83, v87, v83
	s_nop 0
	v_add_f32_e32 v82, v82, v83
	v_add_f32_e32 v81, v81, v82
.LBB0_868:
	s_or_b64 exec, exec, s[68:69]
	ds_bpermute_b32 v82, v153, v81
	s_waitcnt lgkmcnt(0)
	v_add_f32_e32 v81, v81, v82
	ds_bpermute_b32 v84, v154, v81
	v_mov_b64_e32 v[82:83], s[50:51]
	s_waitcnt lgkmcnt(0)
	v_add_f32_e32 v81, v81, v84
	v_fmamk_f32 v81, v81, 0x3a000000, v158
	v_rsq_f32_e32 v84, v81
	v_mad_i64_i32 v[80:81], s[68:69], v80, s82, v[82:83]
	v_lshl_add_u64 v[80:81], v[146:147], 1, v[80:81]
	v_mul_f32_e32 v78, v78, v84
	v_mul_f32_e32 v79, v79, v84
	v_mul_f32_e32 v76, v76, v84
	v_mul_f32_e32 v77, v77, v84
	v_mul_f32_e32 v74, v74, v84
	v_mul_f32_e32 v75, v75, v84
	v_mul_f32_e32 v72, v72, v84
	v_mul_f32_e32 v73, v73, v84
	v_mul_f32_e32 v82, v70, v84
	v_mul_f32_e32 v83, v71, v84
	v_cvt_pk_bf16_f32 v70, v76, v77
	v_cvt_pk_bf16_f32 v71, v78, v79
	v_cvt_pk_bf16_f32 v72, v72, v73
	v_cvt_pk_bf16_f32 v73, v74, v75
	global_store_dwordx4 v[80:81], v[70:73], off
	v_mul_f32_e32 v68, v68, v84
	v_mul_f32_e32 v69, v69, v84
	s_nop 0
	v_mul_f32_e32 v70, v66, v84
	v_mul_f32_e32 v71, v67, v84
	v_mul_f32_e32 v66, v64, v84
	v_mul_f32_e32 v67, v65, v84
	v_cvt_pk_bf16_f32 v64, v68, v69
	v_cvt_pk_bf16_f32 v65, v82, v83
	v_cvt_pk_bf16_f32 v66, v66, v67
	v_cvt_pk_bf16_f32 v67, v70, v71
	global_store_dwordx4 v[80:81], v[64:67], off offset:256
	s_nop 1
	v_add_u32_e32 v64, 0x80, v148
	v_ashrrev_i32_e32 v65, 31, v64
	v_lshlrev_b64 v[66:67], 7, v[64:65]
	v_lshl_add_u64 v[66:67], s[52:53], 0, v[66:67]
	v_mov_b32_e32 v65, 0
	v_lshl_add_u64 v[66:67], v[136:137], 4, v[66:67]
	s_and_saveexec_b64 s[68:69], s[8:9]
	s_cbranch_execz .LBB0_870
	global_load_dwordx4 v[68:71], v[66:67], off
	s_waitcnt vmcnt(0)
	v_mov_b32_e32 v72, v69
	v_mov_b32_e32 v73, v70
	v_mov_b32_e32 v69, v71
	v_add_f32_e32 v68, v72, v68
	v_add_f32_e32 v69, v73, v69
	s_nop 0
	v_add_f32_e32 v65, v68, v69
	v_add_f32_e32 v65, 0, v65
.LBB0_870:
	s_or_b64 exec, exec, s[68:69]
	s_and_saveexec_b64 s[68:69], s[10:11]
	s_cbranch_execz .LBB0_872
	global_load_dwordx4 v[66:69], v[66:67], off offset:64
	s_waitcnt vmcnt(0)
	v_mov_b32_e32 v70, v67
	v_mov_b32_e32 v71, v68
	v_mov_b32_e32 v67, v69
	v_add_f32_e32 v66, v70, v66
	v_add_f32_e32 v67, v71, v67
	s_nop 0
	v_add_f32_e32 v66, v66, v67
	v_add_f32_e32 v65, v65, v66
.LBB0_872:
	s_or_b64 exec, exec, s[68:69]
	ds_bpermute_b32 v66, v153, v65
	s_waitcnt lgkmcnt(0)
	v_add_f32_e32 v65, v65, v66
	ds_bpermute_b32 v68, v154, v65
	v_mov_b64_e32 v[66:67], s[50:51]
	s_waitcnt lgkmcnt(0)
	v_add_f32_e32 v65, v65, v68
	v_fmamk_f32 v65, v65, 0x3a000000, v158
	v_rsq_f32_e32 v68, v65
	v_mad_i64_i32 v[64:65], s[68:69], v64, s82, v[66:67]
	v_lshl_add_u64 v[64:65], v[146:147], 1, v[64:65]
	v_mul_f32_e32 v62, v62, v68
	v_mul_f32_e32 v63, v63, v68
	v_mul_f32_e32 v60, v60, v68
	v_mul_f32_e32 v61, v61, v68
	v_mul_f32_e32 v58, v58, v68
	v_mul_f32_e32 v59, v59, v68
	v_mul_f32_e32 v56, v56, v68
	v_mul_f32_e32 v57, v57, v68
	v_mul_f32_e32 v66, v54, v68
	v_mul_f32_e32 v67, v55, v68
	v_cvt_pk_bf16_f32 v54, v60, v61
	v_cvt_pk_bf16_f32 v55, v62, v63
	v_cvt_pk_bf16_f32 v56, v56, v57
	v_cvt_pk_bf16_f32 v57, v58, v59
	global_store_dwordx4 v[64:65], v[54:57], off
	v_mul_f32_e32 v52, v52, v68
	v_mul_f32_e32 v53, v53, v68
	s_nop 0
	v_mul_f32_e32 v54, v50, v68
	v_mul_f32_e32 v55, v51, v68
	v_mul_f32_e32 v50, v48, v68
	v_mul_f32_e32 v51, v49, v68
	v_cvt_pk_bf16_f32 v48, v52, v53
	v_cvt_pk_bf16_f32 v49, v66, v67
	v_cvt_pk_bf16_f32 v50, v50, v51
	v_cvt_pk_bf16_f32 v51, v54, v55
	global_store_dwordx4 v[64:65], v[48:51], off offset:256
	s_nop 1
	v_add_u32_e32 v48, 0x90, v148
	v_ashrrev_i32_e32 v49, 31, v48
	v_lshlrev_b64 v[50:51], 7, v[48:49]
	v_lshl_add_u64 v[50:51], s[52:53], 0, v[50:51]
	v_mov_b32_e32 v49, 0
	v_lshl_add_u64 v[50:51], v[136:137], 4, v[50:51]
	s_and_saveexec_b64 s[68:69], s[8:9]
	s_cbranch_execz .LBB0_874
	global_load_dwordx4 v[52:55], v[50:51], off
	s_waitcnt vmcnt(0)
	v_mov_b32_e32 v56, v53
	v_mov_b32_e32 v57, v54
	v_mov_b32_e32 v53, v55
	v_add_f32_e32 v52, v56, v52
	v_add_f32_e32 v53, v57, v53
	s_nop 0
	v_add_f32_e32 v49, v52, v53
	v_add_f32_e32 v49, 0, v49
.LBB0_874:
	s_or_b64 exec, exec, s[68:69]
	s_and_saveexec_b64 s[68:69], s[10:11]
	s_cbranch_execz .LBB0_876
	global_load_dwordx4 v[50:53], v[50:51], off offset:64
	s_waitcnt vmcnt(0)
	v_mov_b32_e32 v54, v51
	v_mov_b32_e32 v55, v52
	v_mov_b32_e32 v51, v53
	v_add_f32_e32 v50, v54, v50
	v_add_f32_e32 v51, v55, v51
	s_nop 0
	v_add_f32_e32 v50, v50, v51
	v_add_f32_e32 v49, v49, v50
.LBB0_876:
	s_or_b64 exec, exec, s[68:69]
	ds_bpermute_b32 v50, v153, v49
	s_waitcnt lgkmcnt(0)
	v_add_f32_e32 v49, v49, v50
	ds_bpermute_b32 v52, v154, v49
	v_mov_b64_e32 v[50:51], s[50:51]
	s_waitcnt lgkmcnt(0)
	v_add_f32_e32 v49, v49, v52
	v_fmamk_f32 v49, v49, 0x3a000000, v158
	v_rsq_f32_e32 v52, v49
	v_mad_i64_i32 v[48:49], s[68:69], v48, s82, v[50:51]
	v_lshl_add_u64 v[48:49], v[146:147], 1, v[48:49]
	v_mul_f32_e32 v46, v46, v52
	v_mul_f32_e32 v47, v47, v52
	v_mul_f32_e32 v44, v44, v52
	v_mul_f32_e32 v45, v45, v52
	v_mul_f32_e32 v42, v42, v52
	v_mul_f32_e32 v43, v43, v52
	v_mul_f32_e32 v40, v40, v52
	v_mul_f32_e32 v41, v41, v52
	v_mul_f32_e32 v50, v38, v52
	v_mul_f32_e32 v51, v39, v52
	v_cvt_pk_bf16_f32 v38, v44, v45
	v_cvt_pk_bf16_f32 v39, v46, v47
	v_cvt_pk_bf16_f32 v40, v40, v41
	v_cvt_pk_bf16_f32 v41, v42, v43
	global_store_dwordx4 v[48:49], v[38:41], off
	v_mul_f32_e32 v36, v36, v52
	v_mul_f32_e32 v37, v37, v52
	s_nop 0
	v_mul_f32_e32 v38, v34, v52
	v_mul_f32_e32 v39, v35, v52
	v_mul_f32_e32 v34, v32, v52
	v_mul_f32_e32 v35, v33, v52
	v_cvt_pk_bf16_f32 v32, v36, v37
	v_cvt_pk_bf16_f32 v33, v50, v51
	v_cvt_pk_bf16_f32 v34, v34, v35
	v_cvt_pk_bf16_f32 v35, v38, v39
	global_store_dwordx4 v[48:49], v[32:35], off offset:256
	s_nop 1
	v_add_u32_e32 v32, 0xa0, v148
	v_ashrrev_i32_e32 v33, 31, v32
	v_lshlrev_b64 v[34:35], 7, v[32:33]
	v_lshl_add_u64 v[34:35], s[52:53], 0, v[34:35]
	v_mov_b32_e32 v33, 0
	v_lshl_add_u64 v[34:35], v[136:137], 4, v[34:35]
	s_and_saveexec_b64 s[68:69], s[8:9]
	s_cbranch_execz .LBB0_878
	global_load_dwordx4 v[36:39], v[34:35], off
	s_waitcnt vmcnt(0)
	v_mov_b32_e32 v40, v37
	v_mov_b32_e32 v41, v38
	v_mov_b32_e32 v37, v39
	v_add_f32_e32 v36, v40, v36
	v_add_f32_e32 v37, v41, v37
	s_nop 0
	v_add_f32_e32 v33, v36, v37
	v_add_f32_e32 v33, 0, v33
.LBB0_878:
	s_or_b64 exec, exec, s[68:69]
	s_and_saveexec_b64 s[68:69], s[10:11]
	s_cbranch_execz .LBB0_880
	global_load_dwordx4 v[34:37], v[34:35], off offset:64
	s_waitcnt vmcnt(0)
	v_mov_b32_e32 v38, v35
	v_mov_b32_e32 v39, v36
	v_mov_b32_e32 v35, v37
	v_add_f32_e32 v34, v38, v34
	v_add_f32_e32 v35, v39, v35
	s_nop 0
	v_add_f32_e32 v34, v34, v35
	v_add_f32_e32 v33, v33, v34
.LBB0_880:
	s_or_b64 exec, exec, s[68:69]
	ds_bpermute_b32 v34, v153, v33
	s_waitcnt lgkmcnt(0)
	v_add_f32_e32 v33, v33, v34
	ds_bpermute_b32 v36, v154, v33
	v_mov_b64_e32 v[34:35], s[50:51]
	s_waitcnt lgkmcnt(0)
	v_add_f32_e32 v33, v33, v36
	v_fmamk_f32 v33, v33, 0x3a000000, v158
	v_rsq_f32_e32 v36, v33
	v_mad_i64_i32 v[32:33], s[68:69], v32, s82, v[34:35]
	v_lshl_add_u64 v[32:33], v[146:147], 1, v[32:33]
	v_mul_f32_e32 v30, v30, v36
	v_mul_f32_e32 v31, v31, v36
	v_mul_f32_e32 v28, v28, v36
	v_mul_f32_e32 v29, v29, v36
	v_mul_f32_e32 v26, v26, v36
	v_mul_f32_e32 v27, v27, v36
	v_mul_f32_e32 v24, v24, v36
	v_mul_f32_e32 v25, v25, v36
	v_mul_f32_e32 v34, v22, v36
	v_mul_f32_e32 v35, v23, v36
	v_cvt_pk_bf16_f32 v22, v28, v29
	v_cvt_pk_bf16_f32 v23, v30, v31
	v_cvt_pk_bf16_f32 v24, v24, v25
	v_cvt_pk_bf16_f32 v25, v26, v27
	global_store_dwordx4 v[32:33], v[22:25], off
	v_mul_f32_e32 v20, v20, v36
	v_mul_f32_e32 v21, v21, v36
	s_nop 0
	v_mul_f32_e32 v22, v18, v36
	v_mul_f32_e32 v23, v19, v36
	v_mul_f32_e32 v18, v16, v36
	v_mul_f32_e32 v19, v17, v36
	v_cvt_pk_bf16_f32 v16, v20, v21
	v_cvt_pk_bf16_f32 v17, v34, v35
	v_cvt_pk_bf16_f32 v18, v18, v19
	v_cvt_pk_bf16_f32 v19, v22, v23
	global_store_dwordx4 v[32:33], v[16:19], off offset:256
	s_nop 1
	v_add_u32_e32 v16, 0xb0, v148
	v_ashrrev_i32_e32 v17, 31, v16
	v_lshlrev_b64 v[18:19], 7, v[16:17]
	v_lshl_add_u64 v[18:19], s[52:53], 0, v[18:19]
	v_mov_b32_e32 v17, 0
	v_lshl_add_u64 v[18:19], v[136:137], 4, v[18:19]
	s_and_saveexec_b64 s[68:69], s[8:9]
	s_cbranch_execz .LBB0_882
	global_load_dwordx4 v[20:23], v[18:19], off
	s_waitcnt vmcnt(0)
	v_mov_b32_e32 v24, v21
	v_mov_b32_e32 v25, v22
	v_mov_b32_e32 v21, v23
	v_add_f32_e32 v20, v24, v20
	v_add_f32_e32 v21, v25, v21
	s_nop 0
	v_add_f32_e32 v17, v20, v21
	v_add_f32_e32 v17, 0, v17
.LBB0_882:
	s_or_b64 exec, exec, s[68:69]
	s_and_saveexec_b64 s[68:69], s[10:11]
	s_cbranch_execz .LBB0_884
	global_load_dwordx4 v[18:21], v[18:19], off offset:64
	s_waitcnt vmcnt(0)
	v_mov_b32_e32 v22, v19
	v_mov_b32_e32 v23, v20
	v_mov_b32_e32 v19, v21
	v_add_f32_e32 v18, v22, v18
	v_add_f32_e32 v19, v23, v19
	s_nop 0
	v_add_f32_e32 v18, v18, v19
	v_add_f32_e32 v17, v17, v18
.LBB0_884:
	s_or_b64 exec, exec, s[68:69]
	ds_bpermute_b32 v18, v153, v17
	s_andn2_b64 vcc, exec, s[12:13]
	s_mov_b64 s[12:13], -1
	s_waitcnt lgkmcnt(0)
	v_add_f32_e32 v17, v17, v18
	ds_bpermute_b32 v20, v154, v17
	v_mov_b64_e32 v[18:19], s[50:51]
	s_waitcnt lgkmcnt(0)
	v_add_f32_e32 v17, v17, v20
	v_fmamk_f32 v17, v17, 0x3a000000, v158
	v_rsq_f32_e32 v20, v17
	v_mad_i64_i32 v[16:17], s[68:69], v16, s82, v[18:19]
	v_lshl_add_u64 v[16:17], v[146:147], 1, v[16:17]
	v_mul_f32_e32 v14, v14, v20
	v_mul_f32_e32 v15, v15, v20
	v_mul_f32_e32 v12, v12, v20
	v_mul_f32_e32 v13, v13, v20
	v_mul_f32_e32 v10, v10, v20
	v_mul_f32_e32 v11, v11, v20
	v_mul_f32_e32 v8, v8, v20
	v_mul_f32_e32 v9, v9, v20
	v_mul_f32_e32 v18, v6, v20
	v_mul_f32_e32 v19, v7, v20
	v_cvt_pk_bf16_f32 v6, v12, v13
	v_cvt_pk_bf16_f32 v7, v14, v15
	v_cvt_pk_bf16_f32 v8, v8, v9
	v_cvt_pk_bf16_f32 v9, v10, v11
	global_store_dwordx4 v[16:17], v[6:9], off
	v_mul_f32_e32 v4, v4, v20
	v_mul_f32_e32 v5, v5, v20
	s_nop 0
	v_mul_f32_e32 v6, v2, v20
	v_mul_f32_e32 v7, v3, v20
	v_mul_f32_e32 v2, v0, v20
	v_mul_f32_e32 v3, v1, v20
	v_cvt_pk_bf16_f32 v0, v4, v5
	v_cvt_pk_bf16_f32 v1, v18, v19
	v_cvt_pk_bf16_f32 v2, v2, v3
	v_cvt_pk_bf16_f32 v3, v6, v7
	global_store_dwordx4 v[16:17], v[0:3], off offset:256
	s_cbranch_vccnz .LBB0_845
	s_andn2_b64 vcc, exec, s[16:17]
	s_cbranch_vccnz .LBB0_844
	s_barrier
	s_branch .LBB0_844

.LBB0_949:
	v_lshl_add_u32 v130, s2, 8, v142
	v_ashrrev_i32_e32 v131, 31, v130
	v_ashrrev_i32_e32 v128, 4, v140
	v_lshlrev_b64 v[132:133], 7, v[130:131]
	v_ashrrev_i32_e32 v129, 31, v128
	v_lshl_add_u64 v[132:133], s[52:53], 0, v[132:133]
	v_cmp_gt_i32_e32 vcc, 8, v128
	v_mov_b32_e32 v135, 0
	v_lshl_add_u64 v[132:133], v[128:129], 4, v[132:133]
	s_and_saveexec_b64 s[8:9], vcc
	s_cbranch_execz .LBB0_951
	global_load_dwordx4 v[134:137], v[132:133], off
	s_waitcnt vmcnt(0)
	v_mov_b32_e32 v138, v135
	v_mov_b32_e32 v139, v136
	v_mov_b32_e32 v135, v137
	v_add_f32_e32 v134, v138, v134
	v_add_f32_e32 v135, v139, v135
	s_nop 0
	v_add_f32_e32 v131, v134, v135
	v_add_f32_e32 v135, 0, v131
.LBB0_951:
	s_or_b64 exec, exec, s[8:9]
	v_cmp_gt_i32_e64 s[8:9], 4, v128
	s_and_saveexec_b64 s[10:11], s[8:9]
	s_cbranch_execz .LBB0_953
	global_load_dwordx4 v[136:139], v[132:133], off offset:64
	s_waitcnt vmcnt(0)
	v_mov_b32_e32 v132, v137
	v_mov_b32_e32 v133, v138
	v_mov_b32_e32 v137, v139
	v_add_f32_e32 v132, v132, v136
	v_add_f32_e32 v133, v133, v137
	s_nop 0
	v_add_f32_e32 v131, v132, v133
	v_add_f32_e32 v135, v135, v131
.LBB0_953:
	s_or_b64 exec, exec, s[10:11]
	v_lshlrev_b32_e32 v132, 6, v128
	v_bitop3_b32 v131, v132, 64, v141 bitop3:0x36
	ds_bpermute_b32 v133, v131, v135
	v_readlane_b32 s3, v255, 10
	v_mov_b32_e32 v139, 0x358637bd
	v_mov_b64_e32 v[136:137], s[50:51]
	v_lshl_add_u32 v138, v128, 3, s3
	s_movk_i32 s3, 0x80
	v_bitop3_b32 v134, v132, s3, v141 bitop3:0x36
	s_waitcnt lgkmcnt(0)
	v_add_f32_e32 v133, v135, v133
	ds_bpermute_b32 v135, v134, v133
	v_add_u32_e32 v132, 0xc00, v138
	s_movk_i32 s3, 0x1a00
	v_mad_i64_i32 v[136:137], s[6:7], v130, s3, v[136:137]
	s_waitcnt lgkmcnt(0)
	v_add_f32_e32 v133, v133, v135
	v_fmac_f32_e32 v139, 0x3a000000, v133
	v_rsq_f32_e32 v138, v139
	v_ashrrev_i32_e32 v133, 31, v132
	v_lshl_add_u64 v[136:137], v[132:133], 1, v[136:137]
	v_mul_f32_e32 v126, v126, v138
	v_mul_f32_e32 v127, v127, v138
	v_mul_f32_e32 v124, v124, v138
	v_mul_f32_e32 v125, v125, v138
	v_mul_f32_e32 v140, v122, v138
	v_mul_f32_e32 v141, v123, v138
	v_mul_f32_e32 v122, v120, v138
	v_mul_f32_e32 v123, v121, v138
	v_cvt_pk_bf16_f32 v120, v124, v125
	v_cvt_pk_bf16_f32 v121, v126, v127
	v_cvt_pk_bf16_f32 v122, v122, v123
	v_cvt_pk_bf16_f32 v123, v140, v141
	global_store_dwordx4 v[136:137], v[120:123], off
	v_mul_f32_e32 v118, v118, v138
	v_mul_f32_e32 v119, v119, v138
	v_mul_f32_e32 v116, v116, v138
	v_mul_f32_e32 v117, v117, v138
	v_mul_f32_e32 v120, v114, v138
	v_mul_f32_e32 v121, v115, v138
	v_mul_f32_e32 v114, v112, v138
	v_mul_f32_e32 v115, v113, v138
	v_cvt_pk_bf16_f32 v112, v116, v117
	v_cvt_pk_bf16_f32 v113, v118, v119
	v_cvt_pk_bf16_f32 v114, v114, v115
	v_cvt_pk_bf16_f32 v115, v120, v121
	global_store_dwordx4 v[136:137], v[112:115], off offset:256
	s_nop 1
	v_or_b32_e32 v112, 16, v130
	v_ashrrev_i32_e32 v113, 31, v112
	v_lshlrev_b64 v[114:115], 7, v[112:113]
	v_lshl_add_u64 v[114:115], s[52:53], 0, v[114:115]
	v_mov_b32_e32 v113, 0
	v_lshl_add_u64 v[114:115], v[128:129], 4, v[114:115]
	s_and_saveexec_b64 s[10:11], vcc
	s_cbranch_execz .LBB0_955
	global_load_dwordx4 v[116:119], v[114:115], off
	s_waitcnt vmcnt(0)
	v_mov_b32_e32 v120, v117
	v_mov_b32_e32 v121, v118
	v_mov_b32_e32 v117, v119
	v_add_f32_e32 v116, v120, v116
	v_add_f32_e32 v117, v121, v117
	s_nop 0
	v_add_f32_e32 v113, v116, v117
	v_add_f32_e32 v113, 0, v113
.LBB0_955:
	s_or_b64 exec, exec, s[10:11]
	s_and_saveexec_b64 s[10:11], s[8:9]
	s_cbranch_execz .LBB0_957
	global_load_dwordx4 v[114:117], v[114:115], off offset:64
	s_waitcnt vmcnt(0)
	v_mov_b32_e32 v118, v115
	v_mov_b32_e32 v119, v116
	v_mov_b32_e32 v115, v117
	v_add_f32_e32 v114, v118, v114
	v_add_f32_e32 v115, v119, v115
	s_nop 0
	v_add_f32_e32 v114, v114, v115
	v_add_f32_e32 v113, v113, v114
.LBB0_957:
	s_or_b64 exec, exec, s[10:11]
	ds_bpermute_b32 v114, v131, v113
	v_mov_b32_e32 v117, 0x358637bd
	s_waitcnt lgkmcnt(0)
	v_add_f32_e32 v113, v113, v114
	ds_bpermute_b32 v116, v134, v113
	v_mov_b64_e32 v[114:115], s[50:51]
	s_waitcnt lgkmcnt(0)
	v_add_f32_e32 v113, v113, v116
	v_fmac_f32_e32 v117, 0x3a000000, v113
	v_rsq_f32_e32 v116, v117
	v_mad_i64_i32 v[112:113], s[6:7], v112, s3, v[114:115]
	v_lshl_add_u64 v[112:113], v[132:133], 1, v[112:113]
	v_mul_f32_e32 v110, v110, v116
	v_mul_f32_e32 v111, v111, v116
	v_mul_f32_e32 v108, v108, v116
	v_mul_f32_e32 v109, v109, v116
	v_mul_f32_e32 v114, v106, v116
	v_mul_f32_e32 v115, v107, v116
	v_mul_f32_e32 v106, v104, v116
	v_mul_f32_e32 v107, v105, v116
	v_cvt_pk_bf16_f32 v104, v108, v109
	v_cvt_pk_bf16_f32 v105, v110, v111
	v_cvt_pk_bf16_f32 v106, v106, v107
	v_cvt_pk_bf16_f32 v107, v114, v115
	global_store_dwordx4 v[112:113], v[104:107], off
	v_mul_f32_e32 v102, v102, v116
	v_mul_f32_e32 v103, v103, v116
	v_mul_f32_e32 v100, v100, v116
	v_mul_f32_e32 v101, v101, v116
	v_mul_f32_e32 v104, v98, v116
	v_mul_f32_e32 v105, v99, v116
	v_mul_f32_e32 v98, v96, v116
	v_mul_f32_e32 v99, v97, v116
	v_cvt_pk_bf16_f32 v96, v100, v101
	v_cvt_pk_bf16_f32 v97, v102, v103
	v_cvt_pk_bf16_f32 v98, v98, v99
	v_cvt_pk_bf16_f32 v99, v104, v105
	global_store_dwordx4 v[112:113], v[96:99], off offset:256
	s_nop 1
	v_or_b32_e32 v96, 32, v130
	v_ashrrev_i32_e32 v97, 31, v96
	v_lshlrev_b64 v[98:99], 7, v[96:97]
	v_lshl_add_u64 v[98:99], s[52:53], 0, v[98:99]
	v_mov_b32_e32 v97, 0
	v_lshl_add_u64 v[98:99], v[128:129], 4, v[98:99]
	s_and_saveexec_b64 s[10:11], vcc
	s_cbranch_execz .LBB0_959
	global_load_dwordx4 v[100:103], v[98:99], off
	s_waitcnt vmcnt(0)
	v_mov_b32_e32 v104, v101
	v_mov_b32_e32 v105, v102
	v_mov_b32_e32 v101, v103
	v_add_f32_e32 v100, v104, v100
	v_add_f32_e32 v101, v105, v101
	s_nop 0
	v_add_f32_e32 v97, v100, v101
	v_add_f32_e32 v97, 0, v97
.LBB0_959:
	s_or_b64 exec, exec, s[10:11]
	s_and_saveexec_b64 s[10:11], s[8:9]
	s_cbranch_execz .LBB0_961
	global_load_dwordx4 v[98:101], v[98:99], off offset:64
	s_waitcnt vmcnt(0)
	v_mov_b32_e32 v102, v99
	v_mov_b32_e32 v103, v100
	v_mov_b32_e32 v99, v101
	v_add_f32_e32 v98, v102, v98
	v_add_f32_e32 v99, v103, v99
	s_nop 0
	v_add_f32_e32 v98, v98, v99
	v_add_f32_e32 v97, v97, v98
.LBB0_961:
	s_or_b64 exec, exec, s[10:11]
	ds_bpermute_b32 v98, v131, v97
	v_mov_b32_e32 v101, 0x358637bd
	s_waitcnt lgkmcnt(0)
	v_add_f32_e32 v97, v97, v98
	ds_bpermute_b32 v100, v134, v97
	v_mov_b64_e32 v[98:99], s[50:51]
	s_waitcnt lgkmcnt(0)
	v_add_f32_e32 v97, v97, v100
	v_fmac_f32_e32 v101, 0x3a000000, v97
	v_rsq_f32_e32 v100, v101
	v_mad_i64_i32 v[96:97], s[6:7], v96, s3, v[98:99]
	v_lshl_add_u64 v[96:97], v[132:133], 1, v[96:97]
	v_mul_f32_e32 v94, v94, v100
	v_mul_f32_e32 v95, v95, v100
	v_mul_f32_e32 v92, v92, v100
	v_mul_f32_e32 v93, v93, v100
	v_mul_f32_e32 v98, v90, v100
	v_mul_f32_e32 v99, v91, v100
	v_mul_f32_e32 v90, v88, v100
	v_mul_f32_e32 v91, v89, v100
	v_cvt_pk_bf16_f32 v88, v92, v93
	v_cvt_pk_bf16_f32 v89, v94, v95
	v_cvt_pk_bf16_f32 v90, v90, v91
	v_cvt_pk_bf16_f32 v91, v98, v99
	global_store_dwordx4 v[96:97], v[88:91], off
	v_mul_f32_e32 v86, v86, v100
	v_mul_f32_e32 v87, v87, v100
	v_mul_f32_e32 v84, v84, v100
	v_mul_f32_e32 v85, v85, v100
	v_mul_f32_e32 v88, v82, v100
	v_mul_f32_e32 v89, v83, v100
	v_mul_f32_e32 v82, v80, v100
	v_mul_f32_e32 v83, v81, v100
	v_cvt_pk_bf16_f32 v80, v84, v85
	v_cvt_pk_bf16_f32 v81, v86, v87
	v_cvt_pk_bf16_f32 v82, v82, v83
	v_cvt_pk_bf16_f32 v83, v88, v89
	global_store_dwordx4 v[96:97], v[80:83], off offset:256
	s_nop 1
	v_or_b32_e32 v80, 48, v130
	v_ashrrev_i32_e32 v81, 31, v80
	v_lshlrev_b64 v[82:83], 7, v[80:81]
	v_lshl_add_u64 v[82:83], s[52:53], 0, v[82:83]
	v_mov_b32_e32 v81, 0
	v_lshl_add_u64 v[82:83], v[128:129], 4, v[82:83]
	s_and_saveexec_b64 s[10:11], vcc
	s_cbranch_execz .LBB0_963
	global_load_dwordx4 v[84:87], v[82:83], off
	s_waitcnt vmcnt(0)
	v_mov_b32_e32 v88, v85
	v_mov_b32_e32 v89, v86
	v_mov_b32_e32 v85, v87
	v_add_f32_e32 v84, v88, v84
	v_add_f32_e32 v85, v89, v85
	s_nop 0
	v_add_f32_e32 v81, v84, v85
	v_add_f32_e32 v81, 0, v81
.LBB0_963:
	s_or_b64 exec, exec, s[10:11]
	s_and_saveexec_b64 s[10:11], s[8:9]
	s_cbranch_execz .LBB0_965
	global_load_dwordx4 v[82:85], v[82:83], off offset:64
	s_waitcnt vmcnt(0)
	v_mov_b32_e32 v86, v83
	v_mov_b32_e32 v87, v84
	v_mov_b32_e32 v83, v85
	v_add_f32_e32 v82, v86, v82
	v_add_f32_e32 v83, v87, v83
	s_nop 0
	v_add_f32_e32 v82, v82, v83
	v_add_f32_e32 v81, v81, v82
.LBB0_965:
	s_or_b64 exec, exec, s[10:11]
	ds_bpermute_b32 v82, v131, v81
	v_mov_b32_e32 v85, 0x358637bd
	s_waitcnt lgkmcnt(0)
	v_add_f32_e32 v81, v81, v82
	ds_bpermute_b32 v84, v134, v81
	v_mov_b64_e32 v[82:83], s[50:51]
	s_waitcnt lgkmcnt(0)
	v_add_f32_e32 v81, v81, v84
	v_fmac_f32_e32 v85, 0x3a000000, v81
	v_rsq_f32_e32 v84, v85
	v_mad_i64_i32 v[80:81], s[6:7], v80, s3, v[82:83]
	v_lshl_add_u64 v[80:81], v[132:133], 1, v[80:81]
	v_mul_f32_e32 v78, v78, v84
	v_mul_f32_e32 v79, v79, v84
	v_mul_f32_e32 v76, v76, v84
	v_mul_f32_e32 v77, v77, v84
	v_mul_f32_e32 v82, v74, v84
	v_mul_f32_e32 v83, v75, v84
	v_mul_f32_e32 v74, v72, v84
	v_mul_f32_e32 v75, v73, v84
	v_cvt_pk_bf16_f32 v72, v76, v77
	v_cvt_pk_bf16_f32 v73, v78, v79
	v_cvt_pk_bf16_f32 v74, v74, v75
	v_cvt_pk_bf16_f32 v75, v82, v83
	global_store_dwordx4 v[80:81], v[72:75], off
	v_mul_f32_e32 v70, v70, v84
	v_mul_f32_e32 v71, v71, v84
	v_mul_f32_e32 v68, v68, v84
	v_mul_f32_e32 v69, v69, v84
	v_mul_f32_e32 v72, v66, v84
	v_mul_f32_e32 v73, v67, v84
	v_mul_f32_e32 v66, v64, v84
	v_mul_f32_e32 v67, v65, v84
	v_cvt_pk_bf16_f32 v64, v68, v69
	v_cvt_pk_bf16_f32 v65, v70, v71
	v_cvt_pk_bf16_f32 v66, v66, v67
	v_cvt_pk_bf16_f32 v67, v72, v73
	global_store_dwordx4 v[80:81], v[64:67], off offset:256
	s_nop 1
	v_add_u32_e32 v64, 0x80, v130
	v_ashrrev_i32_e32 v65, 31, v64
	v_lshlrev_b64 v[66:67], 7, v[64:65]
	v_lshl_add_u64 v[66:67], s[52:53], 0, v[66:67]
	v_mov_b32_e32 v65, 0
	v_lshl_add_u64 v[66:67], v[128:129], 4, v[66:67]
	s_and_saveexec_b64 s[10:11], vcc
	s_cbranch_execz .LBB0_967
	global_load_dwordx4 v[68:71], v[66:67], off
	s_waitcnt vmcnt(0)
	v_mov_b32_e32 v72, v69
	v_mov_b32_e32 v73, v70
	v_mov_b32_e32 v69, v71
	v_add_f32_e32 v68, v72, v68
	v_add_f32_e32 v69, v73, v69
	s_nop 0
	v_add_f32_e32 v65, v68, v69
	v_add_f32_e32 v65, 0, v65
.LBB0_967:
	s_or_b64 exec, exec, s[10:11]
	s_and_saveexec_b64 s[10:11], s[8:9]
	s_cbranch_execz .LBB0_969
	global_load_dwordx4 v[66:69], v[66:67], off offset:64
	s_waitcnt vmcnt(0)
	v_mov_b32_e32 v70, v67
	v_mov_b32_e32 v71, v68
	v_mov_b32_e32 v67, v69
	v_add_f32_e32 v66, v70, v66
	v_add_f32_e32 v67, v71, v67
	s_nop 0
	v_add_f32_e32 v66, v66, v67
	v_add_f32_e32 v65, v65, v66
.LBB0_969:
	s_or_b64 exec, exec, s[10:11]
	ds_bpermute_b32 v66, v131, v65
	v_mov_b32_e32 v69, 0x358637bd
	s_waitcnt lgkmcnt(0)
	v_add_f32_e32 v65, v65, v66
	ds_bpermute_b32 v68, v134, v65
	v_mov_b64_e32 v[66:67], s[50:51]
	s_waitcnt lgkmcnt(0)
	v_add_f32_e32 v65, v65, v68
	v_fmac_f32_e32 v69, 0x3a000000, v65
	v_rsq_f32_e32 v68, v69
	v_mad_i64_i32 v[64:65], s[6:7], v64, s3, v[66:67]
	v_lshl_add_u64 v[64:65], v[132:133], 1, v[64:65]
	v_mul_f32_e32 v62, v62, v68
	v_mul_f32_e32 v63, v63, v68
	v_mul_f32_e32 v60, v60, v68
	v_mul_f32_e32 v61, v61, v68
	v_mul_f32_e32 v66, v58, v68
	v_mul_f32_e32 v67, v59, v68
	v_mul_f32_e32 v58, v56, v68
	v_mul_f32_e32 v59, v57, v68
	v_cvt_pk_bf16_f32 v56, v60, v61
	v_cvt_pk_bf16_f32 v57, v62, v63
	v_cvt_pk_bf16_f32 v58, v58, v59
	v_cvt_pk_bf16_f32 v59, v66, v67
	global_store_dwordx4 v[64:65], v[56:59], off
	v_mul_f32_e32 v54, v54, v68
	v_mul_f32_e32 v55, v55, v68
	v_mul_f32_e32 v52, v52, v68
	v_mul_f32_e32 v53, v53, v68
	v_mul_f32_e32 v56, v50, v68
	v_mul_f32_e32 v57, v51, v68
	v_mul_f32_e32 v50, v48, v68
	v_mul_f32_e32 v51, v49, v68
	v_cvt_pk_bf16_f32 v48, v52, v53
	v_cvt_pk_bf16_f32 v49, v54, v55
	v_cvt_pk_bf16_f32 v50, v50, v51
	v_cvt_pk_bf16_f32 v51, v56, v57
	global_store_dwordx4 v[64:65], v[48:51], off offset:256
	s_nop 1
	v_add_u32_e32 v48, 0x90, v130
	v_ashrrev_i32_e32 v49, 31, v48
	v_lshlrev_b64 v[50:51], 7, v[48:49]
	v_lshl_add_u64 v[50:51], s[52:53], 0, v[50:51]
	v_mov_b32_e32 v49, 0
	v_lshl_add_u64 v[50:51], v[128:129], 4, v[50:51]
	s_and_saveexec_b64 s[10:11], vcc
	s_cbranch_execz .LBB0_971
	global_load_dwordx4 v[52:55], v[50:51], off
	s_waitcnt vmcnt(0)
	v_mov_b32_e32 v56, v53
	v_mov_b32_e32 v57, v54
	v_mov_b32_e32 v53, v55
	v_add_f32_e32 v52, v56, v52
	v_add_f32_e32 v53, v57, v53
	s_nop 0
	v_add_f32_e32 v49, v52, v53
	v_add_f32_e32 v49, 0, v49
.LBB0_971:
	s_or_b64 exec, exec, s[10:11]
	s_and_saveexec_b64 s[10:11], s[8:9]
	s_cbranch_execz .LBB0_973
	global_load_dwordx4 v[50:53], v[50:51], off offset:64
	s_waitcnt vmcnt(0)
	v_mov_b32_e32 v54, v51
	v_mov_b32_e32 v55, v52
	v_mov_b32_e32 v51, v53
	v_add_f32_e32 v50, v54, v50
	v_add_f32_e32 v51, v55, v51
	s_nop 0
	v_add_f32_e32 v50, v50, v51
	v_add_f32_e32 v49, v49, v50
.LBB0_973:
	s_or_b64 exec, exec, s[10:11]
	ds_bpermute_b32 v50, v131, v49
	v_mov_b32_e32 v53, 0x358637bd
	s_waitcnt lgkmcnt(0)
	v_add_f32_e32 v49, v49, v50
	ds_bpermute_b32 v52, v134, v49
	v_mov_b64_e32 v[50:51], s[50:51]
	s_waitcnt lgkmcnt(0)
	v_add_f32_e32 v49, v49, v52
	v_fmac_f32_e32 v53, 0x3a000000, v49
	v_rsq_f32_e32 v52, v53
	v_mad_i64_i32 v[48:49], s[6:7], v48, s3, v[50:51]
	v_lshl_add_u64 v[48:49], v[132:133], 1, v[48:49]
	v_mul_f32_e32 v46, v46, v52
	v_mul_f32_e32 v47, v47, v52
	v_mul_f32_e32 v44, v44, v52
	v_mul_f32_e32 v45, v45, v52
	v_mul_f32_e32 v50, v42, v52
	v_mul_f32_e32 v51, v43, v52
	v_mul_f32_e32 v42, v40, v52
	v_mul_f32_e32 v43, v41, v52
	v_cvt_pk_bf16_f32 v40, v44, v45
	v_cvt_pk_bf16_f32 v41, v46, v47
	v_cvt_pk_bf16_f32 v42, v42, v43
	v_cvt_pk_bf16_f32 v43, v50, v51
	global_store_dwordx4 v[48:49], v[40:43], off
	v_mul_f32_e32 v38, v38, v52
	v_mul_f32_e32 v39, v39, v52
	v_mul_f32_e32 v36, v36, v52
	v_mul_f32_e32 v37, v37, v52
	v_mul_f32_e32 v40, v34, v52
	v_mul_f32_e32 v41, v35, v52
	v_mul_f32_e32 v34, v32, v52
	v_mul_f32_e32 v35, v33, v52
	v_cvt_pk_bf16_f32 v32, v36, v37
	v_cvt_pk_bf16_f32 v33, v38, v39
	v_cvt_pk_bf16_f32 v34, v34, v35
	v_cvt_pk_bf16_f32 v35, v40, v41
	global_store_dwordx4 v[48:49], v[32:35], off offset:256
	s_nop 1
	v_add_u32_e32 v32, 0xa0, v130
	v_ashrrev_i32_e32 v33, 31, v32
	v_lshlrev_b64 v[34:35], 7, v[32:33]
	v_lshl_add_u64 v[34:35], s[52:53], 0, v[34:35]
	v_mov_b32_e32 v33, 0
	v_lshl_add_u64 v[34:35], v[128:129], 4, v[34:35]
	s_and_saveexec_b64 s[10:11], vcc
	s_cbranch_execz .LBB0_975
	global_load_dwordx4 v[36:39], v[34:35], off
	s_waitcnt vmcnt(0)
	v_mov_b32_e32 v40, v37
	v_mov_b32_e32 v41, v38
	v_mov_b32_e32 v37, v39
	v_add_f32_e32 v36, v40, v36
	v_add_f32_e32 v37, v41, v37
	s_nop 0
	v_add_f32_e32 v33, v36, v37
	v_add_f32_e32 v33, 0, v33
.LBB0_975:
	s_or_b64 exec, exec, s[10:11]
	s_and_saveexec_b64 s[10:11], s[8:9]
	s_cbranch_execz .LBB0_977
	global_load_dwordx4 v[34:37], v[34:35], off offset:64
	s_waitcnt vmcnt(0)
	v_mov_b32_e32 v38, v35
	v_mov_b32_e32 v39, v36
	v_mov_b32_e32 v35, v37
	v_add_f32_e32 v34, v38, v34
	v_add_f32_e32 v35, v39, v35
	s_nop 0
	v_add_f32_e32 v34, v34, v35
	v_add_f32_e32 v33, v33, v34
.LBB0_977:
	s_or_b64 exec, exec, s[10:11]
	ds_bpermute_b32 v34, v131, v33
	v_mov_b32_e32 v37, 0x358637bd
	s_waitcnt lgkmcnt(0)
	v_add_f32_e32 v33, v33, v34
	ds_bpermute_b32 v36, v134, v33
	v_mov_b64_e32 v[34:35], s[50:51]
	s_waitcnt lgkmcnt(0)
	v_add_f32_e32 v33, v33, v36
	v_fmac_f32_e32 v37, 0x3a000000, v33
	v_rsq_f32_e32 v36, v37
	v_mad_i64_i32 v[32:33], s[6:7], v32, s3, v[34:35]
	v_lshl_add_u64 v[32:33], v[132:133], 1, v[32:33]
	v_mul_f32_e32 v30, v30, v36
	v_mul_f32_e32 v31, v31, v36
	v_mul_f32_e32 v28, v28, v36
	v_mul_f32_e32 v29, v29, v36
	v_mul_f32_e32 v34, v26, v36
	v_mul_f32_e32 v35, v27, v36
	v_mul_f32_e32 v26, v24, v36
	v_mul_f32_e32 v27, v25, v36
	v_cvt_pk_bf16_f32 v24, v28, v29
	v_cvt_pk_bf16_f32 v25, v30, v31
	v_cvt_pk_bf16_f32 v26, v26, v27
	v_cvt_pk_bf16_f32 v27, v34, v35
	global_store_dwordx4 v[32:33], v[24:27], off
	v_mul_f32_e32 v22, v22, v36
	v_mul_f32_e32 v23, v23, v36
	v_mul_f32_e32 v20, v20, v36
	v_mul_f32_e32 v21, v21, v36
	v_mul_f32_e32 v24, v18, v36
	v_mul_f32_e32 v25, v19, v36
	v_mul_f32_e32 v18, v16, v36
	v_mul_f32_e32 v19, v17, v36
	v_cvt_pk_bf16_f32 v16, v20, v21
	v_cvt_pk_bf16_f32 v17, v22, v23
	v_cvt_pk_bf16_f32 v18, v18, v19
	v_cvt_pk_bf16_f32 v19, v24, v25
	global_store_dwordx4 v[32:33], v[16:19], off offset:256
	s_nop 1
	v_add_u32_e32 v16, 0xb0, v130
	v_ashrrev_i32_e32 v17, 31, v16
	v_lshlrev_b64 v[18:19], 7, v[16:17]
	v_lshl_add_u64 v[18:19], s[52:53], 0, v[18:19]
	v_mov_b32_e32 v17, 0
	v_lshl_add_u64 v[18:19], v[128:129], 4, v[18:19]
	s_and_saveexec_b64 s[10:11], vcc
	s_cbranch_execz .LBB0_979
	global_load_dwordx4 v[20:23], v[18:19], off
	s_waitcnt vmcnt(0)
	v_mov_b32_e32 v24, v21
	v_mov_b32_e32 v25, v22
	v_mov_b32_e32 v21, v23
	v_add_f32_e32 v20, v24, v20
	v_add_f32_e32 v21, v25, v21
	s_nop 0
	v_add_f32_e32 v17, v20, v21
	v_add_f32_e32 v17, 0, v17
.LBB0_979:
	s_or_b64 exec, exec, s[10:11]
	s_and_saveexec_b64 s[10:11], s[8:9]
	s_cbranch_execz .LBB0_981
	global_load_dwordx4 v[18:21], v[18:19], off offset:64
	s_waitcnt vmcnt(0)
	v_mov_b32_e32 v22, v19
	v_mov_b32_e32 v23, v20
	v_mov_b32_e32 v19, v21
	v_add_f32_e32 v18, v22, v18
	v_add_f32_e32 v19, v23, v19
	s_nop 0
	v_add_f32_e32 v18, v18, v19
	v_add_f32_e32 v17, v17, v18
.LBB0_981:
	s_or_b64 exec, exec, s[10:11]
	ds_bpermute_b32 v18, v131, v17
	v_mov_b32_e32 v21, 0x358637bd
	s_waitcnt lgkmcnt(0)
	v_add_f32_e32 v17, v17, v18
	ds_bpermute_b32 v20, v134, v17
	v_mov_b64_e32 v[18:19], s[50:51]
	s_waitcnt lgkmcnt(0)
	v_add_f32_e32 v17, v17, v20
	v_fmac_f32_e32 v21, 0x3a000000, v17
	v_rsq_f32_e32 v20, v21
	v_mad_i64_i32 v[16:17], s[6:7], v16, s3, v[18:19]
	v_lshl_add_u64 v[16:17], v[132:133], 1, v[16:17]
	v_mul_f32_e32 v14, v14, v20
	v_mul_f32_e32 v15, v15, v20
	v_mul_f32_e32 v12, v12, v20
	v_mul_f32_e32 v13, v13, v20
	v_mul_f32_e32 v18, v10, v20
	v_mul_f32_e32 v19, v11, v20
	v_mul_f32_e32 v10, v8, v20
	v_mul_f32_e32 v11, v9, v20
	v_cvt_pk_bf16_f32 v8, v12, v13
	v_cvt_pk_bf16_f32 v9, v14, v15
	v_cvt_pk_bf16_f32 v10, v10, v11
	v_cvt_pk_bf16_f32 v11, v18, v19
	global_store_dwordx4 v[16:17], v[8:11], off
	v_mul_f32_e32 v6, v6, v20
	v_mul_f32_e32 v7, v7, v20
	v_mul_f32_e32 v4, v4, v20
	v_mul_f32_e32 v5, v5, v20
	v_mul_f32_e32 v8, v2, v20
	v_mul_f32_e32 v9, v3, v20
	v_mul_f32_e32 v2, v0, v20
	v_mul_f32_e32 v3, v1, v20
	v_cvt_pk_bf16_f32 v0, v4, v5
	v_cvt_pk_bf16_f32 v1, v6, v7
	v_cvt_pk_bf16_f32 v2, v2, v3
	v_cvt_pk_bf16_f32 v3, v8, v9
	global_store_dwordx4 v[16:17], v[0:3], off offset:256
	s_waitcnt vmcnt(0)
	s_barrier

.LBB0_1696:
	v_lshl_add_u32 v142, s72, 8, v144
	v_lshl_add_u32 v140, s18, 8, v146
	v_lshl_add_u32 v210, v142, 11, v140
	v_lshlrev_b32_e32 v210, 2, v210
	global_load_dwordx4 v[162:165], v210, s[14:15]
	global_load_dwordx4 v[166:169], v210, s[14:15] offset:64
	global_load_dwordx4 v[170:173], v210, s[14:15] offset:512
	global_load_dwordx4 v[174:177], v210, s[14:15] offset:576
	v_add_u32_e32 v211, 0x20000, v210
	global_load_dwordx4 v[178:181], v211, s[14:15]
	global_load_dwordx4 v[182:185], v211, s[14:15] offset:64
	global_load_dwordx4 v[186:189], v211, s[14:15] offset:512
	global_load_dwordx4 v[190:193], v211, s[14:15] offset:576
	v_add_u32_e32 v211, 0x40000, v210
	global_load_dwordx4 v[194:197], v211, s[14:15]
	global_load_dwordx4 v[198:201], v211, s[14:15] offset:64
	global_load_dwordx4 v[202:205], v211, s[14:15] offset:512
	global_load_dwordx4 v[206:209], v211, s[14:15] offset:576
	v_ashrrev_i32_e32 v143, 31, v142
	v_ashrrev_i32_e32 v141, 31, v140
	v_lshlrev_b64 v[152:153], 11, v[142:143]
	v_lshl_add_u64 v[156:157], v[152:153], 0, v[140:141]
	v_lshlrev_b64 v[158:159], 2, v[156:157]
	v_lshl_add_u64 v[160:161], s[14:15], 0, v[158:159]
	s_nop 0
	v_lshl_add_u64 v[156:157], v[156:157], 1, s[54:55]
	v_lshl_add_u64 v[158:159], s[16:17], 0, v[158:159]
	s_lshl_b32 s72, s18, 2
	s_ashr_i32 s73, s72, 31
	s_waitcnt vmcnt(11)
	v_add_f32_e32 v126, v126, v164
	v_add_f32_e32 v127, v127, v165
	v_add_f32_e32 v124, v124, v162
	v_add_f32_e32 v125, v125, v163
	v_cvt_pk_bf16_f32 v153, v126, v127
	v_cvt_pk_bf16_f32 v152, v124, v125
	global_store_dwordx4 v[158:159], v[124:127], off
	global_store_dwordx2 v[156:157], v[152:153], off
	s_nop 0
	v_mul_f32_e32 v125, v125, v125
	v_mul_f32_e32 v127, v127, v127
	v_fmac_f32_e32 v125, v124, v124
	v_fmac_f32_e32 v127, v126, v126
	v_add_f32_e32 v124, v125, v127
	s_waitcnt vmcnt(12)
	v_add_f32_e32 v122, v122, v168
	v_add_f32_e32 v123, v123, v169
	v_add_f32_e32 v120, v120, v166
	v_add_f32_e32 v121, v121, v167
	v_cvt_pk_bf16_f32 v153, v122, v123
	v_cvt_pk_bf16_f32 v152, v120, v121
	global_store_dwordx4 v[158:159], v[120:123], off offset:64
	global_store_dwordx2 v[156:157], v[152:153], off offset:32
	s_nop 0
	v_mul_f32_e32 v121, v121, v121
	v_mul_f32_e32 v123, v123, v123
	v_fmac_f32_e32 v121, v120, v120
	v_fmac_f32_e32 v123, v122, v122
	v_add_f32_e32 v120, v121, v123
	v_add_f32_e32 v120, v124, v120
	s_waitcnt vmcnt(13)
	v_add_f32_e32 v118, v118, v172
	v_add_f32_e32 v119, v119, v173
	v_add_f32_e32 v116, v116, v170
	v_add_f32_e32 v117, v117, v171
	v_cvt_pk_bf16_f32 v153, v118, v119
	v_cvt_pk_bf16_f32 v152, v116, v117
	global_store_dwordx4 v[158:159], v[116:119], off offset:512
	global_store_dwordx2 v[156:157], v[152:153], off offset:256
	s_nop 0
	v_mul_f32_e32 v117, v117, v117
	v_mul_f32_e32 v119, v119, v119
	v_fmac_f32_e32 v117, v116, v116
	v_fmac_f32_e32 v119, v118, v118
	v_add_f32_e32 v116, v117, v119
	v_add_f32_e32 v118, v120, v116
	s_waitcnt vmcnt(14)
	v_add_f32_e32 v116, v114, v176
	v_add_f32_e32 v117, v115, v177
	v_add_f32_e32 v114, v112, v174
	v_add_f32_e32 v115, v113, v175
	v_add_u32_e32 v211, 0x60000, v210
	global_load_dwordx4 v[162:165], v211, s[14:15]
	global_load_dwordx4 v[166:169], v211, s[14:15] offset:64
	global_load_dwordx4 v[170:173], v211, s[14:15] offset:512
	global_load_dwordx4 v[174:177], v211, s[14:15] offset:576
	v_mul_f32_e32 v113, v117, v117
	v_mul_f32_e32 v112, v115, v115
	v_fmac_f32_e32 v112, v114, v114
	v_fmac_f32_e32 v113, v116, v116
	v_add_f32_e32 v112, v112, v113
	v_add_f32_e32 v112, v118, v112
	ds_bpermute_b32 v113, v147, v112
	global_store_dwordx4 v[158:159], v[114:117], off offset:576
	s_waitcnt lgkmcnt(0)
	v_add_f32_e32 v112, v112, v113
	ds_bpermute_b32 v113, v148, v112
	v_cvt_pk_bf16_f32 v114, v114, v115
	v_cvt_pk_bf16_f32 v115, v116, v117
	global_store_dwordx2 v[156:157], v[114:115], off offset:288
	s_and_saveexec_b64 s[74:75], s[10:11]
	s_cbranch_execz .LBB0_1698
	v_lshlrev_b64 v[114:115], 7, v[142:143]
	v_lshl_add_u64 v[114:115], s[52:53], 0, v[114:115]
	v_lshl_add_u64 v[114:115], s[72:73], 2, v[114:115]
	s_lshl_b32 s18, s3, 2
	v_lshl_add_u64 v[114:115], v[114:115], 0, s[18:19]
	s_waitcnt lgkmcnt(0)
	v_add_f32_e32 v112, v112, v113
	global_store_dword v[114:115], v112, off
.LBB0_1698:
	s_or_b64 exec, exec, s[74:75]
	v_or_b32_e32 v112, 16, v142
	s_waitcnt lgkmcnt(0)
	v_ashrrev_i32_e32 v113, 31, v112
	v_lshlrev_b64 v[114:115], 11, v[112:113]
	v_lshl_add_u64 v[118:119], v[114:115], 0, v[140:141]
	v_lshlrev_b64 v[120:121], 2, v[118:119]
	v_lshl_add_u64 v[122:123], s[14:15], 0, v[120:121]
	s_nop 0
	v_lshl_add_u64 v[118:119], v[118:119], 1, s[54:55]
	v_lshl_add_u64 v[120:121], s[16:17], 0, v[120:121]
	s_waitcnt vmcnt(19)
	v_add_f32_e32 v110, v110, v180
	v_add_f32_e32 v111, v111, v181
	v_add_f32_e32 v108, v108, v178
	v_add_f32_e32 v109, v109, v179
	v_cvt_pk_bf16_f32 v115, v110, v111
	v_cvt_pk_bf16_f32 v114, v108, v109
	global_store_dwordx4 v[120:121], v[108:111], off
	global_store_dwordx2 v[118:119], v[114:115], off
	s_nop 0
	v_mul_f32_e32 v109, v109, v109
	v_mul_f32_e32 v111, v111, v111
	v_fmac_f32_e32 v109, v108, v108
	v_fmac_f32_e32 v111, v110, v110
	v_add_f32_e32 v108, v109, v111
	s_waitcnt vmcnt(20)
	v_add_f32_e32 v106, v106, v184
	v_add_f32_e32 v107, v107, v185
	v_add_f32_e32 v104, v104, v182
	v_add_f32_e32 v105, v105, v183
	v_cvt_pk_bf16_f32 v115, v106, v107
	v_cvt_pk_bf16_f32 v114, v104, v105
	global_store_dwordx4 v[120:121], v[104:107], off offset:64
	global_store_dwordx2 v[118:119], v[114:115], off offset:32
	s_nop 0
	v_mul_f32_e32 v105, v105, v105
	v_mul_f32_e32 v107, v107, v107
	v_fmac_f32_e32 v105, v104, v104
	v_fmac_f32_e32 v107, v106, v106
	v_add_f32_e32 v104, v105, v107
	v_add_f32_e32 v104, v108, v104
	s_waitcnt vmcnt(21)
	v_add_f32_e32 v102, v102, v188
	v_add_f32_e32 v103, v103, v189
	v_add_f32_e32 v100, v100, v186
	v_add_f32_e32 v101, v101, v187
	v_cvt_pk_bf16_f32 v115, v102, v103
	v_cvt_pk_bf16_f32 v114, v100, v101
	global_store_dwordx4 v[120:121], v[100:103], off offset:512
	global_store_dwordx2 v[118:119], v[114:115], off offset:256
	s_nop 0
	v_mul_f32_e32 v101, v101, v101
	v_mul_f32_e32 v103, v103, v103
	v_fmac_f32_e32 v101, v100, v100
	v_fmac_f32_e32 v103, v102, v102
	v_add_f32_e32 v100, v101, v103
	v_add_f32_e32 v102, v104, v100
	s_waitcnt vmcnt(22)
	v_add_f32_e32 v100, v98, v192
	v_add_f32_e32 v101, v99, v193
	v_add_f32_e32 v98, v96, v190
	v_add_f32_e32 v99, v97, v191
	v_add_u32_e32 v211, 0x100000, v210
	global_load_dwordx4 v[178:181], v211, s[14:15]
	global_load_dwordx4 v[182:185], v211, s[14:15] offset:64
	global_load_dwordx4 v[186:189], v211, s[14:15] offset:512
	global_load_dwordx4 v[190:193], v211, s[14:15] offset:576
	v_mul_f32_e32 v97, v101, v101
	v_mul_f32_e32 v96, v99, v99
	v_fmac_f32_e32 v96, v98, v98
	v_fmac_f32_e32 v97, v100, v100
	v_add_f32_e32 v96, v96, v97
	v_add_f32_e32 v96, v102, v96
	ds_bpermute_b32 v97, v147, v96
	global_store_dwordx4 v[120:121], v[98:101], off offset:576
	s_waitcnt lgkmcnt(0)
	v_add_f32_e32 v96, v96, v97
	ds_bpermute_b32 v97, v148, v96
	v_cvt_pk_bf16_f32 v98, v98, v99
	v_cvt_pk_bf16_f32 v99, v100, v101
	global_store_dwordx2 v[118:119], v[98:99], off offset:288
	s_and_saveexec_b64 s[74:75], s[10:11]
	s_cbranch_execz .LBB0_1700
	v_lshlrev_b64 v[98:99], 7, v[112:113]
	v_lshl_add_u64 v[98:99], s[52:53], 0, v[98:99]
	v_lshl_add_u64 v[98:99], s[72:73], 2, v[98:99]
	s_lshl_b32 s18, s3, 2
	v_lshl_add_u64 v[98:99], v[98:99], 0, s[18:19]
	s_waitcnt lgkmcnt(0)
	v_add_f32_e32 v96, v96, v97
	global_store_dword v[98:99], v96, off
.LBB0_1700:
	s_or_b64 exec, exec, s[74:75]
	v_or_b32_e32 v96, 32, v142
	s_waitcnt lgkmcnt(0)
	v_ashrrev_i32_e32 v97, 31, v96
	v_lshlrev_b64 v[98:99], 11, v[96:97]
	v_lshl_add_u64 v[102:103], v[98:99], 0, v[140:141]
	v_lshlrev_b64 v[104:105], 2, v[102:103]
	v_lshl_add_u64 v[106:107], s[14:15], 0, v[104:105]
	s_nop 0
	v_lshl_add_u64 v[102:103], v[102:103], 1, s[54:55]
	v_lshl_add_u64 v[104:105], s[16:17], 0, v[104:105]
	s_waitcnt vmcnt(27)
	v_add_f32_e32 v94, v94, v196
	v_add_f32_e32 v95, v95, v197
	v_add_f32_e32 v92, v92, v194
	v_add_f32_e32 v93, v93, v195
	v_cvt_pk_bf16_f32 v99, v94, v95
	v_cvt_pk_bf16_f32 v98, v92, v93
	global_store_dwordx4 v[104:105], v[92:95], off
	global_store_dwordx2 v[102:103], v[98:99], off
	s_nop 0
	v_mul_f32_e32 v93, v93, v93
	v_mul_f32_e32 v95, v95, v95
	v_fmac_f32_e32 v93, v92, v92
	v_fmac_f32_e32 v95, v94, v94
	v_add_f32_e32 v92, v93, v95
	s_waitcnt vmcnt(28)
	v_add_f32_e32 v90, v90, v200
	v_add_f32_e32 v91, v91, v201
	v_add_f32_e32 v88, v88, v198
	v_add_f32_e32 v89, v89, v199
	v_cvt_pk_bf16_f32 v99, v90, v91
	v_cvt_pk_bf16_f32 v98, v88, v89
	global_store_dwordx4 v[104:105], v[88:91], off offset:64
	global_store_dwordx2 v[102:103], v[98:99], off offset:32
	s_nop 0
	v_mul_f32_e32 v89, v89, v89
	v_mul_f32_e32 v91, v91, v91
	v_fmac_f32_e32 v89, v88, v88
	v_fmac_f32_e32 v91, v90, v90
	v_add_f32_e32 v88, v89, v91
	v_add_f32_e32 v88, v92, v88
	s_waitcnt vmcnt(29)
	v_add_f32_e32 v86, v86, v204
	v_add_f32_e32 v87, v87, v205
	v_add_f32_e32 v84, v84, v202
	v_add_f32_e32 v85, v85, v203
	v_cvt_pk_bf16_f32 v99, v86, v87
	v_cvt_pk_bf16_f32 v98, v84, v85
	global_store_dwordx4 v[104:105], v[84:87], off offset:512
	global_store_dwordx2 v[102:103], v[98:99], off offset:256
	s_nop 0
	v_mul_f32_e32 v85, v85, v85
	v_mul_f32_e32 v87, v87, v87
	v_fmac_f32_e32 v85, v84, v84
	v_fmac_f32_e32 v87, v86, v86
	v_add_f32_e32 v84, v85, v87
	v_add_f32_e32 v86, v88, v84
	s_waitcnt vmcnt(30)
	v_add_f32_e32 v84, v82, v208
	v_add_f32_e32 v85, v83, v209
	v_add_f32_e32 v82, v80, v206
	v_add_f32_e32 v83, v81, v207
	v_add_u32_e32 v211, 0x120000, v210
	global_load_dwordx4 v[194:197], v211, s[14:15]
	global_load_dwordx4 v[198:201], v211, s[14:15] offset:64
	global_load_dwordx4 v[202:205], v211, s[14:15] offset:512
	global_load_dwordx4 v[206:209], v211, s[14:15] offset:576
	v_mul_f32_e32 v81, v85, v85
	v_mul_f32_e32 v80, v83, v83
	v_fmac_f32_e32 v80, v82, v82
	v_fmac_f32_e32 v81, v84, v84
	v_add_f32_e32 v80, v80, v81
	v_add_f32_e32 v80, v86, v80
	ds_bpermute_b32 v81, v147, v80
	global_store_dwordx4 v[104:105], v[82:85], off offset:576
	s_waitcnt lgkmcnt(0)
	v_add_f32_e32 v80, v80, v81
	ds_bpermute_b32 v81, v148, v80
	v_cvt_pk_bf16_f32 v82, v82, v83
	v_cvt_pk_bf16_f32 v83, v84, v85
	global_store_dwordx2 v[102:103], v[82:83], off offset:288
	s_and_saveexec_b64 s[74:75], s[10:11]
	s_cbranch_execz .LBB0_1702
	v_lshlrev_b64 v[82:83], 7, v[96:97]
	v_lshl_add_u64 v[82:83], s[52:53], 0, v[82:83]
	v_lshl_add_u64 v[82:83], s[72:73], 2, v[82:83]
	s_lshl_b32 s18, s3, 2
	v_lshl_add_u64 v[82:83], v[82:83], 0, s[18:19]
	s_waitcnt lgkmcnt(0)
	v_add_f32_e32 v80, v80, v81
	global_store_dword v[82:83], v80, off
.LBB0_1702:
	s_or_b64 exec, exec, s[74:75]
	v_or_b32_e32 v80, 48, v142
	s_waitcnt lgkmcnt(0)
	v_ashrrev_i32_e32 v81, 31, v80
	v_lshlrev_b64 v[82:83], 11, v[80:81]
	v_lshl_add_u64 v[86:87], v[82:83], 0, v[140:141]
	v_lshlrev_b64 v[88:89], 2, v[86:87]
	v_lshl_add_u64 v[90:91], s[14:15], 0, v[88:89]
	s_nop 0
	v_lshl_add_u64 v[86:87], v[86:87], 1, s[54:55]
	v_lshl_add_u64 v[88:89], s[16:17], 0, v[88:89]
	s_waitcnt vmcnt(29)
	v_add_f32_e32 v78, v78, v164
	v_add_f32_e32 v79, v79, v165
	v_add_f32_e32 v76, v76, v162
	v_add_f32_e32 v77, v77, v163
	v_cvt_pk_bf16_f32 v83, v78, v79
	v_cvt_pk_bf16_f32 v82, v76, v77
	global_store_dwordx4 v[88:89], v[76:79], off
	global_store_dwordx2 v[86:87], v[82:83], off
	s_nop 0
	v_mul_f32_e32 v77, v77, v77
	v_mul_f32_e32 v79, v79, v79
	v_fmac_f32_e32 v77, v76, v76
	v_fmac_f32_e32 v79, v78, v78
	v_add_f32_e32 v76, v77, v79
	s_waitcnt vmcnt(30)
	v_add_f32_e32 v74, v74, v168
	v_add_f32_e32 v75, v75, v169
	v_add_f32_e32 v72, v72, v166
	v_add_f32_e32 v73, v73, v167
	v_cvt_pk_bf16_f32 v83, v74, v75
	v_cvt_pk_bf16_f32 v82, v72, v73
	global_store_dwordx4 v[88:89], v[72:75], off offset:64
	global_store_dwordx2 v[86:87], v[82:83], off offset:32
	s_nop 0
	v_mul_f32_e32 v73, v73, v73
	v_mul_f32_e32 v75, v75, v75
	v_fmac_f32_e32 v73, v72, v72
	v_fmac_f32_e32 v75, v74, v74
	v_add_f32_e32 v72, v73, v75
	v_add_f32_e32 v72, v76, v72
	s_waitcnt vmcnt(31)
	v_add_f32_e32 v70, v70, v172
	v_add_f32_e32 v71, v71, v173
	v_add_f32_e32 v68, v68, v170
	v_add_f32_e32 v69, v69, v171
	v_cvt_pk_bf16_f32 v83, v70, v71
	v_cvt_pk_bf16_f32 v82, v68, v69
	global_store_dwordx4 v[88:89], v[68:71], off offset:512
	global_store_dwordx2 v[86:87], v[82:83], off offset:256
	s_nop 0
	v_mul_f32_e32 v69, v69, v69
	v_mul_f32_e32 v71, v71, v71
	v_fmac_f32_e32 v69, v68, v68
	v_fmac_f32_e32 v71, v70, v70
	v_add_f32_e32 v68, v69, v71
	v_add_f32_e32 v70, v72, v68
	s_waitcnt vmcnt(32)
	v_add_f32_e32 v68, v66, v176
	v_add_f32_e32 v69, v67, v177
	v_add_f32_e32 v66, v64, v174
	v_add_f32_e32 v67, v65, v175
	v_add_u32_e32 v211, 0x140000, v210
	global_load_dwordx4 v[162:165], v211, s[14:15]
	global_load_dwordx4 v[166:169], v211, s[14:15] offset:64
	global_load_dwordx4 v[170:173], v211, s[14:15] offset:512
	global_load_dwordx4 v[174:177], v211, s[14:15] offset:576
	v_mul_f32_e32 v65, v69, v69
	v_mul_f32_e32 v64, v67, v67
	v_fmac_f32_e32 v64, v66, v66
	v_fmac_f32_e32 v65, v68, v68
	v_add_f32_e32 v64, v64, v65
	v_add_f32_e32 v64, v70, v64
	ds_bpermute_b32 v65, v147, v64
	global_store_dwordx4 v[88:89], v[66:69], off offset:576
	s_waitcnt lgkmcnt(0)
	v_add_f32_e32 v64, v64, v65
	ds_bpermute_b32 v65, v148, v64
	v_cvt_pk_bf16_f32 v66, v66, v67
	v_cvt_pk_bf16_f32 v67, v68, v69
	global_store_dwordx2 v[86:87], v[66:67], off offset:288
	s_and_saveexec_b64 s[74:75], s[10:11]
	s_cbranch_execz .LBB0_1704
	v_lshlrev_b64 v[66:67], 7, v[80:81]
	v_lshl_add_u64 v[66:67], s[52:53], 0, v[66:67]
	v_lshl_add_u64 v[66:67], s[72:73], 2, v[66:67]
	s_lshl_b32 s18, s3, 2
	v_lshl_add_u64 v[66:67], v[66:67], 0, s[18:19]
	s_waitcnt lgkmcnt(0)
	v_add_f32_e32 v64, v64, v65
	global_store_dword v[66:67], v64, off
.LBB0_1704:
	s_or_b64 exec, exec, s[74:75]
	v_add_u32_e32 v64, 0x80, v142
	s_waitcnt lgkmcnt(0)
	v_ashrrev_i32_e32 v65, 31, v64
	v_lshlrev_b64 v[66:67], 11, v[64:65]
	v_lshl_add_u64 v[70:71], v[66:67], 0, v[140:141]
	v_lshlrev_b64 v[72:73], 2, v[70:71]
	v_lshl_add_u64 v[74:75], s[14:15], 0, v[72:73]
	s_nop 0
	v_lshl_add_u64 v[70:71], v[70:71], 1, s[54:55]
	v_lshl_add_u64 v[72:73], s[16:17], 0, v[72:73]
	s_waitcnt vmcnt(29)
	v_add_f32_e32 v62, v62, v180
	v_add_f32_e32 v63, v63, v181
	v_add_f32_e32 v60, v60, v178
	v_add_f32_e32 v61, v61, v179
	v_cvt_pk_bf16_f32 v67, v62, v63
	v_cvt_pk_bf16_f32 v66, v60, v61
	global_store_dwordx4 v[72:73], v[60:63], off
	global_store_dwordx2 v[70:71], v[66:67], off
	s_nop 0
	v_mul_f32_e32 v61, v61, v61
	v_mul_f32_e32 v63, v63, v63
	v_fmac_f32_e32 v61, v60, v60
	v_fmac_f32_e32 v63, v62, v62
	v_add_f32_e32 v60, v61, v63
	s_waitcnt vmcnt(30)
	v_add_f32_e32 v58, v58, v184
	v_add_f32_e32 v59, v59, v185
	v_add_f32_e32 v56, v56, v182
	v_add_f32_e32 v57, v57, v183
	v_cvt_pk_bf16_f32 v67, v58, v59
	v_cvt_pk_bf16_f32 v66, v56, v57
	global_store_dwordx4 v[72:73], v[56:59], off offset:64
	global_store_dwordx2 v[70:71], v[66:67], off offset:32
	s_nop 0
	v_mul_f32_e32 v57, v57, v57
	v_mul_f32_e32 v59, v59, v59
	v_fmac_f32_e32 v57, v56, v56
	v_fmac_f32_e32 v59, v58, v58
	v_add_f32_e32 v56, v57, v59
	v_add_f32_e32 v56, v60, v56
	s_waitcnt vmcnt(31)
	v_add_f32_e32 v54, v54, v188
	v_add_f32_e32 v55, v55, v189
	v_add_f32_e32 v52, v52, v186
	v_add_f32_e32 v53, v53, v187
	v_cvt_pk_bf16_f32 v67, v54, v55
	v_cvt_pk_bf16_f32 v66, v52, v53
	global_store_dwordx4 v[72:73], v[52:55], off offset:512
	global_store_dwordx2 v[70:71], v[66:67], off offset:256
	s_nop 0
	v_mul_f32_e32 v53, v53, v53
	v_mul_f32_e32 v55, v55, v55
	v_fmac_f32_e32 v53, v52, v52
	v_fmac_f32_e32 v55, v54, v54
	v_add_f32_e32 v52, v53, v55
	v_add_f32_e32 v54, v56, v52
	s_waitcnt vmcnt(32)
	v_add_f32_e32 v52, v50, v192
	v_add_f32_e32 v53, v51, v193
	v_add_f32_e32 v50, v48, v190
	v_add_f32_e32 v51, v49, v191
	v_add_u32_e32 v211, 0x160000, v210
	global_load_dwordx4 v[178:181], v211, s[14:15]
	global_load_dwordx4 v[182:185], v211, s[14:15] offset:64
	global_load_dwordx4 v[186:189], v211, s[14:15] offset:512
	global_load_dwordx4 v[190:193], v211, s[14:15] offset:576
	v_mul_f32_e32 v49, v53, v53
	v_mul_f32_e32 v48, v51, v51
	v_fmac_f32_e32 v48, v50, v50
	v_fmac_f32_e32 v49, v52, v52
	v_add_f32_e32 v48, v48, v49
	v_add_f32_e32 v48, v54, v48
	ds_bpermute_b32 v49, v147, v48
	global_store_dwordx4 v[72:73], v[50:53], off offset:576
	s_waitcnt lgkmcnt(0)
	v_add_f32_e32 v48, v48, v49
	ds_bpermute_b32 v49, v148, v48
	v_cvt_pk_bf16_f32 v50, v50, v51
	v_cvt_pk_bf16_f32 v51, v52, v53
	global_store_dwordx2 v[70:71], v[50:51], off offset:288
	s_and_saveexec_b64 s[74:75], s[10:11]
	s_cbranch_execz .LBB0_1706
	v_lshlrev_b64 v[50:51], 7, v[64:65]
	v_lshl_add_u64 v[50:51], s[52:53], 0, v[50:51]
	v_lshl_add_u64 v[50:51], s[72:73], 2, v[50:51]
	s_lshl_b32 s18, s3, 2
	v_lshl_add_u64 v[50:51], v[50:51], 0, s[18:19]
	s_waitcnt lgkmcnt(0)
	v_add_f32_e32 v48, v48, v49
	global_store_dword v[50:51], v48, off
.LBB0_1706:
	s_or_b64 exec, exec, s[74:75]
	v_add_u32_e32 v48, 0x90, v142
	s_waitcnt lgkmcnt(0)
	v_ashrrev_i32_e32 v49, 31, v48
	v_lshlrev_b64 v[50:51], 11, v[48:49]
	v_lshl_add_u64 v[54:55], v[50:51], 0, v[140:141]
	v_lshlrev_b64 v[56:57], 2, v[54:55]
	v_lshl_add_u64 v[58:59], s[14:15], 0, v[56:57]
	s_nop 0
	v_lshl_add_u64 v[54:55], v[54:55], 1, s[54:55]
	v_lshl_add_u64 v[56:57], s[16:17], 0, v[56:57]
	s_waitcnt vmcnt(29)
	v_add_f32_e32 v46, v46, v196
	v_add_f32_e32 v47, v47, v197
	v_add_f32_e32 v44, v44, v194
	v_add_f32_e32 v45, v45, v195
	v_cvt_pk_bf16_f32 v51, v46, v47
	v_cvt_pk_bf16_f32 v50, v44, v45
	global_store_dwordx4 v[56:57], v[44:47], off
	global_store_dwordx2 v[54:55], v[50:51], off
	s_nop 0
	v_mul_f32_e32 v45, v45, v45
	v_mul_f32_e32 v47, v47, v47
	v_fmac_f32_e32 v45, v44, v44
	v_fmac_f32_e32 v47, v46, v46
	v_add_f32_e32 v44, v45, v47
	s_waitcnt vmcnt(30)
	v_add_f32_e32 v42, v42, v200
	v_add_f32_e32 v43, v43, v201
	v_add_f32_e32 v40, v40, v198
	v_add_f32_e32 v41, v41, v199
	v_cvt_pk_bf16_f32 v51, v42, v43
	v_cvt_pk_bf16_f32 v50, v40, v41
	global_store_dwordx4 v[56:57], v[40:43], off offset:64
	global_store_dwordx2 v[54:55], v[50:51], off offset:32
	s_nop 0
	v_mul_f32_e32 v41, v41, v41
	v_mul_f32_e32 v43, v43, v43
	v_fmac_f32_e32 v41, v40, v40
	v_fmac_f32_e32 v43, v42, v42
	v_add_f32_e32 v40, v41, v43
	v_add_f32_e32 v40, v44, v40
	s_waitcnt vmcnt(31)
	v_add_f32_e32 v38, v38, v204
	v_add_f32_e32 v39, v39, v205
	v_add_f32_e32 v36, v36, v202
	v_add_f32_e32 v37, v37, v203
	v_cvt_pk_bf16_f32 v51, v38, v39
	v_cvt_pk_bf16_f32 v50, v36, v37
	global_store_dwordx4 v[56:57], v[36:39], off offset:512
	global_store_dwordx2 v[54:55], v[50:51], off offset:256
	s_nop 0
	v_mul_f32_e32 v37, v37, v37
	v_mul_f32_e32 v39, v39, v39
	v_fmac_f32_e32 v37, v36, v36
	v_fmac_f32_e32 v39, v38, v38
	v_add_f32_e32 v36, v37, v39
	v_add_f32_e32 v38, v40, v36
	s_waitcnt vmcnt(32)
	v_add_f32_e32 v36, v34, v208
	v_add_f32_e32 v37, v35, v209
	v_add_f32_e32 v34, v32, v206
	v_add_f32_e32 v35, v33, v207
	v_mul_f32_e32 v33, v37, v37
	v_mul_f32_e32 v32, v35, v35
	v_fmac_f32_e32 v32, v34, v34
	v_fmac_f32_e32 v33, v36, v36
	v_add_f32_e32 v32, v32, v33
	v_add_f32_e32 v32, v38, v32
	ds_bpermute_b32 v33, v147, v32
	global_store_dwordx4 v[56:57], v[34:37], off offset:576
	s_waitcnt lgkmcnt(0)
	v_add_f32_e32 v32, v32, v33
	ds_bpermute_b32 v33, v148, v32
	v_cvt_pk_bf16_f32 v34, v34, v35
	v_cvt_pk_bf16_f32 v35, v36, v37
	global_store_dwordx2 v[54:55], v[34:35], off offset:288
	s_and_saveexec_b64 s[74:75], s[10:11]
	s_cbranch_execz .LBB0_1708
	v_lshlrev_b64 v[34:35], 7, v[48:49]
	v_lshl_add_u64 v[34:35], s[52:53], 0, v[34:35]
	v_lshl_add_u64 v[34:35], s[72:73], 2, v[34:35]
	s_lshl_b32 s18, s3, 2
	v_lshl_add_u64 v[34:35], v[34:35], 0, s[18:19]
	s_waitcnt lgkmcnt(0)
	v_add_f32_e32 v32, v32, v33
	global_store_dword v[34:35], v32, off
.LBB0_1708:
	s_or_b64 exec, exec, s[74:75]
	v_add_u32_e32 v32, 0xa0, v142
	s_waitcnt lgkmcnt(0)
	v_ashrrev_i32_e32 v33, 31, v32
	v_lshlrev_b64 v[34:35], 11, v[32:33]
	v_lshl_add_u64 v[38:39], v[34:35], 0, v[140:141]
	v_lshlrev_b64 v[40:41], 2, v[38:39]
	v_lshl_add_u64 v[42:43], s[14:15], 0, v[40:41]
	s_nop 0
	v_lshl_add_u64 v[38:39], v[38:39], 1, s[54:55]
	v_lshl_add_u64 v[40:41], s[16:17], 0, v[40:41]
	s_waitcnt vmcnt(25)
	v_add_f32_e32 v30, v30, v164
	v_add_f32_e32 v31, v31, v165
	v_add_f32_e32 v28, v28, v162
	v_add_f32_e32 v29, v29, v163
	v_cvt_pk_bf16_f32 v35, v30, v31
	v_cvt_pk_bf16_f32 v34, v28, v29
	global_store_dwordx4 v[40:41], v[28:31], off
	global_store_dwordx2 v[38:39], v[34:35], off
	s_nop 0
	v_mul_f32_e32 v29, v29, v29
	v_mul_f32_e32 v31, v31, v31
	v_fmac_f32_e32 v29, v28, v28
	v_fmac_f32_e32 v31, v30, v30
	v_add_f32_e32 v28, v29, v31
	s_waitcnt vmcnt(26)
	v_add_f32_e32 v26, v26, v168
	v_add_f32_e32 v27, v27, v169
	v_add_f32_e32 v24, v24, v166
	v_add_f32_e32 v25, v25, v167
	v_cvt_pk_bf16_f32 v35, v26, v27
	v_cvt_pk_bf16_f32 v34, v24, v25
	global_store_dwordx4 v[40:41], v[24:27], off offset:64
	global_store_dwordx2 v[38:39], v[34:35], off offset:32
	s_nop 0
	v_mul_f32_e32 v25, v25, v25
	v_mul_f32_e32 v27, v27, v27
	v_fmac_f32_e32 v25, v24, v24
	v_fmac_f32_e32 v27, v26, v26
	v_add_f32_e32 v24, v25, v27
	v_add_f32_e32 v24, v28, v24
	s_waitcnt vmcnt(27)
	v_add_f32_e32 v22, v22, v172
	v_add_f32_e32 v23, v23, v173
	v_add_f32_e32 v20, v20, v170
	v_add_f32_e32 v21, v21, v171
	v_cvt_pk_bf16_f32 v35, v22, v23
	v_cvt_pk_bf16_f32 v34, v20, v21
	global_store_dwordx4 v[40:41], v[20:23], off offset:512
	global_store_dwordx2 v[38:39], v[34:35], off offset:256
	s_nop 0
	v_mul_f32_e32 v21, v21, v21
	v_mul_f32_e32 v23, v23, v23
	v_fmac_f32_e32 v21, v20, v20
	v_fmac_f32_e32 v23, v22, v22
	v_add_f32_e32 v20, v21, v23
	v_add_f32_e32 v22, v24, v20
	s_waitcnt vmcnt(28)
	v_add_f32_e32 v20, v18, v176
	v_add_f32_e32 v21, v19, v177
	v_add_f32_e32 v18, v16, v174
	v_add_f32_e32 v19, v17, v175
	v_mul_f32_e32 v17, v21, v21
	v_mul_f32_e32 v16, v19, v19
	v_fmac_f32_e32 v16, v18, v18
	v_fmac_f32_e32 v17, v20, v20
	v_add_f32_e32 v16, v16, v17
	v_add_f32_e32 v16, v22, v16
	ds_bpermute_b32 v17, v147, v16
	global_store_dwordx4 v[40:41], v[18:21], off offset:576
	s_waitcnt lgkmcnt(0)
	v_add_f32_e32 v16, v16, v17
	ds_bpermute_b32 v17, v148, v16
	v_cvt_pk_bf16_f32 v18, v18, v19
	v_cvt_pk_bf16_f32 v19, v20, v21
	global_store_dwordx2 v[38:39], v[18:19], off offset:288
	s_and_saveexec_b64 s[74:75], s[10:11]
	s_cbranch_execz .LBB0_1710
	v_lshlrev_b64 v[18:19], 7, v[32:33]
	v_lshl_add_u64 v[18:19], s[52:53], 0, v[18:19]
	v_lshl_add_u64 v[18:19], s[72:73], 2, v[18:19]
	s_lshl_b32 s18, s3, 2
	v_lshl_add_u64 v[18:19], v[18:19], 0, s[18:19]
	s_waitcnt lgkmcnt(0)
	v_add_f32_e32 v16, v16, v17
	global_store_dword v[18:19], v16, off
.LBB0_1710:
	s_or_b64 exec, exec, s[74:75]
	v_add_u32_e32 v16, 0xb0, v142
	s_waitcnt lgkmcnt(0)
	v_ashrrev_i32_e32 v17, 31, v16
	v_lshlrev_b64 v[18:19], 11, v[16:17]
	v_lshl_add_u64 v[22:23], v[18:19], 0, v[140:141]
	v_lshlrev_b64 v[24:25], 2, v[22:23]
	v_lshl_add_u64 v[26:27], s[14:15], 0, v[24:25]
	s_nop 0
	v_lshl_add_u64 v[22:23], v[22:23], 1, s[54:55]
	v_lshl_add_u64 v[24:25], s[16:17], 0, v[24:25]
	s_waitcnt vmcnt(21)
	v_add_f32_e32 v14, v14, v180
	v_add_f32_e32 v15, v15, v181
	v_add_f32_e32 v12, v12, v178
	v_add_f32_e32 v13, v13, v179
	v_cvt_pk_bf16_f32 v19, v14, v15
	v_cvt_pk_bf16_f32 v18, v12, v13
	global_store_dwordx4 v[24:25], v[12:15], off
	global_store_dwordx2 v[22:23], v[18:19], off
	s_nop 0
	v_mul_f32_e32 v13, v13, v13
	v_mul_f32_e32 v15, v15, v15
	v_fmac_f32_e32 v13, v12, v12
	v_fmac_f32_e32 v15, v14, v14
	v_add_f32_e32 v12, v13, v15
	s_waitcnt vmcnt(22)
	v_add_f32_e32 v10, v10, v184
	v_add_f32_e32 v11, v11, v185
	v_add_f32_e32 v8, v8, v182
	v_add_f32_e32 v9, v9, v183
	v_cvt_pk_bf16_f32 v19, v10, v11
	v_cvt_pk_bf16_f32 v18, v8, v9
	global_store_dwordx4 v[24:25], v[8:11], off offset:64
	global_store_dwordx2 v[22:23], v[18:19], off offset:32
	s_nop 0
	v_mul_f32_e32 v9, v9, v9
	v_mul_f32_e32 v11, v11, v11
	v_fmac_f32_e32 v9, v8, v8
	v_fmac_f32_e32 v11, v10, v10
	v_add_f32_e32 v8, v9, v11
	v_add_f32_e32 v8, v12, v8
	s_waitcnt vmcnt(23)
	v_add_f32_e32 v6, v6, v188
	v_add_f32_e32 v7, v7, v189
	v_add_f32_e32 v4, v4, v186
	v_add_f32_e32 v5, v5, v187
	v_cvt_pk_bf16_f32 v19, v6, v7
	v_cvt_pk_bf16_f32 v18, v4, v5
	global_store_dwordx4 v[24:25], v[4:7], off offset:512
	global_store_dwordx2 v[22:23], v[18:19], off offset:256
	s_nop 0
	v_mul_f32_e32 v5, v5, v5
	v_mul_f32_e32 v7, v7, v7
	v_fmac_f32_e32 v5, v4, v4
	v_fmac_f32_e32 v7, v6, v6
	v_add_f32_e32 v4, v5, v7
	v_add_f32_e32 v6, v8, v4
	s_waitcnt vmcnt(24)
	v_add_f32_e32 v4, v2, v192
	v_add_f32_e32 v5, v3, v193
	v_add_f32_e32 v2, v0, v190
	v_add_f32_e32 v3, v1, v191
	v_mul_f32_e32 v1, v5, v5
	v_mul_f32_e32 v0, v3, v3
	v_fmac_f32_e32 v0, v2, v2
	v_fmac_f32_e32 v1, v4, v4
	v_add_f32_e32 v0, v0, v1
	v_add_f32_e32 v0, v6, v0
	ds_bpermute_b32 v1, v147, v0
	global_store_dwordx4 v[24:25], v[2:5], off offset:576
	s_waitcnt lgkmcnt(0)
	v_add_f32_e32 v0, v0, v1
	ds_bpermute_b32 v1, v148, v0
	v_cvt_pk_bf16_f32 v2, v2, v3
	v_cvt_pk_bf16_f32 v3, v4, v5
	global_store_dwordx2 v[22:23], v[2:3], off offset:288
	s_and_saveexec_b64 s[74:75], s[10:11]
	s_cbranch_execz .LBB0_1712
	v_lshlrev_b64 v[2:3], 7, v[16:17]
	v_lshl_add_u64 v[2:3], s[52:53], 0, v[2:3]
	v_lshl_add_u64 v[2:3], s[72:73], 2, v[2:3]
	s_lshl_b32 s18, s3, 2
	v_lshl_add_u64 v[2:3], v[2:3], 0, s[18:19]
	s_waitcnt lgkmcnt(0)
	v_add_f32_e32 v0, v0, v1
	global_store_dword v[2:3], v0, off

.LBB0_1788:
	v_lshl_add_u32 v148, s70, 8, v150
	v_ashrrev_i32_e32 v149, 31, v148
	v_lshlrev_b64 v[146:147], 7, v[148:149]
	v_lshl_add_u64 v[146:147], s[52:53], 0, v[146:147]
	v_mov_b32_e32 v159, 0
	v_lshl_add_u64 v[146:147], v[136:137], 4, v[146:147]
	s_and_saveexec_b64 s[70:71], s[14:15]
	s_cbranch_execz .LBB0_1790
	global_load_dwordx4 v[160:163], v[146:147], off
	s_waitcnt vmcnt(0)
	v_mov_b32_e32 v164, v161
	v_mov_b32_e32 v165, v162
	v_mov_b32_e32 v161, v163
	v_add_f32_e32 v160, v164, v160
	v_add_f32_e32 v161, v165, v161
	s_nop 0
	v_add_f32_e32 v159, v160, v161
	v_add_f32_e32 v159, 0, v159
.LBB0_1790:
	s_or_b64 exec, exec, s[70:71]
	s_and_saveexec_b64 s[70:71], s[16:17]
	s_cbranch_execz .LBB0_1792
	global_load_dwordx4 v[160:163], v[146:147], off offset:64
	s_waitcnt vmcnt(0)
	v_mov_b32_e32 v146, v161
	v_mov_b32_e32 v147, v162
	v_mov_b32_e32 v161, v163
	v_add_f32_e32 v146, v146, v160
	v_add_f32_e32 v147, v147, v161
	s_nop 0
	v_add_f32_e32 v146, v146, v147
	v_add_f32_e32 v159, v159, v146
.LBB0_1792:
	s_or_b64 exec, exec, s[70:71]
	ds_bpermute_b32 v146, v153, v159
	v_lshlrev_b64 v[160:161], 14, v[148:149]
	v_lshl_add_u64 v[160:161], s[50:51], 0, v[160:161]
	s_waitcnt lgkmcnt(0)
	v_add_f32_e32 v147, v159, v146
	ds_bpermute_b32 v159, v154, v147
	v_lshl_add_u32 v146, s68, 8, v152
	s_waitcnt lgkmcnt(0)
	v_add_f32_e32 v147, v147, v159
	v_fmamk_f32 v147, v147, 0x3a000000, v158
	v_rsq_f32_e32 v162, v147
	v_ashrrev_i32_e32 v147, 31, v146
	v_lshl_add_u64 v[160:161], v[146:147], 1, v[160:161]
	v_mul_f32_e32 v120, v120, v162
	v_mul_f32_e32 v121, v121, v162
	v_mul_f32_e32 v124, v124, v162
	v_mul_f32_e32 v125, v125, v162
	v_max_f32_e32 v120, 0, v120
	v_mul_f32_e32 v126, v126, v162
	v_mul_f32_e32 v127, v127, v162
	v_mul_f32_e32 v122, v122, v162
	v_mul_f32_e32 v123, v123, v162
	v_max_f32_e32 v125, 0, v125
	v_mul_f32_e32 v149, v120, v120
	v_max_f32_e32 v120, 0, v121
	v_mul_f32_e32 v121, v125, v125
	v_mul_f32_e32 v125, v120, v120
	v_max_f32_e32 v120, 0, v126
	v_max_f32_e32 v122, 0, v122
	v_max_f32_e32 v124, 0, v124
	v_mul_f32_e32 v126, v120, v120
	v_mul_f32_e32 v159, v122, v122
	v_max_f32_e32 v120, 0, v127
	v_max_f32_e32 v122, 0, v123
	v_mul_f32_e32 v124, v124, v124
	v_mul_f32_e32 v123, v120, v120
	v_mul_f32_e32 v127, v122, v122
	v_mul_f32_e32 v114, v114, v162
	v_mul_f32_e32 v115, v115, v162
	v_mul_f32_e32 v112, v112, v162
	v_mul_f32_e32 v113, v113, v162
	v_cvt_pk_bf16_f32 v120, v124, v121
	v_cvt_pk_bf16_f32 v121, v126, v123
	v_cvt_pk_bf16_f32 v122, v149, v125
	v_cvt_pk_bf16_f32 v123, v159, v127
	v_mul_f32_e32 v118, v118, v162
	v_mul_f32_e32 v119, v119, v162
	v_mul_f32_e32 v116, v116, v162
	v_mul_f32_e32 v117, v117, v162
	v_max_f32_e32 v112, 0, v112
	v_max_f32_e32 v113, 0, v113
	v_max_f32_e32 v114, 0, v114
	global_store_dwordx4 v[160:161], v[120:123], off
	v_max_f32_e32 v116, 0, v116
	v_max_f32_e32 v115, 0, v115
	v_mul_f32_e32 v120, v112, v112
	v_max_f32_e32 v112, 0, v117
	v_mul_f32_e32 v117, v113, v113
	v_max_f32_e32 v113, 0, v118
	v_mul_f32_e32 v118, v114, v114
	v_max_f32_e32 v114, 0, v119
	v_mul_f32_e32 v116, v116, v116
	v_mul_f32_e32 v112, v112, v112
	v_mul_f32_e32 v113, v113, v113
	v_mul_f32_e32 v114, v114, v114
	v_mul_f32_e32 v115, v115, v115
	v_cvt_pk_bf16_f32 v112, v116, v112
	v_cvt_pk_bf16_f32 v113, v113, v114
	v_cvt_pk_bf16_f32 v114, v120, v117
	v_cvt_pk_bf16_f32 v115, v118, v115
	global_store_dwordx4 v[160:161], v[112:115], off offset:256
	v_mov_b32_e32 v116, 0
	s_nop 0
	v_or_b32_e32 v112, 16, v148
	v_ashrrev_i32_e32 v113, 31, v112
	v_lshlrev_b64 v[114:115], 7, v[112:113]
	v_lshl_add_u64 v[114:115], s[52:53], 0, v[114:115]
	v_lshl_add_u64 v[114:115], v[136:137], 4, v[114:115]
	s_and_saveexec_b64 s[68:69], s[14:15]
	s_cbranch_execz .LBB0_1794
	global_load_dwordx4 v[116:119], v[114:115], off
	s_waitcnt vmcnt(0)
	v_mov_b32_e32 v120, v117
	v_mov_b32_e32 v121, v118
	v_mov_b32_e32 v117, v119
	v_add_f32_e32 v116, v120, v116
	v_add_f32_e32 v117, v121, v117
	s_nop 0
	v_add_f32_e32 v116, v116, v117
	v_add_f32_e32 v116, 0, v116
.LBB0_1794:
	s_or_b64 exec, exec, s[68:69]
	s_and_saveexec_b64 s[68:69], s[16:17]
	s_cbranch_execz .LBB0_1796
	global_load_dwordx4 v[118:121], v[114:115], off offset:64
	s_waitcnt vmcnt(0)
	v_mov_b32_e32 v114, v119
	v_mov_b32_e32 v115, v120
	v_mov_b32_e32 v119, v121
	v_add_f32_e32 v114, v114, v118
	v_add_f32_e32 v115, v115, v119
	s_nop 0
	v_add_f32_e32 v114, v114, v115
	v_add_f32_e32 v116, v116, v114
.LBB0_1796:
	s_or_b64 exec, exec, s[68:69]
	ds_bpermute_b32 v114, v153, v116
	v_lshlrev_b64 v[112:113], 14, v[112:113]
	v_lshl_add_u64 v[112:113], s[50:51], 0, v[112:113]
	v_lshl_add_u64 v[112:113], v[146:147], 1, v[112:113]
	s_waitcnt lgkmcnt(0)
	v_add_f32_e32 v114, v116, v114
	ds_bpermute_b32 v115, v154, v114
	s_waitcnt lgkmcnt(0)
	v_add_f32_e32 v114, v114, v115
	v_fmamk_f32 v114, v114, 0x3a000000, v158
	v_rsq_f32_e32 v114, v114
	s_nop 0
	v_mul_f32_e32 v108, v108, v114
	v_mul_f32_e32 v109, v109, v114
	v_mul_f32_e32 v106, v106, v114
	v_mul_f32_e32 v107, v107, v114
	v_mul_f32_e32 v104, v104, v114
	v_mul_f32_e32 v105, v105, v114
	v_mul_f32_e32 v110, v110, v114
	v_mul_f32_e32 v111, v111, v114
	v_max_f32_e32 v104, 0, v104
	v_max_f32_e32 v109, 0, v109
	v_max_f32_e32 v105, 0, v105
	v_max_f32_e32 v106, 0, v106
	v_max_f32_e32 v108, 0, v108
	v_mul_f32_e32 v115, v104, v104
	v_mul_f32_e32 v104, v109, v109
	v_mul_f32_e32 v109, v105, v105
	v_max_f32_e32 v105, 0, v110
	v_mul_f32_e32 v110, v106, v106
	v_max_f32_e32 v106, 0, v111
	v_max_f32_e32 v107, 0, v107
	v_mul_f32_e32 v108, v108, v108
	v_mul_f32_e32 v105, v105, v105
	v_mul_f32_e32 v106, v106, v106
	v_mul_f32_e32 v107, v107, v107
	v_mul_f32_e32 v98, v98, v114
	v_mul_f32_e32 v99, v99, v114
	v_mul_f32_e32 v96, v96, v114
	v_mul_f32_e32 v97, v97, v114
	v_cvt_pk_bf16_f32 v104, v108, v104
	v_cvt_pk_bf16_f32 v105, v105, v106
	v_cvt_pk_bf16_f32 v106, v115, v109
	v_cvt_pk_bf16_f32 v107, v110, v107
	v_mul_f32_e32 v102, v102, v114
	v_mul_f32_e32 v103, v103, v114
	v_mul_f32_e32 v100, v100, v114
	v_mul_f32_e32 v101, v101, v114
	v_max_f32_e32 v96, 0, v96
	v_max_f32_e32 v97, 0, v97
	v_max_f32_e32 v98, 0, v98
	global_store_dwordx4 v[112:113], v[104:107], off
	v_max_f32_e32 v100, 0, v100
	v_max_f32_e32 v99, 0, v99
	v_mul_f32_e32 v104, v96, v96
	v_max_f32_e32 v96, 0, v101
	v_mul_f32_e32 v101, v97, v97
	v_max_f32_e32 v97, 0, v102
	v_mul_f32_e32 v102, v98, v98
	v_max_f32_e32 v98, 0, v103
	v_mul_f32_e32 v100, v100, v100
	v_mul_f32_e32 v96, v96, v96
	v_mul_f32_e32 v97, v97, v97
	v_mul_f32_e32 v98, v98, v98
	v_mul_f32_e32 v99, v99, v99
	v_cvt_pk_bf16_f32 v96, v100, v96
	v_cvt_pk_bf16_f32 v97, v97, v98
	v_cvt_pk_bf16_f32 v98, v104, v101
	v_cvt_pk_bf16_f32 v99, v102, v99
	global_store_dwordx4 v[112:113], v[96:99], off offset:256
	v_mov_b32_e32 v100, 0
	s_nop 0
	v_or_b32_e32 v96, 32, v148
	v_ashrrev_i32_e32 v97, 31, v96
	v_lshlrev_b64 v[98:99], 7, v[96:97]
	v_lshl_add_u64 v[98:99], s[52:53], 0, v[98:99]
	v_lshl_add_u64 v[98:99], v[136:137], 4, v[98:99]
	s_and_saveexec_b64 s[68:69], s[14:15]
	s_cbranch_execz .LBB0_1798
	global_load_dwordx4 v[100:103], v[98:99], off
	s_waitcnt vmcnt(0)
	v_mov_b32_e32 v104, v101
	v_mov_b32_e32 v105, v102
	v_mov_b32_e32 v101, v103
	v_add_f32_e32 v100, v104, v100
	v_add_f32_e32 v101, v105, v101
	s_nop 0
	v_add_f32_e32 v100, v100, v101
	v_add_f32_e32 v100, 0, v100
.LBB0_1798:
	s_or_b64 exec, exec, s[68:69]
	s_and_saveexec_b64 s[68:69], s[16:17]
	s_cbranch_execz .LBB0_1800
	global_load_dwordx4 v[102:105], v[98:99], off offset:64
	s_waitcnt vmcnt(0)
	v_mov_b32_e32 v98, v103
	v_mov_b32_e32 v99, v104
	v_mov_b32_e32 v103, v105
	v_add_f32_e32 v98, v98, v102
	v_add_f32_e32 v99, v99, v103
	s_nop 0
	v_add_f32_e32 v98, v98, v99
	v_add_f32_e32 v100, v100, v98
.LBB0_1800:
	s_or_b64 exec, exec, s[68:69]
	ds_bpermute_b32 v98, v153, v100
	v_lshlrev_b64 v[96:97], 14, v[96:97]
	v_lshl_add_u64 v[96:97], s[50:51], 0, v[96:97]
	v_lshl_add_u64 v[96:97], v[146:147], 1, v[96:97]
	s_waitcnt lgkmcnt(0)
	v_add_f32_e32 v98, v100, v98
	ds_bpermute_b32 v99, v154, v98
	s_waitcnt lgkmcnt(0)
	v_add_f32_e32 v98, v98, v99
	v_fmamk_f32 v98, v98, 0x3a000000, v158
	v_rsq_f32_e32 v98, v98
	s_nop 0
	v_mul_f32_e32 v92, v92, v98
	v_mul_f32_e32 v93, v93, v98
	v_mul_f32_e32 v90, v90, v98
	v_mul_f32_e32 v91, v91, v98
	v_mul_f32_e32 v88, v88, v98
	v_mul_f32_e32 v89, v89, v98
	v_mul_f32_e32 v94, v94, v98
	v_mul_f32_e32 v95, v95, v98
	v_max_f32_e32 v88, 0, v88
	v_max_f32_e32 v93, 0, v93
	v_max_f32_e32 v89, 0, v89
	v_max_f32_e32 v90, 0, v90
	v_max_f32_e32 v92, 0, v92
	v_mul_f32_e32 v99, v88, v88
	v_mul_f32_e32 v88, v93, v93
	v_mul_f32_e32 v93, v89, v89
	v_max_f32_e32 v89, 0, v94
	v_mul_f32_e32 v94, v90, v90
	v_max_f32_e32 v90, 0, v95
	v_max_f32_e32 v91, 0, v91
	v_mul_f32_e32 v92, v92, v92
	v_mul_f32_e32 v89, v89, v89
	v_mul_f32_e32 v90, v90, v90
	v_mul_f32_e32 v91, v91, v91
	v_mul_f32_e32 v82, v82, v98
	v_mul_f32_e32 v83, v83, v98
	v_mul_f32_e32 v80, v80, v98
	v_mul_f32_e32 v81, v81, v98
	v_cvt_pk_bf16_f32 v88, v92, v88
	v_cvt_pk_bf16_f32 v89, v89, v90
	v_cvt_pk_bf16_f32 v90, v99, v93
	v_cvt_pk_bf16_f32 v91, v94, v91
	v_mul_f32_e32 v86, v86, v98
	v_mul_f32_e32 v87, v87, v98
	v_mul_f32_e32 v84, v84, v98
	v_mul_f32_e32 v85, v85, v98
	v_max_f32_e32 v80, 0, v80
	v_max_f32_e32 v81, 0, v81
	v_max_f32_e32 v82, 0, v82
	global_store_dwordx4 v[96:97], v[88:91], off
	v_max_f32_e32 v84, 0, v84
	v_max_f32_e32 v83, 0, v83
	v_mul_f32_e32 v88, v80, v80
	v_max_f32_e32 v80, 0, v85
	v_mul_f32_e32 v85, v81, v81
	v_max_f32_e32 v81, 0, v86
	v_mul_f32_e32 v86, v82, v82
	v_max_f32_e32 v82, 0, v87
	v_mul_f32_e32 v84, v84, v84
	v_mul_f32_e32 v80, v80, v80
	v_mul_f32_e32 v81, v81, v81
	v_mul_f32_e32 v82, v82, v82
	v_mul_f32_e32 v83, v83, v83
	v_cvt_pk_bf16_f32 v80, v84, v80
	v_cvt_pk_bf16_f32 v81, v81, v82
	v_cvt_pk_bf16_f32 v82, v88, v85
	v_cvt_pk_bf16_f32 v83, v86, v83
	global_store_dwordx4 v[96:97], v[80:83], off offset:256
	v_mov_b32_e32 v84, 0
	s_nop 0
	v_or_b32_e32 v80, 48, v148
	v_ashrrev_i32_e32 v81, 31, v80
	v_lshlrev_b64 v[82:83], 7, v[80:81]
	v_lshl_add_u64 v[82:83], s[52:53], 0, v[82:83]
	v_lshl_add_u64 v[82:83], v[136:137], 4, v[82:83]
	s_and_saveexec_b64 s[68:69], s[14:15]
	s_cbranch_execz .LBB0_1802
	global_load_dwordx4 v[84:87], v[82:83], off
	s_waitcnt vmcnt(0)
	v_mov_b32_e32 v88, v85
	v_mov_b32_e32 v89, v86
	v_mov_b32_e32 v85, v87
	v_add_f32_e32 v84, v88, v84
	v_add_f32_e32 v85, v89, v85
	s_nop 0
	v_add_f32_e32 v84, v84, v85
	v_add_f32_e32 v84, 0, v84
.LBB0_1802:
	s_or_b64 exec, exec, s[68:69]
	s_and_saveexec_b64 s[68:69], s[16:17]
	s_cbranch_execz .LBB0_1804
	global_load_dwordx4 v[86:89], v[82:83], off offset:64
	s_waitcnt vmcnt(0)
	v_mov_b32_e32 v82, v87
	v_mov_b32_e32 v83, v88
	v_mov_b32_e32 v87, v89
	v_add_f32_e32 v82, v82, v86
	v_add_f32_e32 v83, v83, v87
	s_nop 0
	v_add_f32_e32 v82, v82, v83
	v_add_f32_e32 v84, v84, v82
.LBB0_1804:
	s_or_b64 exec, exec, s[68:69]
	ds_bpermute_b32 v82, v153, v84
	v_lshlrev_b64 v[80:81], 14, v[80:81]
	v_lshl_add_u64 v[80:81], s[50:51], 0, v[80:81]
	v_lshl_add_u64 v[80:81], v[146:147], 1, v[80:81]
	s_waitcnt lgkmcnt(0)
	v_add_f32_e32 v82, v84, v82
	ds_bpermute_b32 v83, v154, v82
	s_waitcnt lgkmcnt(0)
	v_add_f32_e32 v82, v82, v83
	v_fmamk_f32 v82, v82, 0x3a000000, v158
	v_rsq_f32_e32 v82, v82
	s_nop 0
	v_mul_f32_e32 v76, v76, v82
	v_mul_f32_e32 v77, v77, v82
	v_mul_f32_e32 v74, v74, v82
	v_mul_f32_e32 v75, v75, v82
	v_mul_f32_e32 v72, v72, v82
	v_mul_f32_e32 v73, v73, v82
	v_mul_f32_e32 v78, v78, v82
	v_mul_f32_e32 v79, v79, v82
	v_max_f32_e32 v72, 0, v72
	v_max_f32_e32 v77, 0, v77
	v_max_f32_e32 v73, 0, v73
	v_max_f32_e32 v74, 0, v74
	v_max_f32_e32 v76, 0, v76
	v_mul_f32_e32 v83, v72, v72
	v_mul_f32_e32 v72, v77, v77
	v_mul_f32_e32 v77, v73, v73
	v_max_f32_e32 v73, 0, v78
	v_mul_f32_e32 v78, v74, v74
	v_max_f32_e32 v74, 0, v79
	v_max_f32_e32 v75, 0, v75
	v_mul_f32_e32 v76, v76, v76
	v_mul_f32_e32 v73, v73, v73
	v_mul_f32_e32 v74, v74, v74
	v_mul_f32_e32 v75, v75, v75
	v_mul_f32_e32 v66, v66, v82
	v_mul_f32_e32 v67, v67, v82
	v_mul_f32_e32 v64, v64, v82
	v_mul_f32_e32 v65, v65, v82
	v_cvt_pk_bf16_f32 v72, v76, v72
	v_cvt_pk_bf16_f32 v73, v73, v74
	v_cvt_pk_bf16_f32 v74, v83, v77
	v_cvt_pk_bf16_f32 v75, v78, v75
	v_mul_f32_e32 v70, v70, v82
	v_mul_f32_e32 v71, v71, v82
	v_mul_f32_e32 v68, v68, v82
	v_mul_f32_e32 v69, v69, v82
	v_max_f32_e32 v64, 0, v64
	v_max_f32_e32 v65, 0, v65
	v_max_f32_e32 v66, 0, v66
	global_store_dwordx4 v[80:81], v[72:75], off
	v_max_f32_e32 v68, 0, v68
	v_max_f32_e32 v67, 0, v67
	v_mul_f32_e32 v72, v64, v64
	v_max_f32_e32 v64, 0, v69
	v_mul_f32_e32 v69, v65, v65
	v_max_f32_e32 v65, 0, v70
	v_mul_f32_e32 v70, v66, v66
	v_max_f32_e32 v66, 0, v71
	v_mul_f32_e32 v68, v68, v68
	v_mul_f32_e32 v64, v64, v64
	v_mul_f32_e32 v65, v65, v65
	v_mul_f32_e32 v66, v66, v66
	v_mul_f32_e32 v67, v67, v67
	v_cvt_pk_bf16_f32 v64, v68, v64
	v_cvt_pk_bf16_f32 v65, v65, v66
	v_cvt_pk_bf16_f32 v66, v72, v69
	v_cvt_pk_bf16_f32 v67, v70, v67
	global_store_dwordx4 v[80:81], v[64:67], off offset:256
	v_mov_b32_e32 v68, 0
	s_nop 0
	v_add_u32_e32 v64, 0x80, v148
	v_ashrrev_i32_e32 v65, 31, v64
	v_lshlrev_b64 v[66:67], 7, v[64:65]
	v_lshl_add_u64 v[66:67], s[52:53], 0, v[66:67]
	v_lshl_add_u64 v[66:67], v[136:137], 4, v[66:67]
	s_and_saveexec_b64 s[68:69], s[14:15]
	s_cbranch_execz .LBB0_1806
	global_load_dwordx4 v[68:71], v[66:67], off
	s_waitcnt vmcnt(0)
	v_mov_b32_e32 v72, v69
	v_mov_b32_e32 v73, v70
	v_mov_b32_e32 v69, v71
	v_add_f32_e32 v68, v72, v68
	v_add_f32_e32 v69, v73, v69
	s_nop 0
	v_add_f32_e32 v68, v68, v69
	v_add_f32_e32 v68, 0, v68
.LBB0_1806:
	s_or_b64 exec, exec, s[68:69]
	s_and_saveexec_b64 s[68:69], s[16:17]
	s_cbranch_execz .LBB0_1808
	global_load_dwordx4 v[70:73], v[66:67], off offset:64
	s_waitcnt vmcnt(0)
	v_mov_b32_e32 v66, v71
	v_mov_b32_e32 v67, v72
	v_mov_b32_e32 v71, v73
	v_add_f32_e32 v66, v66, v70
	v_add_f32_e32 v67, v67, v71
	s_nop 0
	v_add_f32_e32 v66, v66, v67
	v_add_f32_e32 v68, v68, v66
.LBB0_1808:
	s_or_b64 exec, exec, s[68:69]
	ds_bpermute_b32 v66, v153, v68
	v_lshlrev_b64 v[64:65], 14, v[64:65]
	v_lshl_add_u64 v[64:65], s[50:51], 0, v[64:65]
	v_lshl_add_u64 v[64:65], v[146:147], 1, v[64:65]
	s_waitcnt lgkmcnt(0)
	v_add_f32_e32 v66, v68, v66
	ds_bpermute_b32 v67, v154, v66
	s_waitcnt lgkmcnt(0)
	v_add_f32_e32 v66, v66, v67
	v_fmamk_f32 v66, v66, 0x3a000000, v158
	v_rsq_f32_e32 v66, v66
	s_nop 0
	v_mul_f32_e32 v60, v60, v66
	v_mul_f32_e32 v61, v61, v66
	v_mul_f32_e32 v58, v58, v66
	v_mul_f32_e32 v59, v59, v66
	v_mul_f32_e32 v56, v56, v66
	v_mul_f32_e32 v57, v57, v66
	v_mul_f32_e32 v62, v62, v66
	v_mul_f32_e32 v63, v63, v66
	v_max_f32_e32 v56, 0, v56
	v_max_f32_e32 v61, 0, v61
	v_max_f32_e32 v57, 0, v57
	v_max_f32_e32 v58, 0, v58
	v_max_f32_e32 v60, 0, v60
	v_mul_f32_e32 v67, v56, v56
	v_mul_f32_e32 v56, v61, v61
	v_mul_f32_e32 v61, v57, v57
	v_max_f32_e32 v57, 0, v62
	v_mul_f32_e32 v62, v58, v58
	v_max_f32_e32 v58, 0, v63
	v_max_f32_e32 v59, 0, v59
	v_mul_f32_e32 v60, v60, v60
	v_mul_f32_e32 v57, v57, v57
	v_mul_f32_e32 v58, v58, v58
	v_mul_f32_e32 v59, v59, v59
	v_mul_f32_e32 v50, v50, v66
	v_mul_f32_e32 v51, v51, v66
	v_mul_f32_e32 v48, v48, v66
	v_mul_f32_e32 v49, v49, v66
	v_cvt_pk_bf16_f32 v56, v60, v56
	v_cvt_pk_bf16_f32 v57, v57, v58
	v_cvt_pk_bf16_f32 v58, v67, v61
	v_cvt_pk_bf16_f32 v59, v62, v59
	v_mul_f32_e32 v54, v54, v66
	v_mul_f32_e32 v55, v55, v66
	v_mul_f32_e32 v52, v52, v66
	v_mul_f32_e32 v53, v53, v66
	v_max_f32_e32 v48, 0, v48
	v_max_f32_e32 v49, 0, v49
	v_max_f32_e32 v50, 0, v50
	global_store_dwordx4 v[64:65], v[56:59], off
	v_max_f32_e32 v52, 0, v52
	v_max_f32_e32 v51, 0, v51
	v_mul_f32_e32 v56, v48, v48
	v_max_f32_e32 v48, 0, v53
	v_mul_f32_e32 v53, v49, v49
	v_max_f32_e32 v49, 0, v54
	v_mul_f32_e32 v54, v50, v50
	v_max_f32_e32 v50, 0, v55
	v_mul_f32_e32 v52, v52, v52
	v_mul_f32_e32 v48, v48, v48
	v_mul_f32_e32 v49, v49, v49
	v_mul_f32_e32 v50, v50, v50
	v_mul_f32_e32 v51, v51, v51
	v_cvt_pk_bf16_f32 v48, v52, v48
	v_cvt_pk_bf16_f32 v49, v49, v50
	v_cvt_pk_bf16_f32 v50, v56, v53
	v_cvt_pk_bf16_f32 v51, v54, v51
	global_store_dwordx4 v[64:65], v[48:51], off offset:256
	v_mov_b32_e32 v52, 0
	s_nop 0
	v_add_u32_e32 v48, 0x90, v148
	v_ashrrev_i32_e32 v49, 31, v48
	v_lshlrev_b64 v[50:51], 7, v[48:49]
	v_lshl_add_u64 v[50:51], s[52:53], 0, v[50:51]
	v_lshl_add_u64 v[50:51], v[136:137], 4, v[50:51]
	s_and_saveexec_b64 s[68:69], s[14:15]
	s_cbranch_execz .LBB0_1810
	global_load_dwordx4 v[52:55], v[50:51], off
	s_waitcnt vmcnt(0)
	v_mov_b32_e32 v56, v53
	v_mov_b32_e32 v57, v54
	v_mov_b32_e32 v53, v55
	v_add_f32_e32 v52, v56, v52
	v_add_f32_e32 v53, v57, v53
	s_nop 0
	v_add_f32_e32 v52, v52, v53
	v_add_f32_e32 v52, 0, v52
.LBB0_1810:
	s_or_b64 exec, exec, s[68:69]
	s_and_saveexec_b64 s[68:69], s[16:17]
	s_cbranch_execz .LBB0_1812
	global_load_dwordx4 v[54:57], v[50:51], off offset:64
	s_waitcnt vmcnt(0)
	v_mov_b32_e32 v50, v55
	v_mov_b32_e32 v51, v56
	v_mov_b32_e32 v55, v57
	v_add_f32_e32 v50, v50, v54
	v_add_f32_e32 v51, v51, v55
	s_nop 0
	v_add_f32_e32 v50, v50, v51
	v_add_f32_e32 v52, v52, v50
.LBB0_1812:
	s_or_b64 exec, exec, s[68:69]
	ds_bpermute_b32 v50, v153, v52
	v_lshlrev_b64 v[48:49], 14, v[48:49]
	v_lshl_add_u64 v[48:49], s[50:51], 0, v[48:49]
	v_lshl_add_u64 v[48:49], v[146:147], 1, v[48:49]
	s_waitcnt lgkmcnt(0)
	v_add_f32_e32 v50, v52, v50
	ds_bpermute_b32 v51, v154, v50
	s_waitcnt lgkmcnt(0)
	v_add_f32_e32 v50, v50, v51
	v_fmamk_f32 v50, v50, 0x3a000000, v158
	v_rsq_f32_e32 v50, v50
	s_nop 0
	v_mul_f32_e32 v44, v44, v50
	v_mul_f32_e32 v45, v45, v50
	v_mul_f32_e32 v42, v42, v50
	v_mul_f32_e32 v43, v43, v50
	v_mul_f32_e32 v40, v40, v50
	v_mul_f32_e32 v41, v41, v50
	v_mul_f32_e32 v46, v46, v50
	v_mul_f32_e32 v47, v47, v50
	v_max_f32_e32 v40, 0, v40
	v_max_f32_e32 v45, 0, v45
	v_max_f32_e32 v41, 0, v41
	v_max_f32_e32 v42, 0, v42
	v_max_f32_e32 v44, 0, v44
	v_mul_f32_e32 v51, v40, v40
	v_mul_f32_e32 v40, v45, v45
	v_mul_f32_e32 v45, v41, v41
	v_max_f32_e32 v41, 0, v46
	v_mul_f32_e32 v46, v42, v42
	v_max_f32_e32 v42, 0, v47
	v_max_f32_e32 v43, 0, v43
	v_mul_f32_e32 v44, v44, v44
	v_mul_f32_e32 v41, v41, v41
	v_mul_f32_e32 v42, v42, v42
	v_mul_f32_e32 v43, v43, v43
	v_mul_f32_e32 v34, v34, v50
	v_mul_f32_e32 v35, v35, v50
	v_mul_f32_e32 v32, v32, v50
	v_mul_f32_e32 v33, v33, v50
	v_cvt_pk_bf16_f32 v40, v44, v40
	v_cvt_pk_bf16_f32 v41, v41, v42
	v_cvt_pk_bf16_f32 v42, v51, v45
	v_cvt_pk_bf16_f32 v43, v46, v43
	v_mul_f32_e32 v38, v38, v50
	v_mul_f32_e32 v39, v39, v50
	v_mul_f32_e32 v36, v36, v50
	v_mul_f32_e32 v37, v37, v50
	v_max_f32_e32 v32, 0, v32
	v_max_f32_e32 v33, 0, v33
	v_max_f32_e32 v34, 0, v34
	global_store_dwordx4 v[48:49], v[40:43], off
	v_max_f32_e32 v36, 0, v36
	v_max_f32_e32 v35, 0, v35
	v_mul_f32_e32 v40, v32, v32
	v_max_f32_e32 v32, 0, v37
	v_mul_f32_e32 v37, v33, v33
	v_max_f32_e32 v33, 0, v38
	v_mul_f32_e32 v38, v34, v34
	v_max_f32_e32 v34, 0, v39
	v_mul_f32_e32 v36, v36, v36
	v_mul_f32_e32 v32, v32, v32
	v_mul_f32_e32 v33, v33, v33
	v_mul_f32_e32 v34, v34, v34
	v_mul_f32_e32 v35, v35, v35
	v_cvt_pk_bf16_f32 v32, v36, v32
	v_cvt_pk_bf16_f32 v33, v33, v34
	v_cvt_pk_bf16_f32 v34, v40, v37
	v_cvt_pk_bf16_f32 v35, v38, v35
	global_store_dwordx4 v[48:49], v[32:35], off offset:256
	v_mov_b32_e32 v36, 0
	s_nop 0
	v_add_u32_e32 v32, 0xa0, v148
	v_ashrrev_i32_e32 v33, 31, v32
	v_lshlrev_b64 v[34:35], 7, v[32:33]
	v_lshl_add_u64 v[34:35], s[52:53], 0, v[34:35]
	v_lshl_add_u64 v[34:35], v[136:137], 4, v[34:35]
	s_and_saveexec_b64 s[68:69], s[14:15]
	s_cbranch_execz .LBB0_1814
	global_load_dwordx4 v[36:39], v[34:35], off
	s_waitcnt vmcnt(0)
	v_mov_b32_e32 v40, v37
	v_mov_b32_e32 v41, v38
	v_mov_b32_e32 v37, v39
	v_add_f32_e32 v36, v40, v36
	v_add_f32_e32 v37, v41, v37
	s_nop 0
	v_add_f32_e32 v36, v36, v37
	v_add_f32_e32 v36, 0, v36
.LBB0_1814:
	s_or_b64 exec, exec, s[68:69]
	s_and_saveexec_b64 s[68:69], s[16:17]
	s_cbranch_execz .LBB0_1816
	global_load_dwordx4 v[38:41], v[34:35], off offset:64
	s_waitcnt vmcnt(0)
	v_mov_b32_e32 v34, v39
	v_mov_b32_e32 v35, v40
	v_mov_b32_e32 v39, v41
	v_add_f32_e32 v34, v34, v38
	v_add_f32_e32 v35, v35, v39
	s_nop 0
	v_add_f32_e32 v34, v34, v35
	v_add_f32_e32 v36, v36, v34
.LBB0_1816:
	s_or_b64 exec, exec, s[68:69]
	ds_bpermute_b32 v34, v153, v36
	v_lshlrev_b64 v[32:33], 14, v[32:33]
	v_lshl_add_u64 v[32:33], s[50:51], 0, v[32:33]
	v_lshl_add_u64 v[32:33], v[146:147], 1, v[32:33]
	s_waitcnt lgkmcnt(0)
	v_add_f32_e32 v34, v36, v34
	ds_bpermute_b32 v35, v154, v34
	s_waitcnt lgkmcnt(0)
	v_add_f32_e32 v34, v34, v35
	v_fmamk_f32 v34, v34, 0x3a000000, v158
	v_rsq_f32_e32 v34, v34
	s_nop 0
	v_mul_f32_e32 v28, v28, v34
	v_mul_f32_e32 v29, v29, v34
	v_mul_f32_e32 v26, v26, v34
	v_mul_f32_e32 v27, v27, v34
	v_mul_f32_e32 v24, v24, v34
	v_mul_f32_e32 v25, v25, v34
	v_mul_f32_e32 v30, v30, v34
	v_mul_f32_e32 v31, v31, v34
	v_max_f32_e32 v24, 0, v24
	v_max_f32_e32 v29, 0, v29
	v_max_f32_e32 v25, 0, v25
	v_max_f32_e32 v26, 0, v26
	v_max_f32_e32 v28, 0, v28
	v_mul_f32_e32 v35, v24, v24
	v_mul_f32_e32 v24, v29, v29
	v_mul_f32_e32 v29, v25, v25
	v_max_f32_e32 v25, 0, v30
	v_mul_f32_e32 v30, v26, v26
	v_max_f32_e32 v26, 0, v31
	v_max_f32_e32 v27, 0, v27
	v_mul_f32_e32 v28, v28, v28
	v_mul_f32_e32 v25, v25, v25
	v_mul_f32_e32 v26, v26, v26
	v_mul_f32_e32 v27, v27, v27
	v_mul_f32_e32 v18, v18, v34
	v_mul_f32_e32 v19, v19, v34
	v_mul_f32_e32 v16, v16, v34
	v_mul_f32_e32 v17, v17, v34
	v_cvt_pk_bf16_f32 v24, v28, v24
	v_cvt_pk_bf16_f32 v25, v25, v26
	v_cvt_pk_bf16_f32 v26, v35, v29
	v_cvt_pk_bf16_f32 v27, v30, v27
	v_mul_f32_e32 v22, v22, v34
	v_mul_f32_e32 v23, v23, v34
	v_mul_f32_e32 v20, v20, v34
	v_mul_f32_e32 v21, v21, v34
	v_max_f32_e32 v16, 0, v16
	v_max_f32_e32 v17, 0, v17
	v_max_f32_e32 v18, 0, v18
	global_store_dwordx4 v[32:33], v[24:27], off
	v_max_f32_e32 v20, 0, v20
	v_max_f32_e32 v19, 0, v19
	v_mul_f32_e32 v24, v16, v16
	v_max_f32_e32 v16, 0, v21
	v_mul_f32_e32 v21, v17, v17
	v_max_f32_e32 v17, 0, v22
	v_mul_f32_e32 v22, v18, v18
	v_max_f32_e32 v18, 0, v23
	v_mul_f32_e32 v20, v20, v20
	v_mul_f32_e32 v16, v16, v16
	v_mul_f32_e32 v17, v17, v17
	v_mul_f32_e32 v18, v18, v18
	v_mul_f32_e32 v19, v19, v19
	v_cvt_pk_bf16_f32 v16, v20, v16
	v_cvt_pk_bf16_f32 v17, v17, v18
	v_cvt_pk_bf16_f32 v18, v24, v21
	v_cvt_pk_bf16_f32 v19, v22, v19
	global_store_dwordx4 v[32:33], v[16:19], off offset:256
	v_mov_b32_e32 v20, 0
	s_nop 0
	v_add_u32_e32 v16, 0xb0, v148
	v_ashrrev_i32_e32 v17, 31, v16
	v_lshlrev_b64 v[18:19], 7, v[16:17]
	v_lshl_add_u64 v[18:19], s[52:53], 0, v[18:19]
	v_lshl_add_u64 v[18:19], v[136:137], 4, v[18:19]
	s_and_saveexec_b64 s[68:69], s[14:15]
	s_cbranch_execz .LBB0_1818
	global_load_dwordx4 v[20:23], v[18:19], off
	s_waitcnt vmcnt(0)
	v_mov_b32_e32 v24, v21
	v_mov_b32_e32 v25, v22
	v_mov_b32_e32 v21, v23
	v_add_f32_e32 v20, v24, v20
	v_add_f32_e32 v21, v25, v21
	s_nop 0
	v_add_f32_e32 v20, v20, v21
	v_add_f32_e32 v20, 0, v20
.LBB0_1818:
	s_or_b64 exec, exec, s[68:69]
	s_and_saveexec_b64 s[68:69], s[16:17]
	s_cbranch_execz .LBB0_1820
	global_load_dwordx4 v[22:25], v[18:19], off offset:64
	s_waitcnt vmcnt(0)
	v_mov_b32_e32 v18, v23
	v_mov_b32_e32 v19, v24
	v_mov_b32_e32 v23, v25
	v_add_f32_e32 v18, v18, v22
	v_add_f32_e32 v19, v19, v23
	s_nop 0
	v_add_f32_e32 v18, v18, v19
	v_add_f32_e32 v20, v20, v18
.LBB0_1820:
	s_or_b64 exec, exec, s[68:69]
	ds_bpermute_b32 v18, v153, v20
	v_lshlrev_b64 v[16:17], 14, v[16:17]
	v_lshl_add_u64 v[16:17], s[50:51], 0, v[16:17]
	v_lshl_add_u64 v[16:17], v[146:147], 1, v[16:17]
	s_andn2_b64 vcc, exec, s[18:19]
	s_waitcnt lgkmcnt(0)
	v_add_f32_e32 v18, v20, v18
	ds_bpermute_b32 v19, v154, v18
	s_mov_b64 s[18:19], -1
	s_waitcnt lgkmcnt(0)
	v_add_f32_e32 v18, v18, v19
	v_fmamk_f32 v18, v18, 0x3a000000, v158
	v_rsq_f32_e32 v18, v18
	s_nop 0
	v_mul_f32_e32 v12, v12, v18
	v_mul_f32_e32 v13, v13, v18
	v_mul_f32_e32 v10, v10, v18
	v_mul_f32_e32 v11, v11, v18
	v_mul_f32_e32 v8, v8, v18
	v_mul_f32_e32 v9, v9, v18
	v_mul_f32_e32 v14, v14, v18
	v_mul_f32_e32 v15, v15, v18
	v_max_f32_e32 v8, 0, v8
	v_max_f32_e32 v13, 0, v13
	v_max_f32_e32 v9, 0, v9
	v_max_f32_e32 v10, 0, v10
	v_max_f32_e32 v12, 0, v12
	v_mul_f32_e32 v19, v8, v8
	v_mul_f32_e32 v8, v13, v13
	v_mul_f32_e32 v13, v9, v9
	v_max_f32_e32 v9, 0, v14
	v_mul_f32_e32 v14, v10, v10
	v_max_f32_e32 v10, 0, v15
	v_max_f32_e32 v11, 0, v11
	v_mul_f32_e32 v12, v12, v12
	v_mul_f32_e32 v9, v9, v9
	v_mul_f32_e32 v10, v10, v10
	v_mul_f32_e32 v11, v11, v11
	v_mul_f32_e32 v2, v2, v18
	v_mul_f32_e32 v3, v3, v18
	v_mul_f32_e32 v0, v0, v18
	v_mul_f32_e32 v1, v1, v18
	v_cvt_pk_bf16_f32 v8, v12, v8
	v_cvt_pk_bf16_f32 v9, v9, v10
	v_cvt_pk_bf16_f32 v10, v19, v13
	v_cvt_pk_bf16_f32 v11, v14, v11
	v_mul_f32_e32 v6, v6, v18
	v_mul_f32_e32 v7, v7, v18
	v_mul_f32_e32 v4, v4, v18
	v_mul_f32_e32 v5, v5, v18
	v_max_f32_e32 v0, 0, v0
	v_max_f32_e32 v1, 0, v1
	v_max_f32_e32 v2, 0, v2
	global_store_dwordx4 v[16:17], v[8:11], off
	v_max_f32_e32 v4, 0, v4
	v_max_f32_e32 v3, 0, v3
	v_mul_f32_e32 v8, v0, v0
	v_max_f32_e32 v0, 0, v5
	v_mul_f32_e32 v5, v1, v1
	v_max_f32_e32 v1, 0, v6
	v_mul_f32_e32 v6, v2, v2
	v_max_f32_e32 v2, 0, v7
	v_mul_f32_e32 v4, v4, v4
	v_mul_f32_e32 v0, v0, v0
	v_mul_f32_e32 v1, v1, v1
	v_mul_f32_e32 v2, v2, v2
	v_mul_f32_e32 v3, v3, v3
	v_cvt_pk_bf16_f32 v0, v4, v0
	v_cvt_pk_bf16_f32 v1, v1, v2
	v_cvt_pk_bf16_f32 v2, v8, v5
	v_cvt_pk_bf16_f32 v3, v6, v3
	global_store_dwordx4 v[16:17], v[0:3], off offset:256
	s_cbranch_vccnz .LBB0_1777
	s_and_b64 vcc, exec, s[10:11]
	s_cbranch_vccnz .LBB0_1776
	s_barrier
	s_branch .LBB0_1776

.LBB0_1900:
	v_lshl_add_u32 v142, s70, 8, v144
	v_lshl_add_u32 v140, s20, 8, v146
	v_lshl_add_u32 v208, v142, 11, v140
	v_lshlrev_b32_e32 v208, 2, v208
	global_load_dwordx4 v[160:163], v208, s[18:19]
	global_load_dwordx4 v[164:167], v208, s[18:19] offset:64
	global_load_dwordx4 v[168:171], v208, s[18:19] offset:512
	global_load_dwordx4 v[172:175], v208, s[18:19] offset:576
	v_add_u32_e32 v209, 0x20000, v208
	global_load_dwordx4 v[176:179], v209, s[18:19]
	global_load_dwordx4 v[180:183], v209, s[18:19] offset:64
	global_load_dwordx4 v[184:187], v209, s[18:19] offset:512
	global_load_dwordx4 v[188:191], v209, s[18:19] offset:576
	v_add_u32_e32 v209, 0x40000, v208
	global_load_dwordx4 v[192:195], v209, s[18:19]
	global_load_dwordx4 v[196:199], v209, s[18:19] offset:64
	global_load_dwordx4 v[200:203], v209, s[18:19] offset:512
	global_load_dwordx4 v[204:207], v209, s[18:19] offset:576
	v_ashrrev_i32_e32 v143, 31, v142
	v_ashrrev_i32_e32 v141, 31, v140
	v_lshlrev_b64 v[152:153], 11, v[142:143]
	v_lshl_add_u64 v[156:157], v[152:153], 0, v[140:141]
	v_lshl_add_u64 v[158:159], v[156:157], 2, s[18:19]
	s_nop 0
	v_lshl_add_u64 v[156:157], v[156:157], 1, s[54:55]
	s_lshl_b32 s70, s20, 2
	s_ashr_i32 s71, s70, 31
	s_waitcnt vmcnt(11)
	v_add_f32_e32 v126, v126, v162
	v_add_f32_e32 v127, v127, v163
	v_add_f32_e32 v124, v124, v160
	v_add_f32_e32 v125, v125, v161
	v_cvt_pk_bf16_f32 v153, v126, v127
	v_cvt_pk_bf16_f32 v152, v124, v125
	global_store_dwordx4 v[158:159], v[124:127], off
	global_store_dwordx2 v[156:157], v[152:153], off
	s_nop 0
	v_mul_f32_e32 v125, v125, v125
	v_mul_f32_e32 v127, v127, v127
	v_fmac_f32_e32 v125, v124, v124
	v_fmac_f32_e32 v127, v126, v126
	v_add_f32_e32 v124, v125, v127
	s_waitcnt vmcnt(12)
	v_add_f32_e32 v122, v122, v166
	v_add_f32_e32 v123, v123, v167
	v_add_f32_e32 v120, v120, v164
	v_add_f32_e32 v121, v121, v165
	v_cvt_pk_bf16_f32 v153, v122, v123
	v_cvt_pk_bf16_f32 v152, v120, v121
	global_store_dwordx4 v[158:159], v[120:123], off offset:64
	global_store_dwordx2 v[156:157], v[152:153], off offset:32
	s_nop 0
	v_mul_f32_e32 v121, v121, v121
	v_mul_f32_e32 v123, v123, v123
	v_fmac_f32_e32 v121, v120, v120
	v_fmac_f32_e32 v123, v122, v122
	v_add_f32_e32 v120, v121, v123
	v_add_f32_e32 v120, v124, v120
	s_waitcnt vmcnt(13)
	v_add_f32_e32 v118, v118, v170
	v_add_f32_e32 v119, v119, v171
	v_add_f32_e32 v116, v116, v168
	v_add_f32_e32 v117, v117, v169
	v_cvt_pk_bf16_f32 v153, v118, v119
	v_cvt_pk_bf16_f32 v152, v116, v117
	global_store_dwordx4 v[158:159], v[116:119], off offset:512
	global_store_dwordx2 v[156:157], v[152:153], off offset:256
	s_nop 0
	v_mul_f32_e32 v117, v117, v117
	v_mul_f32_e32 v119, v119, v119
	v_fmac_f32_e32 v117, v116, v116
	v_fmac_f32_e32 v119, v118, v118
	v_add_f32_e32 v116, v117, v119
	v_add_f32_e32 v118, v120, v116
	s_waitcnt vmcnt(14)
	v_add_f32_e32 v116, v114, v174
	v_add_f32_e32 v117, v115, v175
	v_add_f32_e32 v114, v112, v172
	v_add_f32_e32 v115, v113, v173
	v_add_u32_e32 v209, 0x60000, v208
	global_load_dwordx4 v[160:163], v209, s[18:19]
	global_load_dwordx4 v[164:167], v209, s[18:19] offset:64
	global_load_dwordx4 v[168:171], v209, s[18:19] offset:512
	global_load_dwordx4 v[172:175], v209, s[18:19] offset:576
	v_mul_f32_e32 v113, v117, v117
	v_mul_f32_e32 v112, v115, v115
	v_fmac_f32_e32 v112, v114, v114
	v_fmac_f32_e32 v113, v116, v116
	v_add_f32_e32 v112, v112, v113
	v_add_f32_e32 v112, v118, v112
	ds_bpermute_b32 v113, v147, v112
	global_store_dwordx4 v[158:159], v[114:117], off offset:576
	s_waitcnt lgkmcnt(0)
	v_add_f32_e32 v112, v112, v113
	ds_bpermute_b32 v113, v148, v112
	v_cvt_pk_bf16_f32 v114, v114, v115
	v_cvt_pk_bf16_f32 v115, v116, v117
	global_store_dwordx2 v[156:157], v[114:115], off offset:288
	s_and_saveexec_b64 s[72:73], s[14:15]
	s_cbranch_execz .LBB0_1902
	v_lshlrev_b64 v[114:115], 7, v[142:143]
	v_lshl_add_u64 v[114:115], s[52:53], 0, v[114:115]
	v_lshl_add_u64 v[114:115], s[70:71], 2, v[114:115]
	s_lshl_b32 s20, s3, 2
	v_lshl_add_u64 v[114:115], v[114:115], 0, s[20:21]
	s_waitcnt lgkmcnt(0)
	v_add_f32_e32 v112, v112, v113
	global_store_dword v[114:115], v112, off
.LBB0_1902:
	s_or_b64 exec, exec, s[72:73]
	v_or_b32_e32 v112, 16, v142
	s_waitcnt lgkmcnt(0)
	v_ashrrev_i32_e32 v113, 31, v112
	v_lshlrev_b64 v[114:115], 11, v[112:113]
	v_lshl_add_u64 v[118:119], v[114:115], 0, v[140:141]
	v_lshl_add_u64 v[120:121], v[118:119], 2, s[18:19]
	s_nop 0
	v_lshl_add_u64 v[118:119], v[118:119], 1, s[54:55]
	s_waitcnt vmcnt(19)
	v_add_f32_e32 v110, v110, v178
	v_add_f32_e32 v111, v111, v179
	v_add_f32_e32 v108, v108, v176
	v_add_f32_e32 v109, v109, v177
	v_cvt_pk_bf16_f32 v115, v110, v111
	v_cvt_pk_bf16_f32 v114, v108, v109
	global_store_dwordx4 v[120:121], v[108:111], off
	global_store_dwordx2 v[118:119], v[114:115], off
	s_nop 0
	v_mul_f32_e32 v109, v109, v109
	v_mul_f32_e32 v111, v111, v111
	v_fmac_f32_e32 v109, v108, v108
	v_fmac_f32_e32 v111, v110, v110
	v_add_f32_e32 v108, v109, v111
	s_waitcnt vmcnt(20)
	v_add_f32_e32 v106, v106, v182
	v_add_f32_e32 v107, v107, v183
	v_add_f32_e32 v104, v104, v180
	v_add_f32_e32 v105, v105, v181
	v_cvt_pk_bf16_f32 v115, v106, v107
	v_cvt_pk_bf16_f32 v114, v104, v105
	global_store_dwordx4 v[120:121], v[104:107], off offset:64
	global_store_dwordx2 v[118:119], v[114:115], off offset:32
	s_nop 0
	v_mul_f32_e32 v105, v105, v105
	v_mul_f32_e32 v107, v107, v107
	v_fmac_f32_e32 v105, v104, v104
	v_fmac_f32_e32 v107, v106, v106
	v_add_f32_e32 v104, v105, v107
	v_add_f32_e32 v104, v108, v104
	s_waitcnt vmcnt(21)
	v_add_f32_e32 v102, v102, v186
	v_add_f32_e32 v103, v103, v187
	v_add_f32_e32 v100, v100, v184
	v_add_f32_e32 v101, v101, v185
	v_cvt_pk_bf16_f32 v115, v102, v103
	v_cvt_pk_bf16_f32 v114, v100, v101
	global_store_dwordx4 v[120:121], v[100:103], off offset:512
	global_store_dwordx2 v[118:119], v[114:115], off offset:256
	s_nop 0
	v_mul_f32_e32 v101, v101, v101
	v_mul_f32_e32 v103, v103, v103
	v_fmac_f32_e32 v101, v100, v100
	v_fmac_f32_e32 v103, v102, v102
	v_add_f32_e32 v100, v101, v103
	v_add_f32_e32 v102, v104, v100
	s_waitcnt vmcnt(22)
	v_add_f32_e32 v100, v98, v190
	v_add_f32_e32 v101, v99, v191
	v_add_f32_e32 v98, v96, v188
	v_add_f32_e32 v99, v97, v189
	v_add_u32_e32 v209, 0x100000, v208
	global_load_dwordx4 v[176:179], v209, s[18:19]
	global_load_dwordx4 v[180:183], v209, s[18:19] offset:64
	global_load_dwordx4 v[184:187], v209, s[18:19] offset:512
	global_load_dwordx4 v[188:191], v209, s[18:19] offset:576
	v_mul_f32_e32 v97, v101, v101
	v_mul_f32_e32 v96, v99, v99
	v_fmac_f32_e32 v96, v98, v98
	v_fmac_f32_e32 v97, v100, v100
	v_add_f32_e32 v96, v96, v97
	v_add_f32_e32 v96, v102, v96
	ds_bpermute_b32 v97, v147, v96
	global_store_dwordx4 v[120:121], v[98:101], off offset:576
	s_waitcnt lgkmcnt(0)
	v_add_f32_e32 v96, v96, v97
	ds_bpermute_b32 v97, v148, v96
	v_cvt_pk_bf16_f32 v98, v98, v99
	v_cvt_pk_bf16_f32 v99, v100, v101
	global_store_dwordx2 v[118:119], v[98:99], off offset:288
	s_and_saveexec_b64 s[72:73], s[14:15]
	s_cbranch_execz .LBB0_1904
	v_lshlrev_b64 v[98:99], 7, v[112:113]
	v_lshl_add_u64 v[98:99], s[52:53], 0, v[98:99]
	v_lshl_add_u64 v[98:99], s[70:71], 2, v[98:99]
	s_lshl_b32 s20, s3, 2
	v_lshl_add_u64 v[98:99], v[98:99], 0, s[20:21]
	s_waitcnt lgkmcnt(0)
	v_add_f32_e32 v96, v96, v97
	global_store_dword v[98:99], v96, off
.LBB0_1904:
	s_or_b64 exec, exec, s[72:73]
	v_or_b32_e32 v96, 32, v142
	s_waitcnt lgkmcnt(0)
	v_ashrrev_i32_e32 v97, 31, v96
	v_lshlrev_b64 v[98:99], 11, v[96:97]
	v_lshl_add_u64 v[102:103], v[98:99], 0, v[140:141]
	v_lshl_add_u64 v[104:105], v[102:103], 2, s[18:19]
	s_nop 0
	v_lshl_add_u64 v[102:103], v[102:103], 1, s[54:55]
	s_waitcnt vmcnt(27)
	v_add_f32_e32 v94, v94, v194
	v_add_f32_e32 v95, v95, v195
	v_add_f32_e32 v92, v92, v192
	v_add_f32_e32 v93, v93, v193
	v_cvt_pk_bf16_f32 v99, v94, v95
	v_cvt_pk_bf16_f32 v98, v92, v93
	global_store_dwordx4 v[104:105], v[92:95], off
	global_store_dwordx2 v[102:103], v[98:99], off
	s_nop 0
	v_mul_f32_e32 v93, v93, v93
	v_mul_f32_e32 v95, v95, v95
	v_fmac_f32_e32 v93, v92, v92
	v_fmac_f32_e32 v95, v94, v94
	v_add_f32_e32 v92, v93, v95
	s_waitcnt vmcnt(28)
	v_add_f32_e32 v90, v90, v198
	v_add_f32_e32 v91, v91, v199
	v_add_f32_e32 v88, v88, v196
	v_add_f32_e32 v89, v89, v197
	v_cvt_pk_bf16_f32 v99, v90, v91
	v_cvt_pk_bf16_f32 v98, v88, v89
	global_store_dwordx4 v[104:105], v[88:91], off offset:64
	global_store_dwordx2 v[102:103], v[98:99], off offset:32
	s_nop 0
	v_mul_f32_e32 v89, v89, v89
	v_mul_f32_e32 v91, v91, v91
	v_fmac_f32_e32 v89, v88, v88
	v_fmac_f32_e32 v91, v90, v90
	v_add_f32_e32 v88, v89, v91
	v_add_f32_e32 v88, v92, v88
	s_waitcnt vmcnt(29)
	v_add_f32_e32 v86, v86, v202
	v_add_f32_e32 v87, v87, v203
	v_add_f32_e32 v84, v84, v200
	v_add_f32_e32 v85, v85, v201
	v_cvt_pk_bf16_f32 v99, v86, v87
	v_cvt_pk_bf16_f32 v98, v84, v85
	global_store_dwordx4 v[104:105], v[84:87], off offset:512
	global_store_dwordx2 v[102:103], v[98:99], off offset:256
	s_nop 0
	v_mul_f32_e32 v85, v85, v85
	v_mul_f32_e32 v87, v87, v87
	v_fmac_f32_e32 v85, v84, v84
	v_fmac_f32_e32 v87, v86, v86
	v_add_f32_e32 v84, v85, v87
	v_add_f32_e32 v86, v88, v84
	s_waitcnt vmcnt(30)
	v_add_f32_e32 v84, v82, v206
	v_add_f32_e32 v85, v83, v207
	v_add_f32_e32 v82, v80, v204
	v_add_f32_e32 v83, v81, v205
	v_add_u32_e32 v209, 0x120000, v208
	global_load_dwordx4 v[192:195], v209, s[18:19]
	global_load_dwordx4 v[196:199], v209, s[18:19] offset:64
	global_load_dwordx4 v[200:203], v209, s[18:19] offset:512
	global_load_dwordx4 v[204:207], v209, s[18:19] offset:576
	v_mul_f32_e32 v81, v85, v85
	v_mul_f32_e32 v80, v83, v83
	v_fmac_f32_e32 v80, v82, v82
	v_fmac_f32_e32 v81, v84, v84
	v_add_f32_e32 v80, v80, v81
	v_add_f32_e32 v80, v86, v80
	ds_bpermute_b32 v81, v147, v80
	global_store_dwordx4 v[104:105], v[82:85], off offset:576
	s_waitcnt lgkmcnt(0)
	v_add_f32_e32 v80, v80, v81
	ds_bpermute_b32 v81, v148, v80
	v_cvt_pk_bf16_f32 v82, v82, v83
	v_cvt_pk_bf16_f32 v83, v84, v85
	global_store_dwordx2 v[102:103], v[82:83], off offset:288
	s_and_saveexec_b64 s[72:73], s[14:15]
	s_cbranch_execz .LBB0_1906
	v_lshlrev_b64 v[82:83], 7, v[96:97]
	v_lshl_add_u64 v[82:83], s[52:53], 0, v[82:83]
	v_lshl_add_u64 v[82:83], s[70:71], 2, v[82:83]
	s_lshl_b32 s20, s3, 2
	v_lshl_add_u64 v[82:83], v[82:83], 0, s[20:21]
	s_waitcnt lgkmcnt(0)
	v_add_f32_e32 v80, v80, v81
	global_store_dword v[82:83], v80, off
.LBB0_1906:
	s_or_b64 exec, exec, s[72:73]
	v_or_b32_e32 v80, 48, v142
	s_waitcnt lgkmcnt(0)
	v_ashrrev_i32_e32 v81, 31, v80
	v_lshlrev_b64 v[82:83], 11, v[80:81]
	v_lshl_add_u64 v[86:87], v[82:83], 0, v[140:141]
	v_lshl_add_u64 v[88:89], v[86:87], 2, s[18:19]
	s_nop 0
	v_lshl_add_u64 v[86:87], v[86:87], 1, s[54:55]
	s_waitcnt vmcnt(29)
	v_add_f32_e32 v78, v78, v162
	v_add_f32_e32 v79, v79, v163
	v_add_f32_e32 v76, v76, v160
	v_add_f32_e32 v77, v77, v161
	v_cvt_pk_bf16_f32 v83, v78, v79
	v_cvt_pk_bf16_f32 v82, v76, v77
	global_store_dwordx4 v[88:89], v[76:79], off
	global_store_dwordx2 v[86:87], v[82:83], off
	s_nop 0
	v_mul_f32_e32 v77, v77, v77
	v_mul_f32_e32 v79, v79, v79
	v_fmac_f32_e32 v77, v76, v76
	v_fmac_f32_e32 v79, v78, v78
	v_add_f32_e32 v76, v77, v79
	s_waitcnt vmcnt(30)
	v_add_f32_e32 v74, v74, v166
	v_add_f32_e32 v75, v75, v167
	v_add_f32_e32 v72, v72, v164
	v_add_f32_e32 v73, v73, v165
	v_cvt_pk_bf16_f32 v83, v74, v75
	v_cvt_pk_bf16_f32 v82, v72, v73
	global_store_dwordx4 v[88:89], v[72:75], off offset:64
	global_store_dwordx2 v[86:87], v[82:83], off offset:32
	s_nop 0
	v_mul_f32_e32 v73, v73, v73
	v_mul_f32_e32 v75, v75, v75
	v_fmac_f32_e32 v73, v72, v72
	v_fmac_f32_e32 v75, v74, v74
	v_add_f32_e32 v72, v73, v75
	v_add_f32_e32 v72, v76, v72
	s_waitcnt vmcnt(31)
	v_add_f32_e32 v70, v70, v170
	v_add_f32_e32 v71, v71, v171
	v_add_f32_e32 v68, v68, v168
	v_add_f32_e32 v69, v69, v169
	v_cvt_pk_bf16_f32 v83, v70, v71
	v_cvt_pk_bf16_f32 v82, v68, v69
	global_store_dwordx4 v[88:89], v[68:71], off offset:512
	global_store_dwordx2 v[86:87], v[82:83], off offset:256
	s_nop 0
	v_mul_f32_e32 v69, v69, v69
	v_mul_f32_e32 v71, v71, v71
	v_fmac_f32_e32 v69, v68, v68
	v_fmac_f32_e32 v71, v70, v70
	v_add_f32_e32 v68, v69, v71
	v_add_f32_e32 v70, v72, v68
	s_waitcnt vmcnt(32)
	v_add_f32_e32 v68, v66, v174
	v_add_f32_e32 v69, v67, v175
	v_add_f32_e32 v66, v64, v172
	v_add_f32_e32 v67, v65, v173
	v_add_u32_e32 v209, 0x140000, v208
	global_load_dwordx4 v[160:163], v209, s[18:19]
	global_load_dwordx4 v[164:167], v209, s[18:19] offset:64
	global_load_dwordx4 v[168:171], v209, s[18:19] offset:512
	global_load_dwordx4 v[172:175], v209, s[18:19] offset:576
	v_mul_f32_e32 v65, v69, v69
	v_mul_f32_e32 v64, v67, v67
	v_fmac_f32_e32 v64, v66, v66
	v_fmac_f32_e32 v65, v68, v68
	v_add_f32_e32 v64, v64, v65
	v_add_f32_e32 v64, v70, v64
	ds_bpermute_b32 v65, v147, v64
	global_store_dwordx4 v[88:89], v[66:69], off offset:576
	s_waitcnt lgkmcnt(0)
	v_add_f32_e32 v64, v64, v65
	ds_bpermute_b32 v65, v148, v64
	v_cvt_pk_bf16_f32 v66, v66, v67
	v_cvt_pk_bf16_f32 v67, v68, v69
	global_store_dwordx2 v[86:87], v[66:67], off offset:288
	s_and_saveexec_b64 s[72:73], s[14:15]
	s_cbranch_execz .LBB0_1908
	v_lshlrev_b64 v[66:67], 7, v[80:81]
	v_lshl_add_u64 v[66:67], s[52:53], 0, v[66:67]
	v_lshl_add_u64 v[66:67], s[70:71], 2, v[66:67]
	s_lshl_b32 s20, s3, 2
	v_lshl_add_u64 v[66:67], v[66:67], 0, s[20:21]
	s_waitcnt lgkmcnt(0)
	v_add_f32_e32 v64, v64, v65
	global_store_dword v[66:67], v64, off
.LBB0_1908:
	s_or_b64 exec, exec, s[72:73]
	v_add_u32_e32 v64, 0x80, v142
	s_waitcnt lgkmcnt(0)
	v_ashrrev_i32_e32 v65, 31, v64
	v_lshlrev_b64 v[66:67], 11, v[64:65]
	v_lshl_add_u64 v[70:71], v[66:67], 0, v[140:141]
	v_lshl_add_u64 v[72:73], v[70:71], 2, s[18:19]
	s_nop 0
	v_lshl_add_u64 v[70:71], v[70:71], 1, s[54:55]
	s_waitcnt vmcnt(29)
	v_add_f32_e32 v62, v62, v178
	v_add_f32_e32 v63, v63, v179
	v_add_f32_e32 v60, v60, v176
	v_add_f32_e32 v61, v61, v177
	v_cvt_pk_bf16_f32 v67, v62, v63
	v_cvt_pk_bf16_f32 v66, v60, v61
	global_store_dwordx4 v[72:73], v[60:63], off
	global_store_dwordx2 v[70:71], v[66:67], off
	s_nop 0
	v_mul_f32_e32 v61, v61, v61
	v_mul_f32_e32 v63, v63, v63
	v_fmac_f32_e32 v61, v60, v60
	v_fmac_f32_e32 v63, v62, v62
	v_add_f32_e32 v60, v61, v63
	s_waitcnt vmcnt(30)
	v_add_f32_e32 v58, v58, v182
	v_add_f32_e32 v59, v59, v183
	v_add_f32_e32 v56, v56, v180
	v_add_f32_e32 v57, v57, v181
	v_cvt_pk_bf16_f32 v67, v58, v59
	v_cvt_pk_bf16_f32 v66, v56, v57
	global_store_dwordx4 v[72:73], v[56:59], off offset:64
	global_store_dwordx2 v[70:71], v[66:67], off offset:32
	s_nop 0
	v_mul_f32_e32 v57, v57, v57
	v_mul_f32_e32 v59, v59, v59
	v_fmac_f32_e32 v57, v56, v56
	v_fmac_f32_e32 v59, v58, v58
	v_add_f32_e32 v56, v57, v59
	v_add_f32_e32 v56, v60, v56
	s_waitcnt vmcnt(31)
	v_add_f32_e32 v54, v54, v186
	v_add_f32_e32 v55, v55, v187
	v_add_f32_e32 v52, v52, v184
	v_add_f32_e32 v53, v53, v185
	v_cvt_pk_bf16_f32 v67, v54, v55
	v_cvt_pk_bf16_f32 v66, v52, v53
	global_store_dwordx4 v[72:73], v[52:55], off offset:512
	global_store_dwordx2 v[70:71], v[66:67], off offset:256
	s_nop 0
	v_mul_f32_e32 v53, v53, v53
	v_mul_f32_e32 v55, v55, v55
	v_fmac_f32_e32 v53, v52, v52
	v_fmac_f32_e32 v55, v54, v54
	v_add_f32_e32 v52, v53, v55
	v_add_f32_e32 v54, v56, v52
	s_waitcnt vmcnt(32)
	v_add_f32_e32 v52, v50, v190
	v_add_f32_e32 v53, v51, v191
	v_add_f32_e32 v50, v48, v188
	v_add_f32_e32 v51, v49, v189
	v_add_u32_e32 v209, 0x160000, v208
	global_load_dwordx4 v[176:179], v209, s[18:19]
	global_load_dwordx4 v[180:183], v209, s[18:19] offset:64
	global_load_dwordx4 v[184:187], v209, s[18:19] offset:512
	global_load_dwordx4 v[188:191], v209, s[18:19] offset:576
	v_mul_f32_e32 v49, v53, v53
	v_mul_f32_e32 v48, v51, v51
	v_fmac_f32_e32 v48, v50, v50
	v_fmac_f32_e32 v49, v52, v52
	v_add_f32_e32 v48, v48, v49
	v_add_f32_e32 v48, v54, v48
	ds_bpermute_b32 v49, v147, v48
	global_store_dwordx4 v[72:73], v[50:53], off offset:576
	s_waitcnt lgkmcnt(0)
	v_add_f32_e32 v48, v48, v49
	ds_bpermute_b32 v49, v148, v48
	v_cvt_pk_bf16_f32 v50, v50, v51
	v_cvt_pk_bf16_f32 v51, v52, v53
	global_store_dwordx2 v[70:71], v[50:51], off offset:288
	s_and_saveexec_b64 s[72:73], s[14:15]
	s_cbranch_execz .LBB0_1910
	v_lshlrev_b64 v[50:51], 7, v[64:65]
	v_lshl_add_u64 v[50:51], s[52:53], 0, v[50:51]
	v_lshl_add_u64 v[50:51], s[70:71], 2, v[50:51]
	s_lshl_b32 s20, s3, 2
	v_lshl_add_u64 v[50:51], v[50:51], 0, s[20:21]
	s_waitcnt lgkmcnt(0)
	v_add_f32_e32 v48, v48, v49
	global_store_dword v[50:51], v48, off
.LBB0_1910:
	s_or_b64 exec, exec, s[72:73]
	v_add_u32_e32 v48, 0x90, v142
	s_waitcnt lgkmcnt(0)
	v_ashrrev_i32_e32 v49, 31, v48
	v_lshlrev_b64 v[50:51], 11, v[48:49]
	v_lshl_add_u64 v[54:55], v[50:51], 0, v[140:141]
	v_lshl_add_u64 v[56:57], v[54:55], 2, s[18:19]
	s_nop 0
	v_lshl_add_u64 v[54:55], v[54:55], 1, s[54:55]
	s_waitcnt vmcnt(29)
	v_add_f32_e32 v46, v46, v194
	v_add_f32_e32 v47, v47, v195
	v_add_f32_e32 v44, v44, v192
	v_add_f32_e32 v45, v45, v193
	v_cvt_pk_bf16_f32 v51, v46, v47
	v_cvt_pk_bf16_f32 v50, v44, v45
	global_store_dwordx4 v[56:57], v[44:47], off
	global_store_dwordx2 v[54:55], v[50:51], off
	s_nop 0
	v_mul_f32_e32 v45, v45, v45
	v_mul_f32_e32 v47, v47, v47
	v_fmac_f32_e32 v45, v44, v44
	v_fmac_f32_e32 v47, v46, v46
	v_add_f32_e32 v44, v45, v47
	s_waitcnt vmcnt(30)
	v_add_f32_e32 v42, v42, v198
	v_add_f32_e32 v43, v43, v199
	v_add_f32_e32 v40, v40, v196
	v_add_f32_e32 v41, v41, v197
	v_cvt_pk_bf16_f32 v51, v42, v43
	v_cvt_pk_bf16_f32 v50, v40, v41
	global_store_dwordx4 v[56:57], v[40:43], off offset:64
	global_store_dwordx2 v[54:55], v[50:51], off offset:32
	s_nop 0
	v_mul_f32_e32 v41, v41, v41
	v_mul_f32_e32 v43, v43, v43
	v_fmac_f32_e32 v41, v40, v40
	v_fmac_f32_e32 v43, v42, v42
	v_add_f32_e32 v40, v41, v43
	v_add_f32_e32 v40, v44, v40
	s_waitcnt vmcnt(31)
	v_add_f32_e32 v38, v38, v202
	v_add_f32_e32 v39, v39, v203
	v_add_f32_e32 v36, v36, v200
	v_add_f32_e32 v37, v37, v201
	v_cvt_pk_bf16_f32 v51, v38, v39
	v_cvt_pk_bf16_f32 v50, v36, v37
	global_store_dwordx4 v[56:57], v[36:39], off offset:512
	global_store_dwordx2 v[54:55], v[50:51], off offset:256
	s_nop 0
	v_mul_f32_e32 v37, v37, v37
	v_mul_f32_e32 v39, v39, v39
	v_fmac_f32_e32 v37, v36, v36
	v_fmac_f32_e32 v39, v38, v38
	v_add_f32_e32 v36, v37, v39
	v_add_f32_e32 v38, v40, v36
	s_waitcnt vmcnt(32)
	v_add_f32_e32 v36, v34, v206
	v_add_f32_e32 v37, v35, v207
	v_add_f32_e32 v34, v32, v204
	v_add_f32_e32 v35, v33, v205
	v_mul_f32_e32 v33, v37, v37
	v_mul_f32_e32 v32, v35, v35
	v_fmac_f32_e32 v32, v34, v34
	v_fmac_f32_e32 v33, v36, v36
	v_add_f32_e32 v32, v32, v33
	v_add_f32_e32 v32, v38, v32
	ds_bpermute_b32 v33, v147, v32
	global_store_dwordx4 v[56:57], v[34:37], off offset:576
	s_waitcnt lgkmcnt(0)
	v_add_f32_e32 v32, v32, v33
	ds_bpermute_b32 v33, v148, v32
	v_cvt_pk_bf16_f32 v34, v34, v35
	v_cvt_pk_bf16_f32 v35, v36, v37
	global_store_dwordx2 v[54:55], v[34:35], off offset:288
	s_and_saveexec_b64 s[72:73], s[14:15]
	s_cbranch_execz .LBB0_1912
	v_lshlrev_b64 v[34:35], 7, v[48:49]
	v_lshl_add_u64 v[34:35], s[52:53], 0, v[34:35]
	v_lshl_add_u64 v[34:35], s[70:71], 2, v[34:35]
	s_lshl_b32 s20, s3, 2
	v_lshl_add_u64 v[34:35], v[34:35], 0, s[20:21]
	s_waitcnt lgkmcnt(0)
	v_add_f32_e32 v32, v32, v33
	global_store_dword v[34:35], v32, off
.LBB0_1912:
	s_or_b64 exec, exec, s[72:73]
	v_add_u32_e32 v32, 0xa0, v142
	s_waitcnt lgkmcnt(0)
	v_ashrrev_i32_e32 v33, 31, v32
	v_lshlrev_b64 v[34:35], 11, v[32:33]
	v_lshl_add_u64 v[38:39], v[34:35], 0, v[140:141]
	v_lshl_add_u64 v[40:41], v[38:39], 2, s[18:19]
	s_nop 0
	v_lshl_add_u64 v[38:39], v[38:39], 1, s[54:55]
	s_waitcnt vmcnt(25)
	v_add_f32_e32 v30, v30, v162
	v_add_f32_e32 v31, v31, v163
	v_add_f32_e32 v28, v28, v160
	v_add_f32_e32 v29, v29, v161
	v_cvt_pk_bf16_f32 v35, v30, v31
	v_cvt_pk_bf16_f32 v34, v28, v29
	global_store_dwordx4 v[40:41], v[28:31], off
	global_store_dwordx2 v[38:39], v[34:35], off
	s_nop 0
	v_mul_f32_e32 v29, v29, v29
	v_mul_f32_e32 v31, v31, v31
	v_fmac_f32_e32 v29, v28, v28
	v_fmac_f32_e32 v31, v30, v30
	v_add_f32_e32 v28, v29, v31
	s_waitcnt vmcnt(26)
	v_add_f32_e32 v26, v26, v166
	v_add_f32_e32 v27, v27, v167
	v_add_f32_e32 v24, v24, v164
	v_add_f32_e32 v25, v25, v165
	v_cvt_pk_bf16_f32 v35, v26, v27
	v_cvt_pk_bf16_f32 v34, v24, v25
	global_store_dwordx4 v[40:41], v[24:27], off offset:64
	global_store_dwordx2 v[38:39], v[34:35], off offset:32
	s_nop 0
	v_mul_f32_e32 v25, v25, v25
	v_mul_f32_e32 v27, v27, v27
	v_fmac_f32_e32 v25, v24, v24
	v_fmac_f32_e32 v27, v26, v26
	v_add_f32_e32 v24, v25, v27
	v_add_f32_e32 v24, v28, v24
	s_waitcnt vmcnt(27)
	v_add_f32_e32 v22, v22, v170
	v_add_f32_e32 v23, v23, v171
	v_add_f32_e32 v20, v20, v168
	v_add_f32_e32 v21, v21, v169
	v_cvt_pk_bf16_f32 v35, v22, v23
	v_cvt_pk_bf16_f32 v34, v20, v21
	global_store_dwordx4 v[40:41], v[20:23], off offset:512
	global_store_dwordx2 v[38:39], v[34:35], off offset:256
	s_nop 0
	v_mul_f32_e32 v21, v21, v21
	v_mul_f32_e32 v23, v23, v23
	v_fmac_f32_e32 v21, v20, v20
	v_fmac_f32_e32 v23, v22, v22
	v_add_f32_e32 v20, v21, v23
	v_add_f32_e32 v22, v24, v20
	s_waitcnt vmcnt(28)
	v_add_f32_e32 v20, v18, v174
	v_add_f32_e32 v21, v19, v175
	v_add_f32_e32 v18, v16, v172
	v_add_f32_e32 v19, v17, v173
	v_mul_f32_e32 v17, v21, v21
	v_mul_f32_e32 v16, v19, v19
	v_fmac_f32_e32 v16, v18, v18
	v_fmac_f32_e32 v17, v20, v20
	v_add_f32_e32 v16, v16, v17
	v_add_f32_e32 v16, v22, v16
	ds_bpermute_b32 v17, v147, v16
	global_store_dwordx4 v[40:41], v[18:21], off offset:576
	s_waitcnt lgkmcnt(0)
	v_add_f32_e32 v16, v16, v17
	ds_bpermute_b32 v17, v148, v16
	v_cvt_pk_bf16_f32 v18, v18, v19
	v_cvt_pk_bf16_f32 v19, v20, v21
	global_store_dwordx2 v[38:39], v[18:19], off offset:288
	s_and_saveexec_b64 s[72:73], s[14:15]
	s_cbranch_execz .LBB0_1914
	v_lshlrev_b64 v[18:19], 7, v[32:33]
	v_lshl_add_u64 v[18:19], s[52:53], 0, v[18:19]
	v_lshl_add_u64 v[18:19], s[70:71], 2, v[18:19]
	s_lshl_b32 s20, s3, 2
	v_lshl_add_u64 v[18:19], v[18:19], 0, s[20:21]
	s_waitcnt lgkmcnt(0)
	v_add_f32_e32 v16, v16, v17
	global_store_dword v[18:19], v16, off
.LBB0_1914:
	s_or_b64 exec, exec, s[72:73]
	v_add_u32_e32 v16, 0xb0, v142
	s_waitcnt lgkmcnt(0)
	v_ashrrev_i32_e32 v17, 31, v16
	v_lshlrev_b64 v[18:19], 11, v[16:17]
	v_lshl_add_u64 v[22:23], v[18:19], 0, v[140:141]
	v_lshl_add_u64 v[24:25], v[22:23], 2, s[18:19]
	s_nop 0
	v_lshl_add_u64 v[22:23], v[22:23], 1, s[54:55]
	s_waitcnt vmcnt(21)
	v_add_f32_e32 v14, v14, v178
	v_add_f32_e32 v15, v15, v179
	v_add_f32_e32 v12, v12, v176
	v_add_f32_e32 v13, v13, v177
	v_cvt_pk_bf16_f32 v19, v14, v15
	v_cvt_pk_bf16_f32 v18, v12, v13
	global_store_dwordx4 v[24:25], v[12:15], off
	global_store_dwordx2 v[22:23], v[18:19], off
	s_nop 0
	v_mul_f32_e32 v13, v13, v13
	v_mul_f32_e32 v15, v15, v15
	v_fmac_f32_e32 v13, v12, v12
	v_fmac_f32_e32 v15, v14, v14
	v_add_f32_e32 v12, v13, v15
	s_waitcnt vmcnt(22)
	v_add_f32_e32 v10, v10, v182
	v_add_f32_e32 v11, v11, v183
	v_add_f32_e32 v8, v8, v180
	v_add_f32_e32 v9, v9, v181
	v_cvt_pk_bf16_f32 v19, v10, v11
	v_cvt_pk_bf16_f32 v18, v8, v9
	global_store_dwordx4 v[24:25], v[8:11], off offset:64
	global_store_dwordx2 v[22:23], v[18:19], off offset:32
	s_nop 0
	v_mul_f32_e32 v9, v9, v9
	v_mul_f32_e32 v11, v11, v11
	v_fmac_f32_e32 v9, v8, v8
	v_fmac_f32_e32 v11, v10, v10
	v_add_f32_e32 v8, v9, v11
	v_add_f32_e32 v8, v12, v8
	s_waitcnt vmcnt(23)
	v_add_f32_e32 v6, v6, v186
	v_add_f32_e32 v7, v7, v187
	v_add_f32_e32 v4, v4, v184
	v_add_f32_e32 v5, v5, v185
	v_cvt_pk_bf16_f32 v19, v6, v7
	v_cvt_pk_bf16_f32 v18, v4, v5
	global_store_dwordx4 v[24:25], v[4:7], off offset:512
	global_store_dwordx2 v[22:23], v[18:19], off offset:256
	s_nop 0
	v_mul_f32_e32 v5, v5, v5
	v_mul_f32_e32 v7, v7, v7
	v_fmac_f32_e32 v5, v4, v4
	v_fmac_f32_e32 v7, v6, v6
	v_add_f32_e32 v4, v5, v7
	v_add_f32_e32 v6, v8, v4
	s_waitcnt vmcnt(24)
	v_add_f32_e32 v4, v2, v190
	v_add_f32_e32 v5, v3, v191
	v_add_f32_e32 v2, v0, v188
	v_add_f32_e32 v3, v1, v189
	v_mul_f32_e32 v1, v5, v5
	v_mul_f32_e32 v0, v3, v3
	v_fmac_f32_e32 v0, v2, v2
	v_fmac_f32_e32 v1, v4, v4
	v_add_f32_e32 v0, v0, v1
	v_add_f32_e32 v0, v6, v0
	ds_bpermute_b32 v1, v147, v0
	global_store_dwordx4 v[24:25], v[2:5], off offset:576
	s_waitcnt lgkmcnt(0)
	v_add_f32_e32 v0, v0, v1
	ds_bpermute_b32 v1, v148, v0
	v_cvt_pk_bf16_f32 v2, v2, v3
	v_cvt_pk_bf16_f32 v3, v4, v5
	global_store_dwordx2 v[22:23], v[2:3], off offset:288
	s_and_saveexec_b64 s[72:73], s[14:15]
	s_cbranch_execz .LBB0_1916
	v_lshlrev_b64 v[2:3], 7, v[16:17]
	v_lshl_add_u64 v[2:3], s[52:53], 0, v[2:3]
	v_lshl_add_u64 v[2:3], s[70:71], 2, v[2:3]
	s_lshl_b32 s20, s3, 2
	v_lshl_add_u64 v[2:3], v[2:3], 0, s[20:21]
	s_waitcnt lgkmcnt(0)
	v_add_f32_e32 v0, v0, v1
	global_store_dword v[2:3], v0, off

.LBB0_2043:
	s_or_b64 exec, exec, s[64:65]
	v_lshl_add_u64 v[168:169], v[168:169], 2, s[20:21]
	global_load_dword v170, v[168:169], off
	global_load_dword v172, v[168:169], off offset:16
	global_load_dword v174, v[168:169], off offset:32
	global_load_dword v176, v[168:169], off offset:48
	global_load_dword v178, v[168:169], off offset:64
	global_load_dword v180, v[168:169], off offset:80
	global_load_dword v182, v[168:169], off offset:96
	global_load_dword v184, v[168:169], off offset:112
	global_load_dword v186, v[168:169], off offset:128
	global_load_dword v188, v[168:169], off offset:144
	global_load_dword v190, v[168:169], off offset:160
	global_load_dword v192, v[168:169], off offset:176
	global_load_dword v194, v[168:169], off offset:192
	global_load_dword v196, v[168:169], off offset:208
	global_load_dword v198, v[168:169], off offset:224
	s_nop 0
	global_load_dword v168, v[168:169], off offset:240
	s_waitcnt vmcnt(15)
	v_mul_f32_e32 v22, v22, v170
	v_mul_f32_e32 v23, v23, v170
	v_mul_f32_e32 v20, v20, v170
	v_mul_f32_e32 v21, v21, v170
	s_waitcnt vmcnt(14)
	v_mul_f32_e32 v26, v26, v172
	v_mul_f32_e32 v27, v27, v172
	v_mul_f32_e32 v24, v24, v172
	v_mul_f32_e32 v25, v25, v172
	s_waitcnt vmcnt(13)
	v_mul_f32_e32 v30, v30, v174
	v_mul_f32_e32 v31, v31, v174
	v_mul_f32_e32 v28, v28, v174
	v_mul_f32_e32 v29, v29, v174
	s_waitcnt vmcnt(12)
	v_mul_f32_e32 v34, v34, v176
	v_mul_f32_e32 v35, v35, v176
	v_mul_f32_e32 v32, v32, v176
	v_mul_f32_e32 v33, v33, v176
	s_waitcnt vmcnt(11)
	v_mul_f32_e32 v38, v38, v178
	v_mul_f32_e32 v39, v39, v178
	v_mul_f32_e32 v36, v36, v178
	v_mul_f32_e32 v37, v37, v178
	s_waitcnt vmcnt(10)
	v_mul_f32_e32 v42, v42, v180
	v_mul_f32_e32 v43, v43, v180
	v_mul_f32_e32 v40, v40, v180
	v_mul_f32_e32 v41, v41, v180
	s_waitcnt vmcnt(9)
	v_mul_f32_e32 v46, v46, v182
	v_mul_f32_e32 v47, v47, v182
	v_mul_f32_e32 v44, v44, v182
	v_mul_f32_e32 v45, v45, v182
	s_waitcnt vmcnt(8)
	v_mul_f32_e32 v50, v50, v184
	v_mul_f32_e32 v51, v51, v184
	v_mul_f32_e32 v48, v48, v184
	v_mul_f32_e32 v49, v49, v184
	s_waitcnt vmcnt(7)
	v_mul_f32_e32 v54, v54, v186
	v_mul_f32_e32 v55, v55, v186
	v_mul_f32_e32 v52, v52, v186
	v_mul_f32_e32 v53, v53, v186
	s_waitcnt vmcnt(6)
	v_mul_f32_e32 v58, v58, v188
	v_mul_f32_e32 v59, v59, v188
	v_mul_f32_e32 v56, v56, v188
	v_mul_f32_e32 v57, v57, v188
	s_waitcnt vmcnt(5)
	v_mul_f32_e32 v62, v62, v190
	v_mul_f32_e32 v63, v63, v190
	v_mul_f32_e32 v60, v60, v190
	v_mul_f32_e32 v61, v61, v190
	s_waitcnt vmcnt(4)
	v_mul_f32_e32 v66, v66, v192
	v_mul_f32_e32 v67, v67, v192
	v_mul_f32_e32 v64, v64, v192
	v_mul_f32_e32 v65, v65, v192
	s_waitcnt vmcnt(3)
	v_mul_f32_e32 v70, v70, v194
	v_mul_f32_e32 v71, v71, v194
	v_mul_f32_e32 v68, v68, v194
	v_mul_f32_e32 v69, v69, v194
	s_waitcnt vmcnt(2)
	v_mul_f32_e32 v78, v78, v196
	v_mul_f32_e32 v79, v79, v196
	v_mul_f32_e32 v76, v76, v196
	v_mul_f32_e32 v77, v77, v196
	s_waitcnt vmcnt(1)
	v_mul_f32_e32 v82, v82, v198
	v_mul_f32_e32 v83, v83, v198
	v_mul_f32_e32 v80, v80, v198
	v_mul_f32_e32 v81, v81, v198
	s_waitcnt vmcnt(0)
	v_mul_f32_e32 v90, v90, v168
	v_mul_f32_e32 v91, v91, v168
	v_mul_f32_e32 v88, v88, v168
	v_mul_f32_e32 v89, v89, v168
.LBB0_2044:
	s_waitcnt vmcnt(15)
	v_mul_f32_e32 v2, v2, v166
	v_mul_f32_e32 v3, v3, v166
	v_mul_f32_e32 v0, v0, v166
	v_mul_f32_e32 v1, v1, v166
	s_waitcnt vmcnt(13)
	v_mul_f32_e32 v4, v4, v162
	v_mul_f32_e32 v5, v5, v162
	ds_write2_b32 v141, v0, v1 offset1:1
	ds_write2_b32 v141, v2, v3 offset0:2 offset1:3
	v_add_u32_e32 v3, 0x820, v141
	v_mul_f32_e32 v8, v8, v164
	v_mul_f32_e32 v9, v9, v164
	v_mul_f32_e32 v6, v6, v162
	v_mul_f32_e32 v7, v7, v162
	v_add_u32_e32 v1, 0x410, v141
	ds_write2_b32 v3, v4, v5 offset1:1
	v_add_u32_e32 v4, 0x828, v141
	v_mul_f32_e32 v10, v10, v164
	v_mul_f32_e32 v11, v11, v164
	s_waitcnt vmcnt(12)
	v_mul_f32_e32 v16, v16, v160
	v_mul_f32_e32 v17, v17, v160
	s_waitcnt vmcnt(11)
	v_mul_f32_e32 v14, v14, v158
	v_mul_f32_e32 v15, v15, v158
	v_mul_f32_e32 v12, v12, v158
	v_mul_f32_e32 v13, v13, v158
	ds_write2_b32 v1, v8, v9 offset1:1
	v_add_u32_e32 v2, 0x418, v141
	ds_write2_b32 v4, v6, v7 offset1:1
	v_add_u32_e32 v5, 0xc30, v141
	v_add_u32_e32 v7, 0x1040, v141
	v_add_u32_e32 v8, 0x1048, v141
	v_mul_f32_e32 v18, v18, v160
	v_mul_f32_e32 v19, v19, v160
	s_waitcnt vmcnt(10)
	v_mul_f32_e32 v86, v86, v156
	v_mul_f32_e32 v87, v87, v156
	v_mul_f32_e32 v84, v84, v156
	v_mul_f32_e32 v85, v85, v156
	s_waitcnt vmcnt(9)
	v_mul_f32_e32 v74, v74, v154
	v_mul_f32_e32 v75, v75, v154
	v_mul_f32_e32 v72, v72, v154
	v_mul_f32_e32 v73, v73, v154
	s_waitcnt vmcnt(7)
	v_mul_f32_e32 v94, v94, v150
	v_mul_f32_e32 v95, v95, v150
	v_mul_f32_e32 v92, v92, v150
	v_mul_f32_e32 v93, v93, v150
	ds_write2_b32 v2, v10, v11 offset1:1
	ds_write2_b32 v5, v16, v17 offset1:1
	v_add_u32_e32 v6, 0xc38, v141
	ds_write2_b32 v7, v12, v13 offset1:1
	ds_write2_b32 v8, v14, v15 offset1:1
	v_add_u32_e32 v9, 0x1450, v141
	v_add_u32_e32 v10, 0x1458, v141
	v_add_u32_e32 v11, 0x1860, v141
	v_add_u32_e32 v12, 0x1868, v141
	v_add_u32_e32 v15, 0x2080, v141
	v_add_u32_e32 v16, 0x2088, v141
	v_mul_f32_e32 v98, v98, v152
	v_mul_f32_e32 v99, v99, v152
	v_mul_f32_e32 v96, v96, v152
	v_mul_f32_e32 v97, v97, v152
	s_waitcnt vmcnt(6)
	v_mul_f32_e32 v106, v106, v148
	v_mul_f32_e32 v107, v107, v148
	v_mul_f32_e32 v104, v104, v148
	v_mul_f32_e32 v105, v105, v148
	s_waitcnt vmcnt(5)
	v_mul_f32_e32 v102, v102, v146
	v_mul_f32_e32 v103, v103, v146
	v_mul_f32_e32 v100, v100, v146
	v_mul_f32_e32 v101, v101, v146
	s_waitcnt vmcnt(4)
	v_mul_f32_e32 v114, v114, v144
	v_mul_f32_e32 v115, v115, v144
	v_mul_f32_e32 v112, v112, v144
	v_mul_f32_e32 v113, v113, v144
	s_waitcnt vmcnt(3)
	v_mul_f32_e32 v110, v110, v142
	v_mul_f32_e32 v111, v111, v142
	v_mul_f32_e32 v108, v108, v142
	v_mul_f32_e32 v109, v109, v142
	s_waitcnt vmcnt(2)
	v_mul_f32_e32 v122, v122, v140
	v_mul_f32_e32 v123, v123, v140
	v_mul_f32_e32 v120, v120, v140
	v_mul_f32_e32 v121, v121, v140
	s_waitcnt vmcnt(1)
	v_mul_f32_e32 v118, v118, v138
	v_mul_f32_e32 v119, v119, v138
	v_mul_f32_e32 v116, v116, v138
	v_mul_f32_e32 v117, v117, v138
	s_waitcnt vmcnt(0)
	v_mul_f32_e32 v126, v126, v136
	v_mul_f32_e32 v127, v127, v136
	v_mul_f32_e32 v124, v124, v136
	v_mul_f32_e32 v125, v125, v136
	ds_write2_b32 v6, v18, v19 offset1:1
	ds_write2_b32 v9, v84, v85 offset1:1
	ds_write2_b32 v10, v86, v87 offset1:1
	ds_write2_b32 v11, v72, v73 offset1:1
	ds_write2_b32 v12, v74, v75 offset1:1
	v_add_u32_e32 v13, 0x1c70, v141
	v_add_u32_e32 v14, 0x1c78, v141
	ds_write2_b32 v15, v92, v93 offset1:1
	ds_write2_b32 v16, v94, v95 offset1:1
	v_add_u32_e32 v17, 0x2490, v141
	v_add_u32_e32 v18, 0x2498, v141
	v_add_u32_e32 v19, 0x28a0, v141
	v_add_u32_e32 v72, 0x28a8, v141
	v_add_u32_e32 v73, 0x2cb0, v141
	v_add_u32_e32 v74, 0x2cb8, v141
	v_add_u32_e32 v75, 0x30c0, v141
	v_add_u32_e32 v84, 0x30c8, v141
	v_add_u32_e32 v85, 0x34d0, v141
	v_add_u32_e32 v86, 0x34d8, v141
	v_add_u32_e32 v87, 0x38e0, v141
	v_add_u32_e32 v92, 0x38e8, v141
	v_add_u32_e32 v93, 0x3cf0, v141
	v_add_u32_e32 v94, 0x3cf8, v141
	ds_write2_b32 v13, v96, v97 offset1:1
	ds_write2_b32 v14, v98, v99 offset1:1
	ds_write2_b32 v17, v104, v105 offset1:1
	ds_write2_b32 v18, v106, v107 offset1:1
	ds_write2_b32 v19, v100, v101 offset1:1
	ds_write2_b32 v72, v102, v103 offset1:1
	ds_write2_b32 v73, v112, v113 offset1:1
	ds_write2_b32 v74, v114, v115 offset1:1
	ds_write2_b32 v75, v108, v109 offset1:1
	ds_write2_b32 v84, v110, v111 offset1:1
	ds_write2_b32 v85, v120, v121 offset1:1
	ds_write2_b32 v86, v122, v123 offset1:1
	ds_write2_b32 v87, v116, v117 offset1:1
	ds_write2_b32 v92, v118, v119 offset1:1
	ds_write2_b32 v93, v124, v125 offset1:1
	ds_write2_b32 v94, v126, v127 offset1:1
	v_add_u32_e32 v0, 0x400, v145
	s_sub_i32 s14, 0, s23
	ds_read2_b32 v[102:103], v145 offset0:65 offset1:73
	ds_read2_b32 v[104:105], v145 offset1:8
	ds_read2_b32 v[106:107], v145 offset0:130 offset1:138
	ds_read2_b32 v[108:109], v145 offset0:195 offset1:203
	ds_read2_b32 v[110:111], v0 offset0:4 offset1:12
	ds_read2_b32 v[112:113], v0 offset0:69 offset1:77
	ds_read2_b32 v[114:115], v0 offset0:134 offset1:142
	ds_read2_b32 v[116:117], v0 offset0:199 offset1:207
	s_add_i32 s14, s14, s30
	v_add_u32_e32 v118, s14, v143
	s_ashr_i32 s23, s22, 31
	v_ashrrev_i32_e32 v119, 31, v118
	v_lshl_add_u64 v[100:101], s[22:23], 1, v[134:135]
	v_lshlrev_b64 v[120:121], 12, v[118:119]
	s_waitcnt lgkmcnt(6)
	v_cvt_pk_bf16_f32 v96, v104, v102
	s_waitcnt lgkmcnt(4)
	v_cvt_pk_bf16_f32 v97, v106, v108
	s_waitcnt lgkmcnt(2)
	v_cvt_pk_bf16_f32 v98, v110, v112
	s_waitcnt lgkmcnt(0)
	v_cvt_pk_bf16_f32 v99, v114, v116
	v_lshl_add_u64 v[120:121], v[100:101], 0, v[120:121]
	v_add_u32_e32 v102, 8, v118
	global_store_dwordx4 v[120:121], v[96:99], off
	v_add_u32_e32 v120, 16, v118
	v_ashrrev_i32_e32 v121, 31, v120
	v_cvt_pk_bf16_f32 v96, v105, v103
	v_ashrrev_i32_e32 v103, 31, v102
	v_lshlrev_b64 v[102:103], 12, v[102:103]
	v_cvt_pk_bf16_f32 v97, v107, v109
	v_cvt_pk_bf16_f32 v98, v111, v113
	v_cvt_pk_bf16_f32 v99, v115, v117
	v_lshl_add_u64 v[102:103], v[100:101], 0, v[102:103]
	global_store_dwordx4 v[102:103], v[96:99], off
	ds_read2_b32 v[102:103], v145 offset0:81 offset1:89
	ds_read2_b32 v[104:105], v145 offset0:16 offset1:24
	ds_read2_b32 v[106:107], v145 offset0:146 offset1:154
	ds_read2_b32 v[108:109], v145 offset0:211 offset1:219
	ds_read2_b32 v[110:111], v0 offset0:20 offset1:28
	ds_read2_b32 v[112:113], v0 offset0:85 offset1:93
	ds_read2_b32 v[114:115], v0 offset0:150 offset1:158
	ds_read2_b32 v[116:117], v0 offset0:215 offset1:223
	v_lshlrev_b64 v[120:121], 12, v[120:121]
	s_waitcnt lgkmcnt(6)
	v_cvt_pk_bf16_f32 v96, v104, v102
	s_waitcnt lgkmcnt(4)
	v_cvt_pk_bf16_f32 v97, v106, v108
	s_waitcnt lgkmcnt(2)
	v_cvt_pk_bf16_f32 v98, v110, v112
	s_waitcnt lgkmcnt(0)
	v_cvt_pk_bf16_f32 v99, v114, v116
	v_lshl_add_u64 v[120:121], v[100:101], 0, v[120:121]
	v_add_u32_e32 v102, 24, v118
	global_store_dwordx4 v[120:121], v[96:99], off
	v_add_u32_e32 v120, 32, v118
	v_ashrrev_i32_e32 v121, 31, v120
	v_cvt_pk_bf16_f32 v96, v105, v103
	v_ashrrev_i32_e32 v103, 31, v102
	v_lshlrev_b64 v[102:103], 12, v[102:103]
	v_cvt_pk_bf16_f32 v97, v107, v109
	v_cvt_pk_bf16_f32 v98, v111, v113
	v_cvt_pk_bf16_f32 v99, v115, v117
	v_lshl_add_u64 v[102:103], v[100:101], 0, v[102:103]
	global_store_dwordx4 v[102:103], v[96:99], off
	ds_read2_b32 v[102:103], v145 offset0:32 offset1:40
	ds_read2_b32 v[104:105], v145 offset0:97 offset1:105
	ds_read2_b32 v[106:107], v145 offset0:162 offset1:170
	ds_read2_b32 v[108:109], v145 offset0:227 offset1:235
	ds_read2_b32 v[110:111], v0 offset0:36 offset1:44
	ds_read2_b32 v[112:113], v0 offset0:101 offset1:109
	ds_read2_b32 v[114:115], v0 offset0:166 offset1:174
	ds_read2_b32 v[116:117], v0 offset0:231 offset1:239
	v_lshlrev_b64 v[120:121], 12, v[120:121]
	s_waitcnt lgkmcnt(6)
	v_cvt_pk_bf16_f32 v96, v102, v104
	s_waitcnt lgkmcnt(4)
	v_cvt_pk_bf16_f32 v97, v106, v108
	s_waitcnt lgkmcnt(2)
	v_cvt_pk_bf16_f32 v98, v110, v112
	s_waitcnt lgkmcnt(0)
	v_cvt_pk_bf16_f32 v99, v114, v116
	v_lshl_add_u64 v[120:121], v[100:101], 0, v[120:121]
	v_add_u32_e32 v102, 40, v118
	global_store_dwordx4 v[120:121], v[96:99], off
	v_add_u32_e32 v120, 48, v118
	v_ashrrev_i32_e32 v121, 31, v120
	v_cvt_pk_bf16_f32 v96, v103, v105
	v_ashrrev_i32_e32 v103, 31, v102
	v_lshlrev_b64 v[102:103], 12, v[102:103]
	v_cvt_pk_bf16_f32 v97, v107, v109
	v_cvt_pk_bf16_f32 v98, v111, v113
	v_cvt_pk_bf16_f32 v99, v115, v117
	v_lshl_add_u64 v[102:103], v[100:101], 0, v[102:103]
	global_store_dwordx4 v[102:103], v[96:99], off
	ds_read2_b32 v[102:103], v145 offset0:48 offset1:56
	ds_read2_b32 v[104:105], v145 offset0:113 offset1:121
	ds_read2_b32 v[106:107], v145 offset0:178 offset1:186
	ds_read2_b32 v[108:109], v145 offset0:243 offset1:251
	ds_read2_b32 v[110:111], v0 offset0:52 offset1:60
	ds_read2_b32 v[112:113], v0 offset0:117 offset1:125
	ds_read2_b32 v[114:115], v0 offset0:182 offset1:190
	ds_read2_b32 v[116:117], v0 offset0:247 offset1:255
	v_lshlrev_b64 v[120:121], 12, v[120:121]
	s_waitcnt lgkmcnt(6)
	v_cvt_pk_bf16_f32 v96, v102, v104
	s_waitcnt lgkmcnt(4)
	v_cvt_pk_bf16_f32 v97, v106, v108
	s_waitcnt lgkmcnt(2)
	v_cvt_pk_bf16_f32 v98, v110, v112
	s_waitcnt lgkmcnt(0)
	v_cvt_pk_bf16_f32 v99, v114, v116
	v_lshl_add_u64 v[120:121], v[100:101], 0, v[120:121]
	v_add_u32_e32 v102, 56, v118
	global_store_dwordx4 v[120:121], v[96:99], off
	s_andn2_b64 vcc, exec, s[62:63]
	s_nop 0
	v_cvt_pk_bf16_f32 v96, v103, v105
	v_ashrrev_i32_e32 v103, 31, v102
	v_lshlrev_b64 v[102:103], 12, v[102:103]
	v_cvt_pk_bf16_f32 v97, v107, v109
	v_cvt_pk_bf16_f32 v98, v111, v113
	v_cvt_pk_bf16_f32 v99, v115, v117
	v_lshl_add_u64 v[100:101], v[100:101], 0, v[102:103]
	global_store_dwordx4 v[100:101], v[96:99], off
	s_cbranch_vccnz .LBB0_1977
	s_ashr_i32 s14, s46, 31
	s_lshr_b32 s14, s14, 25
	s_add_i32 s15, s46, s14
	s_ashr_i32 s14, s15, 7
	ds_write2_b32 v141, v20, v21 offset1:1
	ds_write2_b32 v141, v22, v23 offset0:2 offset1:3
	ds_write2_b32 v1, v24, v25 offset1:1
	ds_write2_b32 v2, v26, v27 offset1:1
	ds_write2_b32 v3, v28, v29 offset1:1
	ds_write2_b32 v4, v30, v31 offset1:1
	ds_write2_b32 v5, v32, v33 offset1:1
	ds_write2_b32 v6, v34, v35 offset1:1
	ds_write2_b32 v7, v36, v37 offset1:1
	ds_write2_b32 v8, v38, v39 offset1:1
	ds_write2_b32 v9, v40, v41 offset1:1
	ds_write2_b32 v10, v42, v43 offset1:1
	ds_write2_b32 v11, v44, v45 offset1:1
	ds_write2_b32 v12, v46, v47 offset1:1
	ds_write2_b32 v13, v48, v49 offset1:1
	ds_write2_b32 v14, v50, v51 offset1:1
	ds_write2_b32 v15, v52, v53 offset1:1
	ds_write2_b32 v16, v54, v55 offset1:1
	ds_write2_b32 v17, v56, v57 offset1:1
	ds_write2_b32 v18, v58, v59 offset1:1
	ds_write2_b32 v19, v60, v61 offset1:1
	ds_write2_b32 v72, v62, v63 offset1:1
	ds_write2_b32 v73, v64, v65 offset1:1
	ds_write2_b32 v74, v66, v67 offset1:1
	ds_write2_b32 v75, v68, v69 offset1:1
	ds_write2_b32 v84, v70, v71 offset1:1
	ds_write2_b32 v85, v76, v77 offset1:1
	ds_write2_b32 v86, v78, v79 offset1:1
	ds_write2_b32 v87, v80, v81 offset1:1
	ds_write2_b32 v92, v82, v83 offset1:1
	ds_write2_b32 v93, v88, v89 offset1:1
	ds_write2_b32 v94, v90, v91 offset1:1
	s_and_b32 s15, s15, 0x3ffff80
	s_sub_i32 s15, s46, s15
	ds_read2_b32 v[8:9], v145 offset0:65 offset1:73
	ds_read2_b32 v[10:11], v145 offset1:8
	ds_read2_b32 v[12:13], v145 offset0:130 offset1:138
	ds_read2_b32 v[14:15], v145 offset0:195 offset1:203
	ds_read2_b32 v[16:17], v0 offset0:4 offset1:12
	ds_read2_b32 v[18:19], v0 offset0:69 offset1:77
	ds_read2_b32 v[72:73], v0 offset0:134 offset1:142
	ds_read2_b32 v[74:75], v0 offset0:199 offset1:207
	s_lshl_b32 s22, s15, 6
	s_lshl_b32 s14, s14, 6
	v_add_u32_e32 v84, s22, v143
	s_ashr_i32 s15, s14, 31
	v_ashrrev_i32_e32 v85, 31, v84
	v_lshl_add_u64 v[6:7], s[14:15], 1, v[134:135]
	v_lshlrev_b64 v[84:85], 12, v[84:85]
	s_waitcnt lgkmcnt(6)
	v_cvt_pk_bf16_f32 v2, v10, v8
	s_waitcnt lgkmcnt(4)
	v_cvt_pk_bf16_f32 v3, v12, v14
	s_waitcnt lgkmcnt(2)
	v_cvt_pk_bf16_f32 v4, v16, v18
	s_waitcnt lgkmcnt(0)
	v_cvt_pk_bf16_f32 v5, v72, v74
	v_lshl_add_u64 v[84:85], v[6:7], 0, v[84:85]
	v_add_u32_e32 v8, s22, v147
	global_store_dwordx4 v[84:85], v[2:5], off
	v_add_u32_e32 v84, s22, v149
	v_ashrrev_i32_e32 v85, 31, v84
	v_cvt_pk_bf16_f32 v2, v11, v9
	v_ashrrev_i32_e32 v9, 31, v8
	v_lshlrev_b64 v[8:9], 12, v[8:9]
	v_cvt_pk_bf16_f32 v3, v13, v15
	v_cvt_pk_bf16_f32 v4, v17, v19
	v_cvt_pk_bf16_f32 v5, v73, v75
	v_lshl_add_u64 v[8:9], v[6:7], 0, v[8:9]
	global_store_dwordx4 v[8:9], v[2:5], off
	ds_read2_b32 v[8:9], v145 offset0:16 offset1:24
	ds_read2_b32 v[10:11], v145 offset0:81 offset1:89
	ds_read2_b32 v[12:13], v145 offset0:146 offset1:154
	ds_read2_b32 v[14:15], v145 offset0:211 offset1:219
	ds_read2_b32 v[16:17], v0 offset0:20 offset1:28
	ds_read2_b32 v[18:19], v0 offset0:85 offset1:93
	ds_read2_b32 v[72:73], v0 offset0:150 offset1:158
	ds_read2_b32 v[74:75], v0 offset0:215 offset1:223
	v_lshlrev_b64 v[84:85], 12, v[84:85]
	s_waitcnt lgkmcnt(6)
	v_cvt_pk_bf16_f32 v2, v8, v10
	s_waitcnt lgkmcnt(4)
	v_cvt_pk_bf16_f32 v3, v12, v14
	s_waitcnt lgkmcnt(2)
	v_cvt_pk_bf16_f32 v4, v16, v18
	s_waitcnt lgkmcnt(0)
	v_cvt_pk_bf16_f32 v5, v72, v74
	v_lshl_add_u64 v[84:85], v[6:7], 0, v[84:85]
	v_add_u32_e32 v8, s22, v151
	global_store_dwordx4 v[84:85], v[2:5], off
	v_add_u32_e32 v84, s22, v153
	v_ashrrev_i32_e32 v85, 31, v84
	v_cvt_pk_bf16_f32 v2, v9, v11
	v_ashrrev_i32_e32 v9, 31, v8
	v_lshlrev_b64 v[8:9], 12, v[8:9]
	v_cvt_pk_bf16_f32 v3, v13, v15
	v_cvt_pk_bf16_f32 v4, v17, v19
	v_cvt_pk_bf16_f32 v5, v73, v75
	v_lshl_add_u64 v[8:9], v[6:7], 0, v[8:9]
	global_store_dwordx4 v[8:9], v[2:5], off
	ds_read2_b32 v[8:9], v145 offset0:32 offset1:40
	ds_read2_b32 v[10:11], v145 offset0:97 offset1:105
	ds_read2_b32 v[12:13], v145 offset0:162 offset1:170
	ds_read2_b32 v[14:15], v145 offset0:227 offset1:235
	ds_read2_b32 v[16:17], v0 offset0:36 offset1:44
	ds_read2_b32 v[18:19], v0 offset0:101 offset1:109
	ds_read2_b32 v[72:73], v0 offset0:166 offset1:174
	ds_read2_b32 v[74:75], v0 offset0:231 offset1:239
	v_lshlrev_b64 v[84:85], 12, v[84:85]
	s_waitcnt lgkmcnt(6)
	v_cvt_pk_bf16_f32 v2, v8, v10
	s_waitcnt lgkmcnt(4)
	v_cvt_pk_bf16_f32 v3, v12, v14
	s_waitcnt lgkmcnt(2)
	v_cvt_pk_bf16_f32 v4, v16, v18
	s_waitcnt lgkmcnt(0)
	v_cvt_pk_bf16_f32 v5, v72, v74
	v_lshl_add_u64 v[84:85], v[6:7], 0, v[84:85]
	v_add_u32_e32 v8, s22, v155
	global_store_dwordx4 v[84:85], v[2:5], off
	v_add_u32_e32 v74, s22, v157
	s_nop 0
	v_cvt_pk_bf16_f32 v2, v9, v11
	v_ashrrev_i32_e32 v9, 31, v8
	v_lshlrev_b64 v[8:9], 12, v[8:9]
	v_cvt_pk_bf16_f32 v3, v13, v15
	v_cvt_pk_bf16_f32 v4, v17, v19
	v_cvt_pk_bf16_f32 v5, v73, v75
	v_lshl_add_u64 v[8:9], v[6:7], 0, v[8:9]
	global_store_dwordx4 v[8:9], v[2:5], off
	ds_read2_b32 v[4:5], v145 offset0:48 offset1:56
	ds_read2_b32 v[8:9], v145 offset0:113 offset1:121
	ds_read2_b32 v[10:11], v145 offset0:178 offset1:186
	ds_read2_b32 v[12:13], v145 offset0:243 offset1:251
	ds_read2_b32 v[14:15], v0 offset0:52 offset1:60
	ds_read2_b32 v[16:17], v0 offset0:117 offset1:125
	ds_read2_b32 v[18:19], v0 offset0:182 offset1:190
	ds_read2_b32 v[72:73], v0 offset0:247 offset1:255
	v_ashrrev_i32_e32 v75, 31, v74
	v_lshlrev_b64 v[74:75], 12, v[74:75]
	s_waitcnt lgkmcnt(6)
	v_cvt_pk_bf16_f32 v0, v4, v8
	s_waitcnt lgkmcnt(4)
	v_cvt_pk_bf16_f32 v1, v10, v12
	s_waitcnt lgkmcnt(2)
	v_cvt_pk_bf16_f32 v2, v14, v16
	s_waitcnt lgkmcnt(0)
	v_cvt_pk_bf16_f32 v3, v18, v72
	v_lshl_add_u64 v[74:75], v[6:7], 0, v[74:75]
	v_add_u32_e32 v4, s22, v159
	global_store_dwordx4 v[74:75], v[0:3], off
	s_nop 1
	v_cvt_pk_bf16_f32 v0, v5, v9
	v_ashrrev_i32_e32 v5, 31, v4
	v_lshlrev_b64 v[4:5], 12, v[4:5]
	v_cvt_pk_bf16_f32 v1, v11, v13
	v_cvt_pk_bf16_f32 v2, v15, v17
	v_cvt_pk_bf16_f32 v3, v19, v73
	v_lshl_add_u64 v[4:5], v[6:7], 0, v[4:5]
	global_store_dwordx4 v[4:5], v[0:3], off
	s_branch .LBB0_1977

.LBB0_2131:
	v_lshl_add_u32 v154, s22, 8, v174
	v_ashrrev_i32_e32 v155, 31, v154
	v_lshlrev_b64 v[156:157], 7, v[154:155]
	v_lshl_add_u64 v[148:149], s[52:53], 0, v[156:157]
	v_mov_b32_e32 v136, 0
	v_lshl_add_u64 v[148:149], v[138:139], 4, v[148:149]
	s_and_saveexec_b64 s[22:23], s[14:15]
	s_cbranch_execz .LBB0_2133
	global_load_dwordx4 v[150:153], v[148:149], off
	s_waitcnt vmcnt(0)
	v_mov_b32_e32 v158, v151
	v_mov_b32_e32 v159, v152
	v_mov_b32_e32 v151, v153
	v_add_f32_e32 v150, v158, v150
	v_add_f32_e32 v151, v159, v151
	s_nop 0
	v_add_f32_e32 v136, v150, v151
	v_add_f32_e32 v136, 0, v136
.LBB0_2133:
	s_or_b64 exec, exec, s[22:23]
	s_and_saveexec_b64 s[22:23], s[16:17]
	s_cbranch_execz .LBB0_2135
	global_load_dwordx4 v[148:151], v[148:149], off offset:64
	s_waitcnt vmcnt(0)
	v_mov_b32_e32 v152, v149
	v_mov_b32_e32 v153, v150
	v_mov_b32_e32 v149, v151
	v_add_f32_e32 v148, v152, v148
	v_add_f32_e32 v149, v153, v149
	s_nop 0
	v_add_f32_e32 v148, v148, v149
	v_add_f32_e32 v136, v136, v148
.LBB0_2135:
	s_or_b64 exec, exec, s[22:23]
	ds_bpermute_b32 v149, v177, v136
	v_lshl_add_u32 v148, s72, 8, v176
	v_lshlrev_b32_e32 v150, 5, v154
	v_and_b32_e32 v151, 0xf9e0, v150
	v_and_b32_e32 v155, 0xffffffc0, v148
	s_waitcnt lgkmcnt(0)
	v_add_f32_e32 v136, v136, v149
	ds_bpermute_b32 v149, v178, v136
	v_add_u32_e32 v150, 0xfffffb00, v148
	s_movk_i32 s8, 0x500
	v_cmp_eq_u32_e32 vcc, s8, v155
	v_lshrrev_b32_e32 v152, 1, v150
	s_waitcnt lgkmcnt(0)
	v_add_f32_e32 v136, v136, v149
	v_fmamk_f32 v136, v136, 0x3a000000, v182
	v_rsq_f32_e32 v164, v136
	v_lshlrev_b32_e32 v136, 2, v151
	v_mul_f32_e32 v158, v124, v164
	v_mul_f32_e32 v159, v125, v164
	v_mul_f32_e32 v124, v126, v164
	v_mul_f32_e32 v125, v127, v164
	v_mul_f32_e32 v160, v120, v164
	v_mul_f32_e32 v161, v121, v164
	v_mul_f32_e32 v126, v122, v164
	v_mul_f32_e32 v127, v123, v164
	v_mov_b32_e32 v122, v159
	v_mov_b32_e32 v123, v125
	v_mov_b32_e32 v166, v161
	v_mov_b32_e32 v167, v127
	v_mov_b32_e32 v120, v158
	v_mov_b32_e32 v121, v124
	v_mov_b32_e32 v162, v160
	v_mov_b32_e32 v163, v126
	s_and_saveexec_b64 s[22:23], vcc
	s_cbranch_execz .LBB0_2137
	v_mov_b32_e32 v153, v137
	v_lshl_add_u64 v[120:121], s[66:67], 0, v[136:137]
	v_lshlrev_b64 v[170:171], 2, v[152:153]
	v_lshl_add_u64 v[120:121], v[120:121], 0, v[170:171]
	global_load_dwordx4 v[166:169], v[120:121], off
	v_lshl_add_u64 v[120:121], s[68:69], 0, v[136:137]
	v_lshl_add_u64 v[120:121], v[120:121], 0, v[170:171]
	global_load_dwordx4 v[170:173], v[120:121], off
	v_mov_b32_e32 v122, v159
	v_mov_b32_e32 v123, v125
	v_mov_b32_e32 v162, v158
	v_mov_b32_e32 v163, v124
	v_mov_b32_e32 v184, v161
	v_mov_b32_e32 v185, v127
	v_mov_b32_e32 v186, v160
	v_mov_b32_e32 v187, v126
	s_waitcnt vmcnt(0)
	v_mul_f32_e32 v120, v122, v170
	v_mul_f32_e32 v121, v123, v171
	s_nop 0
	v_fma_f32 v120, v162, v166, -v120
	v_fma_f32 v121, v163, v167, -v121
	v_mul_f32_e32 v162, v162, v170
	v_mul_f32_e32 v163, v163, v171
	s_nop 0
	v_fma_f32 v122, v122, v166, v162
	v_fma_f32 v123, v123, v167, v163
	v_mul_f32_e32 v162, v184, v172
	v_mul_f32_e32 v163, v185, v173
	v_mul_f32_e32 v166, v186, v172
	v_mul_f32_e32 v167, v187, v173
	v_fma_f32 v162, v186, v168, -v162
	v_fma_f32 v163, v187, v169, -v163
	v_fma_f32 v166, v184, v168, v166
	v_fma_f32 v167, v185, v169, v167

.LBB0_2139:
	s_or_b64 exec, exec, s[22:23]
	v_mov_b64_e32 v[162:163], s[50:51]
	v_ashrrev_i32_e32 v149, 31, v148
	v_mad_i64_i32 v[162:163], s[22:23], v154, s29, v[162:163]
	v_mov_b32_e32 v165, v164
	v_lshl_add_u64 v[162:163], v[148:149], 1, v[162:163]
	v_mov_b32_e32 v168, v164
	v_mov_b32_e32 v169, v164
	global_store_dwordx4 v[162:163], v[120:123], off
	s_movk_i32 s8, 0x480
	v_cmp_eq_u32_e64 s[22:23], s8, v155
	v_mul_f32_e32 v120, v118, v168
	v_mul_f32_e32 v121, v119, v169
	v_mul_f32_e32 v122, v116, v164
	v_mul_f32_e32 v123, v117, v165
	v_mul_f32_e32 v168, v114, v168
	v_mul_f32_e32 v169, v115, v169
	v_mul_f32_e32 v164, v112, v164
	v_mul_f32_e32 v165, v113, v165
	v_add_u32_e32 v116, 0xfffffb80, v148
	v_lshrrev_b32_e32 v118, 1, v116
	v_mov_b32_e32 v114, v123
	v_mov_b32_e32 v115, v121
	v_mov_b32_e32 v172, v165
	v_mov_b32_e32 v173, v169
	v_mov_b32_e32 v112, v122
	v_mov_b32_e32 v113, v120
	v_mov_b32_e32 v170, v164
	v_mov_b32_e32 v171, v168
	s_and_saveexec_b64 s[84:85], s[22:23]
	s_cbranch_execz .LBB0_2141
	v_mov_b32_e32 v119, v137
	v_lshl_add_u64 v[112:113], s[66:67], 0, v[136:137]
	v_lshlrev_b64 v[184:185], 2, v[118:119]
	v_lshl_add_u64 v[112:113], v[112:113], 0, v[184:185]
	global_load_dwordx4 v[170:173], v[112:113], off
	v_lshl_add_u64 v[112:113], s[68:69], 0, v[136:137]
	v_lshl_add_u64 v[112:113], v[112:113], 0, v[184:185]
	global_load_dwordx4 v[184:187], v[112:113], off
	v_mov_b32_e32 v114, v123
	v_mov_b32_e32 v115, v121
	v_mov_b32_e32 v190, v122
	v_mov_b32_e32 v191, v120
	v_mov_b32_e32 v188, v165
	v_mov_b32_e32 v189, v169
	v_mov_b32_e32 v192, v164
	v_mov_b32_e32 v193, v168
	s_waitcnt vmcnt(0)
	v_mul_f32_e32 v112, v114, v184
	v_mul_f32_e32 v113, v115, v185
	v_mul_f32_e32 v184, v190, v184
	v_mul_f32_e32 v185, v191, v185
	v_fma_f32 v112, v190, v170, -v112
	v_fma_f32 v113, v191, v171, -v113
	v_fma_f32 v114, v114, v170, v184
	v_fma_f32 v115, v115, v171, v185
	v_mul_f32_e32 v170, v188, v186
	v_mul_f32_e32 v171, v189, v187
	v_mul_f32_e32 v184, v192, v186
	v_mul_f32_e32 v185, v193, v187
	v_fma_f32 v170, v192, v172, -v170
	v_fma_f32 v171, v193, v173, -v171
	v_fma_f32 v172, v188, v172, v184
	v_fma_f32 v173, v189, v173, v185

.LBB0_2145:
	s_or_b64 exec, exec, s[86:87]
	v_or_b32_e32 v122, 16, v154
	v_ashrrev_i32_e32 v123, 31, v122
	v_lshlrev_b64 v[112:113], 7, v[122:123]
	v_lshl_add_u64 v[114:115], s[52:53], 0, v[112:113]
	v_mov_b32_e32 v117, 0
	v_lshl_add_u64 v[114:115], v[138:139], 4, v[114:115]
	s_and_saveexec_b64 s[86:87], s[14:15]
	s_cbranch_execz .LBB0_2147
	global_load_dwordx4 v[124:127], v[114:115], off
	s_waitcnt vmcnt(0)
	v_mov_b32_e32 v120, v125
	v_mov_b32_e32 v121, v126
	v_mov_b32_e32 v125, v127
	v_add_f32_e32 v120, v120, v124
	v_add_f32_e32 v121, v121, v125
	s_nop 0
	v_add_f32_e32 v117, v120, v121
	v_add_f32_e32 v117, 0, v117
.LBB0_2147:
	s_or_b64 exec, exec, s[86:87]
	s_and_saveexec_b64 s[86:87], s[16:17]
	s_cbranch_execz .LBB0_2149
	global_load_dwordx4 v[124:127], v[114:115], off offset:64
	s_waitcnt vmcnt(0)
	v_mov_b32_e32 v114, v125
	v_mov_b32_e32 v115, v126
	v_mov_b32_e32 v125, v127
	v_add_f32_e32 v114, v114, v124
	v_add_f32_e32 v115, v115, v125
	s_nop 0
	v_add_f32_e32 v114, v114, v115
	v_add_f32_e32 v117, v117, v114
.LBB0_2149:
	s_or_b64 exec, exec, s[86:87]
	ds_bpermute_b32 v114, v177, v117
	s_waitcnt lgkmcnt(0)
	v_add_f32_e32 v114, v117, v114
	ds_bpermute_b32 v115, v178, v114
	s_waitcnt lgkmcnt(0)
	v_add_f32_e32 v114, v114, v115
	v_fmamk_f32 v114, v114, 0x3a000000, v182
	v_rsq_f32_e32 v124, v114
	v_lshlrev_b32_e32 v114, 5, v122
	v_and_b32_e32 v114, 0xfbe0, v114
	v_lshlrev_b32_e32 v136, 2, v114
	v_mul_f32_e32 v114, v108, v124
	v_mul_f32_e32 v115, v109, v124
	v_mul_f32_e32 v108, v110, v124
	v_mul_f32_e32 v109, v111, v124
	v_mul_f32_e32 v120, v104, v124
	v_mul_f32_e32 v121, v105, v124
	v_mul_f32_e32 v110, v106, v124
	v_mul_f32_e32 v111, v107, v124
	v_mov_b32_e32 v106, v115
	v_mov_b32_e32 v107, v109
	v_mov_b32_e32 v156, v121
	v_mov_b32_e32 v157, v111
	v_mov_b32_e32 v104, v114
	v_mov_b32_e32 v105, v108
	v_mov_b32_e32 v126, v120
	v_mov_b32_e32 v127, v110
	s_and_saveexec_b64 s[86:87], vcc
	s_cbranch_execz .LBB0_2151
	v_mov_b32_e32 v153, v137
	v_lshl_add_u64 v[104:105], s[66:67], 0, v[136:137]
	v_lshlrev_b64 v[160:161], 2, v[152:153]
	v_lshl_add_u64 v[104:105], v[104:105], 0, v[160:161]
	global_load_dwordx4 v[156:159], v[104:105], off
	v_lshl_add_u64 v[104:105], s[68:69], 0, v[136:137]
	v_lshl_add_u64 v[104:105], v[104:105], 0, v[160:161]
	global_load_dwordx4 v[160:163], v[104:105], off
	v_mov_b32_e32 v106, v115
	v_mov_b32_e32 v107, v109
	v_mov_b32_e32 v126, v114
	v_mov_b32_e32 v127, v108
	v_mov_b32_e32 v164, v121
	v_mov_b32_e32 v165, v111
	v_mov_b32_e32 v166, v120
	v_mov_b32_e32 v167, v110
	s_waitcnt vmcnt(0)
	v_mul_f32_e32 v104, v106, v160
	v_mul_f32_e32 v105, v107, v161
	s_nop 0
	v_fma_f32 v104, v126, v156, -v104
	v_fma_f32 v105, v127, v157, -v105
	v_mul_f32_e32 v126, v126, v160
	v_mul_f32_e32 v127, v127, v161
	s_nop 0
	v_fma_f32 v106, v106, v156, v126
	v_fma_f32 v107, v107, v157, v127
	v_mul_f32_e32 v126, v164, v162
	v_mul_f32_e32 v127, v165, v163
	v_mul_f32_e32 v156, v166, v162
	v_mul_f32_e32 v157, v167, v163
	v_fma_f32 v126, v166, v158, -v126
	v_fma_f32 v127, v167, v159, -v127
	v_fma_f32 v156, v164, v158, v156
	v_fma_f32 v157, v165, v159, v157

.LBB0_2153:
	s_or_b64 exec, exec, s[86:87]
	v_mov_b64_e32 v[156:157], s[50:51]
	v_mad_i64_i32 v[122:123], s[60:61], v122, s29, v[156:157]
	v_lshl_add_u64 v[122:123], v[148:149], 1, v[122:123]
	v_mov_b32_e32 v125, v124
	global_store_dwordx4 v[122:123], v[104:107], off
	v_mul_f32_e32 v100, v100, v124
	v_mul_f32_e32 v101, v101, v125
	s_nop 0
	v_mov_b32_e32 v104, v124
	v_mov_b32_e32 v105, v124
	v_mul_f32_e32 v102, v102, v104
	v_mul_f32_e32 v103, v103, v105
	v_mul_f32_e32 v104, v98, v104
	v_mul_f32_e32 v105, v99, v105
	v_mul_f32_e32 v106, v96, v124
	v_mul_f32_e32 v107, v97, v125
	v_mov_b32_e32 v98, v101
	v_mov_b32_e32 v99, v103
	v_mov_b32_e32 v156, v107
	v_mov_b32_e32 v157, v105
	v_mov_b32_e32 v96, v100
	v_mov_b32_e32 v97, v102
	v_mov_b32_e32 v124, v106
	v_mov_b32_e32 v125, v104
	s_and_saveexec_b64 s[86:87], s[22:23]
	s_cbranch_execz .LBB0_2155
	v_mov_b32_e32 v119, v137
	v_lshl_add_u64 v[96:97], s[66:67], 0, v[136:137]
	v_lshlrev_b64 v[160:161], 2, v[118:119]
	v_lshl_add_u64 v[96:97], v[96:97], 0, v[160:161]
	global_load_dwordx4 v[156:159], v[96:97], off
	v_lshl_add_u64 v[96:97], s[68:69], 0, v[136:137]
	v_lshl_add_u64 v[96:97], v[96:97], 0, v[160:161]
	global_load_dwordx4 v[160:163], v[96:97], off
	v_mov_b32_e32 v98, v101
	v_mov_b32_e32 v99, v103
	v_mov_b32_e32 v124, v100
	v_mov_b32_e32 v125, v102
	v_mov_b32_e32 v164, v107
	v_mov_b32_e32 v165, v105
	v_mov_b32_e32 v166, v106
	v_mov_b32_e32 v167, v104
	s_waitcnt vmcnt(0)
	v_mul_f32_e32 v96, v98, v160
	v_mul_f32_e32 v97, v99, v161
	s_nop 0
	v_fma_f32 v96, v124, v156, -v96
	v_fma_f32 v97, v125, v157, -v97
	v_mul_f32_e32 v124, v124, v160
	v_mul_f32_e32 v125, v125, v161
	s_nop 0
	v_fma_f32 v98, v98, v156, v124
	v_fma_f32 v99, v99, v157, v125
	v_mul_f32_e32 v124, v164, v162
	v_mul_f32_e32 v125, v165, v163
	v_mul_f32_e32 v156, v166, v162
	v_mul_f32_e32 v157, v167, v163
	v_fma_f32 v124, v166, v158, -v124
	v_fma_f32 v125, v167, v159, -v125
	v_fma_f32 v156, v164, v158, v156
	v_fma_f32 v157, v165, v159, v157

.LBB0_2159:
	s_or_b64 exec, exec, s[86:87]
	v_or_b32_e32 v102, 32, v154
	v_ashrrev_i32_e32 v103, 31, v102
	v_lshlrev_b64 v[96:97], 7, v[102:103]
	v_lshl_add_u64 v[98:99], s[52:53], 0, v[96:97]
	v_mov_b32_e32 v100, 0
	v_lshl_add_u64 v[98:99], v[138:139], 4, v[98:99]
	s_and_saveexec_b64 s[86:87], s[14:15]
	s_cbranch_execz .LBB0_2161
	global_load_dwordx4 v[104:107], v[98:99], off
	s_waitcnt vmcnt(0)
	v_mov_b32_e32 v100, v105
	s_waitcnt lgkmcnt(0)
	v_mov_b32_e32 v101, v106
	v_mov_b32_e32 v105, v107
	v_add_f32_e32 v100, v100, v104
	v_add_f32_e32 v101, v101, v105
	s_nop 0
	v_add_f32_e32 v100, v100, v101
	v_add_f32_e32 v100, 0, v100
.LBB0_2161:
	s_or_b64 exec, exec, s[86:87]
	s_and_saveexec_b64 s[86:87], s[16:17]
	s_cbranch_execz .LBB0_2163
	global_load_dwordx4 v[104:107], v[98:99], off offset:64
	s_waitcnt vmcnt(0)
	v_mov_b32_e32 v98, v105
	v_mov_b32_e32 v99, v106
	v_mov_b32_e32 v105, v107
	v_add_f32_e32 v98, v98, v104
	v_add_f32_e32 v99, v99, v105
	s_nop 0
	v_add_f32_e32 v98, v98, v99
	v_add_f32_e32 v100, v100, v98
.LBB0_2163:
	s_or_b64 exec, exec, s[86:87]
	ds_bpermute_b32 v98, v177, v100
	s_waitcnt lgkmcnt(0)
	v_add_f32_e32 v98, v100, v98
	ds_bpermute_b32 v99, v178, v98
	s_waitcnt lgkmcnt(0)
	v_add_f32_e32 v98, v98, v99
	v_fmamk_f32 v98, v98, 0x3a000000, v182
	v_rsq_f32_e32 v104, v98
	v_lshlrev_b32_e32 v98, 5, v102
	v_and_b32_e32 v98, 0xfde0, v98
	v_lshlrev_b32_e32 v136, 2, v98
	v_mul_f32_e32 v98, v92, v104
	v_mul_f32_e32 v99, v93, v104
	v_mul_f32_e32 v92, v94, v104
	v_mul_f32_e32 v93, v95, v104
	v_mul_f32_e32 v100, v88, v104
	v_mul_f32_e32 v101, v89, v104
	v_mul_f32_e32 v94, v90, v104
	v_mul_f32_e32 v95, v91, v104
	v_mov_b32_e32 v90, v99
	v_mov_b32_e32 v91, v93
	v_mov_b32_e32 v108, v101
	v_mov_b32_e32 v109, v95
	v_mov_b32_e32 v88, v98
	v_mov_b32_e32 v89, v92
	v_mov_b32_e32 v106, v100
	v_mov_b32_e32 v107, v94
	s_and_saveexec_b64 s[86:87], vcc
	s_cbranch_execz .LBB0_2165
	v_mov_b32_e32 v153, v137
	v_lshl_add_u64 v[88:89], s[66:67], 0, v[136:137]
	v_lshlrev_b64 v[110:111], 2, v[152:153]
	v_lshl_add_u64 v[88:89], v[88:89], 0, v[110:111]
	global_load_dwordx4 v[106:109], v[88:89], off
	v_lshl_add_u64 v[88:89], s[68:69], 0, v[136:137]
	v_lshl_add_u64 v[88:89], v[88:89], 0, v[110:111]
	global_load_dwordx4 v[110:113], v[88:89], off
	v_mov_b32_e32 v90, v99
	v_mov_b32_e32 v91, v93
	v_mov_b32_e32 v120, v98
	v_mov_b32_e32 v121, v92
	v_mov_b32_e32 v114, v101
	v_mov_b32_e32 v115, v95
	v_mov_b32_e32 v122, v100
	v_mov_b32_e32 v123, v94
	s_waitcnt vmcnt(0)
	v_mul_f32_e32 v88, v90, v110
	v_mul_f32_e32 v89, v91, v111
	v_mul_f32_e32 v110, v120, v110
	v_mul_f32_e32 v111, v121, v111
	v_fma_f32 v88, v120, v106, -v88
	v_fma_f32 v89, v121, v107, -v89
	v_fma_f32 v90, v90, v106, v110
	v_fma_f32 v91, v91, v107, v111
	v_mul_f32_e32 v106, v114, v112
	v_mul_f32_e32 v107, v115, v113
	v_mul_f32_e32 v110, v122, v112
	v_mul_f32_e32 v111, v123, v113
	v_fma_f32 v106, v122, v108, -v106
	v_fma_f32 v107, v123, v109, -v107
	v_fma_f32 v108, v114, v108, v110
	v_fma_f32 v109, v115, v109, v111

.LBB0_2167:
	s_or_b64 exec, exec, s[86:87]
	v_mov_b64_e32 v[108:109], s[50:51]
	v_mad_i64_i32 v[102:103], s[60:61], v102, s29, v[108:109]
	v_lshl_add_u64 v[102:103], v[148:149], 1, v[102:103]
	v_mov_b32_e32 v105, v104
	global_store_dwordx4 v[102:103], v[88:91], off
	v_mul_f32_e32 v84, v84, v104
	v_mul_f32_e32 v85, v85, v105
	s_nop 0
	v_mov_b32_e32 v88, v104
	v_mov_b32_e32 v89, v104
	v_mul_f32_e32 v86, v86, v88
	v_mul_f32_e32 v87, v87, v89
	v_mul_f32_e32 v88, v82, v88
	v_mul_f32_e32 v89, v83, v89
	v_mul_f32_e32 v90, v80, v104
	v_mul_f32_e32 v91, v81, v105
	v_mov_b32_e32 v82, v85
	v_mov_b32_e32 v83, v87
	v_mov_b32_e32 v108, v91
	v_mov_b32_e32 v109, v89
	v_mov_b32_e32 v80, v84
	v_mov_b32_e32 v81, v86
	v_mov_b32_e32 v104, v90
	v_mov_b32_e32 v105, v88
	s_and_saveexec_b64 s[86:87], s[22:23]
	s_cbranch_execz .LBB0_2169
	v_mov_b32_e32 v119, v137
	v_lshl_add_u64 v[80:81], s[66:67], 0, v[136:137]
	v_lshlrev_b64 v[112:113], 2, v[118:119]
	v_lshl_add_u64 v[80:81], v[80:81], 0, v[112:113]
	global_load_dwordx4 v[108:111], v[80:81], off
	v_lshl_add_u64 v[80:81], s[68:69], 0, v[136:137]
	v_lshl_add_u64 v[80:81], v[80:81], 0, v[112:113]
	global_load_dwordx4 v[112:115], v[80:81], off
	v_mov_b32_e32 v82, v85
	v_mov_b32_e32 v83, v87
	v_mov_b32_e32 v104, v84
	v_mov_b32_e32 v105, v86
	v_mov_b32_e32 v120, v91
	v_mov_b32_e32 v121, v89
	v_mov_b32_e32 v122, v90
	v_mov_b32_e32 v123, v88
	s_waitcnt vmcnt(0)
	v_mul_f32_e32 v80, v82, v112
	v_mul_f32_e32 v81, v83, v113
	s_nop 0
	v_fma_f32 v80, v104, v108, -v80
	v_fma_f32 v81, v105, v109, -v81
	v_mul_f32_e32 v104, v104, v112
	v_mul_f32_e32 v105, v105, v113
	s_nop 0
	v_fma_f32 v82, v82, v108, v104
	v_fma_f32 v83, v83, v109, v105
	v_mul_f32_e32 v104, v120, v114
	v_mul_f32_e32 v105, v121, v115
	v_mul_f32_e32 v108, v122, v114
	v_mul_f32_e32 v109, v123, v115
	v_fma_f32 v104, v122, v110, -v104
	v_fma_f32 v105, v123, v111, -v105
	v_fma_f32 v108, v120, v110, v108
	v_fma_f32 v109, v121, v111, v109

.LBB0_2173:
	s_or_b64 exec, exec, s[86:87]
	v_or_b32_e32 v86, 48, v154
	v_ashrrev_i32_e32 v87, 31, v86
	v_lshlrev_b64 v[80:81], 7, v[86:87]
	v_lshl_add_u64 v[82:83], s[52:53], 0, v[80:81]
	v_mov_b32_e32 v84, 0
	v_lshl_add_u64 v[82:83], v[138:139], 4, v[82:83]
	s_and_saveexec_b64 s[86:87], s[14:15]
	s_cbranch_execz .LBB0_2175
	global_load_dwordx4 v[88:91], v[82:83], off
	s_waitcnt vmcnt(0)
	v_mov_b32_e32 v84, v89
	s_waitcnt lgkmcnt(0)
	v_mov_b32_e32 v85, v90
	v_mov_b32_e32 v89, v91
	v_add_f32_e32 v84, v84, v88
	v_add_f32_e32 v85, v85, v89
	s_nop 0
	v_add_f32_e32 v84, v84, v85
	v_add_f32_e32 v84, 0, v84
.LBB0_2175:
	s_or_b64 exec, exec, s[86:87]
	s_and_saveexec_b64 s[86:87], s[16:17]
	s_cbranch_execz .LBB0_2177
	global_load_dwordx4 v[88:91], v[82:83], off offset:64
	s_waitcnt vmcnt(0)
	v_mov_b32_e32 v82, v89
	v_mov_b32_e32 v83, v90
	v_mov_b32_e32 v89, v91
	v_add_f32_e32 v82, v82, v88
	v_add_f32_e32 v83, v83, v89
	s_nop 0
	v_add_f32_e32 v82, v82, v83
	v_add_f32_e32 v84, v84, v82
.LBB0_2177:
	s_or_b64 exec, exec, s[86:87]
	ds_bpermute_b32 v82, v177, v84
	s_waitcnt lgkmcnt(0)
	v_add_f32_e32 v82, v84, v82
	ds_bpermute_b32 v83, v178, v82
	s_waitcnt lgkmcnt(0)
	v_add_f32_e32 v82, v82, v83
	v_fmamk_f32 v82, v82, 0x3a000000, v182
	v_rsq_f32_e32 v88, v82
	v_lshlrev_b32_e32 v82, 5, v86
	v_and_b32_e32 v82, 0xffe0, v82
	v_lshlrev_b32_e32 v136, 2, v82
	v_mul_f32_e32 v82, v76, v88
	v_mul_f32_e32 v83, v77, v88
	v_mul_f32_e32 v76, v78, v88
	v_mul_f32_e32 v77, v79, v88
	v_mul_f32_e32 v84, v72, v88
	v_mul_f32_e32 v85, v73, v88
	v_mul_f32_e32 v78, v74, v88
	v_mul_f32_e32 v79, v75, v88
	v_mov_b32_e32 v74, v83
	v_mov_b32_e32 v75, v77
	v_mov_b32_e32 v92, v85
	v_mov_b32_e32 v93, v79
	v_mov_b32_e32 v72, v82
	v_mov_b32_e32 v73, v76
	v_mov_b32_e32 v90, v84
	v_mov_b32_e32 v91, v78
	s_and_saveexec_b64 s[86:87], vcc
	s_cbranch_execz .LBB0_2179
	v_mov_b32_e32 v153, v137
	v_lshl_add_u64 v[72:73], s[66:67], 0, v[136:137]
	v_lshlrev_b64 v[94:95], 2, v[152:153]
	v_lshl_add_u64 v[72:73], v[72:73], 0, v[94:95]
	global_load_dwordx4 v[90:93], v[72:73], off
	v_lshl_add_u64 v[72:73], s[68:69], 0, v[136:137]
	v_lshl_add_u64 v[72:73], v[72:73], 0, v[94:95]
	global_load_dwordx4 v[94:97], v[72:73], off
	v_mov_b32_e32 v74, v83
	v_mov_b32_e32 v75, v77
	v_mov_b32_e32 v100, v82
	v_mov_b32_e32 v101, v76
	v_mov_b32_e32 v98, v85
	v_mov_b32_e32 v99, v79
	v_mov_b32_e32 v102, v84
	v_mov_b32_e32 v103, v78
	s_waitcnt vmcnt(0)
	v_mul_f32_e32 v72, v74, v94
	v_mul_f32_e32 v73, v75, v95
	v_mul_f32_e32 v94, v100, v94
	v_mul_f32_e32 v95, v101, v95
	v_fma_f32 v72, v100, v90, -v72
	v_fma_f32 v73, v101, v91, -v73
	v_fma_f32 v74, v74, v90, v94
	v_fma_f32 v75, v75, v91, v95
	v_mul_f32_e32 v90, v98, v96
	v_mul_f32_e32 v91, v99, v97
	v_mul_f32_e32 v94, v102, v96
	v_mul_f32_e32 v95, v103, v97
	v_fma_f32 v90, v102, v92, -v90
	v_fma_f32 v91, v103, v93, -v91
	v_fma_f32 v92, v98, v92, v94
	v_fma_f32 v93, v99, v93, v95

.LBB0_2181:
	s_or_b64 exec, exec, s[86:87]
	v_mov_b64_e32 v[92:93], s[50:51]
	v_mad_i64_i32 v[86:87], s[60:61], v86, s29, v[92:93]
	v_lshl_add_u64 v[86:87], v[148:149], 1, v[86:87]
	v_mov_b32_e32 v89, v88
	global_store_dwordx4 v[86:87], v[72:75], off
	v_mul_f32_e32 v68, v68, v88
	v_mul_f32_e32 v69, v69, v89
	s_nop 0
	v_mov_b32_e32 v72, v88
	v_mov_b32_e32 v73, v88
	v_mul_f32_e32 v70, v70, v72
	v_mul_f32_e32 v71, v71, v73
	v_mul_f32_e32 v72, v66, v72
	v_mul_f32_e32 v73, v67, v73
	v_mul_f32_e32 v74, v64, v88
	v_mul_f32_e32 v75, v65, v89
	v_mov_b32_e32 v66, v69
	v_mov_b32_e32 v67, v71
	v_mov_b32_e32 v92, v75
	v_mov_b32_e32 v93, v73
	v_mov_b32_e32 v64, v68
	v_mov_b32_e32 v65, v70
	v_mov_b32_e32 v88, v74
	v_mov_b32_e32 v89, v72
	s_and_saveexec_b64 s[86:87], s[22:23]
	s_cbranch_execz .LBB0_2183
	v_mov_b32_e32 v119, v137
	v_lshl_add_u64 v[64:65], s[66:67], 0, v[136:137]
	v_lshlrev_b64 v[96:97], 2, v[118:119]
	v_lshl_add_u64 v[64:65], v[64:65], 0, v[96:97]
	global_load_dwordx4 v[92:95], v[64:65], off
	v_lshl_add_u64 v[64:65], s[68:69], 0, v[136:137]
	v_lshl_add_u64 v[64:65], v[64:65], 0, v[96:97]
	global_load_dwordx4 v[96:99], v[64:65], off
	v_mov_b32_e32 v66, v69
	v_mov_b32_e32 v67, v71
	v_mov_b32_e32 v88, v68
	v_mov_b32_e32 v89, v70
	v_mov_b32_e32 v100, v75
	v_mov_b32_e32 v101, v73
	v_mov_b32_e32 v102, v74
	v_mov_b32_e32 v103, v72
	s_waitcnt vmcnt(0)
	v_mul_f32_e32 v64, v66, v96
	v_mul_f32_e32 v65, v67, v97
	s_nop 0
	v_fma_f32 v64, v88, v92, -v64
	v_fma_f32 v65, v89, v93, -v65
	v_mul_f32_e32 v88, v88, v96
	v_mul_f32_e32 v89, v89, v97
	s_nop 0
	v_fma_f32 v66, v66, v92, v88
	v_fma_f32 v67, v67, v93, v89
	v_mul_f32_e32 v88, v100, v98
	v_mul_f32_e32 v89, v101, v99
	v_mul_f32_e32 v92, v102, v98
	v_mul_f32_e32 v93, v103, v99
	v_fma_f32 v88, v102, v94, -v88
	v_fma_f32 v89, v103, v95, -v89
	v_fma_f32 v92, v100, v94, v92
	v_fma_f32 v93, v101, v95, v93

.LBB0_2187:
	s_or_b64 exec, exec, s[86:87]
	v_add_u32_e32 v70, 0x80, v154
	v_ashrrev_i32_e32 v71, 31, v70
	v_lshlrev_b64 v[64:65], 7, v[70:71]
	v_lshl_add_u64 v[66:67], s[52:53], 0, v[64:65]
	v_mov_b32_e32 v68, 0
	v_lshl_add_u64 v[66:67], v[138:139], 4, v[66:67]
	s_and_saveexec_b64 s[86:87], s[14:15]
	s_cbranch_execz .LBB0_2189
	global_load_dwordx4 v[72:75], v[66:67], off
	s_waitcnt vmcnt(0)
	v_mov_b32_e32 v68, v73
	s_waitcnt lgkmcnt(0)
	v_mov_b32_e32 v69, v74
	v_mov_b32_e32 v73, v75
	v_add_f32_e32 v68, v68, v72
	v_add_f32_e32 v69, v69, v73
	s_nop 0
	v_add_f32_e32 v68, v68, v69
	v_add_f32_e32 v68, 0, v68
.LBB0_2189:
	s_or_b64 exec, exec, s[86:87]
	s_and_saveexec_b64 s[86:87], s[16:17]
	s_cbranch_execz .LBB0_2191
	global_load_dwordx4 v[72:75], v[66:67], off offset:64
	s_waitcnt vmcnt(0)
	v_mov_b32_e32 v66, v73
	v_mov_b32_e32 v67, v74
	v_mov_b32_e32 v73, v75
	v_add_f32_e32 v66, v66, v72
	v_add_f32_e32 v67, v67, v73
	s_nop 0
	v_add_f32_e32 v66, v66, v67
	v_add_f32_e32 v68, v68, v66
.LBB0_2191:
	s_or_b64 exec, exec, s[86:87]
	ds_bpermute_b32 v66, v177, v68
	s_waitcnt lgkmcnt(0)
	v_add_f32_e32 v66, v68, v66
	ds_bpermute_b32 v67, v178, v66
	s_waitcnt lgkmcnt(0)
	v_add_f32_e32 v66, v66, v67
	v_fmamk_f32 v66, v66, 0x3a000000, v182
	v_rsq_f32_e32 v72, v66
	v_lshlrev_b32_e32 v66, 5, v70
	v_and_b32_e32 v66, 0xf9e0, v66
	v_lshlrev_b32_e32 v136, 2, v66
	v_mul_f32_e32 v66, v60, v72
	v_mul_f32_e32 v67, v61, v72
	v_mul_f32_e32 v60, v62, v72
	v_mul_f32_e32 v61, v63, v72
	v_mul_f32_e32 v68, v56, v72
	v_mul_f32_e32 v69, v57, v72
	v_mul_f32_e32 v62, v58, v72
	v_mul_f32_e32 v63, v59, v72
	v_mov_b32_e32 v58, v67
	v_mov_b32_e32 v59, v61
	v_mov_b32_e32 v76, v69
	v_mov_b32_e32 v77, v63
	v_mov_b32_e32 v56, v66
	v_mov_b32_e32 v57, v60
	v_mov_b32_e32 v74, v68
	v_mov_b32_e32 v75, v62
	s_and_saveexec_b64 s[86:87], vcc
	s_cbranch_execz .LBB0_2193
	v_mov_b32_e32 v153, v137
	v_lshl_add_u64 v[56:57], s[66:67], 0, v[136:137]
	v_lshlrev_b64 v[78:79], 2, v[152:153]
	v_lshl_add_u64 v[56:57], v[56:57], 0, v[78:79]
	global_load_dwordx4 v[74:77], v[56:57], off
	v_lshl_add_u64 v[56:57], s[68:69], 0, v[136:137]
	v_lshl_add_u64 v[56:57], v[56:57], 0, v[78:79]
	global_load_dwordx4 v[78:81], v[56:57], off
	v_mov_b32_e32 v58, v67
	v_mov_b32_e32 v59, v61
	v_mov_b32_e32 v84, v66
	v_mov_b32_e32 v85, v60
	v_mov_b32_e32 v82, v69
	v_mov_b32_e32 v83, v63
	v_mov_b32_e32 v86, v68
	v_mov_b32_e32 v87, v62
	s_waitcnt vmcnt(0)
	v_mul_f32_e32 v56, v58, v78
	v_mul_f32_e32 v57, v59, v79
	v_mul_f32_e32 v78, v84, v78
	v_mul_f32_e32 v79, v85, v79
	v_fma_f32 v56, v84, v74, -v56
	v_fma_f32 v57, v85, v75, -v57
	v_fma_f32 v58, v58, v74, v78
	v_fma_f32 v59, v59, v75, v79
	v_mul_f32_e32 v74, v82, v80
	v_mul_f32_e32 v75, v83, v81
	v_mul_f32_e32 v78, v86, v80
	v_mul_f32_e32 v79, v87, v81
	v_fma_f32 v74, v86, v76, -v74
	v_fma_f32 v75, v87, v77, -v75
	v_fma_f32 v76, v82, v76, v78
	v_fma_f32 v77, v83, v77, v79

.LBB0_2195:
	s_or_b64 exec, exec, s[86:87]
	v_mov_b64_e32 v[76:77], s[50:51]
	v_mad_i64_i32 v[70:71], s[60:61], v70, s29, v[76:77]
	v_lshl_add_u64 v[70:71], v[148:149], 1, v[70:71]
	v_mov_b32_e32 v73, v72
	global_store_dwordx4 v[70:71], v[56:59], off
	v_mul_f32_e32 v52, v52, v72
	v_mul_f32_e32 v53, v53, v73
	s_nop 0
	v_mov_b32_e32 v56, v72
	v_mov_b32_e32 v57, v72
	v_mul_f32_e32 v54, v54, v56
	v_mul_f32_e32 v55, v55, v57
	v_mul_f32_e32 v56, v50, v56
	v_mul_f32_e32 v57, v51, v57
	v_mul_f32_e32 v58, v48, v72
	v_mul_f32_e32 v59, v49, v73
	v_mov_b32_e32 v50, v53
	v_mov_b32_e32 v51, v55
	v_mov_b32_e32 v76, v59
	v_mov_b32_e32 v77, v57
	v_mov_b32_e32 v48, v52
	v_mov_b32_e32 v49, v54
	v_mov_b32_e32 v72, v58
	v_mov_b32_e32 v73, v56
	s_and_saveexec_b64 s[86:87], s[22:23]
	s_cbranch_execz .LBB0_2197
	v_mov_b32_e32 v119, v137
	v_lshl_add_u64 v[48:49], s[66:67], 0, v[136:137]
	v_lshlrev_b64 v[80:81], 2, v[118:119]
	v_lshl_add_u64 v[48:49], v[48:49], 0, v[80:81]
	global_load_dwordx4 v[76:79], v[48:49], off
	v_lshl_add_u64 v[48:49], s[68:69], 0, v[136:137]
	v_lshl_add_u64 v[48:49], v[48:49], 0, v[80:81]
	global_load_dwordx4 v[80:83], v[48:49], off
	v_mov_b32_e32 v50, v53
	v_mov_b32_e32 v51, v55
	v_mov_b32_e32 v72, v52
	v_mov_b32_e32 v73, v54
	v_mov_b32_e32 v84, v59
	v_mov_b32_e32 v85, v57
	v_mov_b32_e32 v86, v58
	v_mov_b32_e32 v87, v56
	s_waitcnt vmcnt(0)
	v_mul_f32_e32 v48, v50, v80
	v_mul_f32_e32 v49, v51, v81
	s_nop 0
	v_fma_f32 v48, v72, v76, -v48
	v_fma_f32 v49, v73, v77, -v49
	v_mul_f32_e32 v72, v72, v80
	v_mul_f32_e32 v73, v73, v81
	s_nop 0
	v_fma_f32 v50, v50, v76, v72
	v_fma_f32 v51, v51, v77, v73
	v_mul_f32_e32 v72, v84, v82
	v_mul_f32_e32 v73, v85, v83
	v_mul_f32_e32 v76, v86, v82
	v_mul_f32_e32 v77, v87, v83
	v_fma_f32 v72, v86, v78, -v72
	v_fma_f32 v73, v87, v79, -v73
	v_fma_f32 v76, v84, v78, v76
	v_fma_f32 v77, v85, v79, v77

.LBB0_2201:
	s_or_b64 exec, exec, s[86:87]
	v_add_u32_e32 v54, 0x90, v154
	v_ashrrev_i32_e32 v55, 31, v54
	v_lshlrev_b64 v[48:49], 7, v[54:55]
	v_lshl_add_u64 v[50:51], s[52:53], 0, v[48:49]
	v_mov_b32_e32 v52, 0
	v_lshl_add_u64 v[50:51], v[138:139], 4, v[50:51]
	s_and_saveexec_b64 s[86:87], s[14:15]
	s_cbranch_execz .LBB0_2203
	global_load_dwordx4 v[56:59], v[50:51], off
	s_waitcnt vmcnt(0)
	v_mov_b32_e32 v52, v57
	s_waitcnt lgkmcnt(0)
	v_mov_b32_e32 v53, v58
	v_mov_b32_e32 v57, v59
	v_add_f32_e32 v52, v52, v56
	v_add_f32_e32 v53, v53, v57
	s_nop 0
	v_add_f32_e32 v52, v52, v53
	v_add_f32_e32 v52, 0, v52
.LBB0_2203:
	s_or_b64 exec, exec, s[86:87]
	s_and_saveexec_b64 s[86:87], s[16:17]
	s_cbranch_execz .LBB0_2205
	global_load_dwordx4 v[56:59], v[50:51], off offset:64
	s_waitcnt vmcnt(0)
	v_mov_b32_e32 v50, v57
	v_mov_b32_e32 v51, v58
	v_mov_b32_e32 v57, v59
	v_add_f32_e32 v50, v50, v56
	v_add_f32_e32 v51, v51, v57
	s_nop 0
	v_add_f32_e32 v50, v50, v51
	v_add_f32_e32 v52, v52, v50
.LBB0_2205:
	s_or_b64 exec, exec, s[86:87]
	ds_bpermute_b32 v50, v177, v52
	s_waitcnt lgkmcnt(0)
	v_add_f32_e32 v50, v52, v50
	ds_bpermute_b32 v51, v178, v50
	s_waitcnt lgkmcnt(0)
	v_add_f32_e32 v50, v50, v51
	v_fmamk_f32 v50, v50, 0x3a000000, v182
	v_rsq_f32_e32 v56, v50
	v_lshlrev_b32_e32 v50, 5, v54
	v_and_b32_e32 v50, 0xfbe0, v50
	v_lshlrev_b32_e32 v136, 2, v50
	v_mul_f32_e32 v50, v44, v56
	v_mul_f32_e32 v51, v45, v56
	v_mul_f32_e32 v44, v46, v56
	v_mul_f32_e32 v45, v47, v56
	v_mul_f32_e32 v52, v40, v56
	v_mul_f32_e32 v53, v41, v56
	v_mul_f32_e32 v46, v42, v56
	v_mul_f32_e32 v47, v43, v56
	v_mov_b32_e32 v42, v51
	v_mov_b32_e32 v43, v45
	v_mov_b32_e32 v60, v53
	v_mov_b32_e32 v61, v47
	v_mov_b32_e32 v40, v50
	v_mov_b32_e32 v41, v44
	v_mov_b32_e32 v58, v52
	v_mov_b32_e32 v59, v46
	s_and_saveexec_b64 s[86:87], vcc
	s_cbranch_execz .LBB0_2207
	v_mov_b32_e32 v153, v137
	v_lshl_add_u64 v[40:41], s[66:67], 0, v[136:137]
	v_lshlrev_b64 v[62:63], 2, v[152:153]
	v_lshl_add_u64 v[40:41], v[40:41], 0, v[62:63]
	global_load_dwordx4 v[58:61], v[40:41], off
	v_lshl_add_u64 v[40:41], s[68:69], 0, v[136:137]
	v_lshl_add_u64 v[40:41], v[40:41], 0, v[62:63]
	global_load_dwordx4 v[62:65], v[40:41], off
	v_mov_b32_e32 v42, v51
	v_mov_b32_e32 v43, v45
	v_mov_b32_e32 v68, v50
	v_mov_b32_e32 v69, v44
	v_mov_b32_e32 v66, v53
	v_mov_b32_e32 v67, v47
	v_mov_b32_e32 v70, v52
	v_mov_b32_e32 v71, v46
	s_waitcnt vmcnt(0)
	v_mul_f32_e32 v40, v42, v62
	v_mul_f32_e32 v41, v43, v63
	v_mul_f32_e32 v62, v68, v62
	v_mul_f32_e32 v63, v69, v63
	v_fma_f32 v40, v68, v58, -v40
	v_fma_f32 v41, v69, v59, -v41
	v_fma_f32 v42, v42, v58, v62
	v_fma_f32 v43, v43, v59, v63
	v_mul_f32_e32 v58, v66, v64
	v_mul_f32_e32 v59, v67, v65
	v_mul_f32_e32 v62, v70, v64
	v_mul_f32_e32 v63, v71, v65
	v_fma_f32 v58, v70, v60, -v58
	v_fma_f32 v59, v71, v61, -v59
	v_fma_f32 v60, v66, v60, v62
	v_fma_f32 v61, v67, v61, v63

.LBB0_2209:
	s_or_b64 exec, exec, s[86:87]
	v_mov_b64_e32 v[60:61], s[50:51]
	v_mad_i64_i32 v[54:55], s[60:61], v54, s29, v[60:61]
	v_lshl_add_u64 v[54:55], v[148:149], 1, v[54:55]
	v_mov_b32_e32 v57, v56
	global_store_dwordx4 v[54:55], v[40:43], off
	v_mul_f32_e32 v36, v36, v56
	v_mul_f32_e32 v37, v37, v57
	s_nop 0
	v_mov_b32_e32 v40, v56
	v_mov_b32_e32 v41, v56
	v_mul_f32_e32 v38, v38, v40
	v_mul_f32_e32 v39, v39, v41
	v_mul_f32_e32 v40, v34, v40
	v_mul_f32_e32 v41, v35, v41
	v_mul_f32_e32 v42, v32, v56
	v_mul_f32_e32 v43, v33, v57
	v_mov_b32_e32 v34, v37
	v_mov_b32_e32 v35, v39
	v_mov_b32_e32 v60, v43
	v_mov_b32_e32 v61, v41
	v_mov_b32_e32 v32, v36
	v_mov_b32_e32 v33, v38
	v_mov_b32_e32 v56, v42
	v_mov_b32_e32 v57, v40
	s_and_saveexec_b64 s[86:87], s[22:23]
	s_cbranch_execz .LBB0_2211
	v_mov_b32_e32 v119, v137
	v_lshl_add_u64 v[32:33], s[66:67], 0, v[136:137]
	v_lshlrev_b64 v[64:65], 2, v[118:119]
	v_lshl_add_u64 v[32:33], v[32:33], 0, v[64:65]
	global_load_dwordx4 v[60:63], v[32:33], off
	v_lshl_add_u64 v[32:33], s[68:69], 0, v[136:137]
	v_lshl_add_u64 v[32:33], v[32:33], 0, v[64:65]
	global_load_dwordx4 v[64:67], v[32:33], off
	v_mov_b32_e32 v34, v37
	v_mov_b32_e32 v35, v39
	v_mov_b32_e32 v56, v36
	v_mov_b32_e32 v57, v38
	v_mov_b32_e32 v68, v43
	v_mov_b32_e32 v69, v41
	v_mov_b32_e32 v70, v42
	v_mov_b32_e32 v71, v40
	s_waitcnt vmcnt(0)
	v_mul_f32_e32 v32, v34, v64
	v_mul_f32_e32 v33, v35, v65
	s_nop 0
	v_fma_f32 v32, v56, v60, -v32
	v_fma_f32 v33, v57, v61, -v33
	v_mul_f32_e32 v56, v56, v64
	v_mul_f32_e32 v57, v57, v65
	s_nop 0
	v_fma_f32 v34, v34, v60, v56
	v_fma_f32 v35, v35, v61, v57
	v_mul_f32_e32 v56, v68, v66
	v_mul_f32_e32 v57, v69, v67
	v_mul_f32_e32 v60, v70, v66
	v_mul_f32_e32 v61, v71, v67
	v_fma_f32 v56, v70, v62, -v56
	v_fma_f32 v57, v71, v63, -v57
	v_fma_f32 v60, v68, v62, v60
	v_fma_f32 v61, v69, v63, v61

.LBB0_2215:
	s_or_b64 exec, exec, s[86:87]
	v_add_u32_e32 v38, 0xa0, v154
	v_ashrrev_i32_e32 v39, 31, v38
	v_lshlrev_b64 v[32:33], 7, v[38:39]
	v_lshl_add_u64 v[34:35], s[52:53], 0, v[32:33]
	v_mov_b32_e32 v36, 0
	v_lshl_add_u64 v[34:35], v[138:139], 4, v[34:35]
	s_and_saveexec_b64 s[86:87], s[14:15]
	s_cbranch_execz .LBB0_2217
	global_load_dwordx4 v[40:43], v[34:35], off
	s_waitcnt vmcnt(0)
	v_mov_b32_e32 v36, v41
	s_waitcnt lgkmcnt(0)
	v_mov_b32_e32 v37, v42
	v_mov_b32_e32 v41, v43
	v_add_f32_e32 v36, v36, v40
	v_add_f32_e32 v37, v37, v41
	s_nop 0
	v_add_f32_e32 v36, v36, v37
	v_add_f32_e32 v36, 0, v36
.LBB0_2217:
	s_or_b64 exec, exec, s[86:87]
	s_and_saveexec_b64 s[86:87], s[16:17]
	s_cbranch_execz .LBB0_2219
	global_load_dwordx4 v[40:43], v[34:35], off offset:64
	s_waitcnt vmcnt(0)
	v_mov_b32_e32 v34, v41
	v_mov_b32_e32 v35, v42
	v_mov_b32_e32 v41, v43
	v_add_f32_e32 v34, v34, v40
	v_add_f32_e32 v35, v35, v41
	s_nop 0
	v_add_f32_e32 v34, v34, v35
	v_add_f32_e32 v36, v36, v34
.LBB0_2219:
	s_or_b64 exec, exec, s[86:87]
	ds_bpermute_b32 v34, v177, v36
	s_waitcnt lgkmcnt(0)
	v_add_f32_e32 v34, v36, v34
	ds_bpermute_b32 v35, v178, v34
	s_waitcnt lgkmcnt(0)
	v_add_f32_e32 v34, v34, v35
	v_fmamk_f32 v34, v34, 0x3a000000, v182
	v_rsq_f32_e32 v40, v34
	v_lshlrev_b32_e32 v34, 5, v38
	v_and_b32_e32 v34, 0xfde0, v34
	v_lshlrev_b32_e32 v136, 2, v34
	v_mul_f32_e32 v34, v28, v40
	v_mul_f32_e32 v35, v29, v40
	v_mul_f32_e32 v28, v30, v40
	v_mul_f32_e32 v29, v31, v40
	v_mul_f32_e32 v36, v24, v40
	v_mul_f32_e32 v37, v25, v40
	v_mul_f32_e32 v30, v26, v40
	v_mul_f32_e32 v31, v27, v40
	v_mov_b32_e32 v26, v35
	v_mov_b32_e32 v27, v29
	v_mov_b32_e32 v44, v37
	v_mov_b32_e32 v45, v31
	v_mov_b32_e32 v24, v34
	v_mov_b32_e32 v25, v28
	v_mov_b32_e32 v42, v36
	v_mov_b32_e32 v43, v30
	s_and_saveexec_b64 s[86:87], vcc
	s_cbranch_execz .LBB0_2221
	v_mov_b32_e32 v153, v137
	v_lshl_add_u64 v[24:25], s[66:67], 0, v[136:137]
	v_lshlrev_b64 v[46:47], 2, v[152:153]
	v_lshl_add_u64 v[24:25], v[24:25], 0, v[46:47]
	global_load_dwordx4 v[42:45], v[24:25], off
	v_lshl_add_u64 v[24:25], s[68:69], 0, v[136:137]
	v_lshl_add_u64 v[24:25], v[24:25], 0, v[46:47]
	global_load_dwordx4 v[46:49], v[24:25], off
	v_mov_b32_e32 v26, v35
	v_mov_b32_e32 v27, v29
	v_mov_b32_e32 v52, v34
	v_mov_b32_e32 v53, v28
	v_mov_b32_e32 v50, v37
	v_mov_b32_e32 v51, v31
	v_mov_b32_e32 v54, v36
	v_mov_b32_e32 v55, v30
	s_waitcnt vmcnt(0)
	v_mul_f32_e32 v24, v26, v46
	v_mul_f32_e32 v25, v27, v47
	v_mul_f32_e32 v46, v52, v46
	v_mul_f32_e32 v47, v53, v47
	v_fma_f32 v24, v52, v42, -v24
	v_fma_f32 v25, v53, v43, -v25
	v_fma_f32 v26, v26, v42, v46
	v_fma_f32 v27, v27, v43, v47
	v_mul_f32_e32 v42, v50, v48
	v_mul_f32_e32 v43, v51, v49
	v_mul_f32_e32 v46, v54, v48
	v_mul_f32_e32 v47, v55, v49
	v_fma_f32 v42, v54, v44, -v42
	v_fma_f32 v43, v55, v45, -v43
	v_fma_f32 v44, v50, v44, v46
	v_fma_f32 v45, v51, v45, v47

.LBB0_2223:
	s_or_b64 exec, exec, s[86:87]
	v_mov_b64_e32 v[44:45], s[50:51]
	v_mad_i64_i32 v[38:39], s[60:61], v38, s29, v[44:45]
	v_lshl_add_u64 v[38:39], v[148:149], 1, v[38:39]
	v_mov_b32_e32 v41, v40
	global_store_dwordx4 v[38:39], v[24:27], off
	v_mul_f32_e32 v20, v20, v40
	v_mul_f32_e32 v21, v21, v41
	s_nop 0
	v_mov_b32_e32 v24, v40
	v_mov_b32_e32 v25, v40
	v_mul_f32_e32 v22, v22, v24
	v_mul_f32_e32 v23, v23, v25
	v_mul_f32_e32 v24, v18, v24
	v_mul_f32_e32 v25, v19, v25
	v_mul_f32_e32 v26, v16, v40
	v_mul_f32_e32 v27, v17, v41
	v_mov_b32_e32 v18, v21
	v_mov_b32_e32 v19, v23
	v_mov_b32_e32 v44, v27
	v_mov_b32_e32 v45, v25
	v_mov_b32_e32 v16, v20
	v_mov_b32_e32 v17, v22
	v_mov_b32_e32 v40, v26
	v_mov_b32_e32 v41, v24
	s_and_saveexec_b64 s[86:87], s[22:23]
	s_cbranch_execz .LBB0_2225
	v_mov_b32_e32 v119, v137
	v_lshl_add_u64 v[16:17], s[66:67], 0, v[136:137]
	v_lshlrev_b64 v[48:49], 2, v[118:119]
	v_lshl_add_u64 v[16:17], v[16:17], 0, v[48:49]
	global_load_dwordx4 v[44:47], v[16:17], off
	v_lshl_add_u64 v[16:17], s[68:69], 0, v[136:137]
	v_lshl_add_u64 v[16:17], v[16:17], 0, v[48:49]
	global_load_dwordx4 v[48:51], v[16:17], off
	v_mov_b32_e32 v18, v21
	v_mov_b32_e32 v19, v23
	v_mov_b32_e32 v40, v20
	v_mov_b32_e32 v41, v22
	v_mov_b32_e32 v52, v27
	v_mov_b32_e32 v53, v25
	v_mov_b32_e32 v54, v26
	v_mov_b32_e32 v55, v24
	s_waitcnt vmcnt(0)
	v_mul_f32_e32 v16, v18, v48
	v_mul_f32_e32 v17, v19, v49
	s_nop 0
	v_fma_f32 v16, v40, v44, -v16
	v_fma_f32 v17, v41, v45, -v17
	v_mul_f32_e32 v40, v40, v48
	v_mul_f32_e32 v41, v41, v49
	s_nop 0
	v_fma_f32 v18, v18, v44, v40
	v_fma_f32 v19, v19, v45, v41
	v_mul_f32_e32 v40, v52, v50
	v_mul_f32_e32 v41, v53, v51
	v_mul_f32_e32 v44, v54, v50
	v_mul_f32_e32 v45, v55, v51
	v_fma_f32 v40, v54, v46, -v40
	v_fma_f32 v41, v55, v47, -v41
	v_fma_f32 v44, v52, v46, v44
	v_fma_f32 v45, v53, v47, v45

.LBB0_2229:
	s_or_b64 exec, exec, s[86:87]
	v_add_u32_e32 v22, 0xb0, v154
	v_ashrrev_i32_e32 v23, 31, v22
	v_lshlrev_b64 v[16:17], 7, v[22:23]
	v_lshl_add_u64 v[18:19], s[52:53], 0, v[16:17]
	v_mov_b32_e32 v20, 0
	v_lshl_add_u64 v[18:19], v[138:139], 4, v[18:19]
	s_and_saveexec_b64 s[86:87], s[14:15]
	s_cbranch_execz .LBB0_2231
	global_load_dwordx4 v[24:27], v[18:19], off
	s_waitcnt vmcnt(0)
	v_mov_b32_e32 v20, v25
	s_waitcnt lgkmcnt(0)
	v_mov_b32_e32 v21, v26
	v_mov_b32_e32 v25, v27
	v_add_f32_e32 v20, v20, v24
	v_add_f32_e32 v21, v21, v25
	s_nop 0
	v_add_f32_e32 v20, v20, v21
	v_add_f32_e32 v20, 0, v20
.LBB0_2231:
	s_or_b64 exec, exec, s[86:87]
	s_and_saveexec_b64 s[86:87], s[16:17]
	s_cbranch_execz .LBB0_2233
	global_load_dwordx4 v[24:27], v[18:19], off offset:64
	s_waitcnt vmcnt(0)
	v_mov_b32_e32 v18, v25
	v_mov_b32_e32 v19, v26
	v_mov_b32_e32 v25, v27
	v_add_f32_e32 v18, v18, v24
	v_add_f32_e32 v19, v19, v25
	s_nop 0
	v_add_f32_e32 v18, v18, v19
	v_add_f32_e32 v20, v20, v18
.LBB0_2233:
	s_or_b64 exec, exec, s[86:87]
	ds_bpermute_b32 v18, v177, v20
	s_waitcnt lgkmcnt(0)
	v_add_f32_e32 v18, v20, v18
	ds_bpermute_b32 v19, v178, v18
	s_waitcnt lgkmcnt(0)
	v_add_f32_e32 v18, v18, v19
	v_fmamk_f32 v18, v18, 0x3a000000, v182
	v_rsq_f32_e32 v24, v18
	v_lshlrev_b32_e32 v18, 5, v22
	v_and_b32_e32 v18, 0xffe0, v18
	v_lshlrev_b32_e32 v136, 2, v18
	v_mul_f32_e32 v18, v12, v24
	v_mul_f32_e32 v19, v13, v24
	v_mul_f32_e32 v12, v14, v24
	v_mul_f32_e32 v13, v15, v24
	v_mul_f32_e32 v20, v8, v24
	v_mul_f32_e32 v21, v9, v24
	v_mul_f32_e32 v14, v10, v24
	v_mul_f32_e32 v15, v11, v24
	v_mov_b32_e32 v10, v19
	v_mov_b32_e32 v11, v13
	v_mov_b32_e32 v28, v21
	v_mov_b32_e32 v29, v15
	v_mov_b32_e32 v8, v18
	v_mov_b32_e32 v9, v12
	v_mov_b32_e32 v26, v20
	v_mov_b32_e32 v27, v14
	s_and_saveexec_b64 s[86:87], vcc
	s_cbranch_execz .LBB0_2235
	v_mov_b32_e32 v153, v137
	v_lshl_add_u64 v[8:9], s[66:67], 0, v[136:137]
	v_lshlrev_b64 v[30:31], 2, v[152:153]
	v_lshl_add_u64 v[8:9], v[8:9], 0, v[30:31]
	global_load_dwordx4 v[26:29], v[8:9], off
	v_lshl_add_u64 v[8:9], s[68:69], 0, v[136:137]
	v_lshl_add_u64 v[8:9], v[8:9], 0, v[30:31]
	global_load_dwordx4 v[30:33], v[8:9], off
	v_mov_b32_e32 v10, v19
	v_mov_b32_e32 v11, v13
	v_mov_b32_e32 v36, v18
	v_mov_b32_e32 v37, v12
	v_mov_b32_e32 v34, v21
	v_mov_b32_e32 v35, v15
	v_mov_b32_e32 v38, v20
	v_mov_b32_e32 v39, v14
	s_waitcnt vmcnt(0)
	v_mul_f32_e32 v8, v10, v30
	v_mul_f32_e32 v9, v11, v31
	v_mul_f32_e32 v30, v36, v30
	v_mul_f32_e32 v31, v37, v31
	v_fma_f32 v8, v36, v26, -v8
	v_fma_f32 v9, v37, v27, -v9
	v_fma_f32 v10, v10, v26, v30
	v_fma_f32 v11, v11, v27, v31
	v_mul_f32_e32 v26, v34, v32
	v_mul_f32_e32 v27, v35, v33
	v_mul_f32_e32 v30, v38, v32
	v_mul_f32_e32 v31, v39, v33
	v_fma_f32 v26, v38, v28, -v26
	v_fma_f32 v27, v39, v29, -v27
	v_fma_f32 v28, v34, v28, v30
	v_fma_f32 v29, v35, v29, v31

.LBB0_2237:
	s_or_b64 exec, exec, s[86:87]
	v_mov_b64_e32 v[28:29], s[50:51]
	v_mad_i64_i32 v[22:23], s[60:61], v22, s29, v[28:29]
	v_lshl_add_u64 v[22:23], v[148:149], 1, v[22:23]
	v_mov_b32_e32 v25, v24
	global_store_dwordx4 v[22:23], v[8:11], off
	v_mul_f32_e32 v4, v4, v24
	v_mul_f32_e32 v5, v5, v25
	s_nop 0
	v_mov_b32_e32 v8, v24
	v_mov_b32_e32 v9, v24
	v_mul_f32_e32 v6, v6, v8
	v_mul_f32_e32 v7, v7, v9
	v_mul_f32_e32 v8, v2, v8
	v_mul_f32_e32 v9, v3, v9
	v_mul_f32_e32 v10, v0, v24
	v_mul_f32_e32 v11, v1, v25
	v_mov_b32_e32 v2, v5
	v_mov_b32_e32 v3, v7
	v_mov_b32_e32 v28, v11
	v_mov_b32_e32 v29, v9
	v_mov_b32_e32 v0, v4
	v_mov_b32_e32 v1, v6
	v_mov_b32_e32 v24, v10
	v_mov_b32_e32 v25, v8
	s_and_saveexec_b64 s[86:87], s[22:23]
	s_cbranch_execz .LBB0_2239
	v_mov_b32_e32 v119, v137
	v_lshl_add_u64 v[0:1], s[66:67], 0, v[136:137]
	v_lshlrev_b64 v[32:33], 2, v[118:119]
	v_lshl_add_u64 v[0:1], v[0:1], 0, v[32:33]
	global_load_dwordx4 v[28:31], v[0:1], off
	v_lshl_add_u64 v[0:1], s[68:69], 0, v[136:137]
	v_lshl_add_u64 v[0:1], v[0:1], 0, v[32:33]
	global_load_dwordx4 v[32:35], v[0:1], off
	v_mov_b32_e32 v2, v5
	v_mov_b32_e32 v3, v7
	v_mov_b32_e32 v24, v4
	v_mov_b32_e32 v25, v6
	v_mov_b32_e32 v36, v11
	v_mov_b32_e32 v37, v9
	v_mov_b32_e32 v38, v10
	v_mov_b32_e32 v39, v8
	s_waitcnt vmcnt(0)
	v_mul_f32_e32 v0, v2, v32
	v_mul_f32_e32 v1, v3, v33
	s_nop 0
	v_fma_f32 v0, v24, v28, -v0
	v_fma_f32 v1, v25, v29, -v1
	v_mul_f32_e32 v24, v24, v32
	v_mul_f32_e32 v25, v25, v33
	s_nop 0
	v_fma_f32 v2, v2, v28, v24
	v_fma_f32 v3, v3, v29, v25
	v_mul_f32_e32 v24, v36, v34
	v_mul_f32_e32 v25, v37, v35
	v_mul_f32_e32 v28, v38, v34
	v_mul_f32_e32 v29, v39, v35
	v_fma_f32 v24, v38, v30, -v24
	v_fma_f32 v25, v39, v31, -v25
	v_fma_f32 v28, v36, v30, v28
	v_fma_f32 v29, v37, v31, v29

.LBB0_2316:
	s_or_b64 exec, exec, s[70:71]
	v_lshl_add_u64 v[166:167], v[166:167], 2, s[20:21]
	global_load_dword v168, v[166:167], off
	global_load_dword v170, v[166:167], off offset:16
	global_load_dword v172, v[166:167], off offset:32
	global_load_dword v174, v[166:167], off offset:48
	global_load_dword v176, v[166:167], off offset:64
	global_load_dword v178, v[166:167], off offset:80
	global_load_dword v180, v[166:167], off offset:96
	global_load_dword v182, v[166:167], off offset:112
	global_load_dword v184, v[166:167], off offset:128
	global_load_dword v186, v[166:167], off offset:144
	global_load_dword v188, v[166:167], off offset:160
	global_load_dword v190, v[166:167], off offset:176
	global_load_dword v192, v[166:167], off offset:192
	global_load_dword v194, v[166:167], off offset:208
	global_load_dword v196, v[166:167], off offset:224
	s_nop 0
	global_load_dword v166, v[166:167], off offset:240
	s_waitcnt vmcnt(15)
	v_mul_f32_e32 v22, v22, v168
	v_mul_f32_e32 v23, v23, v168
	v_mul_f32_e32 v20, v20, v168
	v_mul_f32_e32 v21, v21, v168
	s_waitcnt vmcnt(14)
	v_mul_f32_e32 v26, v26, v170
	v_mul_f32_e32 v27, v27, v170
	v_mul_f32_e32 v24, v24, v170
	v_mul_f32_e32 v25, v25, v170
	s_waitcnt vmcnt(13)
	v_mul_f32_e32 v30, v30, v172
	v_mul_f32_e32 v31, v31, v172
	v_mul_f32_e32 v28, v28, v172
	v_mul_f32_e32 v29, v29, v172
	s_waitcnt vmcnt(12)
	v_mul_f32_e32 v34, v34, v174
	v_mul_f32_e32 v35, v35, v174
	v_mul_f32_e32 v32, v32, v174
	v_mul_f32_e32 v33, v33, v174
	s_waitcnt vmcnt(11)
	v_mul_f32_e32 v38, v38, v176
	v_mul_f32_e32 v39, v39, v176
	v_mul_f32_e32 v36, v36, v176
	v_mul_f32_e32 v37, v37, v176
	s_waitcnt vmcnt(10)
	v_mul_f32_e32 v42, v42, v178
	v_mul_f32_e32 v43, v43, v178
	v_mul_f32_e32 v40, v40, v178
	v_mul_f32_e32 v41, v41, v178
	s_waitcnt vmcnt(9)
	v_mul_f32_e32 v46, v46, v180
	v_mul_f32_e32 v47, v47, v180
	v_mul_f32_e32 v44, v44, v180
	v_mul_f32_e32 v45, v45, v180
	s_waitcnt vmcnt(8)
	v_mul_f32_e32 v50, v50, v182
	v_mul_f32_e32 v51, v51, v182
	v_mul_f32_e32 v48, v48, v182
	v_mul_f32_e32 v49, v49, v182
	s_waitcnt vmcnt(7)
	v_mul_f32_e32 v54, v54, v184
	v_mul_f32_e32 v55, v55, v184
	v_mul_f32_e32 v52, v52, v184
	v_mul_f32_e32 v53, v53, v184
	s_waitcnt vmcnt(6)
	v_mul_f32_e32 v58, v58, v186
	v_mul_f32_e32 v59, v59, v186
	v_mul_f32_e32 v56, v56, v186
	v_mul_f32_e32 v57, v57, v186
	s_waitcnt vmcnt(5)
	v_mul_f32_e32 v62, v62, v188
	v_mul_f32_e32 v63, v63, v188
	v_mul_f32_e32 v60, v60, v188
	v_mul_f32_e32 v61, v61, v188
	s_waitcnt vmcnt(4)
	v_mul_f32_e32 v66, v66, v190
	v_mul_f32_e32 v67, v67, v190
	v_mul_f32_e32 v64, v64, v190
	v_mul_f32_e32 v65, v65, v190
	s_waitcnt vmcnt(3)
	v_mul_f32_e32 v70, v70, v192
	v_mul_f32_e32 v71, v71, v192
	v_mul_f32_e32 v68, v68, v192
	v_mul_f32_e32 v69, v69, v192
	s_waitcnt vmcnt(2)
	v_mul_f32_e32 v78, v78, v194
	v_mul_f32_e32 v79, v79, v194
	v_mul_f32_e32 v76, v76, v194
	v_mul_f32_e32 v77, v77, v194
	s_waitcnt vmcnt(1)
	v_mul_f32_e32 v82, v82, v196
	v_mul_f32_e32 v83, v83, v196
	v_mul_f32_e32 v80, v80, v196
	v_mul_f32_e32 v81, v81, v196
	s_waitcnt vmcnt(0)
	v_mul_f32_e32 v90, v90, v166
	v_mul_f32_e32 v91, v91, v166
	v_mul_f32_e32 v88, v88, v166
	v_mul_f32_e32 v89, v89, v166
.LBB0_2317:
	s_waitcnt vmcnt(15)
	v_mul_f32_e32 v2, v2, v164
	v_mul_f32_e32 v3, v3, v164
	v_mul_f32_e32 v0, v0, v164
	v_mul_f32_e32 v1, v1, v164
	s_waitcnt vmcnt(13)
	v_mul_f32_e32 v4, v4, v160
	v_mul_f32_e32 v5, v5, v160
	ds_write2_b32 v161, v0, v1 offset1:1
	ds_write2_b32 v161, v2, v3 offset0:2 offset1:3
	v_add_u32_e32 v3, 0x820, v161
	v_mul_f32_e32 v8, v8, v162
	v_mul_f32_e32 v9, v9, v162
	v_mul_f32_e32 v6, v6, v160
	v_mul_f32_e32 v7, v7, v160
	v_add_u32_e32 v1, 0x410, v161
	ds_write2_b32 v3, v4, v5 offset1:1
	v_add_u32_e32 v4, 0x828, v161
	v_mul_f32_e32 v10, v10, v162
	v_mul_f32_e32 v11, v11, v162
	s_waitcnt vmcnt(12)
	v_mul_f32_e32 v16, v16, v158
	v_mul_f32_e32 v17, v17, v158
	s_waitcnt vmcnt(11)
	v_mul_f32_e32 v14, v14, v156
	v_mul_f32_e32 v15, v15, v156
	v_mul_f32_e32 v12, v12, v156
	v_mul_f32_e32 v13, v13, v156
	ds_write2_b32 v1, v8, v9 offset1:1
	v_add_u32_e32 v2, 0x418, v161
	ds_write2_b32 v4, v6, v7 offset1:1
	v_add_u32_e32 v5, 0xc30, v161
	v_add_u32_e32 v7, 0x1040, v161
	v_add_u32_e32 v8, 0x1048, v161
	v_mul_f32_e32 v18, v18, v158
	v_mul_f32_e32 v19, v19, v158
	s_waitcnt vmcnt(10)
	v_mul_f32_e32 v86, v86, v154
	v_mul_f32_e32 v87, v87, v154
	v_mul_f32_e32 v84, v84, v154
	v_mul_f32_e32 v85, v85, v154
	s_waitcnt vmcnt(9)
	v_mul_f32_e32 v74, v74, v152
	v_mul_f32_e32 v75, v75, v152
	v_mul_f32_e32 v72, v72, v152
	v_mul_f32_e32 v73, v73, v152
	s_waitcnt vmcnt(7)
	v_mul_f32_e32 v94, v94, v148
	v_mul_f32_e32 v95, v95, v148
	v_mul_f32_e32 v92, v92, v148
	v_mul_f32_e32 v93, v93, v148
	ds_write2_b32 v2, v10, v11 offset1:1
	ds_write2_b32 v5, v16, v17 offset1:1
	v_add_u32_e32 v6, 0xc38, v161
	ds_write2_b32 v7, v12, v13 offset1:1
	ds_write2_b32 v8, v14, v15 offset1:1
	v_add_u32_e32 v9, 0x1450, v161
	v_add_u32_e32 v10, 0x1458, v161
	v_add_u32_e32 v11, 0x1860, v161
	v_add_u32_e32 v12, 0x1868, v161
	v_add_u32_e32 v15, 0x2080, v161
	v_add_u32_e32 v16, 0x2088, v161
	v_mul_f32_e32 v98, v98, v150
	v_mul_f32_e32 v99, v99, v150
	v_mul_f32_e32 v96, v96, v150
	v_mul_f32_e32 v97, v97, v150
	s_waitcnt vmcnt(6)
	v_mul_f32_e32 v106, v106, v146
	v_mul_f32_e32 v107, v107, v146
	v_mul_f32_e32 v104, v104, v146
	v_mul_f32_e32 v105, v105, v146
	s_waitcnt vmcnt(5)
	v_mul_f32_e32 v102, v102, v144
	v_mul_f32_e32 v103, v103, v144
	v_mul_f32_e32 v100, v100, v144
	v_mul_f32_e32 v101, v101, v144
	s_waitcnt vmcnt(4)
	v_mul_f32_e32 v114, v114, v142
	v_mul_f32_e32 v115, v115, v142
	v_mul_f32_e32 v112, v112, v142
	v_mul_f32_e32 v113, v113, v142
	s_waitcnt vmcnt(3)
	v_mul_f32_e32 v110, v110, v140
	v_mul_f32_e32 v111, v111, v140
	v_mul_f32_e32 v108, v108, v140
	v_mul_f32_e32 v109, v109, v140
	s_waitcnt vmcnt(2)
	v_mul_f32_e32 v122, v122, v138
	v_mul_f32_e32 v123, v123, v138
	v_mul_f32_e32 v120, v120, v138
	v_mul_f32_e32 v121, v121, v138
	s_waitcnt vmcnt(1)
	v_mul_f32_e32 v118, v118, v136
	v_mul_f32_e32 v119, v119, v136
	v_mul_f32_e32 v116, v116, v136
	v_mul_f32_e32 v117, v117, v136
	s_waitcnt vmcnt(0)
	v_mul_f32_e32 v126, v126, v134
	v_mul_f32_e32 v127, v127, v134
	v_mul_f32_e32 v124, v124, v134
	v_mul_f32_e32 v125, v125, v134
	ds_write2_b32 v6, v18, v19 offset1:1
	ds_write2_b32 v9, v84, v85 offset1:1
	ds_write2_b32 v10, v86, v87 offset1:1
	ds_write2_b32 v11, v72, v73 offset1:1
	ds_write2_b32 v12, v74, v75 offset1:1
	v_add_u32_e32 v13, 0x1c70, v161
	v_add_u32_e32 v14, 0x1c78, v161
	ds_write2_b32 v15, v92, v93 offset1:1
	ds_write2_b32 v16, v94, v95 offset1:1
	v_add_u32_e32 v17, 0x2490, v161
	v_add_u32_e32 v18, 0x2498, v161
	v_add_u32_e32 v19, 0x28a0, v161
	v_add_u32_e32 v72, 0x28a8, v161
	v_add_u32_e32 v73, 0x2cb0, v161
	v_add_u32_e32 v74, 0x2cb8, v161
	v_add_u32_e32 v75, 0x30c0, v161
	v_add_u32_e32 v84, 0x30c8, v161
	v_add_u32_e32 v85, 0x34d0, v161
	v_add_u32_e32 v86, 0x34d8, v161
	v_add_u32_e32 v87, 0x38e0, v161
	v_add_u32_e32 v92, 0x38e8, v161
	v_add_u32_e32 v93, 0x3cf0, v161
	v_add_u32_e32 v94, 0x3cf8, v161
	ds_write2_b32 v13, v96, v97 offset1:1
	ds_write2_b32 v14, v98, v99 offset1:1
	ds_write2_b32 v17, v104, v105 offset1:1
	ds_write2_b32 v18, v106, v107 offset1:1
	ds_write2_b32 v19, v100, v101 offset1:1
	ds_write2_b32 v72, v102, v103 offset1:1
	ds_write2_b32 v73, v112, v113 offset1:1
	ds_write2_b32 v74, v114, v115 offset1:1
	ds_write2_b32 v75, v108, v109 offset1:1
	ds_write2_b32 v84, v110, v111 offset1:1
	ds_write2_b32 v85, v120, v121 offset1:1
	ds_write2_b32 v86, v122, v123 offset1:1
	ds_write2_b32 v87, v116, v117 offset1:1
	ds_write2_b32 v92, v118, v119 offset1:1
	ds_write2_b32 v93, v124, v125 offset1:1
	ds_write2_b32 v94, v126, v127 offset1:1
	v_add_u32_e32 v0, 0x400, v145
	s_sub_i32 s14, 0, s23
	ds_read2_b32 v[102:103], v145 offset0:65 offset1:73
	ds_read2_b32 v[104:105], v145 offset1:8
	ds_read2_b32 v[106:107], v145 offset0:130 offset1:138
	ds_read2_b32 v[108:109], v145 offset0:195 offset1:203
	ds_read2_b32 v[110:111], v0 offset0:4 offset1:12
	ds_read2_b32 v[112:113], v0 offset0:69 offset1:77
	ds_read2_b32 v[114:115], v0 offset0:134 offset1:142
	ds_read2_b32 v[116:117], v0 offset0:199 offset1:207
	s_add_i32 s14, s14, s13
	v_add_u32_e32 v118, s14, v139
	s_ashr_i32 s23, s22, 31
	v_ashrrev_i32_e32 v119, 31, v118
	v_lshl_add_u64 v[100:101], s[22:23], 1, v[132:133]
	v_lshlrev_b64 v[120:121], 12, v[118:119]
	s_waitcnt lgkmcnt(6)
	v_cvt_pk_bf16_f32 v96, v104, v102
	s_waitcnt lgkmcnt(4)
	v_cvt_pk_bf16_f32 v97, v106, v108
	s_waitcnt lgkmcnt(2)
	v_cvt_pk_bf16_f32 v98, v110, v112
	s_waitcnt lgkmcnt(0)
	v_cvt_pk_bf16_f32 v99, v114, v116
	v_lshl_add_u64 v[120:121], v[100:101], 0, v[120:121]
	v_add_u32_e32 v102, 8, v118
	global_store_dwordx4 v[120:121], v[96:99], off
	v_add_u32_e32 v120, 16, v118
	v_ashrrev_i32_e32 v121, 31, v120
	v_cvt_pk_bf16_f32 v96, v105, v103
	v_ashrrev_i32_e32 v103, 31, v102
	v_lshlrev_b64 v[102:103], 12, v[102:103]
	v_cvt_pk_bf16_f32 v97, v107, v109
	v_cvt_pk_bf16_f32 v98, v111, v113
	v_cvt_pk_bf16_f32 v99, v115, v117
	v_lshl_add_u64 v[102:103], v[100:101], 0, v[102:103]
	global_store_dwordx4 v[102:103], v[96:99], off
	ds_read2_b32 v[102:103], v145 offset0:81 offset1:89
	ds_read2_b32 v[104:105], v145 offset0:16 offset1:24
	ds_read2_b32 v[106:107], v145 offset0:146 offset1:154
	ds_read2_b32 v[108:109], v145 offset0:211 offset1:219
	ds_read2_b32 v[110:111], v0 offset0:20 offset1:28
	ds_read2_b32 v[112:113], v0 offset0:85 offset1:93
	ds_read2_b32 v[114:115], v0 offset0:150 offset1:158
	ds_read2_b32 v[116:117], v0 offset0:215 offset1:223
	v_lshlrev_b64 v[120:121], 12, v[120:121]
	s_waitcnt lgkmcnt(6)
	v_cvt_pk_bf16_f32 v96, v104, v102
	s_waitcnt lgkmcnt(4)
	v_cvt_pk_bf16_f32 v97, v106, v108
	s_waitcnt lgkmcnt(2)
	v_cvt_pk_bf16_f32 v98, v110, v112
	s_waitcnt lgkmcnt(0)
	v_cvt_pk_bf16_f32 v99, v114, v116
	v_lshl_add_u64 v[120:121], v[100:101], 0, v[120:121]
	v_add_u32_e32 v102, 24, v118
	global_store_dwordx4 v[120:121], v[96:99], off
	v_add_u32_e32 v120, 32, v118
	v_ashrrev_i32_e32 v121, 31, v120
	v_cvt_pk_bf16_f32 v96, v105, v103
	v_ashrrev_i32_e32 v103, 31, v102
	v_lshlrev_b64 v[102:103], 12, v[102:103]
	v_cvt_pk_bf16_f32 v97, v107, v109
	v_cvt_pk_bf16_f32 v98, v111, v113
	v_cvt_pk_bf16_f32 v99, v115, v117
	v_lshl_add_u64 v[102:103], v[100:101], 0, v[102:103]
	global_store_dwordx4 v[102:103], v[96:99], off
	ds_read2_b32 v[102:103], v145 offset0:32 offset1:40
	ds_read2_b32 v[104:105], v145 offset0:97 offset1:105
	ds_read2_b32 v[106:107], v145 offset0:162 offset1:170
	ds_read2_b32 v[108:109], v145 offset0:227 offset1:235
	ds_read2_b32 v[110:111], v0 offset0:36 offset1:44
	ds_read2_b32 v[112:113], v0 offset0:101 offset1:109
	ds_read2_b32 v[114:115], v0 offset0:166 offset1:174
	ds_read2_b32 v[116:117], v0 offset0:231 offset1:239
	v_lshlrev_b64 v[120:121], 12, v[120:121]
	s_waitcnt lgkmcnt(6)
	v_cvt_pk_bf16_f32 v96, v102, v104
	s_waitcnt lgkmcnt(4)
	v_cvt_pk_bf16_f32 v97, v106, v108
	s_waitcnt lgkmcnt(2)
	v_cvt_pk_bf16_f32 v98, v110, v112
	s_waitcnt lgkmcnt(0)
	v_cvt_pk_bf16_f32 v99, v114, v116
	v_lshl_add_u64 v[120:121], v[100:101], 0, v[120:121]
	v_add_u32_e32 v102, 40, v118
	global_store_dwordx4 v[120:121], v[96:99], off
	v_add_u32_e32 v120, 48, v118
	v_ashrrev_i32_e32 v121, 31, v120
	v_cvt_pk_bf16_f32 v96, v103, v105
	v_ashrrev_i32_e32 v103, 31, v102
	v_lshlrev_b64 v[102:103], 12, v[102:103]
	v_cvt_pk_bf16_f32 v97, v107, v109
	v_cvt_pk_bf16_f32 v98, v111, v113
	v_cvt_pk_bf16_f32 v99, v115, v117
	v_lshl_add_u64 v[102:103], v[100:101], 0, v[102:103]
	global_store_dwordx4 v[102:103], v[96:99], off
	ds_read2_b32 v[102:103], v145 offset0:48 offset1:56
	ds_read2_b32 v[104:105], v145 offset0:113 offset1:121
	ds_read2_b32 v[106:107], v145 offset0:178 offset1:186
	ds_read2_b32 v[108:109], v145 offset0:243 offset1:251
	ds_read2_b32 v[110:111], v0 offset0:52 offset1:60
	ds_read2_b32 v[112:113], v0 offset0:117 offset1:125
	ds_read2_b32 v[114:115], v0 offset0:182 offset1:190
	ds_read2_b32 v[116:117], v0 offset0:247 offset1:255
	v_lshlrev_b64 v[120:121], 12, v[120:121]
	s_waitcnt lgkmcnt(6)
	v_cvt_pk_bf16_f32 v96, v102, v104
	s_waitcnt lgkmcnt(4)
	v_cvt_pk_bf16_f32 v97, v106, v108
	s_waitcnt lgkmcnt(2)
	v_cvt_pk_bf16_f32 v98, v110, v112
	s_waitcnt lgkmcnt(0)
	v_cvt_pk_bf16_f32 v99, v114, v116
	v_lshl_add_u64 v[120:121], v[100:101], 0, v[120:121]
	v_add_u32_e32 v102, 56, v118
	global_store_dwordx4 v[120:121], v[96:99], off
	s_andn2_b64 vcc, exec, s[48:49]
	s_nop 0
	v_cvt_pk_bf16_f32 v96, v103, v105
	v_ashrrev_i32_e32 v103, 31, v102
	v_lshlrev_b64 v[102:103], 12, v[102:103]
	v_cvt_pk_bf16_f32 v97, v107, v109
	v_cvt_pk_bf16_f32 v98, v111, v113
	v_cvt_pk_bf16_f32 v99, v115, v117
	v_lshl_add_u64 v[100:101], v[100:101], 0, v[102:103]
	global_store_dwordx4 v[100:101], v[96:99], off
	s_cbranch_vccnz .LBB0_2250
	s_ashr_i32 s8, s46, 31
	s_lshr_b32 s8, s8, 25
	s_add_i32 s8, s46, s8
	s_ashr_i32 s9, s8, 7
	ds_write2_b32 v161, v20, v21 offset1:1
	ds_write2_b32 v161, v22, v23 offset0:2 offset1:3
	ds_write2_b32 v1, v24, v25 offset1:1
	ds_write2_b32 v2, v26, v27 offset1:1
	ds_write2_b32 v3, v28, v29 offset1:1
	ds_write2_b32 v4, v30, v31 offset1:1
	ds_write2_b32 v5, v32, v33 offset1:1
	ds_write2_b32 v6, v34, v35 offset1:1
	ds_write2_b32 v7, v36, v37 offset1:1
	ds_write2_b32 v8, v38, v39 offset1:1
	ds_write2_b32 v9, v40, v41 offset1:1
	ds_write2_b32 v10, v42, v43 offset1:1
	ds_write2_b32 v11, v44, v45 offset1:1
	ds_write2_b32 v12, v46, v47 offset1:1
	ds_write2_b32 v13, v48, v49 offset1:1
	ds_write2_b32 v14, v50, v51 offset1:1
	ds_write2_b32 v15, v52, v53 offset1:1
	ds_write2_b32 v16, v54, v55 offset1:1
	ds_write2_b32 v17, v56, v57 offset1:1
	ds_write2_b32 v18, v58, v59 offset1:1
	ds_write2_b32 v19, v60, v61 offset1:1
	ds_write2_b32 v72, v62, v63 offset1:1
	ds_write2_b32 v73, v64, v65 offset1:1
	ds_write2_b32 v74, v66, v67 offset1:1
	ds_write2_b32 v75, v68, v69 offset1:1
	ds_write2_b32 v84, v70, v71 offset1:1
	ds_write2_b32 v85, v76, v77 offset1:1
	ds_write2_b32 v86, v78, v79 offset1:1
	ds_write2_b32 v87, v80, v81 offset1:1
	ds_write2_b32 v92, v82, v83 offset1:1
	ds_write2_b32 v93, v88, v89 offset1:1
	ds_write2_b32 v94, v90, v91 offset1:1
	s_and_b32 s8, s8, 0x3ffff80
	s_sub_i32 s8, s46, s8
	ds_read2_b32 v[8:9], v145 offset0:65 offset1:73
	ds_read2_b32 v[10:11], v145 offset1:8
	ds_read2_b32 v[12:13], v145 offset0:130 offset1:138
	ds_read2_b32 v[14:15], v145 offset0:195 offset1:203
	ds_read2_b32 v[16:17], v0 offset0:4 offset1:12
	ds_read2_b32 v[18:19], v0 offset0:69 offset1:77
	ds_read2_b32 v[72:73], v0 offset0:134 offset1:142
	ds_read2_b32 v[74:75], v0 offset0:199 offset1:207
	s_lshl_b32 s8, s8, 6
	s_lshl_b32 s14, s9, 6
	v_add_u32_e32 v84, s8, v139
	s_ashr_i32 s15, s14, 31
	v_ashrrev_i32_e32 v85, 31, v84
	v_lshl_add_u64 v[6:7], s[14:15], 1, v[132:133]
	v_lshlrev_b64 v[84:85], 12, v[84:85]
	s_waitcnt lgkmcnt(6)
	v_cvt_pk_bf16_f32 v2, v10, v8
	s_waitcnt lgkmcnt(4)
	v_cvt_pk_bf16_f32 v3, v12, v14
	s_waitcnt lgkmcnt(2)
	v_cvt_pk_bf16_f32 v4, v16, v18
	s_waitcnt lgkmcnt(0)
	v_cvt_pk_bf16_f32 v5, v72, v74
	v_lshl_add_u64 v[84:85], v[6:7], 0, v[84:85]
	v_add_u32_e32 v8, s8, v147
	global_store_dwordx4 v[84:85], v[2:5], off
	v_add_u32_e32 v84, s8, v149
	v_ashrrev_i32_e32 v85, 31, v84
	v_cvt_pk_bf16_f32 v2, v11, v9
	v_ashrrev_i32_e32 v9, 31, v8
	v_lshlrev_b64 v[8:9], 12, v[8:9]
	v_cvt_pk_bf16_f32 v3, v13, v15
	v_cvt_pk_bf16_f32 v4, v17, v19
	v_cvt_pk_bf16_f32 v5, v73, v75
	v_lshl_add_u64 v[8:9], v[6:7], 0, v[8:9]
	global_store_dwordx4 v[8:9], v[2:5], off
	ds_read2_b32 v[8:9], v145 offset0:16 offset1:24
	ds_read2_b32 v[10:11], v145 offset0:81 offset1:89
	ds_read2_b32 v[12:13], v145 offset0:146 offset1:154
	ds_read2_b32 v[14:15], v145 offset0:211 offset1:219
	ds_read2_b32 v[16:17], v0 offset0:20 offset1:28
	ds_read2_b32 v[18:19], v0 offset0:85 offset1:93
	ds_read2_b32 v[72:73], v0 offset0:150 offset1:158
	ds_read2_b32 v[74:75], v0 offset0:215 offset1:223
	v_lshlrev_b64 v[84:85], 12, v[84:85]
	s_waitcnt lgkmcnt(6)
	v_cvt_pk_bf16_f32 v2, v8, v10
	s_waitcnt lgkmcnt(4)
	v_cvt_pk_bf16_f32 v3, v12, v14
	s_waitcnt lgkmcnt(2)
	v_cvt_pk_bf16_f32 v4, v16, v18
	s_waitcnt lgkmcnt(0)
	v_cvt_pk_bf16_f32 v5, v72, v74
	v_lshl_add_u64 v[84:85], v[6:7], 0, v[84:85]
	v_add_u32_e32 v8, s8, v151
	global_store_dwordx4 v[84:85], v[2:5], off
	v_add_u32_e32 v84, s8, v153
	v_ashrrev_i32_e32 v85, 31, v84
	v_cvt_pk_bf16_f32 v2, v9, v11
	v_ashrrev_i32_e32 v9, 31, v8
	v_lshlrev_b64 v[8:9], 12, v[8:9]
	v_cvt_pk_bf16_f32 v3, v13, v15
	v_cvt_pk_bf16_f32 v4, v17, v19
	v_cvt_pk_bf16_f32 v5, v73, v75
	v_lshl_add_u64 v[8:9], v[6:7], 0, v[8:9]
	global_store_dwordx4 v[8:9], v[2:5], off
	ds_read2_b32 v[8:9], v145 offset0:32 offset1:40
	ds_read2_b32 v[10:11], v145 offset0:97 offset1:105
	ds_read2_b32 v[12:13], v145 offset0:162 offset1:170
	ds_read2_b32 v[14:15], v145 offset0:227 offset1:235
	ds_read2_b32 v[16:17], v0 offset0:36 offset1:44
	ds_read2_b32 v[18:19], v0 offset0:101 offset1:109
	ds_read2_b32 v[72:73], v0 offset0:166 offset1:174
	ds_read2_b32 v[74:75], v0 offset0:231 offset1:239
	v_lshlrev_b64 v[84:85], 12, v[84:85]
	s_waitcnt lgkmcnt(6)
	v_cvt_pk_bf16_f32 v2, v8, v10
	s_waitcnt lgkmcnt(4)
	v_cvt_pk_bf16_f32 v3, v12, v14
	s_waitcnt lgkmcnt(2)
	v_cvt_pk_bf16_f32 v4, v16, v18
	s_waitcnt lgkmcnt(0)
	v_cvt_pk_bf16_f32 v5, v72, v74
	v_lshl_add_u64 v[84:85], v[6:7], 0, v[84:85]
	v_add_u32_e32 v8, s8, v155
	global_store_dwordx4 v[84:85], v[2:5], off
	v_add_u32_e32 v74, s8, v157
	s_nop 0
	v_cvt_pk_bf16_f32 v2, v9, v11
	v_ashrrev_i32_e32 v9, 31, v8
	v_lshlrev_b64 v[8:9], 12, v[8:9]
	v_cvt_pk_bf16_f32 v3, v13, v15
	v_cvt_pk_bf16_f32 v4, v17, v19
	v_cvt_pk_bf16_f32 v5, v73, v75
	v_lshl_add_u64 v[8:9], v[6:7], 0, v[8:9]
	global_store_dwordx4 v[8:9], v[2:5], off
	ds_read2_b32 v[4:5], v145 offset0:48 offset1:56
	ds_read2_b32 v[8:9], v145 offset0:113 offset1:121
	ds_read2_b32 v[10:11], v145 offset0:178 offset1:186
	ds_read2_b32 v[12:13], v145 offset0:243 offset1:251
	ds_read2_b32 v[14:15], v0 offset0:52 offset1:60
	ds_read2_b32 v[16:17], v0 offset0:117 offset1:125
	ds_read2_b32 v[18:19], v0 offset0:182 offset1:190
	ds_read2_b32 v[72:73], v0 offset0:247 offset1:255
	v_ashrrev_i32_e32 v75, 31, v74
	v_lshlrev_b64 v[74:75], 12, v[74:75]
	s_waitcnt lgkmcnt(6)
	v_cvt_pk_bf16_f32 v0, v4, v8
	s_waitcnt lgkmcnt(4)
	v_cvt_pk_bf16_f32 v1, v10, v12
	s_waitcnt lgkmcnt(2)
	v_cvt_pk_bf16_f32 v2, v14, v16
	s_waitcnt lgkmcnt(0)
	v_cvt_pk_bf16_f32 v3, v18, v72
	v_lshl_add_u64 v[74:75], v[6:7], 0, v[74:75]
	v_add_u32_e32 v4, s8, v159
	global_store_dwordx4 v[74:75], v[0:3], off
	s_nop 1
	v_cvt_pk_bf16_f32 v0, v5, v9
	v_ashrrev_i32_e32 v5, 31, v4
	v_lshlrev_b64 v[4:5], 12, v[4:5]
	v_cvt_pk_bf16_f32 v1, v11, v13
	v_cvt_pk_bf16_f32 v2, v15, v17
	v_cvt_pk_bf16_f32 v3, v19, v73
	v_lshl_add_u64 v[4:5], v[6:7], 0, v[4:5]
	global_store_dwordx4 v[4:5], v[0:3], off
	s_branch .LBB0_2250

.LBB0_2462:
	v_lshl_add_u32 v150, s83, 8, v158
	v_ashrrev_i32_e32 v151, 31, v150
	v_mov_b32_e32 v136, 0
	s_and_saveexec_b64 s[16:17], s[6:7]
	s_cbranch_execz .LBB0_2464
	v_lshlrev_b64 v[148:149], 7, v[150:151]
	v_lshl_add_u64 v[148:149], v[138:139], 0, v[148:149]
	global_load_dwordx4 v[152:155], v[148:149], off
	s_waitcnt vmcnt(0)
	v_mov_b32_e32 v148, v153
	v_mov_b32_e32 v149, v154
	v_mov_b32_e32 v153, v155
	v_add_f32_e32 v148, v148, v152
	v_add_f32_e32 v149, v149, v153
	s_nop 0
	v_add_f32_e32 v136, v148, v149
	v_add_f32_e32 v136, 0, v136
.LBB0_2464:
	s_or_b64 exec, exec, s[16:17]
	ds_bpermute_b32 v149, v161, v136
	v_lshl_add_u32 v148, s82, 8, v160
	v_mul_hi_i32 v153, v148, s57
	v_lshrrev_b32_e32 v154, 31, v153
	v_lshlrev_b32_e32 v151, 5, v150
	s_waitcnt lgkmcnt(0)
	v_add_f32_e32 v136, v136, v149
	ds_bpermute_b32 v149, v162, v136
	v_and_b32_e32 v151, 0xf9e0, v151
	s_waitcnt lgkmcnt(0)
	v_add_f32_e32 v136, v136, v149
	v_fmamk_f32 v136, v136, 0x3aaaaaab, v166
	v_rsq_f32_e32 v152, v136
	v_lshrrev_b32_e32 v136, 5, v153
	v_add_u32_e32 v136, v136, v154
	v_mul_lo_u32 v136, v136, s34
	v_mul_f32_e32 v156, v126, v152
	v_mul_f32_e32 v157, v127, v152
	v_mul_f32_e32 v126, v124, v152
	v_mul_f32_e32 v127, v125, v152
	v_mul_f32_e32 v124, v120, v152
	v_mul_f32_e32 v125, v121, v152
	v_sub_u32_e32 v120, v148, v136
	v_cmp_lt_i32_e32 vcc, s78, v120
	v_add_u32_e32 v120, 0xffffff80, v120
	v_mul_f32_e32 v154, v122, v152
	v_mul_f32_e32 v155, v123, v152
	v_lshrrev_b32_e32 v120, 1, v120
	v_lshlrev_b32_e32 v136, 2, v151
	s_and_saveexec_b64 s[16:17], vcc
	s_cbranch_execz .LBB0_2466
	v_mov_b32_e32 v121, v137
	v_lshl_add_u64 v[122:123], s[66:67], 0, v[136:137]
	v_lshlrev_b64 v[168:169], 2, v[120:121]
	v_lshl_add_u64 v[170:171], s[68:69], 0, v[136:137]
	v_lshl_add_u64 v[122:123], v[122:123], 0, v[168:169]
	v_lshl_add_u64 v[172:173], v[170:171], 0, v[168:169]
	global_load_dwordx4 v[168:171], v[122:123], off
	s_nop 0
	global_load_dwordx4 v[172:175], v[172:173], off
	s_waitcnt vmcnt(0)
	v_mul_f32_e32 v122, v126, v168
	v_mul_f32_e32 v123, v127, v169
	v_mul_f32_e32 v176, v127, v172
	v_mul_f32_e32 v177, v126, v172
	v_mul_f32_e32 v184, v125, v174
	v_mul_f32_e32 v185, v124, v174
	v_mov_b32_e32 v172, v169
	v_mul_f32_e32 v178, v157, v173
	v_mul_f32_e32 v180, v157, v169
	v_mul_f32_e32 v182, v124, v170
	v_mul_f32_e32 v183, v125, v171
	v_mov_b32_e32 v174, v171
	v_mul_f32_e32 v186, v155, v175
	v_mul_f32_e32 v188, v155, v171
	v_fma_f32 v126, v126, v168, v176
	v_fma_f32 v127, v127, v168, v177
	v_mov_b32_e32 v168, v173
	v_fma_f32 v124, v124, v170, v184
	v_fma_f32 v125, v125, v170, v185
	v_mov_b32_e32 v170, v175
	v_fma_f32 v179, v157, v173, -v178
	v_fma_f32 v178, v156, v172, -v178
	v_fma_f32 v172, v154, v174, -v186
	v_fma_f32 v173, v155, v175, -v186
	v_fma_f32 v168, v156, v168, v180
	v_fma_f32 v169, v157, v169, v180
	v_fma_f32 v170, v154, v170, v188
	v_fma_f32 v171, v155, v171, v188
	v_sub_f32_e32 v124, v182, v184
	v_sub_f32_e32 v126, v122, v176
	v_mov_b32_e32 v154, v172
	v_mov_b32_e32 v156, v178
	v_mov_b32_e32 v155, v170
	v_mov_b32_e32 v157, v168
.LBB0_2466:
	s_or_b64 exec, exec, s[16:17]
	v_mov_b32_e32 v153, v152
	v_cvt_pk_bf16_f32 v168, v126, v127
	v_mov_b32_e32 v126, v152
	v_mov_b32_e32 v127, v152
	v_cvt_pk_bf16_f32 v170, v124, v125
	v_mul_f32_e32 v124, v118, v126
	v_mul_f32_e32 v125, v119, v127
	v_mul_f32_e32 v118, v114, v126
	v_mul_f32_e32 v119, v115, v127
	v_mul_f32_e32 v114, v112, v152
	v_mul_f32_e32 v115, v113, v153
	v_add_u32_e32 v112, 0x80, v148
	v_mul_hi_i32 v113, v112, s57
	v_lshrrev_b32_e32 v121, 31, v113
	v_lshrrev_b32_e32 v113, 5, v113
	v_add_u32_e32 v113, v113, v121
	v_mov_b64_e32 v[122:123], s[18:19]
	v_mul_lo_u32 v113, v113, s34
	v_mad_i64_i32 v[122:123], s[16:17], v150, s79, v[122:123]
	v_sub_u32_e32 v112, v112, v113
	v_ashrrev_i32_e32 v149, 31, v148
	v_cmp_lt_i32_e64 s[16:17], s78, v112
	v_add_u32_e32 v112, 0xffffff80, v112
	v_lshl_add_u64 v[122:123], v[148:149], 1, v[122:123]
	v_cvt_pk_bf16_f32 v169, v156, v157
	v_cvt_pk_bf16_f32 v171, v154, v155
	v_mul_f32_e32 v116, v116, v152
	v_mul_f32_e32 v117, v117, v153
	v_lshrrev_b32_e32 v112, 1, v112
	global_store_dwordx4 v[122:123], v[168:171], off
	s_and_saveexec_b64 s[70:71], s[16:17]
	s_cbranch_execz .LBB0_2468
	v_mov_b32_e32 v113, v137
	v_lshl_add_u64 v[126:127], s[66:67], 0, v[136:137]
	v_lshlrev_b64 v[152:153], 2, v[112:113]
	v_lshl_add_u64 v[126:127], v[126:127], 0, v[152:153]
	v_lshl_add_u64 v[154:155], s[68:69], 0, v[136:137]
	v_lshl_add_u64 v[156:157], v[154:155], 0, v[152:153]
	global_load_dwordx4 v[152:155], v[126:127], off
	global_load_dwordx4 v[168:171], v[156:157], off
	s_waitcnt vmcnt(0)
	v_mul_f32_e32 v126, v116, v152
	v_mul_f32_e32 v127, v117, v153
	v_mul_f32_e32 v156, v117, v168
	v_mul_f32_e32 v157, v116, v168
	v_mul_f32_e32 v176, v115, v170
	v_mul_f32_e32 v177, v114, v170
	v_mov_b32_e32 v168, v153
	v_mul_f32_e32 v136, v125, v169
	v_mul_f32_e32 v172, v125, v153
	v_mul_f32_e32 v174, v114, v154
	v_mul_f32_e32 v175, v115, v155
	v_mov_b32_e32 v170, v155
	v_mul_f32_e32 v178, v119, v171
	v_mul_f32_e32 v180, v119, v155
	v_fma_f32 v116, v116, v152, v156
	v_fma_f32 v117, v117, v152, v157
	v_mov_b32_e32 v152, v169
	v_fma_f32 v114, v114, v154, v176
	v_fma_f32 v115, v115, v154, v177
	v_mov_b32_e32 v154, v171
	v_fma_f32 v182, v124, v168, -v136
	v_fma_f32 v183, v125, v169, -v136
	v_fma_f32 v168, v118, v170, -v178
	v_fma_f32 v169, v119, v171, -v178
	v_fma_f32 v152, v124, v152, v172
	v_fma_f32 v153, v125, v153, v172
	v_fma_f32 v154, v118, v154, v180
	v_fma_f32 v155, v119, v155, v180
	v_sub_f32_e32 v114, v174, v176
	v_sub_f32_e32 v116, v126, v156
	v_mov_b32_e32 v118, v168
	v_mov_b32_e32 v124, v182
	v_mov_b32_e32 v119, v154
	v_mov_b32_e32 v125, v152
.LBB0_2468:
	s_or_b64 exec, exec, s[70:71]
	v_cvt_pk_bf16_f32 v152, v116, v117
	v_cvt_pk_bf16_f32 v153, v124, v125
	v_cvt_pk_bf16_f32 v154, v114, v115
	v_cvt_pk_bf16_f32 v155, v118, v119
	global_store_dwordx4 v[122:123], v[152:155], off offset:256
	v_or_b32_e32 v114, 16, v150
	v_ashrrev_i32_e32 v115, 31, v114
	v_mov_b32_e32 v113, 0
	s_and_saveexec_b64 s[70:71], s[6:7]
	s_cbranch_execz .LBB0_2470
	v_lshlrev_b64 v[116:117], 7, v[114:115]
	v_lshl_add_u64 v[116:117], v[138:139], 0, v[116:117]
	global_load_dwordx4 v[116:119], v[116:117], off
	s_waitcnt vmcnt(0)
	v_mov_b32_e32 v122, v117
	v_mov_b32_e32 v123, v118
	v_mov_b32_e32 v117, v119
	v_add_f32_e32 v116, v122, v116
	v_add_f32_e32 v117, v123, v117
	s_nop 0
	v_add_f32_e32 v113, v116, v117
	v_add_f32_e32 v113, 0, v113
.LBB0_2470:
	s_or_b64 exec, exec, s[70:71]
	ds_bpermute_b32 v115, v161, v113
	s_waitcnt lgkmcnt(0)
	v_add_f32_e32 v113, v113, v115
	ds_bpermute_b32 v115, v162, v113
	s_waitcnt lgkmcnt(0)
	v_add_f32_e32 v113, v113, v115
	v_fmamk_f32 v113, v113, 0x3aaaaaab, v166
	v_rsq_f32_e32 v116, v113
	v_lshlrev_b32_e32 v113, 5, v114
	v_and_b32_e32 v113, 0xfbe0, v113
	v_lshlrev_b32_e32 v136, 2, v113
	v_mul_f32_e32 v118, v110, v116
	v_mul_f32_e32 v119, v111, v116
	v_mul_f32_e32 v108, v108, v116
	v_mul_f32_e32 v109, v109, v116
	v_mul_f32_e32 v110, v106, v116
	v_mul_f32_e32 v111, v107, v116
	v_mul_f32_e32 v106, v104, v116
	v_mul_f32_e32 v107, v105, v116
	s_and_saveexec_b64 s[70:71], vcc
	s_cbranch_execz .LBB0_2472
	v_mov_b32_e32 v121, v137
	v_lshl_add_u64 v[104:105], s[66:67], 0, v[136:137]
	v_lshlrev_b64 v[122:123], 2, v[120:121]
	v_lshl_add_u64 v[104:105], v[104:105], 0, v[122:123]
	v_lshl_add_u64 v[124:125], s[68:69], 0, v[136:137]
	v_lshl_add_u64 v[126:127], v[124:125], 0, v[122:123]
	global_load_dwordx4 v[122:125], v[104:105], off
	global_load_dwordx4 v[152:155], v[126:127], off
	s_waitcnt vmcnt(0)
	v_mul_f32_e32 v104, v108, v122
	v_mul_f32_e32 v105, v109, v123
	v_mul_f32_e32 v126, v109, v152
	v_mul_f32_e32 v127, v108, v152
	v_mul_f32_e32 v172, v107, v154
	v_mul_f32_e32 v173, v106, v154
	v_mov_b32_e32 v152, v123
	v_mul_f32_e32 v156, v119, v153
	v_mul_f32_e32 v168, v119, v123
	v_mul_f32_e32 v170, v106, v124
	v_mul_f32_e32 v171, v107, v125
	v_mov_b32_e32 v154, v125
	v_mul_f32_e32 v174, v111, v155
	v_mul_f32_e32 v176, v111, v125
	v_fma_f32 v108, v108, v122, v126
	v_fma_f32 v109, v109, v122, v127
	v_mov_b32_e32 v122, v153
	v_fma_f32 v106, v106, v124, v172
	v_fma_f32 v107, v107, v124, v173
	v_mov_b32_e32 v124, v155
	v_fma_f32 v157, v119, v153, -v156
	v_fma_f32 v156, v118, v152, -v156
	v_fma_f32 v152, v110, v154, -v174
	v_fma_f32 v153, v111, v155, -v174
	v_fma_f32 v122, v118, v122, v168
	v_fma_f32 v123, v119, v123, v168
	v_fma_f32 v124, v110, v124, v176
	v_fma_f32 v125, v111, v125, v176
	v_sub_f32_e32 v106, v170, v172
	v_sub_f32_e32 v108, v104, v126
	v_mov_b32_e32 v110, v152
	v_mov_b32_e32 v118, v156
	v_mov_b32_e32 v111, v124
	v_mov_b32_e32 v119, v122
.LBB0_2472:
	s_or_b64 exec, exec, s[70:71]
	v_mov_b64_e32 v[104:105], s[18:19]
	v_mov_b32_e32 v117, v116
	v_mad_i64_i32 v[104:105], s[60:61], v114, s79, v[104:105]
	v_cvt_pk_bf16_f32 v124, v106, v107
	v_mov_b32_e32 v106, v116
	v_mov_b32_e32 v107, v116
	v_lshl_add_u64 v[104:105], v[148:149], 1, v[104:105]
	v_cvt_pk_bf16_f32 v122, v108, v109
	v_cvt_pk_bf16_f32 v123, v118, v119
	v_cvt_pk_bf16_f32 v125, v110, v111
	v_mul_f32_e32 v102, v102, v106
	v_mul_f32_e32 v103, v103, v107
	v_mul_f32_e32 v100, v100, v116
	v_mul_f32_e32 v101, v101, v117
	v_mul_f32_e32 v98, v98, v106
	v_mul_f32_e32 v99, v99, v107
	v_mul_f32_e32 v96, v96, v116
	v_mul_f32_e32 v97, v97, v117
	global_store_dwordx4 v[104:105], v[122:125], off
	s_and_saveexec_b64 s[70:71], s[16:17]
	s_cbranch_execz .LBB0_2474
	v_mov_b32_e32 v113, v137
	v_lshl_add_u64 v[106:107], s[66:67], 0, v[136:137]
	v_lshlrev_b64 v[108:109], 2, v[112:113]
	v_lshl_add_u64 v[106:107], v[106:107], 0, v[108:109]
	v_lshl_add_u64 v[110:111], s[68:69], 0, v[136:137]
	v_lshl_add_u64 v[110:111], v[110:111], 0, v[108:109]
	global_load_dwordx4 v[106:109], v[106:107], off
	s_nop 0
	global_load_dwordx4 v[114:117], v[110:111], off
	s_waitcnt vmcnt(0)
	v_mul_f32_e32 v110, v100, v106
	v_mul_f32_e32 v111, v101, v107
	v_mul_f32_e32 v118, v101, v114
	v_mul_f32_e32 v119, v100, v114
	v_mul_f32_e32 v152, v97, v116
	v_mul_f32_e32 v153, v96, v116
	v_mov_b32_e32 v114, v107
	v_mul_f32_e32 v122, v103, v115
	v_mul_f32_e32 v124, v103, v107
	v_mul_f32_e32 v126, v96, v108
	v_mul_f32_e32 v127, v97, v109
	v_mov_b32_e32 v116, v109
	v_mul_f32_e32 v136, v99, v117
	v_mul_f32_e32 v154, v99, v109
	v_fma_f32 v100, v100, v106, v118
	v_fma_f32 v101, v101, v106, v119
	v_mov_b32_e32 v106, v115
	v_fma_f32 v96, v96, v108, v152
	v_fma_f32 v97, v97, v108, v153
	v_mov_b32_e32 v108, v117
	v_fma_f32 v123, v103, v115, -v122
	v_fma_f32 v122, v102, v114, -v122
	v_fma_f32 v114, v98, v116, -v136
	v_fma_f32 v115, v99, v117, -v136
	v_fma_f32 v106, v102, v106, v124
	v_fma_f32 v107, v103, v107, v124
	v_fma_f32 v108, v98, v108, v154
	v_fma_f32 v109, v99, v109, v154
	v_sub_f32_e32 v96, v126, v152
	v_sub_f32_e32 v100, v110, v118
	v_mov_b32_e32 v98, v114
	v_mov_b32_e32 v102, v122
	v_mov_b32_e32 v99, v108
	v_mov_b32_e32 v103, v106
.LBB0_2474:
	s_or_b64 exec, exec, s[70:71]
	v_cvt_pk_bf16_f32 v100, v100, v101
	v_cvt_pk_bf16_f32 v101, v102, v103
	v_cvt_pk_bf16_f32 v102, v96, v97
	v_cvt_pk_bf16_f32 v103, v98, v99
	global_store_dwordx4 v[104:105], v[100:103], off offset:256
	v_or_b32_e32 v96, 32, v150
	v_ashrrev_i32_e32 v97, 31, v96
	v_mov_b32_e32 v98, 0
	s_and_saveexec_b64 s[70:71], s[6:7]
	s_cbranch_execz .LBB0_2476
	v_lshlrev_b64 v[98:99], 7, v[96:97]
	v_lshl_add_u64 v[98:99], v[138:139], 0, v[98:99]
	global_load_dwordx4 v[98:101], v[98:99], off
	s_waitcnt vmcnt(0)
	v_mov_b32_e32 v102, v99
	v_mov_b32_e32 v103, v100
	v_mov_b32_e32 v99, v101
	v_add_f32_e32 v98, v102, v98
	v_add_f32_e32 v99, v103, v99
	s_nop 0
	v_add_f32_e32 v97, v98, v99
	v_add_f32_e32 v98, 0, v97
.LBB0_2476:
	s_or_b64 exec, exec, s[70:71]
	ds_bpermute_b32 v97, v161, v98
	s_waitcnt lgkmcnt(0)
	v_add_f32_e32 v97, v98, v97
	ds_bpermute_b32 v98, v162, v97
	s_waitcnt lgkmcnt(0)
	v_add_f32_e32 v97, v97, v98
	v_fmamk_f32 v97, v97, 0x3aaaaaab, v166
	v_rsq_f32_e32 v98, v97
	v_lshlrev_b32_e32 v97, 5, v96
	v_and_b32_e32 v97, 0xfde0, v97
	v_lshlrev_b32_e32 v136, 2, v97
	v_mul_f32_e32 v100, v94, v98
	v_mul_f32_e32 v101, v95, v98
	v_mul_f32_e32 v92, v92, v98
	v_mul_f32_e32 v93, v93, v98
	v_mul_f32_e32 v94, v90, v98
	v_mul_f32_e32 v95, v91, v98
	v_mul_f32_e32 v90, v88, v98
	v_mul_f32_e32 v91, v89, v98
	s_and_saveexec_b64 s[70:71], vcc
	s_cbranch_execz .LBB0_2478
	v_mov_b32_e32 v121, v137
	v_lshl_add_u64 v[88:89], s[66:67], 0, v[136:137]
	v_lshlrev_b64 v[102:103], 2, v[120:121]
	v_lshl_add_u64 v[104:105], s[68:69], 0, v[136:137]
	v_lshl_add_u64 v[88:89], v[88:89], 0, v[102:103]
	v_lshl_add_u64 v[106:107], v[104:105], 0, v[102:103]
	global_load_dwordx4 v[102:105], v[88:89], off
	s_nop 0
	global_load_dwordx4 v[106:109], v[106:107], off
	s_waitcnt vmcnt(0)
	v_mul_f32_e32 v88, v92, v102
	v_mul_f32_e32 v89, v93, v103
	v_mul_f32_e32 v110, v93, v106
	v_mul_f32_e32 v111, v92, v106
	v_mul_f32_e32 v122, v91, v108
	v_mul_f32_e32 v123, v90, v108
	v_mov_b32_e32 v106, v103
	v_mul_f32_e32 v114, v101, v107
	v_mul_f32_e32 v116, v101, v103
	v_mul_f32_e32 v118, v90, v104
	v_mul_f32_e32 v119, v91, v105
	v_mov_b32_e32 v108, v105
	v_mul_f32_e32 v124, v95, v109
	v_mul_f32_e32 v126, v95, v105
	v_fma_f32 v92, v92, v102, v110
	v_fma_f32 v93, v93, v102, v111
	v_mov_b32_e32 v102, v107
	v_fma_f32 v90, v90, v104, v122
	v_fma_f32 v91, v91, v104, v123
	v_mov_b32_e32 v104, v109
	v_fma_f32 v115, v101, v107, -v114
	v_fma_f32 v114, v100, v106, -v114
	v_fma_f32 v106, v94, v108, -v124
	v_fma_f32 v107, v95, v109, -v124
	v_fma_f32 v102, v100, v102, v116
	v_fma_f32 v103, v101, v103, v116
	v_fma_f32 v104, v94, v104, v126
	v_fma_f32 v105, v95, v105, v126
	v_sub_f32_e32 v90, v118, v122
	v_sub_f32_e32 v92, v88, v110
	v_mov_b32_e32 v94, v106
	v_mov_b32_e32 v100, v114
	v_mov_b32_e32 v95, v104
	v_mov_b32_e32 v101, v102
.LBB0_2478:
	s_or_b64 exec, exec, s[70:71]
	v_mov_b64_e32 v[88:89], s[18:19]
	v_mov_b32_e32 v99, v98
	v_mad_i64_i32 v[88:89], s[60:61], v96, s79, v[88:89]
	v_cvt_pk_bf16_f32 v104, v90, v91
	v_mov_b32_e32 v90, v98
	v_mov_b32_e32 v91, v98
	v_lshl_add_u64 v[88:89], v[148:149], 1, v[88:89]
	v_cvt_pk_bf16_f32 v102, v92, v93
	v_cvt_pk_bf16_f32 v103, v100, v101
	v_cvt_pk_bf16_f32 v105, v94, v95
	v_mul_f32_e32 v86, v86, v90
	v_mul_f32_e32 v87, v87, v91
	v_mul_f32_e32 v84, v84, v98
	v_mul_f32_e32 v85, v85, v99
	v_mul_f32_e32 v82, v82, v90
	v_mul_f32_e32 v83, v83, v91
	v_mul_f32_e32 v80, v80, v98
	v_mul_f32_e32 v81, v81, v99
	global_store_dwordx4 v[88:89], v[102:105], off
	s_and_saveexec_b64 s[70:71], s[16:17]
	s_cbranch_execz .LBB0_2480
	v_mov_b32_e32 v113, v137
	v_lshl_add_u64 v[90:91], s[66:67], 0, v[136:137]
	v_lshlrev_b64 v[92:93], 2, v[112:113]
	v_lshl_add_u64 v[94:95], s[68:69], 0, v[136:137]
	v_lshl_add_u64 v[90:91], v[90:91], 0, v[92:93]
	v_lshl_add_u64 v[94:95], v[94:95], 0, v[92:93]
	global_load_dwordx4 v[90:93], v[90:91], off
	s_nop 0
	global_load_dwordx4 v[94:97], v[94:95], off
	s_waitcnt vmcnt(0)
	v_mul_f32_e32 v98, v84, v90
	v_mul_f32_e32 v99, v85, v91
	v_mul_f32_e32 v100, v85, v94
	v_mul_f32_e32 v101, v84, v94
	v_mul_f32_e32 v108, v81, v96
	v_mul_f32_e32 v109, v80, v96
	v_mov_b32_e32 v94, v91
	v_mul_f32_e32 v102, v87, v95
	v_mul_f32_e32 v104, v87, v91
	v_mul_f32_e32 v106, v80, v92
	v_mul_f32_e32 v107, v81, v93
	v_mov_b32_e32 v96, v93
	v_mul_f32_e32 v110, v83, v97
	v_mul_f32_e32 v114, v83, v93
	v_fma_f32 v84, v84, v90, v100
	v_fma_f32 v85, v85, v90, v101
	v_mov_b32_e32 v90, v95
	v_fma_f32 v80, v80, v92, v108
	v_fma_f32 v81, v81, v92, v109
	v_mov_b32_e32 v92, v97
	v_fma_f32 v103, v87, v95, -v102
	v_fma_f32 v102, v86, v94, -v102
	v_fma_f32 v94, v82, v96, -v110
	v_fma_f32 v95, v83, v97, -v110
	v_fma_f32 v90, v86, v90, v104
	v_fma_f32 v91, v87, v91, v104
	v_fma_f32 v92, v82, v92, v114
	v_fma_f32 v93, v83, v93, v114
	v_sub_f32_e32 v80, v106, v108
	v_sub_f32_e32 v84, v98, v100
	v_mov_b32_e32 v82, v94
	v_mov_b32_e32 v86, v102
	v_mov_b32_e32 v83, v92
	v_mov_b32_e32 v87, v90
.LBB0_2480:
	s_or_b64 exec, exec, s[70:71]
	v_cvt_pk_bf16_f32 v84, v84, v85
	v_cvt_pk_bf16_f32 v85, v86, v87
	v_cvt_pk_bf16_f32 v86, v80, v81
	v_cvt_pk_bf16_f32 v87, v82, v83
	global_store_dwordx4 v[88:89], v[84:87], off offset:256
	v_or_b32_e32 v80, 48, v150
	v_ashrrev_i32_e32 v81, 31, v80
	v_mov_b32_e32 v82, 0
	s_and_saveexec_b64 s[70:71], s[6:7]
	s_cbranch_execz .LBB0_2482
	v_lshlrev_b64 v[82:83], 7, v[80:81]
	v_lshl_add_u64 v[82:83], v[138:139], 0, v[82:83]
	global_load_dwordx4 v[82:85], v[82:83], off
	s_waitcnt vmcnt(0)
	v_mov_b32_e32 v86, v83
	v_mov_b32_e32 v87, v84
	v_mov_b32_e32 v83, v85
	v_add_f32_e32 v82, v86, v82
	v_add_f32_e32 v83, v87, v83
	s_nop 0
	v_add_f32_e32 v81, v82, v83
	v_add_f32_e32 v82, 0, v81
.LBB0_2482:
	s_or_b64 exec, exec, s[70:71]
	ds_bpermute_b32 v81, v161, v82
	s_waitcnt lgkmcnt(0)
	v_add_f32_e32 v81, v82, v81
	ds_bpermute_b32 v82, v162, v81
	s_waitcnt lgkmcnt(0)
	v_add_f32_e32 v81, v81, v82
	v_fmamk_f32 v81, v81, 0x3aaaaaab, v166
	v_rsq_f32_e32 v82, v81
	v_lshlrev_b32_e32 v81, 5, v80
	v_and_b32_e32 v81, 0xffe0, v81
	v_lshlrev_b32_e32 v136, 2, v81
	v_mul_f32_e32 v84, v78, v82
	v_mul_f32_e32 v85, v79, v82
	v_mul_f32_e32 v76, v76, v82
	v_mul_f32_e32 v77, v77, v82
	v_mul_f32_e32 v78, v74, v82
	v_mul_f32_e32 v79, v75, v82
	v_mul_f32_e32 v74, v72, v82
	v_mul_f32_e32 v75, v73, v82
	s_and_saveexec_b64 s[70:71], vcc
	s_cbranch_execz .LBB0_2484
	v_mov_b32_e32 v121, v137
	v_lshl_add_u64 v[72:73], s[66:67], 0, v[136:137]
	v_lshlrev_b64 v[86:87], 2, v[120:121]
	v_lshl_add_u64 v[88:89], s[68:69], 0, v[136:137]
	v_lshl_add_u64 v[72:73], v[72:73], 0, v[86:87]
	v_lshl_add_u64 v[90:91], v[88:89], 0, v[86:87]
	global_load_dwordx4 v[86:89], v[72:73], off
	s_nop 0
	global_load_dwordx4 v[90:93], v[90:91], off
	s_waitcnt vmcnt(0)
	v_mul_f32_e32 v72, v76, v86
	v_mul_f32_e32 v73, v77, v87
	v_mul_f32_e32 v94, v77, v90
	v_mul_f32_e32 v95, v76, v90
	v_mul_f32_e32 v102, v75, v92
	v_mul_f32_e32 v103, v74, v92
	v_mov_b32_e32 v90, v87
	v_mul_f32_e32 v96, v85, v91
	v_mul_f32_e32 v98, v85, v87
	v_mul_f32_e32 v100, v74, v88
	v_mul_f32_e32 v101, v75, v89
	v_mov_b32_e32 v92, v89
	v_mul_f32_e32 v104, v79, v93
	v_mul_f32_e32 v106, v79, v89
	v_fma_f32 v76, v76, v86, v94
	v_fma_f32 v77, v77, v86, v95
	v_mov_b32_e32 v86, v91
	v_fma_f32 v74, v74, v88, v102
	v_fma_f32 v75, v75, v88, v103
	v_mov_b32_e32 v88, v93
	v_fma_f32 v97, v85, v91, -v96
	v_fma_f32 v96, v84, v90, -v96
	v_fma_f32 v90, v78, v92, -v104
	v_fma_f32 v91, v79, v93, -v104
	v_fma_f32 v86, v84, v86, v98
	v_fma_f32 v87, v85, v87, v98
	v_fma_f32 v88, v78, v88, v106
	v_fma_f32 v89, v79, v89, v106
	v_sub_f32_e32 v74, v100, v102
	v_sub_f32_e32 v76, v72, v94
	v_mov_b32_e32 v78, v90
	v_mov_b32_e32 v84, v96
	v_mov_b32_e32 v79, v88
	v_mov_b32_e32 v85, v86
.LBB0_2484:
	s_or_b64 exec, exec, s[70:71]
	v_mov_b64_e32 v[72:73], s[18:19]
	v_mov_b32_e32 v83, v82
	v_mad_i64_i32 v[72:73], s[60:61], v80, s79, v[72:73]
	v_cvt_pk_bf16_f32 v88, v74, v75
	v_mov_b32_e32 v74, v82
	v_mov_b32_e32 v75, v82
	v_lshl_add_u64 v[72:73], v[148:149], 1, v[72:73]
	v_cvt_pk_bf16_f32 v86, v76, v77
	v_cvt_pk_bf16_f32 v87, v84, v85
	v_cvt_pk_bf16_f32 v89, v78, v79
	v_mul_f32_e32 v70, v70, v74
	v_mul_f32_e32 v71, v71, v75
	v_mul_f32_e32 v68, v68, v82
	v_mul_f32_e32 v69, v69, v83
	v_mul_f32_e32 v66, v66, v74
	v_mul_f32_e32 v67, v67, v75
	v_mul_f32_e32 v64, v64, v82
	v_mul_f32_e32 v65, v65, v83
	global_store_dwordx4 v[72:73], v[86:89], off
	s_and_saveexec_b64 s[70:71], s[16:17]
	s_cbranch_execz .LBB0_2486
	v_mov_b32_e32 v113, v137
	v_lshl_add_u64 v[74:75], s[66:67], 0, v[136:137]
	v_lshlrev_b64 v[76:77], 2, v[112:113]
	v_lshl_add_u64 v[78:79], s[68:69], 0, v[136:137]
	v_lshl_add_u64 v[74:75], v[74:75], 0, v[76:77]
	v_lshl_add_u64 v[78:79], v[78:79], 0, v[76:77]
	global_load_dwordx4 v[74:77], v[74:75], off
	s_nop 0
	global_load_dwordx4 v[78:81], v[78:79], off
	s_waitcnt vmcnt(0)
	v_mul_f32_e32 v82, v68, v74
	v_mul_f32_e32 v83, v69, v75
	v_mul_f32_e32 v84, v69, v78
	v_mul_f32_e32 v85, v68, v78
	v_mul_f32_e32 v92, v65, v80
	v_mul_f32_e32 v93, v64, v80
	v_mov_b32_e32 v78, v75
	v_mul_f32_e32 v86, v71, v79
	v_mul_f32_e32 v88, v71, v75
	v_mul_f32_e32 v90, v64, v76
	v_mul_f32_e32 v91, v65, v77
	v_mov_b32_e32 v80, v77
	v_mul_f32_e32 v94, v67, v81
	v_mul_f32_e32 v96, v67, v77
	v_fma_f32 v68, v68, v74, v84
	v_fma_f32 v69, v69, v74, v85
	v_mov_b32_e32 v74, v79
	v_fma_f32 v64, v64, v76, v92
	v_fma_f32 v65, v65, v76, v93
	v_mov_b32_e32 v76, v81
	v_fma_f32 v87, v71, v79, -v86
	v_fma_f32 v86, v70, v78, -v86
	v_fma_f32 v78, v66, v80, -v94
	v_fma_f32 v79, v67, v81, -v94
	v_fma_f32 v74, v70, v74, v88
	v_fma_f32 v75, v71, v75, v88
	v_fma_f32 v76, v66, v76, v96
	v_fma_f32 v77, v67, v77, v96
	v_sub_f32_e32 v64, v90, v92
	v_sub_f32_e32 v68, v82, v84
	v_mov_b32_e32 v66, v78
	v_mov_b32_e32 v70, v86
	v_mov_b32_e32 v67, v76
	v_mov_b32_e32 v71, v74
.LBB0_2486:
	s_or_b64 exec, exec, s[70:71]
	v_cvt_pk_bf16_f32 v68, v68, v69
	v_cvt_pk_bf16_f32 v69, v70, v71
	v_cvt_pk_bf16_f32 v70, v64, v65
	v_cvt_pk_bf16_f32 v71, v66, v67
	global_store_dwordx4 v[72:73], v[68:71], off offset:256
	v_add_u32_e32 v64, 0x80, v150
	v_ashrrev_i32_e32 v65, 31, v64
	v_mov_b32_e32 v66, 0
	s_and_saveexec_b64 s[70:71], s[6:7]
	s_cbranch_execz .LBB0_2488
	v_lshlrev_b64 v[66:67], 7, v[64:65]
	v_lshl_add_u64 v[66:67], v[138:139], 0, v[66:67]
	global_load_dwordx4 v[66:69], v[66:67], off
	s_waitcnt vmcnt(0)
	v_mov_b32_e32 v70, v67
	v_mov_b32_e32 v71, v68
	v_mov_b32_e32 v67, v69
	v_add_f32_e32 v66, v70, v66
	v_add_f32_e32 v67, v71, v67
	s_nop 0
	v_add_f32_e32 v65, v66, v67
	v_add_f32_e32 v66, 0, v65
.LBB0_2488:
	s_or_b64 exec, exec, s[70:71]
	ds_bpermute_b32 v65, v161, v66
	s_waitcnt lgkmcnt(0)
	v_add_f32_e32 v65, v66, v65
	ds_bpermute_b32 v66, v162, v65
	s_waitcnt lgkmcnt(0)
	v_add_f32_e32 v65, v65, v66
	v_fmamk_f32 v65, v65, 0x3aaaaaab, v166
	v_rsq_f32_e32 v66, v65
	v_lshlrev_b32_e32 v65, 5, v64
	v_and_b32_e32 v65, 0xf9e0, v65
	v_lshlrev_b32_e32 v136, 2, v65
	v_mul_f32_e32 v68, v62, v66
	v_mul_f32_e32 v69, v63, v66
	v_mul_f32_e32 v60, v60, v66
	v_mul_f32_e32 v61, v61, v66
	v_mul_f32_e32 v62, v58, v66
	v_mul_f32_e32 v63, v59, v66
	v_mul_f32_e32 v58, v56, v66
	v_mul_f32_e32 v59, v57, v66
	s_and_saveexec_b64 s[70:71], vcc
	s_cbranch_execz .LBB0_2490
	v_mov_b32_e32 v121, v137
	v_lshl_add_u64 v[56:57], s[66:67], 0, v[136:137]
	v_lshlrev_b64 v[70:71], 2, v[120:121]
	v_lshl_add_u64 v[72:73], s[68:69], 0, v[136:137]
	v_lshl_add_u64 v[56:57], v[56:57], 0, v[70:71]
	v_lshl_add_u64 v[74:75], v[72:73], 0, v[70:71]
	global_load_dwordx4 v[70:73], v[56:57], off
	s_nop 0
	global_load_dwordx4 v[74:77], v[74:75], off
	s_waitcnt vmcnt(0)
	v_mul_f32_e32 v56, v60, v70
	v_mul_f32_e32 v57, v61, v71
	v_mul_f32_e32 v78, v61, v74
	v_mul_f32_e32 v79, v60, v74
	v_mul_f32_e32 v86, v59, v76
	v_mul_f32_e32 v87, v58, v76
	v_mov_b32_e32 v74, v71
	v_mul_f32_e32 v80, v69, v75
	v_mul_f32_e32 v82, v69, v71
	v_mul_f32_e32 v84, v58, v72
	v_mul_f32_e32 v85, v59, v73
	v_mov_b32_e32 v76, v73
	v_mul_f32_e32 v88, v63, v77
	v_mul_f32_e32 v90, v63, v73
	v_fma_f32 v60, v60, v70, v78
	v_fma_f32 v61, v61, v70, v79
	v_mov_b32_e32 v70, v75
	v_fma_f32 v58, v58, v72, v86
	v_fma_f32 v59, v59, v72, v87
	v_mov_b32_e32 v72, v77
	v_fma_f32 v81, v69, v75, -v80
	v_fma_f32 v80, v68, v74, -v80
	v_fma_f32 v74, v62, v76, -v88
	v_fma_f32 v75, v63, v77, -v88
	v_fma_f32 v70, v68, v70, v82
	v_fma_f32 v71, v69, v71, v82
	v_fma_f32 v72, v62, v72, v90
	v_fma_f32 v73, v63, v73, v90
	v_sub_f32_e32 v58, v84, v86
	v_sub_f32_e32 v60, v56, v78
	v_mov_b32_e32 v62, v74
	v_mov_b32_e32 v68, v80
	v_mov_b32_e32 v63, v72
	v_mov_b32_e32 v69, v70
.LBB0_2490:
	s_or_b64 exec, exec, s[70:71]
	v_mov_b64_e32 v[56:57], s[18:19]
	v_mov_b32_e32 v67, v66
	v_mad_i64_i32 v[56:57], s[60:61], v64, s79, v[56:57]
	v_cvt_pk_bf16_f32 v72, v58, v59
	v_mov_b32_e32 v58, v66
	v_mov_b32_e32 v59, v66
	v_lshl_add_u64 v[56:57], v[148:149], 1, v[56:57]
	v_cvt_pk_bf16_f32 v70, v60, v61
	v_cvt_pk_bf16_f32 v71, v68, v69
	v_cvt_pk_bf16_f32 v73, v62, v63
	v_mul_f32_e32 v54, v54, v58
	v_mul_f32_e32 v55, v55, v59
	v_mul_f32_e32 v52, v52, v66
	v_mul_f32_e32 v53, v53, v67
	v_mul_f32_e32 v50, v50, v58
	v_mul_f32_e32 v51, v51, v59
	v_mul_f32_e32 v48, v48, v66
	v_mul_f32_e32 v49, v49, v67
	global_store_dwordx4 v[56:57], v[70:73], off
	s_and_saveexec_b64 s[70:71], s[16:17]
	s_cbranch_execz .LBB0_2492
	v_mov_b32_e32 v113, v137
	v_lshl_add_u64 v[58:59], s[66:67], 0, v[136:137]
	v_lshlrev_b64 v[60:61], 2, v[112:113]
	v_lshl_add_u64 v[62:63], s[68:69], 0, v[136:137]
	v_lshl_add_u64 v[58:59], v[58:59], 0, v[60:61]
	v_lshl_add_u64 v[62:63], v[62:63], 0, v[60:61]
	global_load_dwordx4 v[58:61], v[58:59], off
	s_nop 0
	global_load_dwordx4 v[62:65], v[62:63], off
	s_waitcnt vmcnt(0)
	v_mul_f32_e32 v66, v52, v58
	v_mul_f32_e32 v67, v53, v59
	v_mul_f32_e32 v68, v53, v62
	v_mul_f32_e32 v69, v52, v62
	v_mul_f32_e32 v76, v49, v64
	v_mul_f32_e32 v77, v48, v64
	v_mov_b32_e32 v62, v59
	v_mul_f32_e32 v70, v55, v63
	v_mul_f32_e32 v72, v55, v59
	v_mul_f32_e32 v74, v48, v60
	v_mul_f32_e32 v75, v49, v61
	v_mov_b32_e32 v64, v61
	v_mul_f32_e32 v78, v51, v65
	v_mul_f32_e32 v80, v51, v61
	v_fma_f32 v52, v52, v58, v68
	v_fma_f32 v53, v53, v58, v69
	v_mov_b32_e32 v58, v63
	v_fma_f32 v48, v48, v60, v76
	v_fma_f32 v49, v49, v60, v77
	v_mov_b32_e32 v60, v65
	v_fma_f32 v71, v55, v63, -v70
	v_fma_f32 v70, v54, v62, -v70
	v_fma_f32 v62, v50, v64, -v78
	v_fma_f32 v63, v51, v65, -v78
	v_fma_f32 v58, v54, v58, v72
	v_fma_f32 v59, v55, v59, v72
	v_fma_f32 v60, v50, v60, v80
	v_fma_f32 v61, v51, v61, v80
	v_sub_f32_e32 v48, v74, v76
	v_sub_f32_e32 v52, v66, v68
	v_mov_b32_e32 v50, v62
	v_mov_b32_e32 v54, v70
	v_mov_b32_e32 v51, v60
	v_mov_b32_e32 v55, v58
.LBB0_2492:
	s_or_b64 exec, exec, s[70:71]
	v_cvt_pk_bf16_f32 v52, v52, v53
	v_cvt_pk_bf16_f32 v53, v54, v55
	v_cvt_pk_bf16_f32 v54, v48, v49
	v_cvt_pk_bf16_f32 v55, v50, v51
	global_store_dwordx4 v[56:57], v[52:55], off offset:256
	v_add_u32_e32 v48, 0x90, v150
	v_ashrrev_i32_e32 v49, 31, v48
	v_mov_b32_e32 v50, 0
	s_and_saveexec_b64 s[70:71], s[6:7]
	s_cbranch_execz .LBB0_2494
	v_lshlrev_b64 v[50:51], 7, v[48:49]
	v_lshl_add_u64 v[50:51], v[138:139], 0, v[50:51]
	global_load_dwordx4 v[50:53], v[50:51], off
	s_waitcnt vmcnt(0)
	v_mov_b32_e32 v54, v51
	v_mov_b32_e32 v55, v52
	v_mov_b32_e32 v51, v53
	v_add_f32_e32 v50, v54, v50
	v_add_f32_e32 v51, v55, v51
	s_nop 0
	v_add_f32_e32 v49, v50, v51
	v_add_f32_e32 v50, 0, v49
.LBB0_2494:
	s_or_b64 exec, exec, s[70:71]
	ds_bpermute_b32 v49, v161, v50
	s_waitcnt lgkmcnt(0)
	v_add_f32_e32 v49, v50, v49
	ds_bpermute_b32 v50, v162, v49
	s_waitcnt lgkmcnt(0)
	v_add_f32_e32 v49, v49, v50
	v_fmamk_f32 v49, v49, 0x3aaaaaab, v166
	v_rsq_f32_e32 v50, v49
	v_lshlrev_b32_e32 v49, 5, v48
	v_and_b32_e32 v49, 0xfbe0, v49
	v_lshlrev_b32_e32 v136, 2, v49
	v_mul_f32_e32 v52, v46, v50
	v_mul_f32_e32 v53, v47, v50
	v_mul_f32_e32 v44, v44, v50
	v_mul_f32_e32 v45, v45, v50
	v_mul_f32_e32 v46, v42, v50
	v_mul_f32_e32 v47, v43, v50
	v_mul_f32_e32 v42, v40, v50
	v_mul_f32_e32 v43, v41, v50
	s_and_saveexec_b64 s[70:71], vcc
	s_cbranch_execz .LBB0_2496
	v_mov_b32_e32 v121, v137
	v_lshl_add_u64 v[40:41], s[66:67], 0, v[136:137]
	v_lshlrev_b64 v[54:55], 2, v[120:121]
	v_lshl_add_u64 v[56:57], s[68:69], 0, v[136:137]
	v_lshl_add_u64 v[40:41], v[40:41], 0, v[54:55]
	v_lshl_add_u64 v[58:59], v[56:57], 0, v[54:55]
	global_load_dwordx4 v[54:57], v[40:41], off
	s_nop 0
	global_load_dwordx4 v[58:61], v[58:59], off
	s_waitcnt vmcnt(0)
	v_mul_f32_e32 v40, v44, v54
	v_mul_f32_e32 v41, v45, v55
	v_mul_f32_e32 v62, v45, v58
	v_mul_f32_e32 v63, v44, v58
	v_mul_f32_e32 v70, v43, v60
	v_mul_f32_e32 v71, v42, v60
	v_mov_b32_e32 v58, v55
	v_mul_f32_e32 v64, v53, v59
	v_mul_f32_e32 v66, v53, v55
	v_mul_f32_e32 v68, v42, v56
	v_mul_f32_e32 v69, v43, v57
	v_mov_b32_e32 v60, v57
	v_mul_f32_e32 v72, v47, v61
	v_mul_f32_e32 v74, v47, v57
	v_fma_f32 v44, v44, v54, v62
	v_fma_f32 v45, v45, v54, v63
	v_mov_b32_e32 v54, v59
	v_fma_f32 v42, v42, v56, v70
	v_fma_f32 v43, v43, v56, v71
	v_mov_b32_e32 v56, v61
	v_fma_f32 v65, v53, v59, -v64
	v_fma_f32 v64, v52, v58, -v64
	v_fma_f32 v58, v46, v60, -v72
	v_fma_f32 v59, v47, v61, -v72
	v_fma_f32 v54, v52, v54, v66
	v_fma_f32 v55, v53, v55, v66
	v_fma_f32 v56, v46, v56, v74
	v_fma_f32 v57, v47, v57, v74
	v_sub_f32_e32 v42, v68, v70
	v_sub_f32_e32 v44, v40, v62
	v_mov_b32_e32 v46, v58
	v_mov_b32_e32 v52, v64
	v_mov_b32_e32 v47, v56
	v_mov_b32_e32 v53, v54
.LBB0_2496:
	s_or_b64 exec, exec, s[70:71]
	v_mov_b64_e32 v[40:41], s[18:19]
	v_mov_b32_e32 v51, v50
	v_mad_i64_i32 v[40:41], s[60:61], v48, s79, v[40:41]
	v_cvt_pk_bf16_f32 v56, v42, v43
	v_mov_b32_e32 v42, v50
	v_mov_b32_e32 v43, v50
	v_lshl_add_u64 v[40:41], v[148:149], 1, v[40:41]
	v_cvt_pk_bf16_f32 v54, v44, v45
	v_cvt_pk_bf16_f32 v55, v52, v53
	v_cvt_pk_bf16_f32 v57, v46, v47
	v_mul_f32_e32 v38, v38, v42
	v_mul_f32_e32 v39, v39, v43
	v_mul_f32_e32 v36, v36, v50
	v_mul_f32_e32 v37, v37, v51
	v_mul_f32_e32 v34, v34, v42
	v_mul_f32_e32 v35, v35, v43
	v_mul_f32_e32 v32, v32, v50
	v_mul_f32_e32 v33, v33, v51
	global_store_dwordx4 v[40:41], v[54:57], off
	s_and_saveexec_b64 s[70:71], s[16:17]
	s_cbranch_execz .LBB0_2498
	v_mov_b32_e32 v113, v137
	v_lshl_add_u64 v[42:43], s[66:67], 0, v[136:137]
	v_lshlrev_b64 v[44:45], 2, v[112:113]
	v_lshl_add_u64 v[46:47], s[68:69], 0, v[136:137]
	v_lshl_add_u64 v[42:43], v[42:43], 0, v[44:45]
	v_lshl_add_u64 v[46:47], v[46:47], 0, v[44:45]
	global_load_dwordx4 v[42:45], v[42:43], off
	s_nop 0
	global_load_dwordx4 v[46:49], v[46:47], off
	s_waitcnt vmcnt(0)
	v_mul_f32_e32 v50, v36, v42
	v_mul_f32_e32 v51, v37, v43
	v_mul_f32_e32 v52, v37, v46
	v_mul_f32_e32 v53, v36, v46
	v_mul_f32_e32 v60, v33, v48
	v_mul_f32_e32 v61, v32, v48
	v_mov_b32_e32 v46, v43
	v_mul_f32_e32 v54, v39, v47
	v_mul_f32_e32 v56, v39, v43
	v_mul_f32_e32 v58, v32, v44
	v_mul_f32_e32 v59, v33, v45
	v_mov_b32_e32 v48, v45
	v_mul_f32_e32 v62, v35, v49
	v_mul_f32_e32 v64, v35, v45
	v_fma_f32 v36, v36, v42, v52
	v_fma_f32 v37, v37, v42, v53
	v_mov_b32_e32 v42, v47
	v_fma_f32 v32, v32, v44, v60
	v_fma_f32 v33, v33, v44, v61
	v_mov_b32_e32 v44, v49
	v_fma_f32 v55, v39, v47, -v54
	v_fma_f32 v54, v38, v46, -v54
	v_fma_f32 v46, v34, v48, -v62
	v_fma_f32 v47, v35, v49, -v62
	v_fma_f32 v42, v38, v42, v56
	v_fma_f32 v43, v39, v43, v56
	v_fma_f32 v44, v34, v44, v64
	v_fma_f32 v45, v35, v45, v64
	v_sub_f32_e32 v32, v58, v60
	v_sub_f32_e32 v36, v50, v52
	v_mov_b32_e32 v34, v46
	v_mov_b32_e32 v38, v54
	v_mov_b32_e32 v35, v44
	v_mov_b32_e32 v39, v42
.LBB0_2498:
	s_or_b64 exec, exec, s[70:71]
	v_cvt_pk_bf16_f32 v36, v36, v37
	v_cvt_pk_bf16_f32 v37, v38, v39
	v_cvt_pk_bf16_f32 v38, v32, v33
	v_cvt_pk_bf16_f32 v39, v34, v35
	global_store_dwordx4 v[40:41], v[36:39], off offset:256
	v_add_u32_e32 v32, 0xa0, v150
	v_ashrrev_i32_e32 v33, 31, v32
	v_mov_b32_e32 v34, 0
	s_and_saveexec_b64 s[70:71], s[6:7]
	s_cbranch_execz .LBB0_2500
	v_lshlrev_b64 v[34:35], 7, v[32:33]
	v_lshl_add_u64 v[34:35], v[138:139], 0, v[34:35]
	global_load_dwordx4 v[34:37], v[34:35], off
	s_waitcnt vmcnt(0)
	v_mov_b32_e32 v38, v35
	v_mov_b32_e32 v39, v36
	v_mov_b32_e32 v35, v37
	v_add_f32_e32 v34, v38, v34
	v_add_f32_e32 v35, v39, v35
	s_nop 0
	v_add_f32_e32 v33, v34, v35
	v_add_f32_e32 v34, 0, v33
.LBB0_2500:
	s_or_b64 exec, exec, s[70:71]
	ds_bpermute_b32 v33, v161, v34
	s_waitcnt lgkmcnt(0)
	v_add_f32_e32 v33, v34, v33
	ds_bpermute_b32 v34, v162, v33
	s_waitcnt lgkmcnt(0)
	v_add_f32_e32 v33, v33, v34
	v_fmamk_f32 v33, v33, 0x3aaaaaab, v166
	v_rsq_f32_e32 v34, v33
	v_lshlrev_b32_e32 v33, 5, v32
	v_and_b32_e32 v33, 0xfde0, v33
	v_lshlrev_b32_e32 v136, 2, v33
	v_mul_f32_e32 v36, v30, v34
	v_mul_f32_e32 v37, v31, v34
	v_mul_f32_e32 v28, v28, v34
	v_mul_f32_e32 v29, v29, v34
	v_mul_f32_e32 v30, v26, v34
	v_mul_f32_e32 v31, v27, v34
	v_mul_f32_e32 v26, v24, v34
	v_mul_f32_e32 v27, v25, v34
	s_and_saveexec_b64 s[70:71], vcc
	s_cbranch_execz .LBB0_2502
	v_mov_b32_e32 v121, v137
	v_lshl_add_u64 v[24:25], s[66:67], 0, v[136:137]
	v_lshlrev_b64 v[38:39], 2, v[120:121]
	v_lshl_add_u64 v[40:41], s[68:69], 0, v[136:137]
	v_lshl_add_u64 v[24:25], v[24:25], 0, v[38:39]
	v_lshl_add_u64 v[42:43], v[40:41], 0, v[38:39]
	global_load_dwordx4 v[38:41], v[24:25], off
	s_nop 0
	global_load_dwordx4 v[42:45], v[42:43], off
	s_waitcnt vmcnt(0)
	v_mul_f32_e32 v24, v28, v38
	v_mul_f32_e32 v25, v29, v39
	v_mul_f32_e32 v46, v29, v42
	v_mul_f32_e32 v47, v28, v42
	v_mul_f32_e32 v54, v27, v44
	v_mul_f32_e32 v55, v26, v44
	v_mov_b32_e32 v42, v39
	v_mul_f32_e32 v48, v37, v43
	v_mul_f32_e32 v50, v37, v39
	v_mul_f32_e32 v52, v26, v40
	v_mul_f32_e32 v53, v27, v41
	v_mov_b32_e32 v44, v41
	v_mul_f32_e32 v56, v31, v45
	v_mul_f32_e32 v58, v31, v41
	v_fma_f32 v28, v28, v38, v46
	v_fma_f32 v29, v29, v38, v47
	v_mov_b32_e32 v38, v43
	v_fma_f32 v26, v26, v40, v54
	v_fma_f32 v27, v27, v40, v55
	v_mov_b32_e32 v40, v45
	v_fma_f32 v49, v37, v43, -v48
	v_fma_f32 v48, v36, v42, -v48
	v_fma_f32 v42, v30, v44, -v56
	v_fma_f32 v43, v31, v45, -v56
	v_fma_f32 v38, v36, v38, v50
	v_fma_f32 v39, v37, v39, v50
	v_fma_f32 v40, v30, v40, v58
	v_fma_f32 v41, v31, v41, v58
	v_sub_f32_e32 v26, v52, v54
	v_sub_f32_e32 v28, v24, v46
	v_mov_b32_e32 v30, v42
	v_mov_b32_e32 v36, v48
	v_mov_b32_e32 v31, v40
	v_mov_b32_e32 v37, v38
.LBB0_2502:
	s_or_b64 exec, exec, s[70:71]
	v_mov_b64_e32 v[24:25], s[18:19]
	v_mov_b32_e32 v35, v34
	v_mad_i64_i32 v[24:25], s[60:61], v32, s79, v[24:25]
	v_cvt_pk_bf16_f32 v40, v26, v27
	v_mov_b32_e32 v26, v34
	v_mov_b32_e32 v27, v34
	v_lshl_add_u64 v[24:25], v[148:149], 1, v[24:25]
	v_cvt_pk_bf16_f32 v38, v28, v29
	v_cvt_pk_bf16_f32 v39, v36, v37
	v_cvt_pk_bf16_f32 v41, v30, v31
	v_mul_f32_e32 v22, v22, v26
	v_mul_f32_e32 v23, v23, v27
	v_mul_f32_e32 v20, v20, v34
	v_mul_f32_e32 v21, v21, v35
	v_mul_f32_e32 v18, v18, v26
	v_mul_f32_e32 v19, v19, v27
	v_mul_f32_e32 v16, v16, v34
	v_mul_f32_e32 v17, v17, v35
	global_store_dwordx4 v[24:25], v[38:41], off
	s_and_saveexec_b64 s[70:71], s[16:17]
	s_cbranch_execz .LBB0_2504
	v_mov_b32_e32 v113, v137
	v_lshl_add_u64 v[26:27], s[66:67], 0, v[136:137]
	v_lshlrev_b64 v[28:29], 2, v[112:113]
	v_lshl_add_u64 v[30:31], s[68:69], 0, v[136:137]
	v_lshl_add_u64 v[26:27], v[26:27], 0, v[28:29]
	v_lshl_add_u64 v[30:31], v[30:31], 0, v[28:29]
	global_load_dwordx4 v[26:29], v[26:27], off
	s_nop 0
	global_load_dwordx4 v[30:33], v[30:31], off
	s_waitcnt vmcnt(0)
	v_mul_f32_e32 v34, v20, v26
	v_mul_f32_e32 v35, v21, v27
	v_mul_f32_e32 v36, v21, v30
	v_mul_f32_e32 v37, v20, v30
	v_mul_f32_e32 v44, v17, v32
	v_mul_f32_e32 v45, v16, v32
	v_mov_b32_e32 v30, v27
	v_mul_f32_e32 v38, v23, v31
	v_mul_f32_e32 v40, v23, v27
	v_mul_f32_e32 v42, v16, v28
	v_mul_f32_e32 v43, v17, v29
	v_mov_b32_e32 v32, v29
	v_mul_f32_e32 v46, v19, v33
	v_mul_f32_e32 v48, v19, v29
	v_fma_f32 v20, v20, v26, v36
	v_fma_f32 v21, v21, v26, v37
	v_mov_b32_e32 v26, v31
	v_fma_f32 v16, v16, v28, v44
	v_fma_f32 v17, v17, v28, v45
	v_mov_b32_e32 v28, v33
	v_fma_f32 v39, v23, v31, -v38
	v_fma_f32 v38, v22, v30, -v38
	v_fma_f32 v30, v18, v32, -v46
	v_fma_f32 v31, v19, v33, -v46
	v_fma_f32 v26, v22, v26, v40
	v_fma_f32 v27, v23, v27, v40
	v_fma_f32 v28, v18, v28, v48
	v_fma_f32 v29, v19, v29, v48
	v_sub_f32_e32 v16, v42, v44
	v_sub_f32_e32 v20, v34, v36
	v_mov_b32_e32 v18, v30
	v_mov_b32_e32 v22, v38
	v_mov_b32_e32 v19, v28
	v_mov_b32_e32 v23, v26
.LBB0_2504:
	s_or_b64 exec, exec, s[70:71]
	v_cvt_pk_bf16_f32 v20, v20, v21
	v_cvt_pk_bf16_f32 v21, v22, v23
	v_cvt_pk_bf16_f32 v22, v16, v17
	v_cvt_pk_bf16_f32 v23, v18, v19
	global_store_dwordx4 v[24:25], v[20:23], off offset:256
	v_add_u32_e32 v16, 0xb0, v150
	v_ashrrev_i32_e32 v17, 31, v16
	v_mov_b32_e32 v18, 0
	s_and_saveexec_b64 s[70:71], s[6:7]
	s_cbranch_execz .LBB0_2506
	v_lshlrev_b64 v[18:19], 7, v[16:17]
	v_lshl_add_u64 v[18:19], v[138:139], 0, v[18:19]
	global_load_dwordx4 v[18:21], v[18:19], off
	s_waitcnt vmcnt(0)
	v_mov_b32_e32 v22, v19
	v_mov_b32_e32 v23, v20
	v_mov_b32_e32 v19, v21
	v_add_f32_e32 v18, v22, v18
	v_add_f32_e32 v19, v23, v19
	s_nop 0
	v_add_f32_e32 v17, v18, v19
	v_add_f32_e32 v18, 0, v17
.LBB0_2506:
	s_or_b64 exec, exec, s[70:71]
	ds_bpermute_b32 v17, v161, v18
	s_waitcnt lgkmcnt(0)
	v_add_f32_e32 v17, v18, v17
	ds_bpermute_b32 v18, v162, v17
	s_waitcnt lgkmcnt(0)
	v_add_f32_e32 v17, v17, v18
	v_fmamk_f32 v17, v17, 0x3aaaaaab, v166
	v_rsq_f32_e32 v18, v17
	v_lshlrev_b32_e32 v17, 5, v16
	v_and_b32_e32 v17, 0xffe0, v17
	v_lshlrev_b32_e32 v136, 2, v17
	v_mul_f32_e32 v20, v14, v18
	v_mul_f32_e32 v21, v15, v18
	v_mul_f32_e32 v12, v12, v18
	v_mul_f32_e32 v13, v13, v18
	v_mul_f32_e32 v14, v10, v18
	v_mul_f32_e32 v15, v11, v18
	v_mul_f32_e32 v10, v8, v18
	v_mul_f32_e32 v11, v9, v18
	s_and_saveexec_b64 s[70:71], vcc
	s_cbranch_execz .LBB0_2508
	v_mov_b32_e32 v121, v137
	v_lshl_add_u64 v[8:9], s[66:67], 0, v[136:137]
	v_lshlrev_b64 v[22:23], 2, v[120:121]
	v_lshl_add_u64 v[24:25], s[68:69], 0, v[136:137]
	v_lshl_add_u64 v[8:9], v[8:9], 0, v[22:23]
	v_lshl_add_u64 v[26:27], v[24:25], 0, v[22:23]
	global_load_dwordx4 v[22:25], v[8:9], off
	s_nop 0
	global_load_dwordx4 v[26:29], v[26:27], off
	s_waitcnt vmcnt(0)
	v_mul_f32_e32 v8, v12, v22
	v_mul_f32_e32 v9, v13, v23
	v_mul_f32_e32 v30, v13, v26
	v_mul_f32_e32 v31, v12, v26
	v_mul_f32_e32 v38, v11, v28
	v_mul_f32_e32 v39, v10, v28
	v_mov_b32_e32 v26, v23
	v_mul_f32_e32 v32, v21, v27
	v_mul_f32_e32 v34, v21, v23
	v_mul_f32_e32 v36, v10, v24
	v_mul_f32_e32 v37, v11, v25
	v_mov_b32_e32 v28, v25
	v_mul_f32_e32 v40, v15, v29
	v_mul_f32_e32 v42, v15, v25
	v_fma_f32 v12, v12, v22, v30
	v_fma_f32 v13, v13, v22, v31
	v_mov_b32_e32 v22, v27
	v_fma_f32 v10, v10, v24, v38
	v_fma_f32 v11, v11, v24, v39
	v_mov_b32_e32 v24, v29
	v_fma_f32 v33, v21, v27, -v32
	v_fma_f32 v32, v20, v26, -v32
	v_fma_f32 v26, v14, v28, -v40
	v_fma_f32 v27, v15, v29, -v40
	v_fma_f32 v22, v20, v22, v34
	v_fma_f32 v23, v21, v23, v34
	v_fma_f32 v24, v14, v24, v42
	v_fma_f32 v25, v15, v25, v42
	v_sub_f32_e32 v10, v36, v38
	v_sub_f32_e32 v12, v8, v30
	v_mov_b32_e32 v14, v26
	v_mov_b32_e32 v20, v32
	v_mov_b32_e32 v15, v24
	v_mov_b32_e32 v21, v22
.LBB0_2508:
	s_or_b64 exec, exec, s[70:71]
	v_mov_b64_e32 v[8:9], s[18:19]
	v_mov_b32_e32 v19, v18
	v_mad_i64_i32 v[8:9], s[60:61], v16, s79, v[8:9]
	v_cvt_pk_bf16_f32 v24, v10, v11
	v_mov_b32_e32 v10, v18
	v_mov_b32_e32 v11, v18
	v_lshl_add_u64 v[8:9], v[148:149], 1, v[8:9]
	v_cvt_pk_bf16_f32 v22, v12, v13
	v_cvt_pk_bf16_f32 v23, v20, v21
	v_cvt_pk_bf16_f32 v25, v14, v15
	v_mul_f32_e32 v6, v6, v10
	v_mul_f32_e32 v7, v7, v11
	v_mul_f32_e32 v4, v4, v18
	v_mul_f32_e32 v5, v5, v19
	v_mul_f32_e32 v2, v2, v10
	v_mul_f32_e32 v3, v3, v11
	v_mul_f32_e32 v0, v0, v18
	v_mul_f32_e32 v1, v1, v19
	global_store_dwordx4 v[8:9], v[22:25], off
	s_and_saveexec_b64 s[70:71], s[16:17]
	s_cbranch_execz .LBB0_2510
	v_mov_b32_e32 v113, v137
	v_lshl_add_u64 v[10:11], s[66:67], 0, v[136:137]
	v_lshlrev_b64 v[12:13], 2, v[112:113]
	v_lshl_add_u64 v[14:15], s[68:69], 0, v[136:137]
	v_lshl_add_u64 v[10:11], v[10:11], 0, v[12:13]
	v_lshl_add_u64 v[14:15], v[14:15], 0, v[12:13]
	global_load_dwordx4 v[10:13], v[10:11], off
	s_nop 0
	global_load_dwordx4 v[14:17], v[14:15], off
	s_waitcnt vmcnt(0)
	v_mul_f32_e32 v18, v4, v10
	v_mul_f32_e32 v19, v5, v11
	v_mul_f32_e32 v20, v5, v14
	v_mul_f32_e32 v21, v4, v14
	v_mul_f32_e32 v28, v1, v16
	v_mul_f32_e32 v29, v0, v16
	v_mov_b32_e32 v14, v11
	v_mul_f32_e32 v22, v7, v15
	v_mul_f32_e32 v24, v7, v11
	v_mul_f32_e32 v26, v0, v12
	v_mul_f32_e32 v27, v1, v13
	v_mov_b32_e32 v16, v13
	v_mul_f32_e32 v30, v3, v17
	v_mul_f32_e32 v32, v3, v13
	v_fma_f32 v4, v4, v10, v20
	v_fma_f32 v5, v5, v10, v21
	v_mov_b32_e32 v10, v15
	v_fma_f32 v0, v0, v12, v28
	v_fma_f32 v1, v1, v12, v29
	v_mov_b32_e32 v12, v17
	v_fma_f32 v23, v7, v15, -v22
	v_fma_f32 v22, v6, v14, -v22
	v_fma_f32 v14, v2, v16, -v30
	v_fma_f32 v15, v3, v17, -v30
	v_fma_f32 v10, v6, v10, v24
	v_fma_f32 v11, v7, v11, v24
	v_fma_f32 v12, v2, v12, v32
	v_fma_f32 v13, v3, v13, v32
	v_sub_f32_e32 v0, v26, v28
	v_sub_f32_e32 v4, v18, v20
	v_mov_b32_e32 v2, v14
	v_mov_b32_e32 v6, v22
	v_mov_b32_e32 v3, v12
	v_mov_b32_e32 v7, v10

.LBB0_2538:
	v_lshl_add_u32 v146, s76, 8, v150
	v_ashrrev_i32_e32 v147, 31, v146
	v_mov_b32_e32 v159, 0
	v_mov_b32_e32 v148, 0
	s_and_saveexec_b64 s[16:17], s[6:7]
	s_cbranch_execz .LBB0_2540
	v_lshlrev_b64 v[148:149], 7, v[146:147]
	v_lshl_add_u64 v[148:149], v[136:137], 0, v[148:149]
	global_load_dwordx4 v[160:163], v[148:149], off offset:48
	s_waitcnt vmcnt(0)
	v_mov_b32_e32 v148, v161
	v_mov_b32_e32 v149, v162
	v_mov_b32_e32 v161, v163
	v_add_f32_e32 v148, v148, v160
	v_add_f32_e32 v149, v149, v161
	s_nop 0
	v_add_f32_e32 v148, v148, v149
	v_add_f32_e32 v148, 0, v148
.LBB0_2540:
	s_or_b64 exec, exec, s[16:17]
	ds_bpermute_b32 v149, v153, v148
	v_lshlrev_b64 v[160:161], 13, v[146:147]
	v_lshl_add_u64 v[160:161], s[20:21], 0, v[160:161]
	s_waitcnt lgkmcnt(0)
	v_add_f32_e32 v149, v148, v149
	ds_bpermute_b32 v162, v154, v149
	v_lshl_add_u32 v148, s66, 8, v152
	s_waitcnt lgkmcnt(0)
	v_add_f32_e32 v147, v149, v162
	v_fmamk_f32 v147, v147, 0x3b000000, v158
	v_rsq_f32_e32 v162, v147
	v_ashrrev_i32_e32 v149, 31, v148
	v_lshl_add_u64 v[160:161], v[148:149], 1, v[160:161]
	v_mul_f32_e32 v126, v126, v162
	v_mul_f32_e32 v127, v127, v162
	v_mul_f32_e32 v124, v124, v162
	v_mul_f32_e32 v125, v125, v162
	v_mul_f32_e32 v164, v122, v162
	v_mul_f32_e32 v165, v123, v162
	v_mul_f32_e32 v122, v120, v162
	v_mul_f32_e32 v123, v121, v162
	v_cvt_pk_bf16_f32 v120, v124, v125
	v_cvt_pk_bf16_f32 v121, v126, v127
	v_cvt_pk_bf16_f32 v122, v122, v123
	v_cvt_pk_bf16_f32 v123, v164, v165
	global_store_dwordx4 v[160:161], v[120:123], off
	v_mul_f32_e32 v118, v118, v162
	v_mul_f32_e32 v119, v119, v162
	v_mul_f32_e32 v116, v116, v162
	v_mul_f32_e32 v117, v117, v162
	v_mul_f32_e32 v120, v114, v162
	v_mul_f32_e32 v121, v115, v162
	v_mul_f32_e32 v114, v112, v162
	v_mul_f32_e32 v115, v113, v162
	v_cvt_pk_bf16_f32 v112, v116, v117
	v_cvt_pk_bf16_f32 v113, v118, v119
	v_cvt_pk_bf16_f32 v114, v114, v115
	v_cvt_pk_bf16_f32 v115, v120, v121
	global_store_dwordx4 v[160:161], v[112:115], off offset:256
	s_nop 1
	v_or_b32_e32 v112, 16, v146
	v_ashrrev_i32_e32 v113, 31, v112
	s_and_saveexec_b64 s[16:17], s[6:7]
	s_cbranch_execz .LBB0_2542
	v_lshlrev_b64 v[114:115], 7, v[112:113]
	v_lshl_add_u64 v[114:115], v[136:137], 0, v[114:115]
	global_load_dwordx4 v[114:117], v[114:115], off offset:48
	s_waitcnt vmcnt(0)
	v_mov_b32_e32 v118, v115
	v_mov_b32_e32 v119, v116
	v_mov_b32_e32 v115, v117
	v_add_f32_e32 v114, v118, v114
	v_add_f32_e32 v115, v119, v115
	s_nop 0
	v_add_f32_e32 v114, v114, v115
	v_add_f32_e32 v159, 0, v114
.LBB0_2542:
	s_or_b64 exec, exec, s[16:17]
	ds_bpermute_b32 v114, v153, v159
	v_lshlrev_b64 v[112:113], 13, v[112:113]
	v_lshl_add_u64 v[112:113], s[20:21], 0, v[112:113]
	v_lshl_add_u64 v[112:113], v[148:149], 1, v[112:113]
	s_waitcnt lgkmcnt(0)
	v_add_f32_e32 v114, v159, v114
	ds_bpermute_b32 v115, v154, v114
	s_waitcnt lgkmcnt(0)
	v_add_f32_e32 v114, v114, v115
	v_fmamk_f32 v114, v114, 0x3b000000, v158
	v_rsq_f32_e32 v114, v114
	s_nop 0
	v_mul_f32_e32 v110, v110, v114
	v_mul_f32_e32 v111, v111, v114
	v_mul_f32_e32 v108, v108, v114
	v_mul_f32_e32 v109, v109, v114
	v_mul_f32_e32 v106, v106, v114
	v_mul_f32_e32 v107, v107, v114
	v_mul_f32_e32 v104, v104, v114
	v_mul_f32_e32 v105, v105, v114
	v_mul_f32_e32 v116, v102, v114
	v_mul_f32_e32 v117, v103, v114
	v_mul_f32_e32 v118, v100, v114
	v_mul_f32_e32 v119, v101, v114
	v_cvt_pk_bf16_f32 v100, v108, v109
	v_cvt_pk_bf16_f32 v101, v110, v111
	v_cvt_pk_bf16_f32 v102, v104, v105
	v_cvt_pk_bf16_f32 v103, v106, v107
	global_store_dwordx4 v[112:113], v[100:103], off
	s_nop 1
	v_mul_f32_e32 v100, v98, v114
	v_mul_f32_e32 v101, v99, v114
	v_mul_f32_e32 v98, v96, v114
	v_mul_f32_e32 v99, v97, v114
	v_cvt_pk_bf16_f32 v96, v118, v119
	v_cvt_pk_bf16_f32 v97, v116, v117
	v_cvt_pk_bf16_f32 v98, v98, v99
	v_cvt_pk_bf16_f32 v99, v100, v101
	global_store_dwordx4 v[112:113], v[96:99], off offset:256
	s_nop 1
	v_or_b32_e32 v96, 32, v146
	v_ashrrev_i32_e32 v97, 31, v96
	v_mov_b32_e32 v98, 0
	v_mov_b32_e32 v99, 0
	s_and_saveexec_b64 s[16:17], s[6:7]
	s_cbranch_execz .LBB0_2544
	v_lshlrev_b64 v[100:101], 7, v[96:97]
	v_lshl_add_u64 v[100:101], v[136:137], 0, v[100:101]
	global_load_dwordx4 v[100:103], v[100:101], off offset:48
	s_waitcnt vmcnt(0)
	v_mov_b32_e32 v104, v101
	v_mov_b32_e32 v105, v102
	v_mov_b32_e32 v101, v103
	v_add_f32_e32 v100, v104, v100
	v_add_f32_e32 v101, v105, v101
	s_nop 0
	v_add_f32_e32 v99, v100, v101
	v_add_f32_e32 v99, 0, v99
.LBB0_2544:
	s_or_b64 exec, exec, s[16:17]
	ds_bpermute_b32 v100, v153, v99
	v_lshlrev_b64 v[96:97], 13, v[96:97]
	v_lshl_add_u64 v[96:97], s[20:21], 0, v[96:97]
	v_lshl_add_u64 v[96:97], v[148:149], 1, v[96:97]
	s_waitcnt lgkmcnt(0)
	v_add_f32_e32 v99, v99, v100
	ds_bpermute_b32 v100, v154, v99
	s_waitcnt lgkmcnt(0)
	v_add_f32_e32 v99, v99, v100
	v_fmamk_f32 v99, v99, 0x3b000000, v158
	v_rsq_f32_e32 v100, v99
	s_nop 0
	v_mul_f32_e32 v94, v94, v100
	v_mul_f32_e32 v95, v95, v100
	v_mul_f32_e32 v92, v92, v100
	v_mul_f32_e32 v93, v93, v100
	v_mul_f32_e32 v90, v90, v100
	v_mul_f32_e32 v91, v91, v100
	v_mul_f32_e32 v88, v88, v100
	v_mul_f32_e32 v89, v89, v100
	v_mul_f32_e32 v102, v86, v100
	v_mul_f32_e32 v103, v87, v100
	v_mul_f32_e32 v104, v84, v100
	v_mul_f32_e32 v105, v85, v100
	v_cvt_pk_bf16_f32 v84, v92, v93
	v_cvt_pk_bf16_f32 v85, v94, v95
	v_cvt_pk_bf16_f32 v86, v88, v89
	v_cvt_pk_bf16_f32 v87, v90, v91
	global_store_dwordx4 v[96:97], v[84:87], off
	s_nop 1
	v_mul_f32_e32 v84, v82, v100
	v_mul_f32_e32 v85, v83, v100
	v_mul_f32_e32 v82, v80, v100
	v_mul_f32_e32 v83, v81, v100
	v_cvt_pk_bf16_f32 v80, v104, v105
	v_cvt_pk_bf16_f32 v81, v102, v103
	v_cvt_pk_bf16_f32 v82, v82, v83
	v_cvt_pk_bf16_f32 v83, v84, v85
	global_store_dwordx4 v[96:97], v[80:83], off offset:256
	s_nop 1
	v_or_b32_e32 v80, 48, v146
	v_ashrrev_i32_e32 v81, 31, v80
	s_and_saveexec_b64 s[16:17], s[6:7]
	s_cbranch_execz .LBB0_2546
	v_lshlrev_b64 v[82:83], 7, v[80:81]
	v_lshl_add_u64 v[82:83], v[136:137], 0, v[82:83]
	global_load_dwordx4 v[82:85], v[82:83], off offset:48
	s_waitcnt vmcnt(0)
	v_mov_b32_e32 v86, v83
	v_mov_b32_e32 v87, v84
	v_mov_b32_e32 v83, v85
	v_add_f32_e32 v82, v86, v82
	v_add_f32_e32 v83, v87, v83
	s_nop 0
	v_add_f32_e32 v82, v82, v83
	v_add_f32_e32 v98, 0, v82
.LBB0_2546:
	s_or_b64 exec, exec, s[16:17]
	ds_bpermute_b32 v82, v153, v98
	v_lshlrev_b64 v[80:81], 13, v[80:81]
	v_lshl_add_u64 v[80:81], s[20:21], 0, v[80:81]
	v_lshl_add_u64 v[80:81], v[148:149], 1, v[80:81]
	s_waitcnt lgkmcnt(0)
	v_add_f32_e32 v82, v98, v82
	ds_bpermute_b32 v83, v154, v82
	s_waitcnt lgkmcnt(0)
	v_add_f32_e32 v82, v82, v83
	v_fmamk_f32 v82, v82, 0x3b000000, v158
	v_rsq_f32_e32 v82, v82
	s_nop 0
	v_mul_f32_e32 v78, v78, v82
	v_mul_f32_e32 v79, v79, v82
	v_mul_f32_e32 v76, v76, v82
	v_mul_f32_e32 v77, v77, v82
	v_mul_f32_e32 v74, v74, v82
	v_mul_f32_e32 v75, v75, v82
	v_mul_f32_e32 v72, v72, v82
	v_mul_f32_e32 v73, v73, v82
	v_mul_f32_e32 v84, v70, v82
	v_mul_f32_e32 v85, v71, v82
	v_mul_f32_e32 v86, v68, v82
	v_mul_f32_e32 v87, v69, v82
	v_cvt_pk_bf16_f32 v68, v76, v77
	v_cvt_pk_bf16_f32 v69, v78, v79
	v_cvt_pk_bf16_f32 v70, v72, v73
	v_cvt_pk_bf16_f32 v71, v74, v75
	global_store_dwordx4 v[80:81], v[68:71], off
	s_nop 1
	v_mul_f32_e32 v68, v66, v82
	v_mul_f32_e32 v69, v67, v82
	v_mul_f32_e32 v66, v64, v82
	v_mul_f32_e32 v67, v65, v82
	v_cvt_pk_bf16_f32 v64, v86, v87
	v_cvt_pk_bf16_f32 v65, v84, v85
	v_cvt_pk_bf16_f32 v66, v66, v67
	v_cvt_pk_bf16_f32 v67, v68, v69
	global_store_dwordx4 v[80:81], v[64:67], off offset:256
	s_nop 1
	v_add_u32_e32 v64, 0x80, v146
	v_ashrrev_i32_e32 v65, 31, v64
	v_mov_b32_e32 v66, 0
	v_mov_b32_e32 v67, 0
	s_and_saveexec_b64 s[16:17], s[6:7]
	s_cbranch_execz .LBB0_2548
	v_lshlrev_b64 v[68:69], 7, v[64:65]
	v_lshl_add_u64 v[68:69], v[136:137], 0, v[68:69]
	global_load_dwordx4 v[68:71], v[68:69], off offset:48
	s_waitcnt vmcnt(0)
	v_mov_b32_e32 v72, v69
	v_mov_b32_e32 v73, v70
	v_mov_b32_e32 v69, v71
	v_add_f32_e32 v68, v72, v68
	v_add_f32_e32 v69, v73, v69
	s_nop 0
	v_add_f32_e32 v67, v68, v69
	v_add_f32_e32 v67, 0, v67
.LBB0_2548:
	s_or_b64 exec, exec, s[16:17]
	ds_bpermute_b32 v68, v153, v67
	v_lshlrev_b64 v[64:65], 13, v[64:65]
	v_lshl_add_u64 v[64:65], s[20:21], 0, v[64:65]
	v_lshl_add_u64 v[64:65], v[148:149], 1, v[64:65]
	s_waitcnt lgkmcnt(0)
	v_add_f32_e32 v67, v67, v68
	ds_bpermute_b32 v68, v154, v67
	s_waitcnt lgkmcnt(0)
	v_add_f32_e32 v67, v67, v68
	v_fmamk_f32 v67, v67, 0x3b000000, v158
	v_rsq_f32_e32 v68, v67
	s_nop 0
	v_mul_f32_e32 v62, v62, v68
	v_mul_f32_e32 v63, v63, v68
	v_mul_f32_e32 v60, v60, v68
	v_mul_f32_e32 v61, v61, v68
	v_mul_f32_e32 v58, v58, v68
	v_mul_f32_e32 v59, v59, v68
	v_mul_f32_e32 v56, v56, v68
	v_mul_f32_e32 v57, v57, v68
	v_mul_f32_e32 v70, v54, v68
	v_mul_f32_e32 v71, v55, v68
	v_mul_f32_e32 v72, v52, v68
	v_mul_f32_e32 v73, v53, v68
	v_cvt_pk_bf16_f32 v52, v60, v61
	v_cvt_pk_bf16_f32 v53, v62, v63
	v_cvt_pk_bf16_f32 v54, v56, v57
	v_cvt_pk_bf16_f32 v55, v58, v59
	global_store_dwordx4 v[64:65], v[52:55], off
	s_nop 1
	v_mul_f32_e32 v52, v50, v68
	v_mul_f32_e32 v53, v51, v68
	v_mul_f32_e32 v50, v48, v68
	v_mul_f32_e32 v51, v49, v68
	v_cvt_pk_bf16_f32 v48, v72, v73
	v_cvt_pk_bf16_f32 v49, v70, v71
	v_cvt_pk_bf16_f32 v50, v50, v51
	v_cvt_pk_bf16_f32 v51, v52, v53
	global_store_dwordx4 v[64:65], v[48:51], off offset:256
	s_nop 1
	v_add_u32_e32 v48, 0x90, v146
	v_ashrrev_i32_e32 v49, 31, v48
	s_and_saveexec_b64 s[16:17], s[6:7]
	s_cbranch_execz .LBB0_2550
	v_lshlrev_b64 v[50:51], 7, v[48:49]
	v_lshl_add_u64 v[50:51], v[136:137], 0, v[50:51]
	global_load_dwordx4 v[50:53], v[50:51], off offset:48
	s_waitcnt vmcnt(0)
	v_mov_b32_e32 v54, v51
	v_mov_b32_e32 v55, v52
	v_mov_b32_e32 v51, v53
	v_add_f32_e32 v50, v54, v50
	v_add_f32_e32 v51, v55, v51
	s_nop 0
	v_add_f32_e32 v50, v50, v51
	v_add_f32_e32 v66, 0, v50
.LBB0_2550:
	s_or_b64 exec, exec, s[16:17]
	ds_bpermute_b32 v50, v153, v66
	v_lshlrev_b64 v[48:49], 13, v[48:49]
	v_lshl_add_u64 v[48:49], s[20:21], 0, v[48:49]
	v_lshl_add_u64 v[48:49], v[148:149], 1, v[48:49]
	s_waitcnt lgkmcnt(0)
	v_add_f32_e32 v50, v66, v50
	ds_bpermute_b32 v51, v154, v50
	s_waitcnt lgkmcnt(0)
	v_add_f32_e32 v50, v50, v51
	v_fmamk_f32 v50, v50, 0x3b000000, v158
	v_rsq_f32_e32 v50, v50
	s_nop 0
	v_mul_f32_e32 v46, v46, v50
	v_mul_f32_e32 v47, v47, v50
	v_mul_f32_e32 v44, v44, v50
	v_mul_f32_e32 v45, v45, v50
	v_mul_f32_e32 v42, v42, v50
	v_mul_f32_e32 v43, v43, v50
	v_mul_f32_e32 v40, v40, v50
	v_mul_f32_e32 v41, v41, v50
	v_mul_f32_e32 v52, v38, v50
	v_mul_f32_e32 v53, v39, v50
	v_mul_f32_e32 v54, v36, v50
	v_mul_f32_e32 v55, v37, v50
	v_cvt_pk_bf16_f32 v36, v44, v45
	v_cvt_pk_bf16_f32 v37, v46, v47
	v_cvt_pk_bf16_f32 v38, v40, v41
	v_cvt_pk_bf16_f32 v39, v42, v43
	global_store_dwordx4 v[48:49], v[36:39], off
	s_nop 1
	v_mul_f32_e32 v36, v34, v50
	v_mul_f32_e32 v37, v35, v50
	v_mul_f32_e32 v34, v32, v50
	v_mul_f32_e32 v35, v33, v50
	v_cvt_pk_bf16_f32 v32, v54, v55
	v_cvt_pk_bf16_f32 v33, v52, v53
	v_cvt_pk_bf16_f32 v34, v34, v35
	v_cvt_pk_bf16_f32 v35, v36, v37
	global_store_dwordx4 v[48:49], v[32:35], off offset:256
	s_nop 1
	v_add_u32_e32 v32, 0xa0, v146
	v_ashrrev_i32_e32 v33, 31, v32
	v_mov_b32_e32 v34, 0
	v_mov_b32_e32 v35, 0
	s_and_saveexec_b64 s[16:17], s[6:7]
	s_cbranch_execz .LBB0_2552
	v_lshlrev_b64 v[36:37], 7, v[32:33]
	v_lshl_add_u64 v[36:37], v[136:137], 0, v[36:37]
	global_load_dwordx4 v[36:39], v[36:37], off offset:48
	s_waitcnt vmcnt(0)
	v_mov_b32_e32 v40, v37
	v_mov_b32_e32 v41, v38
	v_mov_b32_e32 v37, v39
	v_add_f32_e32 v36, v40, v36
	v_add_f32_e32 v37, v41, v37
	s_nop 0
	v_add_f32_e32 v35, v36, v37
	v_add_f32_e32 v35, 0, v35
.LBB0_2552:
	s_or_b64 exec, exec, s[16:17]
	ds_bpermute_b32 v36, v153, v35
	v_lshlrev_b64 v[32:33], 13, v[32:33]
	v_lshl_add_u64 v[32:33], s[20:21], 0, v[32:33]
	v_lshl_add_u64 v[32:33], v[148:149], 1, v[32:33]
	s_waitcnt lgkmcnt(0)
	v_add_f32_e32 v35, v35, v36
	ds_bpermute_b32 v36, v154, v35
	s_waitcnt lgkmcnt(0)
	v_add_f32_e32 v35, v35, v36
	v_fmamk_f32 v35, v35, 0x3b000000, v158
	v_rsq_f32_e32 v36, v35
	s_nop 0
	v_mul_f32_e32 v30, v30, v36
	v_mul_f32_e32 v31, v31, v36
	v_mul_f32_e32 v28, v28, v36
	v_mul_f32_e32 v29, v29, v36
	v_mul_f32_e32 v26, v26, v36
	v_mul_f32_e32 v27, v27, v36
	v_mul_f32_e32 v24, v24, v36
	v_mul_f32_e32 v25, v25, v36
	v_mul_f32_e32 v38, v22, v36
	v_mul_f32_e32 v39, v23, v36
	v_mul_f32_e32 v40, v20, v36
	v_mul_f32_e32 v41, v21, v36
	v_cvt_pk_bf16_f32 v20, v28, v29
	v_cvt_pk_bf16_f32 v21, v30, v31
	v_cvt_pk_bf16_f32 v22, v24, v25
	v_cvt_pk_bf16_f32 v23, v26, v27
	global_store_dwordx4 v[32:33], v[20:23], off
	s_nop 1
	v_mul_f32_e32 v20, v18, v36
	v_mul_f32_e32 v21, v19, v36
	v_mul_f32_e32 v18, v16, v36
	v_mul_f32_e32 v19, v17, v36
	v_cvt_pk_bf16_f32 v16, v40, v41
	v_cvt_pk_bf16_f32 v17, v38, v39
	v_cvt_pk_bf16_f32 v18, v18, v19
	v_cvt_pk_bf16_f32 v19, v20, v21
	global_store_dwordx4 v[32:33], v[16:19], off offset:256
	s_nop 1
	v_add_u32_e32 v16, 0xb0, v146
	v_ashrrev_i32_e32 v17, 31, v16
	s_and_saveexec_b64 s[16:17], s[6:7]
	s_cbranch_execz .LBB0_2554
	v_lshlrev_b64 v[18:19], 7, v[16:17]
	v_lshl_add_u64 v[18:19], v[136:137], 0, v[18:19]
	global_load_dwordx4 v[18:21], v[18:19], off offset:48
	s_waitcnt vmcnt(0)
	v_mov_b32_e32 v22, v19
	v_mov_b32_e32 v23, v20
	v_mov_b32_e32 v19, v21
	v_add_f32_e32 v18, v22, v18
	v_add_f32_e32 v19, v23, v19
	s_nop 0
	v_add_f32_e32 v18, v18, v19
	v_add_f32_e32 v34, 0, v18
.LBB0_2554:
	s_or_b64 exec, exec, s[16:17]
	ds_bpermute_b32 v18, v153, v34
	v_lshlrev_b64 v[16:17], 13, v[16:17]
	v_lshl_add_u64 v[16:17], s[20:21], 0, v[16:17]
	v_lshl_add_u64 v[16:17], v[148:149], 1, v[16:17]
	s_and_b64 vcc, exec, s[14:15]
	s_waitcnt lgkmcnt(0)
	v_add_f32_e32 v18, v34, v18
	ds_bpermute_b32 v19, v154, v18
	s_mov_b64 s[14:15], -1
	s_waitcnt lgkmcnt(0)
	v_add_f32_e32 v18, v18, v19
	v_fmamk_f32 v18, v18, 0x3b000000, v158
	v_rsq_f32_e32 v18, v18
	s_nop 0
	v_mul_f32_e32 v14, v14, v18
	v_mul_f32_e32 v15, v15, v18
	v_mul_f32_e32 v12, v12, v18
	v_mul_f32_e32 v13, v13, v18
	v_mul_f32_e32 v10, v10, v18
	v_mul_f32_e32 v11, v11, v18
	v_mul_f32_e32 v8, v8, v18
	v_mul_f32_e32 v9, v9, v18
	v_mul_f32_e32 v20, v6, v18
	v_mul_f32_e32 v21, v7, v18
	v_mul_f32_e32 v22, v4, v18
	v_mul_f32_e32 v23, v5, v18
	v_cvt_pk_bf16_f32 v4, v12, v13
	v_cvt_pk_bf16_f32 v5, v14, v15
	v_cvt_pk_bf16_f32 v6, v8, v9
	v_cvt_pk_bf16_f32 v7, v10, v11
	global_store_dwordx4 v[16:17], v[4:7], off
	s_nop 1
	v_mul_f32_e32 v4, v2, v18
	v_mul_f32_e32 v5, v3, v18
	v_mul_f32_e32 v2, v0, v18
	v_mul_f32_e32 v3, v1, v18
	v_cvt_pk_bf16_f32 v0, v22, v23
	v_cvt_pk_bf16_f32 v1, v20, v21
	v_cvt_pk_bf16_f32 v2, v2, v3
	v_cvt_pk_bf16_f32 v3, v4, v5
	global_store_dwordx4 v[16:17], v[0:3], off offset:256
	s_cbranch_vccnz .LBB0_2525
	s_and_b64 vcc, exec, s[10:11]
	s_cbranch_vccnz .LBB0_2524
	s_barrier
	s_branch .LBB0_2524

.LBB0_2716:
	v_lshl_add_u32 v142, s56, 8, v144
	v_lshl_add_u32 v140, s18, 8, v146
	v_lshl_add_u32 v208, v142, 11, v140
	v_lshlrev_b32_e32 v208, 2, v208
	global_load_dwordx4 v[160:163], v208, s[16:17]
	global_load_dwordx4 v[164:167], v208, s[16:17] offset:64
	global_load_dwordx4 v[168:171], v208, s[16:17] offset:512
	global_load_dwordx4 v[172:175], v208, s[16:17] offset:576
	v_add_u32_e32 v209, 0x20000, v208
	global_load_dwordx4 v[176:179], v209, s[16:17]
	global_load_dwordx4 v[180:183], v209, s[16:17] offset:64
	global_load_dwordx4 v[184:187], v209, s[16:17] offset:512
	global_load_dwordx4 v[188:191], v209, s[16:17] offset:576
	v_add_u32_e32 v209, 0x40000, v208
	global_load_dwordx4 v[192:195], v209, s[16:17]
	global_load_dwordx4 v[196:199], v209, s[16:17] offset:64
	global_load_dwordx4 v[200:203], v209, s[16:17] offset:512
	global_load_dwordx4 v[204:207], v209, s[16:17] offset:576
	v_ashrrev_i32_e32 v143, 31, v142
	v_ashrrev_i32_e32 v141, 31, v140
	v_lshlrev_b64 v[152:153], 11, v[142:143]
	v_lshl_add_u64 v[156:157], v[152:153], 0, v[140:141]
	v_lshl_add_u64 v[158:159], v[156:157], 2, s[16:17]
	s_nop 0
	v_lshl_add_u64 v[156:157], v[156:157], 1, s[54:55]
	s_lshl_b32 s56, s18, 2
	s_ashr_i32 s57, s56, 31
	s_waitcnt vmcnt(11)
	v_add_f32_e32 v126, v126, v162
	v_add_f32_e32 v127, v127, v163
	v_add_f32_e32 v124, v124, v160
	v_add_f32_e32 v125, v125, v161
	v_cvt_pk_bf16_f32 v153, v126, v127
	v_cvt_pk_bf16_f32 v152, v124, v125
	global_store_dwordx4 v[158:159], v[124:127], off
	global_store_dwordx2 v[156:157], v[152:153], off
	s_nop 0
	v_mul_f32_e32 v125, v125, v125
	v_mul_f32_e32 v127, v127, v127
	v_fmac_f32_e32 v125, v124, v124
	v_fmac_f32_e32 v127, v126, v126
	v_add_f32_e32 v124, v125, v127
	s_waitcnt vmcnt(12)
	v_add_f32_e32 v122, v122, v166
	v_add_f32_e32 v123, v123, v167
	v_add_f32_e32 v120, v120, v164
	v_add_f32_e32 v121, v121, v165
	v_cvt_pk_bf16_f32 v153, v122, v123
	v_cvt_pk_bf16_f32 v152, v120, v121
	global_store_dwordx4 v[158:159], v[120:123], off offset:64
	global_store_dwordx2 v[156:157], v[152:153], off offset:32
	s_nop 0
	v_mul_f32_e32 v121, v121, v121
	v_mul_f32_e32 v123, v123, v123
	v_fmac_f32_e32 v121, v120, v120
	v_fmac_f32_e32 v123, v122, v122
	v_add_f32_e32 v120, v121, v123
	v_add_f32_e32 v120, v124, v120
	s_waitcnt vmcnt(13)
	v_add_f32_e32 v118, v118, v170
	v_add_f32_e32 v119, v119, v171
	v_add_f32_e32 v116, v116, v168
	v_add_f32_e32 v117, v117, v169
	v_cvt_pk_bf16_f32 v153, v118, v119
	v_cvt_pk_bf16_f32 v152, v116, v117
	global_store_dwordx4 v[158:159], v[116:119], off offset:512
	global_store_dwordx2 v[156:157], v[152:153], off offset:256
	s_nop 0
	v_mul_f32_e32 v117, v117, v117
	v_mul_f32_e32 v119, v119, v119
	v_fmac_f32_e32 v117, v116, v116
	v_fmac_f32_e32 v119, v118, v118
	v_add_f32_e32 v116, v117, v119
	v_add_f32_e32 v118, v120, v116
	s_waitcnt vmcnt(14)
	v_add_f32_e32 v116, v114, v174
	v_add_f32_e32 v117, v115, v175
	v_add_f32_e32 v114, v112, v172
	v_add_f32_e32 v115, v113, v173
	v_add_u32_e32 v209, 0x60000, v208
	global_load_dwordx4 v[160:163], v209, s[16:17]
	global_load_dwordx4 v[164:167], v209, s[16:17] offset:64
	global_load_dwordx4 v[168:171], v209, s[16:17] offset:512
	global_load_dwordx4 v[172:175], v209, s[16:17] offset:576
	v_mul_f32_e32 v113, v117, v117
	v_mul_f32_e32 v112, v115, v115
	v_fmac_f32_e32 v112, v114, v114
	v_fmac_f32_e32 v113, v116, v116
	v_add_f32_e32 v112, v112, v113
	v_add_f32_e32 v112, v118, v112
	ds_bpermute_b32 v113, v147, v112
	global_store_dwordx4 v[158:159], v[114:117], off offset:576
	s_waitcnt lgkmcnt(0)
	v_add_f32_e32 v112, v112, v113
	ds_bpermute_b32 v113, v148, v112
	v_cvt_pk_bf16_f32 v114, v114, v115
	v_cvt_pk_bf16_f32 v115, v116, v117
	global_store_dwordx2 v[156:157], v[114:115], off offset:288
	s_and_saveexec_b64 s[62:63], s[6:7]
	s_cbranch_execz .LBB0_2718
	v_lshlrev_b64 v[114:115], 7, v[142:143]
	v_lshl_add_u64 v[114:115], s[52:53], 0, v[114:115]
	v_lshl_add_u64 v[114:115], s[56:57], 2, v[114:115]
	s_lshl_b32 s18, s3, 2
	v_lshl_add_u64 v[114:115], v[114:115], 0, s[18:19]
	s_waitcnt lgkmcnt(0)
	v_add_f32_e32 v112, v112, v113
	global_store_dword v[114:115], v112, off
.LBB0_2718:
	s_or_b64 exec, exec, s[62:63]
	v_or_b32_e32 v112, 16, v142
	s_waitcnt lgkmcnt(0)
	v_ashrrev_i32_e32 v113, 31, v112
	v_lshlrev_b64 v[114:115], 11, v[112:113]
	v_lshl_add_u64 v[118:119], v[114:115], 0, v[140:141]
	v_lshl_add_u64 v[120:121], v[118:119], 2, s[16:17]
	s_nop 0
	v_lshl_add_u64 v[118:119], v[118:119], 1, s[54:55]
	s_waitcnt vmcnt(19)
	v_add_f32_e32 v110, v110, v178
	v_add_f32_e32 v111, v111, v179
	v_add_f32_e32 v108, v108, v176
	v_add_f32_e32 v109, v109, v177
	v_cvt_pk_bf16_f32 v115, v110, v111
	v_cvt_pk_bf16_f32 v114, v108, v109
	global_store_dwordx4 v[120:121], v[108:111], off
	global_store_dwordx2 v[118:119], v[114:115], off
	s_nop 0
	v_mul_f32_e32 v109, v109, v109
	v_mul_f32_e32 v111, v111, v111
	v_fmac_f32_e32 v109, v108, v108
	v_fmac_f32_e32 v111, v110, v110
	v_add_f32_e32 v108, v109, v111
	s_waitcnt vmcnt(20)
	v_add_f32_e32 v106, v106, v182
	v_add_f32_e32 v107, v107, v183
	v_add_f32_e32 v104, v104, v180
	v_add_f32_e32 v105, v105, v181
	v_cvt_pk_bf16_f32 v115, v106, v107
	v_cvt_pk_bf16_f32 v114, v104, v105
	global_store_dwordx4 v[120:121], v[104:107], off offset:64
	global_store_dwordx2 v[118:119], v[114:115], off offset:32
	s_nop 0
	v_mul_f32_e32 v105, v105, v105
	v_mul_f32_e32 v107, v107, v107
	v_fmac_f32_e32 v105, v104, v104
	v_fmac_f32_e32 v107, v106, v106
	v_add_f32_e32 v104, v105, v107
	v_add_f32_e32 v104, v108, v104
	s_waitcnt vmcnt(21)
	v_add_f32_e32 v102, v102, v186
	v_add_f32_e32 v103, v103, v187
	v_add_f32_e32 v100, v100, v184
	v_add_f32_e32 v101, v101, v185
	v_cvt_pk_bf16_f32 v115, v102, v103
	v_cvt_pk_bf16_f32 v114, v100, v101
	global_store_dwordx4 v[120:121], v[100:103], off offset:512
	global_store_dwordx2 v[118:119], v[114:115], off offset:256
	s_nop 0
	v_mul_f32_e32 v101, v101, v101
	v_mul_f32_e32 v103, v103, v103
	v_fmac_f32_e32 v101, v100, v100
	v_fmac_f32_e32 v103, v102, v102
	v_add_f32_e32 v100, v101, v103
	v_add_f32_e32 v102, v104, v100
	s_waitcnt vmcnt(22)
	v_add_f32_e32 v100, v98, v190
	v_add_f32_e32 v101, v99, v191
	v_add_f32_e32 v98, v96, v188
	v_add_f32_e32 v99, v97, v189
	v_add_u32_e32 v209, 0x100000, v208
	global_load_dwordx4 v[176:179], v209, s[16:17]
	global_load_dwordx4 v[180:183], v209, s[16:17] offset:64
	global_load_dwordx4 v[184:187], v209, s[16:17] offset:512
	global_load_dwordx4 v[188:191], v209, s[16:17] offset:576
	v_mul_f32_e32 v97, v101, v101
	v_mul_f32_e32 v96, v99, v99
	v_fmac_f32_e32 v96, v98, v98
	v_fmac_f32_e32 v97, v100, v100
	v_add_f32_e32 v96, v96, v97
	v_add_f32_e32 v96, v102, v96
	ds_bpermute_b32 v97, v147, v96
	global_store_dwordx4 v[120:121], v[98:101], off offset:576
	s_waitcnt lgkmcnt(0)
	v_add_f32_e32 v96, v96, v97
	ds_bpermute_b32 v97, v148, v96
	v_cvt_pk_bf16_f32 v98, v98, v99
	v_cvt_pk_bf16_f32 v99, v100, v101
	global_store_dwordx2 v[118:119], v[98:99], off offset:288
	s_and_saveexec_b64 s[62:63], s[6:7]
	s_cbranch_execz .LBB0_2720
	v_lshlrev_b64 v[98:99], 7, v[112:113]
	v_lshl_add_u64 v[98:99], s[52:53], 0, v[98:99]
	v_lshl_add_u64 v[98:99], s[56:57], 2, v[98:99]
	s_lshl_b32 s18, s3, 2
	v_lshl_add_u64 v[98:99], v[98:99], 0, s[18:19]
	s_waitcnt lgkmcnt(0)
	v_add_f32_e32 v96, v96, v97
	global_store_dword v[98:99], v96, off
.LBB0_2720:
	s_or_b64 exec, exec, s[62:63]
	v_or_b32_e32 v96, 32, v142
	s_waitcnt lgkmcnt(0)
	v_ashrrev_i32_e32 v97, 31, v96
	v_lshlrev_b64 v[98:99], 11, v[96:97]
	v_lshl_add_u64 v[102:103], v[98:99], 0, v[140:141]
	v_lshl_add_u64 v[104:105], v[102:103], 2, s[16:17]
	s_nop 0
	v_lshl_add_u64 v[102:103], v[102:103], 1, s[54:55]
	s_waitcnt vmcnt(27)
	v_add_f32_e32 v94, v94, v194
	v_add_f32_e32 v95, v95, v195
	v_add_f32_e32 v92, v92, v192
	v_add_f32_e32 v93, v93, v193
	v_cvt_pk_bf16_f32 v99, v94, v95
	v_cvt_pk_bf16_f32 v98, v92, v93
	global_store_dwordx4 v[104:105], v[92:95], off
	global_store_dwordx2 v[102:103], v[98:99], off
	s_nop 0
	v_mul_f32_e32 v93, v93, v93
	v_mul_f32_e32 v95, v95, v95
	v_fmac_f32_e32 v93, v92, v92
	v_fmac_f32_e32 v95, v94, v94
	v_add_f32_e32 v92, v93, v95
	s_waitcnt vmcnt(28)
	v_add_f32_e32 v90, v90, v198
	v_add_f32_e32 v91, v91, v199
	v_add_f32_e32 v88, v88, v196
	v_add_f32_e32 v89, v89, v197
	v_cvt_pk_bf16_f32 v99, v90, v91
	v_cvt_pk_bf16_f32 v98, v88, v89
	global_store_dwordx4 v[104:105], v[88:91], off offset:64
	global_store_dwordx2 v[102:103], v[98:99], off offset:32
	s_nop 0
	v_mul_f32_e32 v89, v89, v89
	v_mul_f32_e32 v91, v91, v91
	v_fmac_f32_e32 v89, v88, v88
	v_fmac_f32_e32 v91, v90, v90
	v_add_f32_e32 v88, v89, v91
	v_add_f32_e32 v88, v92, v88
	s_waitcnt vmcnt(29)
	v_add_f32_e32 v86, v86, v202
	v_add_f32_e32 v87, v87, v203
	v_add_f32_e32 v84, v84, v200
	v_add_f32_e32 v85, v85, v201
	v_cvt_pk_bf16_f32 v99, v86, v87
	v_cvt_pk_bf16_f32 v98, v84, v85
	global_store_dwordx4 v[104:105], v[84:87], off offset:512
	global_store_dwordx2 v[102:103], v[98:99], off offset:256
	s_nop 0
	v_mul_f32_e32 v85, v85, v85
	v_mul_f32_e32 v87, v87, v87
	v_fmac_f32_e32 v85, v84, v84
	v_fmac_f32_e32 v87, v86, v86
	v_add_f32_e32 v84, v85, v87
	v_add_f32_e32 v86, v88, v84
	s_waitcnt vmcnt(30)
	v_add_f32_e32 v84, v82, v206
	v_add_f32_e32 v85, v83, v207
	v_add_f32_e32 v82, v80, v204
	v_add_f32_e32 v83, v81, v205
	v_add_u32_e32 v209, 0x120000, v208
	global_load_dwordx4 v[192:195], v209, s[16:17]
	global_load_dwordx4 v[196:199], v209, s[16:17] offset:64
	global_load_dwordx4 v[200:203], v209, s[16:17] offset:512
	global_load_dwordx4 v[204:207], v209, s[16:17] offset:576
	v_mul_f32_e32 v81, v85, v85
	v_mul_f32_e32 v80, v83, v83
	v_fmac_f32_e32 v80, v82, v82
	v_fmac_f32_e32 v81, v84, v84
	v_add_f32_e32 v80, v80, v81
	v_add_f32_e32 v80, v86, v80
	ds_bpermute_b32 v81, v147, v80
	global_store_dwordx4 v[104:105], v[82:85], off offset:576
	s_waitcnt lgkmcnt(0)
	v_add_f32_e32 v80, v80, v81
	ds_bpermute_b32 v81, v148, v80
	v_cvt_pk_bf16_f32 v82, v82, v83
	v_cvt_pk_bf16_f32 v83, v84, v85
	global_store_dwordx2 v[102:103], v[82:83], off offset:288
	s_and_saveexec_b64 s[62:63], s[6:7]
	s_cbranch_execz .LBB0_2722
	v_lshlrev_b64 v[82:83], 7, v[96:97]
	v_lshl_add_u64 v[82:83], s[52:53], 0, v[82:83]
	v_lshl_add_u64 v[82:83], s[56:57], 2, v[82:83]
	s_lshl_b32 s18, s3, 2
	v_lshl_add_u64 v[82:83], v[82:83], 0, s[18:19]
	s_waitcnt lgkmcnt(0)
	v_add_f32_e32 v80, v80, v81
	global_store_dword v[82:83], v80, off
.LBB0_2722:
	s_or_b64 exec, exec, s[62:63]
	v_or_b32_e32 v80, 48, v142
	s_waitcnt lgkmcnt(0)
	v_ashrrev_i32_e32 v81, 31, v80
	v_lshlrev_b64 v[82:83], 11, v[80:81]
	v_lshl_add_u64 v[86:87], v[82:83], 0, v[140:141]
	v_lshl_add_u64 v[88:89], v[86:87], 2, s[16:17]
	s_nop 0
	v_lshl_add_u64 v[86:87], v[86:87], 1, s[54:55]
	s_waitcnt vmcnt(29)
	v_add_f32_e32 v78, v78, v162
	v_add_f32_e32 v79, v79, v163
	v_add_f32_e32 v76, v76, v160
	v_add_f32_e32 v77, v77, v161
	v_cvt_pk_bf16_f32 v83, v78, v79
	v_cvt_pk_bf16_f32 v82, v76, v77
	global_store_dwordx4 v[88:89], v[76:79], off
	global_store_dwordx2 v[86:87], v[82:83], off
	s_nop 0
	v_mul_f32_e32 v77, v77, v77
	v_mul_f32_e32 v79, v79, v79
	v_fmac_f32_e32 v77, v76, v76
	v_fmac_f32_e32 v79, v78, v78
	v_add_f32_e32 v76, v77, v79
	s_waitcnt vmcnt(30)
	v_add_f32_e32 v74, v74, v166
	v_add_f32_e32 v75, v75, v167
	v_add_f32_e32 v72, v72, v164
	v_add_f32_e32 v73, v73, v165
	v_cvt_pk_bf16_f32 v83, v74, v75
	v_cvt_pk_bf16_f32 v82, v72, v73
	global_store_dwordx4 v[88:89], v[72:75], off offset:64
	global_store_dwordx2 v[86:87], v[82:83], off offset:32
	s_nop 0
	v_mul_f32_e32 v73, v73, v73
	v_mul_f32_e32 v75, v75, v75
	v_fmac_f32_e32 v73, v72, v72
	v_fmac_f32_e32 v75, v74, v74
	v_add_f32_e32 v72, v73, v75
	v_add_f32_e32 v72, v76, v72
	s_waitcnt vmcnt(31)
	v_add_f32_e32 v70, v70, v170
	v_add_f32_e32 v71, v71, v171
	v_add_f32_e32 v68, v68, v168
	v_add_f32_e32 v69, v69, v169
	v_cvt_pk_bf16_f32 v83, v70, v71
	v_cvt_pk_bf16_f32 v82, v68, v69
	global_store_dwordx4 v[88:89], v[68:71], off offset:512
	global_store_dwordx2 v[86:87], v[82:83], off offset:256
	s_nop 0
	v_mul_f32_e32 v69, v69, v69
	v_mul_f32_e32 v71, v71, v71
	v_fmac_f32_e32 v69, v68, v68
	v_fmac_f32_e32 v71, v70, v70
	v_add_f32_e32 v68, v69, v71
	v_add_f32_e32 v70, v72, v68
	s_waitcnt vmcnt(32)
	v_add_f32_e32 v68, v66, v174
	v_add_f32_e32 v69, v67, v175
	v_add_f32_e32 v66, v64, v172
	v_add_f32_e32 v67, v65, v173
	v_add_u32_e32 v209, 0x140000, v208
	global_load_dwordx4 v[160:163], v209, s[16:17]
	global_load_dwordx4 v[164:167], v209, s[16:17] offset:64
	global_load_dwordx4 v[168:171], v209, s[16:17] offset:512
	global_load_dwordx4 v[172:175], v209, s[16:17] offset:576
	v_mul_f32_e32 v65, v69, v69
	v_mul_f32_e32 v64, v67, v67
	v_fmac_f32_e32 v64, v66, v66
	v_fmac_f32_e32 v65, v68, v68
	v_add_f32_e32 v64, v64, v65
	v_add_f32_e32 v64, v70, v64
	ds_bpermute_b32 v65, v147, v64
	global_store_dwordx4 v[88:89], v[66:69], off offset:576
	s_waitcnt lgkmcnt(0)
	v_add_f32_e32 v64, v64, v65
	ds_bpermute_b32 v65, v148, v64
	v_cvt_pk_bf16_f32 v66, v66, v67
	v_cvt_pk_bf16_f32 v67, v68, v69
	global_store_dwordx2 v[86:87], v[66:67], off offset:288
	s_and_saveexec_b64 s[62:63], s[6:7]
	s_cbranch_execz .LBB0_2724
	v_lshlrev_b64 v[66:67], 7, v[80:81]
	v_lshl_add_u64 v[66:67], s[52:53], 0, v[66:67]
	v_lshl_add_u64 v[66:67], s[56:57], 2, v[66:67]
	s_lshl_b32 s18, s3, 2
	v_lshl_add_u64 v[66:67], v[66:67], 0, s[18:19]
	s_waitcnt lgkmcnt(0)
	v_add_f32_e32 v64, v64, v65
	global_store_dword v[66:67], v64, off
.LBB0_2724:
	s_or_b64 exec, exec, s[62:63]
	v_add_u32_e32 v64, 0x80, v142
	s_waitcnt lgkmcnt(0)
	v_ashrrev_i32_e32 v65, 31, v64
	v_lshlrev_b64 v[66:67], 11, v[64:65]
	v_lshl_add_u64 v[70:71], v[66:67], 0, v[140:141]
	v_lshl_add_u64 v[72:73], v[70:71], 2, s[16:17]
	s_nop 0
	v_lshl_add_u64 v[70:71], v[70:71], 1, s[54:55]
	s_waitcnt vmcnt(29)
	v_add_f32_e32 v62, v62, v178
	v_add_f32_e32 v63, v63, v179
	v_add_f32_e32 v60, v60, v176
	v_add_f32_e32 v61, v61, v177
	v_cvt_pk_bf16_f32 v67, v62, v63
	v_cvt_pk_bf16_f32 v66, v60, v61
	global_store_dwordx4 v[72:73], v[60:63], off
	global_store_dwordx2 v[70:71], v[66:67], off
	s_nop 0
	v_mul_f32_e32 v61, v61, v61
	v_mul_f32_e32 v63, v63, v63
	v_fmac_f32_e32 v61, v60, v60
	v_fmac_f32_e32 v63, v62, v62
	v_add_f32_e32 v60, v61, v63
	s_waitcnt vmcnt(30)
	v_add_f32_e32 v58, v58, v182
	v_add_f32_e32 v59, v59, v183
	v_add_f32_e32 v56, v56, v180
	v_add_f32_e32 v57, v57, v181
	v_cvt_pk_bf16_f32 v67, v58, v59
	v_cvt_pk_bf16_f32 v66, v56, v57
	global_store_dwordx4 v[72:73], v[56:59], off offset:64
	global_store_dwordx2 v[70:71], v[66:67], off offset:32
	s_nop 0
	v_mul_f32_e32 v57, v57, v57
	v_mul_f32_e32 v59, v59, v59
	v_fmac_f32_e32 v57, v56, v56
	v_fmac_f32_e32 v59, v58, v58
	v_add_f32_e32 v56, v57, v59
	v_add_f32_e32 v56, v60, v56
	s_waitcnt vmcnt(31)
	v_add_f32_e32 v54, v54, v186
	v_add_f32_e32 v55, v55, v187
	v_add_f32_e32 v52, v52, v184
	v_add_f32_e32 v53, v53, v185
	v_cvt_pk_bf16_f32 v67, v54, v55
	v_cvt_pk_bf16_f32 v66, v52, v53
	global_store_dwordx4 v[72:73], v[52:55], off offset:512
	global_store_dwordx2 v[70:71], v[66:67], off offset:256
	s_nop 0
	v_mul_f32_e32 v53, v53, v53
	v_mul_f32_e32 v55, v55, v55
	v_fmac_f32_e32 v53, v52, v52
	v_fmac_f32_e32 v55, v54, v54
	v_add_f32_e32 v52, v53, v55
	v_add_f32_e32 v54, v56, v52
	s_waitcnt vmcnt(32)
	v_add_f32_e32 v52, v50, v190
	v_add_f32_e32 v53, v51, v191
	v_add_f32_e32 v50, v48, v188
	v_add_f32_e32 v51, v49, v189
	v_add_u32_e32 v209, 0x160000, v208
	global_load_dwordx4 v[176:179], v209, s[16:17]
	global_load_dwordx4 v[180:183], v209, s[16:17] offset:64
	global_load_dwordx4 v[184:187], v209, s[16:17] offset:512
	global_load_dwordx4 v[188:191], v209, s[16:17] offset:576
	v_mul_f32_e32 v49, v53, v53
	v_mul_f32_e32 v48, v51, v51
	v_fmac_f32_e32 v48, v50, v50
	v_fmac_f32_e32 v49, v52, v52
	v_add_f32_e32 v48, v48, v49
	v_add_f32_e32 v48, v54, v48
	ds_bpermute_b32 v49, v147, v48
	global_store_dwordx4 v[72:73], v[50:53], off offset:576
	s_waitcnt lgkmcnt(0)
	v_add_f32_e32 v48, v48, v49
	ds_bpermute_b32 v49, v148, v48
	v_cvt_pk_bf16_f32 v50, v50, v51
	v_cvt_pk_bf16_f32 v51, v52, v53
	global_store_dwordx2 v[70:71], v[50:51], off offset:288
	s_and_saveexec_b64 s[62:63], s[6:7]
	s_cbranch_execz .LBB0_2726
	v_lshlrev_b64 v[50:51], 7, v[64:65]
	v_lshl_add_u64 v[50:51], s[52:53], 0, v[50:51]
	v_lshl_add_u64 v[50:51], s[56:57], 2, v[50:51]
	s_lshl_b32 s18, s3, 2
	v_lshl_add_u64 v[50:51], v[50:51], 0, s[18:19]
	s_waitcnt lgkmcnt(0)
	v_add_f32_e32 v48, v48, v49
	global_store_dword v[50:51], v48, off
.LBB0_2726:
	s_or_b64 exec, exec, s[62:63]
	v_add_u32_e32 v48, 0x90, v142
	s_waitcnt lgkmcnt(0)
	v_ashrrev_i32_e32 v49, 31, v48
	v_lshlrev_b64 v[50:51], 11, v[48:49]
	v_lshl_add_u64 v[54:55], v[50:51], 0, v[140:141]
	v_lshl_add_u64 v[56:57], v[54:55], 2, s[16:17]
	s_nop 0
	v_lshl_add_u64 v[54:55], v[54:55], 1, s[54:55]
	s_waitcnt vmcnt(29)
	v_add_f32_e32 v46, v46, v194
	v_add_f32_e32 v47, v47, v195
	v_add_f32_e32 v44, v44, v192
	v_add_f32_e32 v45, v45, v193
	v_cvt_pk_bf16_f32 v51, v46, v47
	v_cvt_pk_bf16_f32 v50, v44, v45
	global_store_dwordx4 v[56:57], v[44:47], off
	global_store_dwordx2 v[54:55], v[50:51], off
	s_nop 0
	v_mul_f32_e32 v45, v45, v45
	v_mul_f32_e32 v47, v47, v47
	v_fmac_f32_e32 v45, v44, v44
	v_fmac_f32_e32 v47, v46, v46
	v_add_f32_e32 v44, v45, v47
	s_waitcnt vmcnt(30)
	v_add_f32_e32 v42, v42, v198
	v_add_f32_e32 v43, v43, v199
	v_add_f32_e32 v40, v40, v196
	v_add_f32_e32 v41, v41, v197
	v_cvt_pk_bf16_f32 v51, v42, v43
	v_cvt_pk_bf16_f32 v50, v40, v41
	global_store_dwordx4 v[56:57], v[40:43], off offset:64
	global_store_dwordx2 v[54:55], v[50:51], off offset:32
	s_nop 0
	v_mul_f32_e32 v41, v41, v41
	v_mul_f32_e32 v43, v43, v43
	v_fmac_f32_e32 v41, v40, v40
	v_fmac_f32_e32 v43, v42, v42
	v_add_f32_e32 v40, v41, v43
	v_add_f32_e32 v40, v44, v40
	s_waitcnt vmcnt(31)
	v_add_f32_e32 v38, v38, v202
	v_add_f32_e32 v39, v39, v203
	v_add_f32_e32 v36, v36, v200
	v_add_f32_e32 v37, v37, v201
	v_cvt_pk_bf16_f32 v51, v38, v39
	v_cvt_pk_bf16_f32 v50, v36, v37
	global_store_dwordx4 v[56:57], v[36:39], off offset:512
	global_store_dwordx2 v[54:55], v[50:51], off offset:256
	s_nop 0
	v_mul_f32_e32 v37, v37, v37
	v_mul_f32_e32 v39, v39, v39
	v_fmac_f32_e32 v37, v36, v36
	v_fmac_f32_e32 v39, v38, v38
	v_add_f32_e32 v36, v37, v39
	v_add_f32_e32 v38, v40, v36
	s_waitcnt vmcnt(32)
	v_add_f32_e32 v36, v34, v206
	v_add_f32_e32 v37, v35, v207
	v_add_f32_e32 v34, v32, v204
	v_add_f32_e32 v35, v33, v205
	v_mul_f32_e32 v33, v37, v37
	v_mul_f32_e32 v32, v35, v35
	v_fmac_f32_e32 v32, v34, v34
	v_fmac_f32_e32 v33, v36, v36
	v_add_f32_e32 v32, v32, v33
	v_add_f32_e32 v32, v38, v32
	ds_bpermute_b32 v33, v147, v32
	global_store_dwordx4 v[56:57], v[34:37], off offset:576
	s_waitcnt lgkmcnt(0)
	v_add_f32_e32 v32, v32, v33
	ds_bpermute_b32 v33, v148, v32
	v_cvt_pk_bf16_f32 v34, v34, v35
	v_cvt_pk_bf16_f32 v35, v36, v37
	global_store_dwordx2 v[54:55], v[34:35], off offset:288
	s_and_saveexec_b64 s[62:63], s[6:7]
	s_cbranch_execz .LBB0_2728
	v_lshlrev_b64 v[34:35], 7, v[48:49]
	v_lshl_add_u64 v[34:35], s[52:53], 0, v[34:35]
	v_lshl_add_u64 v[34:35], s[56:57], 2, v[34:35]
	s_lshl_b32 s18, s3, 2
	v_lshl_add_u64 v[34:35], v[34:35], 0, s[18:19]
	s_waitcnt lgkmcnt(0)
	v_add_f32_e32 v32, v32, v33
	global_store_dword v[34:35], v32, off
.LBB0_2728:
	s_or_b64 exec, exec, s[62:63]
	v_add_u32_e32 v32, 0xa0, v142
	s_waitcnt lgkmcnt(0)
	v_ashrrev_i32_e32 v33, 31, v32
	v_lshlrev_b64 v[34:35], 11, v[32:33]
	v_lshl_add_u64 v[38:39], v[34:35], 0, v[140:141]
	v_lshl_add_u64 v[40:41], v[38:39], 2, s[16:17]
	s_nop 0
	v_lshl_add_u64 v[38:39], v[38:39], 1, s[54:55]
	s_waitcnt vmcnt(25)
	v_add_f32_e32 v30, v30, v162
	v_add_f32_e32 v31, v31, v163
	v_add_f32_e32 v28, v28, v160
	v_add_f32_e32 v29, v29, v161
	v_cvt_pk_bf16_f32 v35, v30, v31
	v_cvt_pk_bf16_f32 v34, v28, v29
	global_store_dwordx4 v[40:41], v[28:31], off
	global_store_dwordx2 v[38:39], v[34:35], off
	s_nop 0
	v_mul_f32_e32 v29, v29, v29
	v_mul_f32_e32 v31, v31, v31
	v_fmac_f32_e32 v29, v28, v28
	v_fmac_f32_e32 v31, v30, v30
	v_add_f32_e32 v28, v29, v31
	s_waitcnt vmcnt(26)
	v_add_f32_e32 v26, v26, v166
	v_add_f32_e32 v27, v27, v167
	v_add_f32_e32 v24, v24, v164
	v_add_f32_e32 v25, v25, v165
	v_cvt_pk_bf16_f32 v35, v26, v27
	v_cvt_pk_bf16_f32 v34, v24, v25
	global_store_dwordx4 v[40:41], v[24:27], off offset:64
	global_store_dwordx2 v[38:39], v[34:35], off offset:32
	s_nop 0
	v_mul_f32_e32 v25, v25, v25
	v_mul_f32_e32 v27, v27, v27
	v_fmac_f32_e32 v25, v24, v24
	v_fmac_f32_e32 v27, v26, v26
	v_add_f32_e32 v24, v25, v27
	v_add_f32_e32 v24, v28, v24
	s_waitcnt vmcnt(27)
	v_add_f32_e32 v22, v22, v170
	v_add_f32_e32 v23, v23, v171
	v_add_f32_e32 v20, v20, v168
	v_add_f32_e32 v21, v21, v169
	v_cvt_pk_bf16_f32 v35, v22, v23
	v_cvt_pk_bf16_f32 v34, v20, v21
	global_store_dwordx4 v[40:41], v[20:23], off offset:512
	global_store_dwordx2 v[38:39], v[34:35], off offset:256
	s_nop 0
	v_mul_f32_e32 v21, v21, v21
	v_mul_f32_e32 v23, v23, v23
	v_fmac_f32_e32 v21, v20, v20
	v_fmac_f32_e32 v23, v22, v22
	v_add_f32_e32 v20, v21, v23
	v_add_f32_e32 v22, v24, v20
	s_waitcnt vmcnt(28)
	v_add_f32_e32 v20, v18, v174
	v_add_f32_e32 v21, v19, v175
	v_add_f32_e32 v18, v16, v172
	v_add_f32_e32 v19, v17, v173
	v_mul_f32_e32 v17, v21, v21
	v_mul_f32_e32 v16, v19, v19
	v_fmac_f32_e32 v16, v18, v18
	v_fmac_f32_e32 v17, v20, v20
	v_add_f32_e32 v16, v16, v17
	v_add_f32_e32 v16, v22, v16
	ds_bpermute_b32 v17, v147, v16
	global_store_dwordx4 v[40:41], v[18:21], off offset:576
	s_waitcnt lgkmcnt(0)
	v_add_f32_e32 v16, v16, v17
	ds_bpermute_b32 v17, v148, v16
	v_cvt_pk_bf16_f32 v18, v18, v19
	v_cvt_pk_bf16_f32 v19, v20, v21
	global_store_dwordx2 v[38:39], v[18:19], off offset:288
	s_and_saveexec_b64 s[62:63], s[6:7]
	s_cbranch_execz .LBB0_2730
	v_lshlrev_b64 v[18:19], 7, v[32:33]
	v_lshl_add_u64 v[18:19], s[52:53], 0, v[18:19]
	v_lshl_add_u64 v[18:19], s[56:57], 2, v[18:19]
	s_lshl_b32 s18, s3, 2
	v_lshl_add_u64 v[18:19], v[18:19], 0, s[18:19]
	s_waitcnt lgkmcnt(0)
	v_add_f32_e32 v16, v16, v17
	global_store_dword v[18:19], v16, off
.LBB0_2730:
	s_or_b64 exec, exec, s[62:63]
	v_add_u32_e32 v16, 0xb0, v142
	s_waitcnt lgkmcnt(0)
	v_ashrrev_i32_e32 v17, 31, v16
	v_lshlrev_b64 v[18:19], 11, v[16:17]
	v_lshl_add_u64 v[22:23], v[18:19], 0, v[140:141]
	v_lshl_add_u64 v[24:25], v[22:23], 2, s[16:17]
	s_nop 0
	v_lshl_add_u64 v[22:23], v[22:23], 1, s[54:55]
	s_waitcnt vmcnt(21)
	v_add_f32_e32 v14, v14, v178
	v_add_f32_e32 v15, v15, v179
	v_add_f32_e32 v12, v12, v176
	v_add_f32_e32 v13, v13, v177
	v_cvt_pk_bf16_f32 v19, v14, v15
	v_cvt_pk_bf16_f32 v18, v12, v13
	global_store_dwordx4 v[24:25], v[12:15], off
	global_store_dwordx2 v[22:23], v[18:19], off
	s_nop 0
	v_mul_f32_e32 v13, v13, v13
	v_mul_f32_e32 v15, v15, v15
	v_fmac_f32_e32 v13, v12, v12
	v_fmac_f32_e32 v15, v14, v14
	v_add_f32_e32 v12, v13, v15
	s_waitcnt vmcnt(22)
	v_add_f32_e32 v10, v10, v182
	v_add_f32_e32 v11, v11, v183
	v_add_f32_e32 v8, v8, v180
	v_add_f32_e32 v9, v9, v181
	v_cvt_pk_bf16_f32 v19, v10, v11
	v_cvt_pk_bf16_f32 v18, v8, v9
	global_store_dwordx4 v[24:25], v[8:11], off offset:64
	global_store_dwordx2 v[22:23], v[18:19], off offset:32
	s_nop 0
	v_mul_f32_e32 v9, v9, v9
	v_mul_f32_e32 v11, v11, v11
	v_fmac_f32_e32 v9, v8, v8
	v_fmac_f32_e32 v11, v10, v10
	v_add_f32_e32 v8, v9, v11
	v_add_f32_e32 v8, v12, v8
	s_waitcnt vmcnt(23)
	v_add_f32_e32 v6, v6, v186
	v_add_f32_e32 v7, v7, v187
	v_add_f32_e32 v4, v4, v184
	v_add_f32_e32 v5, v5, v185
	v_cvt_pk_bf16_f32 v19, v6, v7
	v_cvt_pk_bf16_f32 v18, v4, v5
	global_store_dwordx4 v[24:25], v[4:7], off offset:512
	global_store_dwordx2 v[22:23], v[18:19], off offset:256
	s_nop 0
	v_mul_f32_e32 v5, v5, v5
	v_mul_f32_e32 v7, v7, v7
	v_fmac_f32_e32 v5, v4, v4
	v_fmac_f32_e32 v7, v6, v6
	v_add_f32_e32 v4, v5, v7
	v_add_f32_e32 v6, v8, v4
	s_waitcnt vmcnt(24)
	v_add_f32_e32 v4, v2, v190
	v_add_f32_e32 v5, v3, v191
	v_add_f32_e32 v2, v0, v188
	v_add_f32_e32 v3, v1, v189
	v_mul_f32_e32 v1, v5, v5
	v_mul_f32_e32 v0, v3, v3
	v_fmac_f32_e32 v0, v2, v2
	v_fmac_f32_e32 v1, v4, v4
	v_add_f32_e32 v0, v0, v1
	v_add_f32_e32 v0, v6, v0
	ds_bpermute_b32 v1, v147, v0
	global_store_dwordx4 v[24:25], v[2:5], off offset:576
	s_waitcnt lgkmcnt(0)
	v_add_f32_e32 v0, v0, v1
	ds_bpermute_b32 v1, v148, v0
	v_cvt_pk_bf16_f32 v2, v2, v3
	v_cvt_pk_bf16_f32 v3, v4, v5
	global_store_dwordx2 v[22:23], v[2:3], off offset:288
	s_and_saveexec_b64 s[62:63], s[6:7]
	s_cbranch_execz .LBB0_2732
	v_lshlrev_b64 v[2:3], 7, v[16:17]
	v_lshl_add_u64 v[2:3], s[52:53], 0, v[2:3]
	v_lshl_add_u64 v[2:3], s[56:57], 2, v[2:3]
	s_lshl_b32 s18, s3, 2
	v_lshl_add_u64 v[2:3], v[2:3], 0, s[18:19]
	s_waitcnt lgkmcnt(0)
	v_add_f32_e32 v0, v0, v1
	global_store_dword v[2:3], v0, off

.LBB0_2808:
	v_lshl_add_u32 v148, s44, 8, v150
	v_ashrrev_i32_e32 v149, 31, v148
	v_lshlrev_b64 v[146:147], 7, v[148:149]
	v_lshl_add_u64 v[146:147], s[52:53], 0, v[146:147]
	v_mov_b32_e32 v159, 0
	v_lshl_add_u64 v[146:147], v[136:137], 4, v[146:147]
	s_and_saveexec_b64 s[44:45], s[6:7]
	s_cbranch_execz .LBB0_2810
	global_load_dwordx4 v[160:163], v[146:147], off
	s_waitcnt vmcnt(0)
	v_mov_b32_e32 v164, v161
	v_mov_b32_e32 v165, v162
	v_mov_b32_e32 v161, v163
	v_add_f32_e32 v160, v164, v160
	v_add_f32_e32 v161, v165, v161
	s_nop 0
	v_add_f32_e32 v159, v160, v161
	v_add_f32_e32 v159, 0, v159
.LBB0_2810:
	s_or_b64 exec, exec, s[44:45]
	s_and_saveexec_b64 s[44:45], s[12:13]
	s_cbranch_execz .LBB0_2812
	global_load_dwordx4 v[160:163], v[146:147], off offset:64
	s_waitcnt vmcnt(0)
	v_mov_b32_e32 v146, v161
	v_mov_b32_e32 v147, v162
	v_mov_b32_e32 v161, v163
	v_add_f32_e32 v146, v146, v160
	v_add_f32_e32 v147, v147, v161
	s_nop 0
	v_add_f32_e32 v146, v146, v147
	v_add_f32_e32 v159, v159, v146
.LBB0_2812:
	s_or_b64 exec, exec, s[44:45]
	ds_bpermute_b32 v146, v153, v159
	v_lshlrev_b64 v[160:161], 14, v[148:149]
	v_lshl_add_u64 v[160:161], s[50:51], 0, v[160:161]
	s_waitcnt lgkmcnt(0)
	v_add_f32_e32 v147, v159, v146
	ds_bpermute_b32 v159, v154, v147
	v_lshl_add_u32 v146, s42, 8, v152
	s_waitcnt lgkmcnt(0)
	v_add_f32_e32 v147, v147, v159
	v_fmamk_f32 v147, v147, 0x3a000000, v158
	v_rsq_f32_e32 v162, v147
	v_ashrrev_i32_e32 v147, 31, v146
	v_lshl_add_u64 v[160:161], v[146:147], 1, v[160:161]
	v_mul_f32_e32 v120, v120, v162
	v_mul_f32_e32 v121, v121, v162
	v_mul_f32_e32 v124, v124, v162
	v_mul_f32_e32 v125, v125, v162
	v_max_f32_e32 v120, 0, v120
	v_mul_f32_e32 v126, v126, v162
	v_mul_f32_e32 v127, v127, v162
	v_mul_f32_e32 v122, v122, v162
	v_mul_f32_e32 v123, v123, v162
	v_max_f32_e32 v125, 0, v125
	v_mul_f32_e32 v149, v120, v120
	v_max_f32_e32 v120, 0, v121
	v_mul_f32_e32 v121, v125, v125
	v_mul_f32_e32 v125, v120, v120
	v_max_f32_e32 v120, 0, v126
	v_max_f32_e32 v122, 0, v122
	v_max_f32_e32 v124, 0, v124
	v_mul_f32_e32 v126, v120, v120
	v_mul_f32_e32 v159, v122, v122
	v_max_f32_e32 v120, 0, v127
	v_max_f32_e32 v122, 0, v123
	v_mul_f32_e32 v124, v124, v124
	v_mul_f32_e32 v123, v120, v120
	v_mul_f32_e32 v127, v122, v122
	v_mul_f32_e32 v114, v114, v162
	v_mul_f32_e32 v115, v115, v162
	v_mul_f32_e32 v112, v112, v162
	v_mul_f32_e32 v113, v113, v162
	v_cvt_pk_bf16_f32 v120, v124, v121
	v_cvt_pk_bf16_f32 v121, v126, v123
	v_cvt_pk_bf16_f32 v122, v149, v125
	v_cvt_pk_bf16_f32 v123, v159, v127
	v_mul_f32_e32 v118, v118, v162
	v_mul_f32_e32 v119, v119, v162
	v_mul_f32_e32 v116, v116, v162
	v_mul_f32_e32 v117, v117, v162
	v_max_f32_e32 v112, 0, v112
	v_max_f32_e32 v113, 0, v113
	v_max_f32_e32 v114, 0, v114
	global_store_dwordx4 v[160:161], v[120:123], off
	v_max_f32_e32 v116, 0, v116
	v_max_f32_e32 v115, 0, v115
	v_mul_f32_e32 v120, v112, v112
	v_max_f32_e32 v112, 0, v117
	v_mul_f32_e32 v117, v113, v113
	v_max_f32_e32 v113, 0, v118
	v_mul_f32_e32 v118, v114, v114
	v_max_f32_e32 v114, 0, v119
	v_mul_f32_e32 v116, v116, v116
	v_mul_f32_e32 v112, v112, v112
	v_mul_f32_e32 v113, v113, v113
	v_mul_f32_e32 v114, v114, v114
	v_mul_f32_e32 v115, v115, v115
	v_cvt_pk_bf16_f32 v112, v116, v112
	v_cvt_pk_bf16_f32 v113, v113, v114
	v_cvt_pk_bf16_f32 v114, v120, v117
	v_cvt_pk_bf16_f32 v115, v118, v115
	global_store_dwordx4 v[160:161], v[112:115], off offset:256
	v_mov_b32_e32 v116, 0
	s_nop 0
	v_or_b32_e32 v112, 16, v148
	v_ashrrev_i32_e32 v113, 31, v112
	v_lshlrev_b64 v[114:115], 7, v[112:113]
	v_lshl_add_u64 v[114:115], s[52:53], 0, v[114:115]
	v_lshl_add_u64 v[114:115], v[136:137], 4, v[114:115]
	s_and_saveexec_b64 s[42:43], s[6:7]
	s_cbranch_execz .LBB0_2814
	global_load_dwordx4 v[116:119], v[114:115], off
	s_waitcnt vmcnt(0)
	v_mov_b32_e32 v120, v117
	v_mov_b32_e32 v121, v118
	v_mov_b32_e32 v117, v119
	v_add_f32_e32 v116, v120, v116
	v_add_f32_e32 v117, v121, v117
	s_nop 0
	v_add_f32_e32 v116, v116, v117
	v_add_f32_e32 v116, 0, v116
.LBB0_2814:
	s_or_b64 exec, exec, s[42:43]
	s_and_saveexec_b64 s[42:43], s[12:13]
	s_cbranch_execz .LBB0_2816
	global_load_dwordx4 v[118:121], v[114:115], off offset:64
	s_waitcnt vmcnt(0)
	v_mov_b32_e32 v114, v119
	v_mov_b32_e32 v115, v120
	v_mov_b32_e32 v119, v121
	v_add_f32_e32 v114, v114, v118
	v_add_f32_e32 v115, v115, v119
	s_nop 0
	v_add_f32_e32 v114, v114, v115
	v_add_f32_e32 v116, v116, v114
.LBB0_2816:
	s_or_b64 exec, exec, s[42:43]
	ds_bpermute_b32 v114, v153, v116
	v_lshlrev_b64 v[112:113], 14, v[112:113]
	v_lshl_add_u64 v[112:113], s[50:51], 0, v[112:113]
	v_lshl_add_u64 v[112:113], v[146:147], 1, v[112:113]
	s_waitcnt lgkmcnt(0)
	v_add_f32_e32 v114, v116, v114
	ds_bpermute_b32 v115, v154, v114
	s_waitcnt lgkmcnt(0)
	v_add_f32_e32 v114, v114, v115
	v_fmamk_f32 v114, v114, 0x3a000000, v158
	v_rsq_f32_e32 v114, v114
	s_nop 0
	v_mul_f32_e32 v108, v108, v114
	v_mul_f32_e32 v109, v109, v114
	v_mul_f32_e32 v106, v106, v114
	v_mul_f32_e32 v107, v107, v114
	v_mul_f32_e32 v104, v104, v114
	v_mul_f32_e32 v105, v105, v114
	v_mul_f32_e32 v110, v110, v114
	v_mul_f32_e32 v111, v111, v114
	v_max_f32_e32 v104, 0, v104
	v_max_f32_e32 v109, 0, v109
	v_max_f32_e32 v105, 0, v105
	v_max_f32_e32 v106, 0, v106
	v_max_f32_e32 v108, 0, v108
	v_mul_f32_e32 v115, v104, v104
	v_mul_f32_e32 v104, v109, v109
	v_mul_f32_e32 v109, v105, v105
	v_max_f32_e32 v105, 0, v110
	v_mul_f32_e32 v110, v106, v106
	v_max_f32_e32 v106, 0, v111
	v_max_f32_e32 v107, 0, v107
	v_mul_f32_e32 v108, v108, v108
	v_mul_f32_e32 v105, v105, v105
	v_mul_f32_e32 v106, v106, v106
	v_mul_f32_e32 v107, v107, v107
	v_mul_f32_e32 v98, v98, v114
	v_mul_f32_e32 v99, v99, v114
	v_mul_f32_e32 v96, v96, v114
	v_mul_f32_e32 v97, v97, v114
	v_cvt_pk_bf16_f32 v104, v108, v104
	v_cvt_pk_bf16_f32 v105, v105, v106
	v_cvt_pk_bf16_f32 v106, v115, v109
	v_cvt_pk_bf16_f32 v107, v110, v107
	v_mul_f32_e32 v102, v102, v114
	v_mul_f32_e32 v103, v103, v114
	v_mul_f32_e32 v100, v100, v114
	v_mul_f32_e32 v101, v101, v114
	v_max_f32_e32 v96, 0, v96
	v_max_f32_e32 v97, 0, v97
	v_max_f32_e32 v98, 0, v98
	global_store_dwordx4 v[112:113], v[104:107], off
	v_max_f32_e32 v100, 0, v100
	v_max_f32_e32 v99, 0, v99
	v_mul_f32_e32 v104, v96, v96
	v_max_f32_e32 v96, 0, v101
	v_mul_f32_e32 v101, v97, v97
	v_max_f32_e32 v97, 0, v102
	v_mul_f32_e32 v102, v98, v98
	v_max_f32_e32 v98, 0, v103
	v_mul_f32_e32 v100, v100, v100
	v_mul_f32_e32 v96, v96, v96
	v_mul_f32_e32 v97, v97, v97
	v_mul_f32_e32 v98, v98, v98
	v_mul_f32_e32 v99, v99, v99
	v_cvt_pk_bf16_f32 v96, v100, v96
	v_cvt_pk_bf16_f32 v97, v97, v98
	v_cvt_pk_bf16_f32 v98, v104, v101
	v_cvt_pk_bf16_f32 v99, v102, v99
	global_store_dwordx4 v[112:113], v[96:99], off offset:256
	v_mov_b32_e32 v100, 0
	s_nop 0
	v_or_b32_e32 v96, 32, v148
	v_ashrrev_i32_e32 v97, 31, v96
	v_lshlrev_b64 v[98:99], 7, v[96:97]
	v_lshl_add_u64 v[98:99], s[52:53], 0, v[98:99]
	v_lshl_add_u64 v[98:99], v[136:137], 4, v[98:99]
	s_and_saveexec_b64 s[42:43], s[6:7]
	s_cbranch_execz .LBB0_2818
	global_load_dwordx4 v[100:103], v[98:99], off
	s_waitcnt vmcnt(0)
	v_mov_b32_e32 v104, v101
	v_mov_b32_e32 v105, v102
	v_mov_b32_e32 v101, v103
	v_add_f32_e32 v100, v104, v100
	v_add_f32_e32 v101, v105, v101
	s_nop 0
	v_add_f32_e32 v100, v100, v101
	v_add_f32_e32 v100, 0, v100
.LBB0_2818:
	s_or_b64 exec, exec, s[42:43]
	s_and_saveexec_b64 s[42:43], s[12:13]
	s_cbranch_execz .LBB0_2820
	global_load_dwordx4 v[102:105], v[98:99], off offset:64
	s_waitcnt vmcnt(0)
	v_mov_b32_e32 v98, v103
	v_mov_b32_e32 v99, v104
	v_mov_b32_e32 v103, v105
	v_add_f32_e32 v98, v98, v102
	v_add_f32_e32 v99, v99, v103
	s_nop 0
	v_add_f32_e32 v98, v98, v99
	v_add_f32_e32 v100, v100, v98
.LBB0_2820:
	s_or_b64 exec, exec, s[42:43]
	ds_bpermute_b32 v98, v153, v100
	v_lshlrev_b64 v[96:97], 14, v[96:97]
	v_lshl_add_u64 v[96:97], s[50:51], 0, v[96:97]
	v_lshl_add_u64 v[96:97], v[146:147], 1, v[96:97]
	s_waitcnt lgkmcnt(0)
	v_add_f32_e32 v98, v100, v98
	ds_bpermute_b32 v99, v154, v98
	s_waitcnt lgkmcnt(0)
	v_add_f32_e32 v98, v98, v99
	v_fmamk_f32 v98, v98, 0x3a000000, v158
	v_rsq_f32_e32 v98, v98
	s_nop 0
	v_mul_f32_e32 v92, v92, v98
	v_mul_f32_e32 v93, v93, v98
	v_mul_f32_e32 v90, v90, v98
	v_mul_f32_e32 v91, v91, v98
	v_mul_f32_e32 v88, v88, v98
	v_mul_f32_e32 v89, v89, v98
	v_mul_f32_e32 v94, v94, v98
	v_mul_f32_e32 v95, v95, v98
	v_max_f32_e32 v88, 0, v88
	v_max_f32_e32 v93, 0, v93
	v_max_f32_e32 v89, 0, v89
	v_max_f32_e32 v90, 0, v90
	v_max_f32_e32 v92, 0, v92
	v_mul_f32_e32 v99, v88, v88
	v_mul_f32_e32 v88, v93, v93
	v_mul_f32_e32 v93, v89, v89
	v_max_f32_e32 v89, 0, v94
	v_mul_f32_e32 v94, v90, v90
	v_max_f32_e32 v90, 0, v95
	v_max_f32_e32 v91, 0, v91
	v_mul_f32_e32 v92, v92, v92
	v_mul_f32_e32 v89, v89, v89
	v_mul_f32_e32 v90, v90, v90
	v_mul_f32_e32 v91, v91, v91
	v_mul_f32_e32 v82, v82, v98
	v_mul_f32_e32 v83, v83, v98
	v_mul_f32_e32 v80, v80, v98
	v_mul_f32_e32 v81, v81, v98
	v_cvt_pk_bf16_f32 v88, v92, v88
	v_cvt_pk_bf16_f32 v89, v89, v90
	v_cvt_pk_bf16_f32 v90, v99, v93
	v_cvt_pk_bf16_f32 v91, v94, v91
	v_mul_f32_e32 v86, v86, v98
	v_mul_f32_e32 v87, v87, v98
	v_mul_f32_e32 v84, v84, v98
	v_mul_f32_e32 v85, v85, v98
	v_max_f32_e32 v80, 0, v80
	v_max_f32_e32 v81, 0, v81
	v_max_f32_e32 v82, 0, v82
	global_store_dwordx4 v[96:97], v[88:91], off
	v_max_f32_e32 v84, 0, v84
	v_max_f32_e32 v83, 0, v83
	v_mul_f32_e32 v88, v80, v80
	v_max_f32_e32 v80, 0, v85
	v_mul_f32_e32 v85, v81, v81
	v_max_f32_e32 v81, 0, v86
	v_mul_f32_e32 v86, v82, v82
	v_max_f32_e32 v82, 0, v87
	v_mul_f32_e32 v84, v84, v84
	v_mul_f32_e32 v80, v80, v80
	v_mul_f32_e32 v81, v81, v81
	v_mul_f32_e32 v82, v82, v82
	v_mul_f32_e32 v83, v83, v83
	v_cvt_pk_bf16_f32 v80, v84, v80
	v_cvt_pk_bf16_f32 v81, v81, v82
	v_cvt_pk_bf16_f32 v82, v88, v85
	v_cvt_pk_bf16_f32 v83, v86, v83
	global_store_dwordx4 v[96:97], v[80:83], off offset:256
	v_mov_b32_e32 v84, 0
	s_nop 0
	v_or_b32_e32 v80, 48, v148
	v_ashrrev_i32_e32 v81, 31, v80
	v_lshlrev_b64 v[82:83], 7, v[80:81]
	v_lshl_add_u64 v[82:83], s[52:53], 0, v[82:83]
	v_lshl_add_u64 v[82:83], v[136:137], 4, v[82:83]
	s_and_saveexec_b64 s[42:43], s[6:7]
	s_cbranch_execz .LBB0_2822
	global_load_dwordx4 v[84:87], v[82:83], off
	s_waitcnt vmcnt(0)
	v_mov_b32_e32 v88, v85
	v_mov_b32_e32 v89, v86
	v_mov_b32_e32 v85, v87
	v_add_f32_e32 v84, v88, v84
	v_add_f32_e32 v85, v89, v85
	s_nop 0
	v_add_f32_e32 v84, v84, v85
	v_add_f32_e32 v84, 0, v84
.LBB0_2822:
	s_or_b64 exec, exec, s[42:43]
	s_and_saveexec_b64 s[42:43], s[12:13]
	s_cbranch_execz .LBB0_2824
	global_load_dwordx4 v[86:89], v[82:83], off offset:64
	s_waitcnt vmcnt(0)
	v_mov_b32_e32 v82, v87
	v_mov_b32_e32 v83, v88
	v_mov_b32_e32 v87, v89
	v_add_f32_e32 v82, v82, v86
	v_add_f32_e32 v83, v83, v87
	s_nop 0
	v_add_f32_e32 v82, v82, v83
	v_add_f32_e32 v84, v84, v82
.LBB0_2824:
	s_or_b64 exec, exec, s[42:43]
	ds_bpermute_b32 v82, v153, v84
	v_lshlrev_b64 v[80:81], 14, v[80:81]
	v_lshl_add_u64 v[80:81], s[50:51], 0, v[80:81]
	v_lshl_add_u64 v[80:81], v[146:147], 1, v[80:81]
	s_waitcnt lgkmcnt(0)
	v_add_f32_e32 v82, v84, v82
	ds_bpermute_b32 v83, v154, v82
	s_waitcnt lgkmcnt(0)
	v_add_f32_e32 v82, v82, v83
	v_fmamk_f32 v82, v82, 0x3a000000, v158
	v_rsq_f32_e32 v82, v82
	s_nop 0
	v_mul_f32_e32 v76, v76, v82
	v_mul_f32_e32 v77, v77, v82
	v_mul_f32_e32 v74, v74, v82
	v_mul_f32_e32 v75, v75, v82
	v_mul_f32_e32 v72, v72, v82
	v_mul_f32_e32 v73, v73, v82
	v_mul_f32_e32 v78, v78, v82
	v_mul_f32_e32 v79, v79, v82
	v_max_f32_e32 v72, 0, v72
	v_max_f32_e32 v77, 0, v77
	v_max_f32_e32 v73, 0, v73
	v_max_f32_e32 v74, 0, v74
	v_max_f32_e32 v76, 0, v76
	v_mul_f32_e32 v83, v72, v72
	v_mul_f32_e32 v72, v77, v77
	v_mul_f32_e32 v77, v73, v73
	v_max_f32_e32 v73, 0, v78
	v_mul_f32_e32 v78, v74, v74
	v_max_f32_e32 v74, 0, v79
	v_max_f32_e32 v75, 0, v75
	v_mul_f32_e32 v76, v76, v76
	v_mul_f32_e32 v73, v73, v73
	v_mul_f32_e32 v74, v74, v74
	v_mul_f32_e32 v75, v75, v75
	v_mul_f32_e32 v66, v66, v82
	v_mul_f32_e32 v67, v67, v82
	v_mul_f32_e32 v64, v64, v82
	v_mul_f32_e32 v65, v65, v82
	v_cvt_pk_bf16_f32 v72, v76, v72
	v_cvt_pk_bf16_f32 v73, v73, v74
	v_cvt_pk_bf16_f32 v74, v83, v77
	v_cvt_pk_bf16_f32 v75, v78, v75
	v_mul_f32_e32 v70, v70, v82
	v_mul_f32_e32 v71, v71, v82
	v_mul_f32_e32 v68, v68, v82
	v_mul_f32_e32 v69, v69, v82
	v_max_f32_e32 v64, 0, v64
	v_max_f32_e32 v65, 0, v65
	v_max_f32_e32 v66, 0, v66
	global_store_dwordx4 v[80:81], v[72:75], off
	v_max_f32_e32 v68, 0, v68
	v_max_f32_e32 v67, 0, v67
	v_mul_f32_e32 v72, v64, v64
	v_max_f32_e32 v64, 0, v69
	v_mul_f32_e32 v69, v65, v65
	v_max_f32_e32 v65, 0, v70
	v_mul_f32_e32 v70, v66, v66
	v_max_f32_e32 v66, 0, v71
	v_mul_f32_e32 v68, v68, v68
	v_mul_f32_e32 v64, v64, v64
	v_mul_f32_e32 v65, v65, v65
	v_mul_f32_e32 v66, v66, v66
	v_mul_f32_e32 v67, v67, v67
	v_cvt_pk_bf16_f32 v64, v68, v64
	v_cvt_pk_bf16_f32 v65, v65, v66
	v_cvt_pk_bf16_f32 v66, v72, v69
	v_cvt_pk_bf16_f32 v67, v70, v67
	global_store_dwordx4 v[80:81], v[64:67], off offset:256
	v_mov_b32_e32 v68, 0
	s_nop 0
	v_add_u32_e32 v64, 0x80, v148
	v_ashrrev_i32_e32 v65, 31, v64
	v_lshlrev_b64 v[66:67], 7, v[64:65]
	v_lshl_add_u64 v[66:67], s[52:53], 0, v[66:67]
	v_lshl_add_u64 v[66:67], v[136:137], 4, v[66:67]
	s_and_saveexec_b64 s[42:43], s[6:7]
	s_cbranch_execz .LBB0_2826
	global_load_dwordx4 v[68:71], v[66:67], off
	s_waitcnt vmcnt(0)
	v_mov_b32_e32 v72, v69
	v_mov_b32_e32 v73, v70
	v_mov_b32_e32 v69, v71
	v_add_f32_e32 v68, v72, v68
	v_add_f32_e32 v69, v73, v69
	s_nop 0
	v_add_f32_e32 v68, v68, v69
	v_add_f32_e32 v68, 0, v68
.LBB0_2826:
	s_or_b64 exec, exec, s[42:43]
	s_and_saveexec_b64 s[42:43], s[12:13]
	s_cbranch_execz .LBB0_2828
	global_load_dwordx4 v[70:73], v[66:67], off offset:64
	s_waitcnt vmcnt(0)
	v_mov_b32_e32 v66, v71
	v_mov_b32_e32 v67, v72
	v_mov_b32_e32 v71, v73
	v_add_f32_e32 v66, v66, v70
	v_add_f32_e32 v67, v67, v71
	s_nop 0
	v_add_f32_e32 v66, v66, v67
	v_add_f32_e32 v68, v68, v66
.LBB0_2828:
	s_or_b64 exec, exec, s[42:43]
	ds_bpermute_b32 v66, v153, v68
	v_lshlrev_b64 v[64:65], 14, v[64:65]
	v_lshl_add_u64 v[64:65], s[50:51], 0, v[64:65]
	v_lshl_add_u64 v[64:65], v[146:147], 1, v[64:65]
	s_waitcnt lgkmcnt(0)
	v_add_f32_e32 v66, v68, v66
	ds_bpermute_b32 v67, v154, v66
	s_waitcnt lgkmcnt(0)
	v_add_f32_e32 v66, v66, v67
	v_fmamk_f32 v66, v66, 0x3a000000, v158
	v_rsq_f32_e32 v66, v66
	s_nop 0
	v_mul_f32_e32 v60, v60, v66
	v_mul_f32_e32 v61, v61, v66
	v_mul_f32_e32 v58, v58, v66
	v_mul_f32_e32 v59, v59, v66
	v_mul_f32_e32 v56, v56, v66
	v_mul_f32_e32 v57, v57, v66
	v_mul_f32_e32 v62, v62, v66
	v_mul_f32_e32 v63, v63, v66
	v_max_f32_e32 v56, 0, v56
	v_max_f32_e32 v61, 0, v61
	v_max_f32_e32 v57, 0, v57
	v_max_f32_e32 v58, 0, v58
	v_max_f32_e32 v60, 0, v60
	v_mul_f32_e32 v67, v56, v56
	v_mul_f32_e32 v56, v61, v61
	v_mul_f32_e32 v61, v57, v57
	v_max_f32_e32 v57, 0, v62
	v_mul_f32_e32 v62, v58, v58
	v_max_f32_e32 v58, 0, v63
	v_max_f32_e32 v59, 0, v59
	v_mul_f32_e32 v60, v60, v60
	v_mul_f32_e32 v57, v57, v57
	v_mul_f32_e32 v58, v58, v58
	v_mul_f32_e32 v59, v59, v59
	v_mul_f32_e32 v50, v50, v66
	v_mul_f32_e32 v51, v51, v66
	v_mul_f32_e32 v48, v48, v66
	v_mul_f32_e32 v49, v49, v66
	v_cvt_pk_bf16_f32 v56, v60, v56
	v_cvt_pk_bf16_f32 v57, v57, v58
	v_cvt_pk_bf16_f32 v58, v67, v61
	v_cvt_pk_bf16_f32 v59, v62, v59
	v_mul_f32_e32 v54, v54, v66
	v_mul_f32_e32 v55, v55, v66
	v_mul_f32_e32 v52, v52, v66
	v_mul_f32_e32 v53, v53, v66
	v_max_f32_e32 v48, 0, v48
	v_max_f32_e32 v49, 0, v49
	v_max_f32_e32 v50, 0, v50
	global_store_dwordx4 v[64:65], v[56:59], off
	v_max_f32_e32 v52, 0, v52
	v_max_f32_e32 v51, 0, v51
	v_mul_f32_e32 v56, v48, v48
	v_max_f32_e32 v48, 0, v53
	v_mul_f32_e32 v53, v49, v49
	v_max_f32_e32 v49, 0, v54
	v_mul_f32_e32 v54, v50, v50
	v_max_f32_e32 v50, 0, v55
	v_mul_f32_e32 v52, v52, v52
	v_mul_f32_e32 v48, v48, v48
	v_mul_f32_e32 v49, v49, v49
	v_mul_f32_e32 v50, v50, v50
	v_mul_f32_e32 v51, v51, v51
	v_cvt_pk_bf16_f32 v48, v52, v48
	v_cvt_pk_bf16_f32 v49, v49, v50
	v_cvt_pk_bf16_f32 v50, v56, v53
	v_cvt_pk_bf16_f32 v51, v54, v51
	global_store_dwordx4 v[64:65], v[48:51], off offset:256
	v_mov_b32_e32 v52, 0
	s_nop 0
	v_add_u32_e32 v48, 0x90, v148
	v_ashrrev_i32_e32 v49, 31, v48
	v_lshlrev_b64 v[50:51], 7, v[48:49]
	v_lshl_add_u64 v[50:51], s[52:53], 0, v[50:51]
	v_lshl_add_u64 v[50:51], v[136:137], 4, v[50:51]
	s_and_saveexec_b64 s[42:43], s[6:7]
	s_cbranch_execz .LBB0_2830
	global_load_dwordx4 v[52:55], v[50:51], off
	s_waitcnt vmcnt(0)
	v_mov_b32_e32 v56, v53
	v_mov_b32_e32 v57, v54
	v_mov_b32_e32 v53, v55
	v_add_f32_e32 v52, v56, v52
	v_add_f32_e32 v53, v57, v53
	s_nop 0
	v_add_f32_e32 v52, v52, v53
	v_add_f32_e32 v52, 0, v52
.LBB0_2830:
	s_or_b64 exec, exec, s[42:43]
	s_and_saveexec_b64 s[42:43], s[12:13]
	s_cbranch_execz .LBB0_2832
	global_load_dwordx4 v[54:57], v[50:51], off offset:64
	s_waitcnt vmcnt(0)
	v_mov_b32_e32 v50, v55
	v_mov_b32_e32 v51, v56
	v_mov_b32_e32 v55, v57
	v_add_f32_e32 v50, v50, v54
	v_add_f32_e32 v51, v51, v55
	s_nop 0
	v_add_f32_e32 v50, v50, v51
	v_add_f32_e32 v52, v52, v50
.LBB0_2832:
	s_or_b64 exec, exec, s[42:43]
	ds_bpermute_b32 v50, v153, v52
	v_lshlrev_b64 v[48:49], 14, v[48:49]
	v_lshl_add_u64 v[48:49], s[50:51], 0, v[48:49]
	v_lshl_add_u64 v[48:49], v[146:147], 1, v[48:49]
	s_waitcnt lgkmcnt(0)
	v_add_f32_e32 v50, v52, v50
	ds_bpermute_b32 v51, v154, v50
	s_waitcnt lgkmcnt(0)
	v_add_f32_e32 v50, v50, v51
	v_fmamk_f32 v50, v50, 0x3a000000, v158
	v_rsq_f32_e32 v50, v50
	s_nop 0
	v_mul_f32_e32 v44, v44, v50
	v_mul_f32_e32 v45, v45, v50
	v_mul_f32_e32 v42, v42, v50
	v_mul_f32_e32 v43, v43, v50
	v_mul_f32_e32 v40, v40, v50
	v_mul_f32_e32 v41, v41, v50
	v_mul_f32_e32 v46, v46, v50
	v_mul_f32_e32 v47, v47, v50
	v_max_f32_e32 v40, 0, v40
	v_max_f32_e32 v45, 0, v45
	v_max_f32_e32 v41, 0, v41
	v_max_f32_e32 v42, 0, v42
	v_max_f32_e32 v44, 0, v44
	v_mul_f32_e32 v51, v40, v40
	v_mul_f32_e32 v40, v45, v45
	v_mul_f32_e32 v45, v41, v41
	v_max_f32_e32 v41, 0, v46
	v_mul_f32_e32 v46, v42, v42
	v_max_f32_e32 v42, 0, v47
	v_max_f32_e32 v43, 0, v43
	v_mul_f32_e32 v44, v44, v44
	v_mul_f32_e32 v41, v41, v41
	v_mul_f32_e32 v42, v42, v42
	v_mul_f32_e32 v43, v43, v43
	v_mul_f32_e32 v34, v34, v50
	v_mul_f32_e32 v35, v35, v50
	v_mul_f32_e32 v32, v32, v50
	v_mul_f32_e32 v33, v33, v50
	v_cvt_pk_bf16_f32 v40, v44, v40
	v_cvt_pk_bf16_f32 v41, v41, v42
	v_cvt_pk_bf16_f32 v42, v51, v45
	v_cvt_pk_bf16_f32 v43, v46, v43
	v_mul_f32_e32 v38, v38, v50
	v_mul_f32_e32 v39, v39, v50
	v_mul_f32_e32 v36, v36, v50
	v_mul_f32_e32 v37, v37, v50
	v_max_f32_e32 v32, 0, v32
	v_max_f32_e32 v33, 0, v33
	v_max_f32_e32 v34, 0, v34
	global_store_dwordx4 v[48:49], v[40:43], off
	v_max_f32_e32 v36, 0, v36
	v_max_f32_e32 v35, 0, v35
	v_mul_f32_e32 v40, v32, v32
	v_max_f32_e32 v32, 0, v37
	v_mul_f32_e32 v37, v33, v33
	v_max_f32_e32 v33, 0, v38
	v_mul_f32_e32 v38, v34, v34
	v_max_f32_e32 v34, 0, v39
	v_mul_f32_e32 v36, v36, v36
	v_mul_f32_e32 v32, v32, v32
	v_mul_f32_e32 v33, v33, v33
	v_mul_f32_e32 v34, v34, v34
	v_mul_f32_e32 v35, v35, v35
	v_cvt_pk_bf16_f32 v32, v36, v32
	v_cvt_pk_bf16_f32 v33, v33, v34
	v_cvt_pk_bf16_f32 v34, v40, v37
	v_cvt_pk_bf16_f32 v35, v38, v35
	global_store_dwordx4 v[48:49], v[32:35], off offset:256
	v_mov_b32_e32 v36, 0
	s_nop 0
	v_add_u32_e32 v32, 0xa0, v148
	v_ashrrev_i32_e32 v33, 31, v32
	v_lshlrev_b64 v[34:35], 7, v[32:33]
	v_lshl_add_u64 v[34:35], s[52:53], 0, v[34:35]
	v_lshl_add_u64 v[34:35], v[136:137], 4, v[34:35]
	s_and_saveexec_b64 s[42:43], s[6:7]
	s_cbranch_execz .LBB0_2834
	global_load_dwordx4 v[36:39], v[34:35], off
	s_waitcnt vmcnt(0)
	v_mov_b32_e32 v40, v37
	v_mov_b32_e32 v41, v38
	v_mov_b32_e32 v37, v39
	v_add_f32_e32 v36, v40, v36
	v_add_f32_e32 v37, v41, v37
	s_nop 0
	v_add_f32_e32 v36, v36, v37
	v_add_f32_e32 v36, 0, v36
.LBB0_2834:
	s_or_b64 exec, exec, s[42:43]
	s_and_saveexec_b64 s[42:43], s[12:13]
	s_cbranch_execz .LBB0_2836
	global_load_dwordx4 v[38:41], v[34:35], off offset:64
	s_waitcnt vmcnt(0)
	v_mov_b32_e32 v34, v39
	v_mov_b32_e32 v35, v40
	v_mov_b32_e32 v39, v41
	v_add_f32_e32 v34, v34, v38
	v_add_f32_e32 v35, v35, v39
	s_nop 0
	v_add_f32_e32 v34, v34, v35
	v_add_f32_e32 v36, v36, v34
.LBB0_2836:
	s_or_b64 exec, exec, s[42:43]
	ds_bpermute_b32 v34, v153, v36
	v_lshlrev_b64 v[32:33], 14, v[32:33]
	v_lshl_add_u64 v[32:33], s[50:51], 0, v[32:33]
	v_lshl_add_u64 v[32:33], v[146:147], 1, v[32:33]
	s_waitcnt lgkmcnt(0)
	v_add_f32_e32 v34, v36, v34
	ds_bpermute_b32 v35, v154, v34
	s_waitcnt lgkmcnt(0)
	v_add_f32_e32 v34, v34, v35
	v_fmamk_f32 v34, v34, 0x3a000000, v158
	v_rsq_f32_e32 v34, v34
	s_nop 0
	v_mul_f32_e32 v28, v28, v34
	v_mul_f32_e32 v29, v29, v34
	v_mul_f32_e32 v26, v26, v34
	v_mul_f32_e32 v27, v27, v34
	v_mul_f32_e32 v24, v24, v34
	v_mul_f32_e32 v25, v25, v34
	v_mul_f32_e32 v30, v30, v34
	v_mul_f32_e32 v31, v31, v34
	v_max_f32_e32 v24, 0, v24
	v_max_f32_e32 v29, 0, v29
	v_max_f32_e32 v25, 0, v25
	v_max_f32_e32 v26, 0, v26
	v_max_f32_e32 v28, 0, v28
	v_mul_f32_e32 v35, v24, v24
	v_mul_f32_e32 v24, v29, v29
	v_mul_f32_e32 v29, v25, v25
	v_max_f32_e32 v25, 0, v30
	v_mul_f32_e32 v30, v26, v26
	v_max_f32_e32 v26, 0, v31
	v_max_f32_e32 v27, 0, v27
	v_mul_f32_e32 v28, v28, v28
	v_mul_f32_e32 v25, v25, v25
	v_mul_f32_e32 v26, v26, v26
	v_mul_f32_e32 v27, v27, v27
	v_mul_f32_e32 v18, v18, v34
	v_mul_f32_e32 v19, v19, v34
	v_mul_f32_e32 v16, v16, v34
	v_mul_f32_e32 v17, v17, v34
	v_cvt_pk_bf16_f32 v24, v28, v24
	v_cvt_pk_bf16_f32 v25, v25, v26
	v_cvt_pk_bf16_f32 v26, v35, v29
	v_cvt_pk_bf16_f32 v27, v30, v27
	v_mul_f32_e32 v22, v22, v34
	v_mul_f32_e32 v23, v23, v34
	v_mul_f32_e32 v20, v20, v34
	v_mul_f32_e32 v21, v21, v34
	v_max_f32_e32 v16, 0, v16
	v_max_f32_e32 v17, 0, v17
	v_max_f32_e32 v18, 0, v18
	global_store_dwordx4 v[32:33], v[24:27], off
	v_max_f32_e32 v20, 0, v20
	v_max_f32_e32 v19, 0, v19
	v_mul_f32_e32 v24, v16, v16
	v_max_f32_e32 v16, 0, v21
	v_mul_f32_e32 v21, v17, v17
	v_max_f32_e32 v17, 0, v22
	v_mul_f32_e32 v22, v18, v18
	v_max_f32_e32 v18, 0, v23
	v_mul_f32_e32 v20, v20, v20
	v_mul_f32_e32 v16, v16, v16
	v_mul_f32_e32 v17, v17, v17
	v_mul_f32_e32 v18, v18, v18
	v_mul_f32_e32 v19, v19, v19
	v_cvt_pk_bf16_f32 v16, v20, v16
	v_cvt_pk_bf16_f32 v17, v17, v18
	v_cvt_pk_bf16_f32 v18, v24, v21
	v_cvt_pk_bf16_f32 v19, v22, v19
	global_store_dwordx4 v[32:33], v[16:19], off offset:256
	v_mov_b32_e32 v20, 0
	s_nop 0
	v_add_u32_e32 v16, 0xb0, v148
	v_ashrrev_i32_e32 v17, 31, v16
	v_lshlrev_b64 v[18:19], 7, v[16:17]
	v_lshl_add_u64 v[18:19], s[52:53], 0, v[18:19]
	v_lshl_add_u64 v[18:19], v[136:137], 4, v[18:19]
	s_and_saveexec_b64 s[42:43], s[6:7]
	s_cbranch_execz .LBB0_2838
	global_load_dwordx4 v[20:23], v[18:19], off
	s_waitcnt vmcnt(0)
	v_mov_b32_e32 v24, v21
	v_mov_b32_e32 v25, v22
	v_mov_b32_e32 v21, v23
	v_add_f32_e32 v20, v24, v20
	v_add_f32_e32 v21, v25, v21
	s_nop 0
	v_add_f32_e32 v20, v20, v21
	v_add_f32_e32 v20, 0, v20
.LBB0_2838:
	s_or_b64 exec, exec, s[42:43]
	s_and_saveexec_b64 s[42:43], s[12:13]
	s_cbranch_execz .LBB0_2840
	global_load_dwordx4 v[22:25], v[18:19], off offset:64
	s_waitcnt vmcnt(0)
	v_mov_b32_e32 v18, v23
	v_mov_b32_e32 v19, v24
	v_mov_b32_e32 v23, v25
	v_add_f32_e32 v18, v18, v22
	v_add_f32_e32 v19, v19, v23
	s_nop 0
	v_add_f32_e32 v18, v18, v19
	v_add_f32_e32 v20, v20, v18
.LBB0_2840:
	s_or_b64 exec, exec, s[42:43]
	ds_bpermute_b32 v18, v153, v20
	v_lshlrev_b64 v[16:17], 14, v[16:17]
	v_lshl_add_u64 v[16:17], s[50:51], 0, v[16:17]
	v_lshl_add_u64 v[16:17], v[146:147], 1, v[16:17]
	s_andn2_b64 vcc, exec, s[14:15]
	s_waitcnt lgkmcnt(0)
	v_add_f32_e32 v18, v20, v18
	ds_bpermute_b32 v19, v154, v18
	s_mov_b64 s[14:15], -1
	s_waitcnt lgkmcnt(0)
	v_add_f32_e32 v18, v18, v19
	v_fmamk_f32 v18, v18, 0x3a000000, v158
	v_rsq_f32_e32 v18, v18
	s_nop 0
	v_mul_f32_e32 v12, v12, v18
	v_mul_f32_e32 v13, v13, v18
	v_mul_f32_e32 v10, v10, v18
	v_mul_f32_e32 v11, v11, v18
	v_mul_f32_e32 v8, v8, v18
	v_mul_f32_e32 v9, v9, v18
	v_mul_f32_e32 v14, v14, v18
	v_mul_f32_e32 v15, v15, v18
	v_max_f32_e32 v8, 0, v8
	v_max_f32_e32 v13, 0, v13
	v_max_f32_e32 v9, 0, v9
	v_max_f32_e32 v10, 0, v10
	v_max_f32_e32 v12, 0, v12
	v_mul_f32_e32 v19, v8, v8
	v_mul_f32_e32 v8, v13, v13
	v_mul_f32_e32 v13, v9, v9
	v_max_f32_e32 v9, 0, v14
	v_mul_f32_e32 v14, v10, v10
	v_max_f32_e32 v10, 0, v15
	v_max_f32_e32 v11, 0, v11
	v_mul_f32_e32 v12, v12, v12
	v_mul_f32_e32 v9, v9, v9
	v_mul_f32_e32 v10, v10, v10
	v_mul_f32_e32 v11, v11, v11
	v_mul_f32_e32 v2, v2, v18
	v_mul_f32_e32 v3, v3, v18
	v_mul_f32_e32 v0, v0, v18
	v_mul_f32_e32 v1, v1, v18
	v_cvt_pk_bf16_f32 v8, v12, v8
	v_cvt_pk_bf16_f32 v9, v9, v10
	v_cvt_pk_bf16_f32 v10, v19, v13
	v_cvt_pk_bf16_f32 v11, v14, v11
	v_mul_f32_e32 v6, v6, v18
	v_mul_f32_e32 v7, v7, v18
	v_mul_f32_e32 v4, v4, v18
	v_mul_f32_e32 v5, v5, v18
	v_max_f32_e32 v0, 0, v0
	v_max_f32_e32 v1, 0, v1
	v_max_f32_e32 v2, 0, v2
	global_store_dwordx4 v[16:17], v[8:11], off
	v_max_f32_e32 v4, 0, v4
	v_max_f32_e32 v3, 0, v3
	v_mul_f32_e32 v8, v0, v0
	v_max_f32_e32 v0, 0, v5
	v_mul_f32_e32 v5, v1, v1
	v_max_f32_e32 v1, 0, v6
	v_mul_f32_e32 v6, v2, v2
	v_max_f32_e32 v2, 0, v7
	v_mul_f32_e32 v4, v4, v4
	v_mul_f32_e32 v0, v0, v0
	v_mul_f32_e32 v1, v1, v1
	v_mul_f32_e32 v2, v2, v2
	v_mul_f32_e32 v3, v3, v3
	v_cvt_pk_bf16_f32 v0, v4, v0
	v_cvt_pk_bf16_f32 v1, v1, v2
	v_cvt_pk_bf16_f32 v2, v8, v5
	v_cvt_pk_bf16_f32 v3, v6, v3
	global_store_dwordx4 v[16:17], v[0:3], off offset:256
	s_cbranch_vccnz .LBB0_2797
	s_and_b64 vcc, exec, s[10:11]
	s_cbranch_vccnz .LBB0_2796
	s_barrier
	s_branch .LBB0_2796

.LBB0_2920:
	v_lshl_add_u32 v142, s38, 8, v144
	v_lshl_add_u32 v140, s14, 8, v146
	v_lshl_add_u32 v208, v142, 11, v140
	v_lshlrev_b32_e32 v208, 2, v208
	global_load_dwordx4 v[160:163], v208, s[12:13]
	global_load_dwordx4 v[164:167], v208, s[12:13] offset:64
	global_load_dwordx4 v[168:171], v208, s[12:13] offset:512
	global_load_dwordx4 v[172:175], v208, s[12:13] offset:576
	v_add_u32_e32 v209, 0x20000, v208
	global_load_dwordx4 v[176:179], v209, s[12:13]
	global_load_dwordx4 v[180:183], v209, s[12:13] offset:64
	global_load_dwordx4 v[184:187], v209, s[12:13] offset:512
	global_load_dwordx4 v[188:191], v209, s[12:13] offset:576
	v_add_u32_e32 v209, 0x40000, v208
	global_load_dwordx4 v[192:195], v209, s[12:13]
	global_load_dwordx4 v[196:199], v209, s[12:13] offset:64
	global_load_dwordx4 v[200:203], v209, s[12:13] offset:512
	global_load_dwordx4 v[204:207], v209, s[12:13] offset:576
	v_ashrrev_i32_e32 v143, 31, v142
	v_ashrrev_i32_e32 v141, 31, v140
	v_lshlrev_b64 v[152:153], 11, v[142:143]
	v_lshl_add_u64 v[156:157], v[152:153], 0, v[140:141]
	v_lshl_add_u64 v[158:159], v[156:157], 2, s[12:13]
	s_nop 0
	v_lshl_add_u64 v[156:157], v[156:157], 1, s[54:55]
	s_lshl_b32 s38, s14, 2
	s_ashr_i32 s39, s38, 31
	s_waitcnt vmcnt(11)
	v_add_f32_e32 v154, v126, v162
	v_add_f32_e32 v155, v127, v163
	v_add_f32_e32 v152, v124, v160
	v_add_f32_e32 v153, v125, v161
	v_cvt_pk_bf16_f32 v125, v154, v155
	v_cvt_pk_bf16_f32 v124, v152, v153
	global_store_dwordx2 v[156:157], v[124:125], off
	s_nop 0
	v_mul_f32_e32 v153, v153, v153
	v_mul_f32_e32 v155, v155, v155
	v_fmac_f32_e32 v153, v152, v152
	v_fmac_f32_e32 v155, v154, v154
	v_add_f32_e32 v152, v153, v155
	s_waitcnt vmcnt(11)
	v_add_f32_e32 v126, v122, v166
	v_add_f32_e32 v127, v123, v167
	v_add_f32_e32 v124, v120, v164
	v_add_f32_e32 v125, v121, v165
	v_cvt_pk_bf16_f32 v121, v126, v127
	v_cvt_pk_bf16_f32 v120, v124, v125
	global_store_dwordx2 v[156:157], v[120:121], off offset:32
	s_nop 0
	v_mul_f32_e32 v125, v125, v125
	v_mul_f32_e32 v127, v127, v127
	v_fmac_f32_e32 v125, v124, v124
	v_fmac_f32_e32 v127, v126, v126
	v_add_f32_e32 v124, v125, v127
	v_add_f32_e32 v124, v152, v124
	s_waitcnt vmcnt(11)
	v_add_f32_e32 v122, v118, v170
	v_add_f32_e32 v123, v119, v171
	v_add_f32_e32 v120, v116, v168
	v_add_f32_e32 v121, v117, v169
	v_cvt_pk_bf16_f32 v117, v122, v123
	v_cvt_pk_bf16_f32 v116, v120, v121
	global_store_dwordx2 v[156:157], v[116:117], off offset:256
	s_nop 0
	v_mul_f32_e32 v121, v121, v121
	v_mul_f32_e32 v123, v123, v123
	v_fmac_f32_e32 v121, v120, v120
	v_fmac_f32_e32 v123, v122, v122
	v_add_f32_e32 v120, v121, v123
	v_add_f32_e32 v120, v124, v120
	s_waitcnt vmcnt(11)
	v_add_f32_e32 v114, v114, v174
	v_add_f32_e32 v115, v115, v175
	v_add_f32_e32 v116, v112, v172
	v_add_f32_e32 v117, v113, v173
	v_add_u32_e32 v209, 0x60000, v208
	global_load_dwordx4 v[160:163], v209, s[12:13]
	global_load_dwordx4 v[164:167], v209, s[12:13] offset:64
	global_load_dwordx4 v[168:171], v209, s[12:13] offset:512
	global_load_dwordx4 v[172:175], v209, s[12:13] offset:576
	v_mul_f32_e32 v113, v115, v115
	v_mul_f32_e32 v112, v117, v117
	v_fmac_f32_e32 v112, v116, v116
	v_fmac_f32_e32 v113, v114, v114
	v_add_f32_e32 v112, v112, v113
	v_add_f32_e32 v112, v120, v112
	ds_bpermute_b32 v113, v147, v112
	v_cvt_pk_bf16_f32 v116, v116, v117
	v_cvt_pk_bf16_f32 v117, v114, v115
	global_store_dwordx2 v[156:157], v[116:117], off offset:288
	s_waitcnt lgkmcnt(0)
	v_add_f32_e32 v112, v112, v113
	ds_bpermute_b32 v113, v148, v112
	s_and_saveexec_b64 s[40:41], s[6:7]
	s_cbranch_execz .LBB0_2922
	v_lshlrev_b64 v[114:115], 7, v[142:143]
	v_lshl_add_u64 v[114:115], s[52:53], 0, v[114:115]
	v_lshl_add_u64 v[114:115], s[38:39], 2, v[114:115]
	s_lshl_b32 s14, s3, 2
	v_lshl_add_u64 v[114:115], v[114:115], 0, s[14:15]
	s_waitcnt lgkmcnt(0)
	v_add_f32_e32 v112, v112, v113
	global_store_dword v[114:115], v112, off
.LBB0_2922:
	s_or_b64 exec, exec, s[40:41]
	v_or_b32_e32 v112, 16, v142
	s_waitcnt lgkmcnt(0)
	v_ashrrev_i32_e32 v113, 31, v112
	v_lshlrev_b64 v[114:115], 11, v[112:113]
	v_lshl_add_u64 v[118:119], v[114:115], 0, v[140:141]
	v_lshl_add_u64 v[120:121], v[118:119], 2, s[12:13]
	s_nop 0
	v_lshl_add_u64 v[118:119], v[118:119], 1, s[54:55]
	s_waitcnt vmcnt(15)
	v_add_f32_e32 v116, v110, v178
	v_add_f32_e32 v117, v111, v179
	v_add_f32_e32 v114, v108, v176
	v_add_f32_e32 v115, v109, v177
	v_cvt_pk_bf16_f32 v109, v116, v117
	v_cvt_pk_bf16_f32 v108, v114, v115
	global_store_dwordx2 v[118:119], v[108:109], off
	s_nop 0
	v_mul_f32_e32 v115, v115, v115
	v_mul_f32_e32 v117, v117, v117
	v_fmac_f32_e32 v115, v114, v114
	v_fmac_f32_e32 v117, v116, v116
	v_add_f32_e32 v114, v115, v117
	s_waitcnt vmcnt(15)
	v_add_f32_e32 v110, v106, v182
	v_add_f32_e32 v111, v107, v183
	v_add_f32_e32 v108, v104, v180
	v_add_f32_e32 v109, v105, v181
	v_cvt_pk_bf16_f32 v105, v110, v111
	v_cvt_pk_bf16_f32 v104, v108, v109
	global_store_dwordx2 v[118:119], v[104:105], off offset:32
	s_nop 0
	v_mul_f32_e32 v109, v109, v109
	v_mul_f32_e32 v111, v111, v111
	v_fmac_f32_e32 v109, v108, v108
	v_fmac_f32_e32 v111, v110, v110
	v_add_f32_e32 v108, v109, v111
	v_add_f32_e32 v108, v114, v108
	s_waitcnt vmcnt(15)
	v_add_f32_e32 v106, v102, v186
	v_add_f32_e32 v107, v103, v187
	v_add_f32_e32 v104, v100, v184
	v_add_f32_e32 v105, v101, v185
	v_cvt_pk_bf16_f32 v101, v106, v107
	v_cvt_pk_bf16_f32 v100, v104, v105
	global_store_dwordx2 v[118:119], v[100:101], off offset:256
	s_nop 0
	v_mul_f32_e32 v105, v105, v105
	v_mul_f32_e32 v107, v107, v107
	v_fmac_f32_e32 v105, v104, v104
	v_fmac_f32_e32 v107, v106, v106
	v_add_f32_e32 v104, v105, v107
	v_add_f32_e32 v104, v108, v104
	s_waitcnt vmcnt(15)
	v_add_f32_e32 v98, v98, v190
	v_add_f32_e32 v99, v99, v191
	v_add_f32_e32 v100, v96, v188
	v_add_f32_e32 v101, v97, v189
	v_add_u32_e32 v209, 0x100000, v208
	global_load_dwordx4 v[176:179], v209, s[12:13]
	global_load_dwordx4 v[180:183], v209, s[12:13] offset:64
	global_load_dwordx4 v[184:187], v209, s[12:13] offset:512
	global_load_dwordx4 v[188:191], v209, s[12:13] offset:576
	v_mul_f32_e32 v97, v99, v99
	v_mul_f32_e32 v96, v101, v101
	v_fmac_f32_e32 v96, v100, v100
	v_fmac_f32_e32 v97, v98, v98
	v_add_f32_e32 v96, v96, v97
	v_add_f32_e32 v96, v104, v96
	ds_bpermute_b32 v97, v147, v96
	v_cvt_pk_bf16_f32 v100, v100, v101
	v_cvt_pk_bf16_f32 v101, v98, v99
	global_store_dwordx2 v[118:119], v[100:101], off offset:288
	s_waitcnt lgkmcnt(0)
	v_add_f32_e32 v96, v96, v97
	ds_bpermute_b32 v97, v148, v96
	s_and_saveexec_b64 s[40:41], s[6:7]
	s_cbranch_execz .LBB0_2924
	v_lshlrev_b64 v[98:99], 7, v[112:113]
	v_lshl_add_u64 v[98:99], s[52:53], 0, v[98:99]
	v_lshl_add_u64 v[98:99], s[38:39], 2, v[98:99]
	s_lshl_b32 s14, s3, 2
	v_lshl_add_u64 v[98:99], v[98:99], 0, s[14:15]
	s_waitcnt lgkmcnt(0)
	v_add_f32_e32 v96, v96, v97
	global_store_dword v[98:99], v96, off
.LBB0_2924:
	s_or_b64 exec, exec, s[40:41]
	v_or_b32_e32 v96, 32, v142
	s_waitcnt lgkmcnt(0)
	v_ashrrev_i32_e32 v97, 31, v96
	v_lshlrev_b64 v[98:99], 11, v[96:97]
	v_lshl_add_u64 v[102:103], v[98:99], 0, v[140:141]
	v_lshl_add_u64 v[104:105], v[102:103], 2, s[12:13]
	s_nop 0
	v_lshl_add_u64 v[102:103], v[102:103], 1, s[54:55]
	s_waitcnt vmcnt(19)
	v_add_f32_e32 v100, v94, v194
	v_add_f32_e32 v101, v95, v195
	v_add_f32_e32 v98, v92, v192
	v_add_f32_e32 v99, v93, v193
	v_cvt_pk_bf16_f32 v93, v100, v101
	v_cvt_pk_bf16_f32 v92, v98, v99
	global_store_dwordx2 v[102:103], v[92:93], off
	s_nop 0
	v_mul_f32_e32 v99, v99, v99
	v_mul_f32_e32 v101, v101, v101
	v_fmac_f32_e32 v99, v98, v98
	v_fmac_f32_e32 v101, v100, v100
	v_add_f32_e32 v98, v99, v101
	s_waitcnt vmcnt(19)
	v_add_f32_e32 v94, v90, v198
	v_add_f32_e32 v95, v91, v199
	v_add_f32_e32 v92, v88, v196
	v_add_f32_e32 v93, v89, v197
	v_cvt_pk_bf16_f32 v89, v94, v95
	v_cvt_pk_bf16_f32 v88, v92, v93
	global_store_dwordx2 v[102:103], v[88:89], off offset:32
	s_nop 0
	v_mul_f32_e32 v93, v93, v93
	v_mul_f32_e32 v95, v95, v95
	v_fmac_f32_e32 v93, v92, v92
	v_fmac_f32_e32 v95, v94, v94
	v_add_f32_e32 v92, v93, v95
	v_add_f32_e32 v92, v98, v92
	s_waitcnt vmcnt(19)
	v_add_f32_e32 v90, v86, v202
	v_add_f32_e32 v91, v87, v203
	v_add_f32_e32 v88, v84, v200
	v_add_f32_e32 v89, v85, v201
	v_cvt_pk_bf16_f32 v85, v90, v91
	v_cvt_pk_bf16_f32 v84, v88, v89
	global_store_dwordx2 v[102:103], v[84:85], off offset:256
	s_nop 0
	v_mul_f32_e32 v89, v89, v89
	v_mul_f32_e32 v91, v91, v91
	v_fmac_f32_e32 v89, v88, v88
	v_fmac_f32_e32 v91, v90, v90
	v_add_f32_e32 v88, v89, v91
	v_add_f32_e32 v88, v92, v88
	s_waitcnt vmcnt(19)
	v_add_f32_e32 v82, v82, v206
	v_add_f32_e32 v83, v83, v207
	v_add_f32_e32 v84, v80, v204
	v_add_f32_e32 v85, v81, v205
	v_add_u32_e32 v209, 0x120000, v208
	global_load_dwordx4 v[192:195], v209, s[12:13]
	global_load_dwordx4 v[196:199], v209, s[12:13] offset:64
	global_load_dwordx4 v[200:203], v209, s[12:13] offset:512
	global_load_dwordx4 v[204:207], v209, s[12:13] offset:576
	v_mul_f32_e32 v81, v83, v83
	v_mul_f32_e32 v80, v85, v85
	v_fmac_f32_e32 v80, v84, v84
	v_fmac_f32_e32 v81, v82, v82
	v_add_f32_e32 v80, v80, v81
	v_add_f32_e32 v80, v88, v80
	ds_bpermute_b32 v81, v147, v80
	v_cvt_pk_bf16_f32 v84, v84, v85
	v_cvt_pk_bf16_f32 v85, v82, v83
	global_store_dwordx2 v[102:103], v[84:85], off offset:288
	s_waitcnt lgkmcnt(0)
	v_add_f32_e32 v80, v80, v81
	ds_bpermute_b32 v81, v148, v80
	s_and_saveexec_b64 s[40:41], s[6:7]
	s_cbranch_execz .LBB0_2926
	v_lshlrev_b64 v[82:83], 7, v[96:97]
	v_lshl_add_u64 v[82:83], s[52:53], 0, v[82:83]
	v_lshl_add_u64 v[82:83], s[38:39], 2, v[82:83]
	s_lshl_b32 s14, s3, 2
	v_lshl_add_u64 v[82:83], v[82:83], 0, s[14:15]
	s_waitcnt lgkmcnt(0)
	v_add_f32_e32 v80, v80, v81
	global_store_dword v[82:83], v80, off
.LBB0_2926:
	s_or_b64 exec, exec, s[40:41]
	v_or_b32_e32 v80, 48, v142
	s_waitcnt lgkmcnt(0)
	v_ashrrev_i32_e32 v81, 31, v80
	v_lshlrev_b64 v[82:83], 11, v[80:81]
	v_lshl_add_u64 v[86:87], v[82:83], 0, v[140:141]
	v_lshl_add_u64 v[88:89], v[86:87], 2, s[12:13]
	s_nop 0
	v_lshl_add_u64 v[86:87], v[86:87], 1, s[54:55]
	s_waitcnt vmcnt(20)
	v_add_f32_e32 v84, v78, v162
	v_add_f32_e32 v85, v79, v163
	v_add_f32_e32 v82, v76, v160
	v_add_f32_e32 v83, v77, v161
	v_cvt_pk_bf16_f32 v77, v84, v85
	v_cvt_pk_bf16_f32 v76, v82, v83
	global_store_dwordx2 v[86:87], v[76:77], off
	s_nop 0
	v_mul_f32_e32 v83, v83, v83
	v_mul_f32_e32 v85, v85, v85
	v_fmac_f32_e32 v83, v82, v82
	v_fmac_f32_e32 v85, v84, v84
	v_add_f32_e32 v82, v83, v85
	s_waitcnt vmcnt(20)
	v_add_f32_e32 v78, v74, v166
	v_add_f32_e32 v79, v75, v167
	v_add_f32_e32 v76, v72, v164
	v_add_f32_e32 v77, v73, v165
	v_cvt_pk_bf16_f32 v73, v78, v79
	v_cvt_pk_bf16_f32 v72, v76, v77
	global_store_dwordx2 v[86:87], v[72:73], off offset:32
	s_nop 0
	v_mul_f32_e32 v77, v77, v77
	v_mul_f32_e32 v79, v79, v79
	v_fmac_f32_e32 v77, v76, v76
	v_fmac_f32_e32 v79, v78, v78
	v_add_f32_e32 v76, v77, v79
	v_add_f32_e32 v76, v82, v76
	s_waitcnt vmcnt(20)
	v_add_f32_e32 v74, v70, v170
	v_add_f32_e32 v75, v71, v171
	v_add_f32_e32 v72, v68, v168
	v_add_f32_e32 v73, v69, v169
	v_cvt_pk_bf16_f32 v69, v74, v75
	v_cvt_pk_bf16_f32 v68, v72, v73
	global_store_dwordx2 v[86:87], v[68:69], off offset:256
	s_nop 0
	v_mul_f32_e32 v73, v73, v73
	v_mul_f32_e32 v75, v75, v75
	v_fmac_f32_e32 v73, v72, v72
	v_fmac_f32_e32 v75, v74, v74
	v_add_f32_e32 v72, v73, v75
	v_add_f32_e32 v72, v76, v72
	s_waitcnt vmcnt(20)
	v_add_f32_e32 v66, v66, v174
	v_add_f32_e32 v67, v67, v175
	v_add_f32_e32 v68, v64, v172
	v_add_f32_e32 v69, v65, v173
	v_add_u32_e32 v209, 0x140000, v208
	global_load_dwordx4 v[160:163], v209, s[12:13]
	global_load_dwordx4 v[164:167], v209, s[12:13] offset:64
	global_load_dwordx4 v[168:171], v209, s[12:13] offset:512
	global_load_dwordx4 v[172:175], v209, s[12:13] offset:576
	v_mul_f32_e32 v65, v67, v67
	v_mul_f32_e32 v64, v69, v69
	v_fmac_f32_e32 v64, v68, v68
	v_fmac_f32_e32 v65, v66, v66
	v_add_f32_e32 v64, v64, v65
	v_add_f32_e32 v64, v72, v64
	ds_bpermute_b32 v65, v147, v64
	v_cvt_pk_bf16_f32 v68, v68, v69
	v_cvt_pk_bf16_f32 v69, v66, v67
	global_store_dwordx2 v[86:87], v[68:69], off offset:288
	s_waitcnt lgkmcnt(0)
	v_add_f32_e32 v64, v64, v65
	ds_bpermute_b32 v65, v148, v64
	s_and_saveexec_b64 s[40:41], s[6:7]
	s_cbranch_execz .LBB0_2928
	v_lshlrev_b64 v[66:67], 7, v[80:81]
	v_lshl_add_u64 v[66:67], s[52:53], 0, v[66:67]
	v_lshl_add_u64 v[66:67], s[38:39], 2, v[66:67]
	s_lshl_b32 s14, s3, 2
	v_lshl_add_u64 v[66:67], v[66:67], 0, s[14:15]
	s_waitcnt lgkmcnt(0)
	v_add_f32_e32 v64, v64, v65
	global_store_dword v[66:67], v64, off
.LBB0_2928:
	s_or_b64 exec, exec, s[40:41]
	v_add_u32_e32 v64, 0x80, v142
	s_waitcnt lgkmcnt(0)
	v_ashrrev_i32_e32 v65, 31, v64
	v_lshlrev_b64 v[66:67], 11, v[64:65]
	v_lshl_add_u64 v[70:71], v[66:67], 0, v[140:141]
	v_lshl_add_u64 v[72:73], v[70:71], 2, s[12:13]
	s_nop 0
	v_lshl_add_u64 v[70:71], v[70:71], 1, s[54:55]
	s_waitcnt vmcnt(20)
	v_add_f32_e32 v68, v62, v178
	v_add_f32_e32 v69, v63, v179
	v_add_f32_e32 v66, v60, v176
	v_add_f32_e32 v67, v61, v177
	v_cvt_pk_bf16_f32 v61, v68, v69
	v_cvt_pk_bf16_f32 v60, v66, v67
	global_store_dwordx2 v[70:71], v[60:61], off
	s_nop 0
	v_mul_f32_e32 v67, v67, v67
	v_mul_f32_e32 v69, v69, v69
	v_fmac_f32_e32 v67, v66, v66
	v_fmac_f32_e32 v69, v68, v68
	v_add_f32_e32 v66, v67, v69
	s_waitcnt vmcnt(20)
	v_add_f32_e32 v62, v58, v182
	v_add_f32_e32 v63, v59, v183
	v_add_f32_e32 v60, v56, v180
	v_add_f32_e32 v61, v57, v181
	v_cvt_pk_bf16_f32 v57, v62, v63
	v_cvt_pk_bf16_f32 v56, v60, v61
	global_store_dwordx2 v[70:71], v[56:57], off offset:32
	s_nop 0
	v_mul_f32_e32 v61, v61, v61
	v_mul_f32_e32 v63, v63, v63
	v_fmac_f32_e32 v61, v60, v60
	v_fmac_f32_e32 v63, v62, v62
	v_add_f32_e32 v60, v61, v63
	v_add_f32_e32 v60, v66, v60
	s_waitcnt vmcnt(20)
	v_add_f32_e32 v58, v54, v186
	v_add_f32_e32 v59, v55, v187
	v_add_f32_e32 v56, v52, v184
	v_add_f32_e32 v57, v53, v185
	v_cvt_pk_bf16_f32 v53, v58, v59
	v_cvt_pk_bf16_f32 v52, v56, v57
	global_store_dwordx2 v[70:71], v[52:53], off offset:256
	s_nop 0
	v_mul_f32_e32 v57, v57, v57
	v_mul_f32_e32 v59, v59, v59
	v_fmac_f32_e32 v57, v56, v56
	v_fmac_f32_e32 v59, v58, v58
	v_add_f32_e32 v56, v57, v59
	v_add_f32_e32 v56, v60, v56
	s_waitcnt vmcnt(20)
	v_add_f32_e32 v50, v50, v190
	v_add_f32_e32 v51, v51, v191
	v_add_f32_e32 v52, v48, v188
	v_add_f32_e32 v53, v49, v189
	v_add_u32_e32 v209, 0x160000, v208
	global_load_dwordx4 v[176:179], v209, s[12:13]
	global_load_dwordx4 v[180:183], v209, s[12:13] offset:64
	global_load_dwordx4 v[184:187], v209, s[12:13] offset:512
	global_load_dwordx4 v[188:191], v209, s[12:13] offset:576
	v_mul_f32_e32 v49, v51, v51
	v_mul_f32_e32 v48, v53, v53
	v_fmac_f32_e32 v48, v52, v52
	v_fmac_f32_e32 v49, v50, v50
	v_add_f32_e32 v48, v48, v49
	v_add_f32_e32 v48, v56, v48
	ds_bpermute_b32 v49, v147, v48
	v_cvt_pk_bf16_f32 v52, v52, v53
	v_cvt_pk_bf16_f32 v53, v50, v51
	global_store_dwordx2 v[70:71], v[52:53], off offset:288
	s_waitcnt lgkmcnt(0)
	v_add_f32_e32 v48, v48, v49
	ds_bpermute_b32 v49, v148, v48
	s_and_saveexec_b64 s[40:41], s[6:7]
	s_cbranch_execz .LBB0_2930
	v_lshlrev_b64 v[50:51], 7, v[64:65]
	v_lshl_add_u64 v[50:51], s[52:53], 0, v[50:51]
	v_lshl_add_u64 v[50:51], s[38:39], 2, v[50:51]
	s_lshl_b32 s14, s3, 2
	v_lshl_add_u64 v[50:51], v[50:51], 0, s[14:15]
	s_waitcnt lgkmcnt(0)
	v_add_f32_e32 v48, v48, v49
	global_store_dword v[50:51], v48, off
.LBB0_2930:
	s_or_b64 exec, exec, s[40:41]
	v_add_u32_e32 v48, 0x90, v142
	s_waitcnt lgkmcnt(0)
	v_ashrrev_i32_e32 v49, 31, v48
	v_lshlrev_b64 v[50:51], 11, v[48:49]
	v_lshl_add_u64 v[54:55], v[50:51], 0, v[140:141]
	v_lshl_add_u64 v[56:57], v[54:55], 2, s[12:13]
	s_nop 0
	v_lshl_add_u64 v[54:55], v[54:55], 1, s[54:55]
	s_waitcnt vmcnt(20)
	v_add_f32_e32 v52, v46, v194
	v_add_f32_e32 v53, v47, v195
	v_add_f32_e32 v50, v44, v192
	v_add_f32_e32 v51, v45, v193
	v_cvt_pk_bf16_f32 v45, v52, v53
	v_cvt_pk_bf16_f32 v44, v50, v51
	global_store_dwordx2 v[54:55], v[44:45], off
	s_nop 0
	v_mul_f32_e32 v51, v51, v51
	v_mul_f32_e32 v53, v53, v53
	v_fmac_f32_e32 v51, v50, v50
	v_fmac_f32_e32 v53, v52, v52
	v_add_f32_e32 v50, v51, v53
	s_waitcnt vmcnt(20)
	v_add_f32_e32 v46, v42, v198
	v_add_f32_e32 v47, v43, v199
	v_add_f32_e32 v44, v40, v196
	v_add_f32_e32 v45, v41, v197
	v_cvt_pk_bf16_f32 v41, v46, v47
	v_cvt_pk_bf16_f32 v40, v44, v45
	global_store_dwordx2 v[54:55], v[40:41], off offset:32
	s_nop 0
	v_mul_f32_e32 v45, v45, v45
	v_mul_f32_e32 v47, v47, v47
	v_fmac_f32_e32 v45, v44, v44
	v_fmac_f32_e32 v47, v46, v46
	v_add_f32_e32 v44, v45, v47
	v_add_f32_e32 v44, v50, v44
	s_waitcnt vmcnt(20)
	v_add_f32_e32 v42, v38, v202
	v_add_f32_e32 v43, v39, v203
	v_add_f32_e32 v40, v36, v200
	v_add_f32_e32 v41, v37, v201
	v_cvt_pk_bf16_f32 v37, v42, v43
	v_cvt_pk_bf16_f32 v36, v40, v41
	global_store_dwordx2 v[54:55], v[36:37], off offset:256
	s_nop 0
	v_mul_f32_e32 v41, v41, v41
	v_mul_f32_e32 v43, v43, v43
	v_fmac_f32_e32 v41, v40, v40
	v_fmac_f32_e32 v43, v42, v42
	v_add_f32_e32 v40, v41, v43
	v_add_f32_e32 v40, v44, v40
	s_waitcnt vmcnt(20)
	v_add_f32_e32 v34, v34, v206
	v_add_f32_e32 v35, v35, v207
	v_add_f32_e32 v36, v32, v204
	v_add_f32_e32 v37, v33, v205
	v_mul_f32_e32 v33, v35, v35
	v_mul_f32_e32 v32, v37, v37
	v_fmac_f32_e32 v32, v36, v36
	v_fmac_f32_e32 v33, v34, v34
	v_add_f32_e32 v32, v32, v33
	v_add_f32_e32 v32, v40, v32
	ds_bpermute_b32 v33, v147, v32
	v_cvt_pk_bf16_f32 v36, v36, v37
	v_cvt_pk_bf16_f32 v37, v34, v35
	global_store_dwordx2 v[54:55], v[36:37], off offset:288
	s_waitcnt lgkmcnt(0)
	v_add_f32_e32 v32, v32, v33
	ds_bpermute_b32 v33, v148, v32
	s_and_saveexec_b64 s[40:41], s[6:7]
	s_cbranch_execz .LBB0_2932
	v_lshlrev_b64 v[34:35], 7, v[48:49]
	v_lshl_add_u64 v[34:35], s[52:53], 0, v[34:35]
	v_lshl_add_u64 v[34:35], s[38:39], 2, v[34:35]
	s_lshl_b32 s14, s3, 2
	v_lshl_add_u64 v[34:35], v[34:35], 0, s[14:15]
	s_waitcnt lgkmcnt(0)
	v_add_f32_e32 v32, v32, v33
	global_store_dword v[34:35], v32, off
.LBB0_2932:
	s_or_b64 exec, exec, s[40:41]
	v_add_u32_e32 v32, 0xa0, v142
	s_waitcnt lgkmcnt(0)
	v_ashrrev_i32_e32 v33, 31, v32
	v_lshlrev_b64 v[34:35], 11, v[32:33]
	v_lshl_add_u64 v[38:39], v[34:35], 0, v[140:141]
	v_lshl_add_u64 v[40:41], v[38:39], 2, s[12:13]
	s_nop 0
	v_lshl_add_u64 v[38:39], v[38:39], 1, s[54:55]
	s_waitcnt vmcnt(16)
	v_add_f32_e32 v36, v30, v162
	v_add_f32_e32 v37, v31, v163
	v_add_f32_e32 v34, v28, v160
	v_add_f32_e32 v35, v29, v161
	v_cvt_pk_bf16_f32 v29, v36, v37
	v_cvt_pk_bf16_f32 v28, v34, v35
	global_store_dwordx2 v[38:39], v[28:29], off
	s_nop 0
	v_mul_f32_e32 v35, v35, v35
	v_mul_f32_e32 v37, v37, v37
	v_fmac_f32_e32 v35, v34, v34
	v_fmac_f32_e32 v37, v36, v36
	v_add_f32_e32 v34, v35, v37
	s_waitcnt vmcnt(16)
	v_add_f32_e32 v30, v26, v166
	v_add_f32_e32 v31, v27, v167
	v_add_f32_e32 v28, v24, v164
	v_add_f32_e32 v29, v25, v165
	v_cvt_pk_bf16_f32 v25, v30, v31
	v_cvt_pk_bf16_f32 v24, v28, v29
	global_store_dwordx2 v[38:39], v[24:25], off offset:32
	s_nop 0
	v_mul_f32_e32 v29, v29, v29
	v_mul_f32_e32 v31, v31, v31
	v_fmac_f32_e32 v29, v28, v28
	v_fmac_f32_e32 v31, v30, v30
	v_add_f32_e32 v28, v29, v31
	v_add_f32_e32 v28, v34, v28
	s_waitcnt vmcnt(16)
	v_add_f32_e32 v26, v22, v170
	v_add_f32_e32 v27, v23, v171
	v_add_f32_e32 v24, v20, v168
	v_add_f32_e32 v25, v21, v169
	v_cvt_pk_bf16_f32 v21, v26, v27
	v_cvt_pk_bf16_f32 v20, v24, v25
	global_store_dwordx2 v[38:39], v[20:21], off offset:256
	s_nop 0
	v_mul_f32_e32 v25, v25, v25
	v_mul_f32_e32 v27, v27, v27
	v_fmac_f32_e32 v25, v24, v24
	v_fmac_f32_e32 v27, v26, v26
	v_add_f32_e32 v24, v25, v27
	v_add_f32_e32 v24, v28, v24
	s_waitcnt vmcnt(16)
	v_add_f32_e32 v18, v18, v174
	v_add_f32_e32 v19, v19, v175
	v_add_f32_e32 v20, v16, v172
	v_add_f32_e32 v21, v17, v173
	v_mul_f32_e32 v17, v19, v19
	v_mul_f32_e32 v16, v21, v21
	v_fmac_f32_e32 v16, v20, v20
	v_fmac_f32_e32 v17, v18, v18
	v_add_f32_e32 v16, v16, v17
	v_add_f32_e32 v16, v24, v16
	ds_bpermute_b32 v17, v147, v16
	v_cvt_pk_bf16_f32 v20, v20, v21
	v_cvt_pk_bf16_f32 v21, v18, v19
	global_store_dwordx2 v[38:39], v[20:21], off offset:288
	s_waitcnt lgkmcnt(0)
	v_add_f32_e32 v16, v16, v17
	ds_bpermute_b32 v17, v148, v16
	s_and_saveexec_b64 s[40:41], s[6:7]
	s_cbranch_execz .LBB0_2934
	v_lshlrev_b64 v[18:19], 7, v[32:33]
	v_lshl_add_u64 v[18:19], s[52:53], 0, v[18:19]
	v_lshl_add_u64 v[18:19], s[38:39], 2, v[18:19]
	s_lshl_b32 s14, s3, 2
	v_lshl_add_u64 v[18:19], v[18:19], 0, s[14:15]
	s_waitcnt lgkmcnt(0)
	v_add_f32_e32 v16, v16, v17
	global_store_dword v[18:19], v16, off
.LBB0_2934:
	s_or_b64 exec, exec, s[40:41]
	v_add_u32_e32 v16, 0xb0, v142
	s_waitcnt lgkmcnt(0)
	v_ashrrev_i32_e32 v17, 31, v16
	v_lshlrev_b64 v[18:19], 11, v[16:17]
	v_lshl_add_u64 v[22:23], v[18:19], 0, v[140:141]
	v_lshl_add_u64 v[24:25], v[22:23], 2, s[12:13]
	s_nop 0
	v_lshl_add_u64 v[22:23], v[22:23], 1, s[54:55]
	s_waitcnt vmcnt(12)
	v_add_f32_e32 v20, v14, v178
	v_add_f32_e32 v21, v15, v179
	v_add_f32_e32 v18, v12, v176
	v_add_f32_e32 v19, v13, v177
	v_cvt_pk_bf16_f32 v13, v20, v21
	v_cvt_pk_bf16_f32 v12, v18, v19
	global_store_dwordx2 v[22:23], v[12:13], off
	s_nop 0
	v_mul_f32_e32 v19, v19, v19
	v_mul_f32_e32 v21, v21, v21
	v_fmac_f32_e32 v19, v18, v18
	v_fmac_f32_e32 v21, v20, v20
	v_add_f32_e32 v18, v19, v21
	s_waitcnt vmcnt(12)
	v_add_f32_e32 v14, v10, v182
	v_add_f32_e32 v15, v11, v183
	v_add_f32_e32 v12, v8, v180
	v_add_f32_e32 v13, v9, v181
	v_cvt_pk_bf16_f32 v9, v14, v15
	v_cvt_pk_bf16_f32 v8, v12, v13
	global_store_dwordx2 v[22:23], v[8:9], off offset:32
	s_nop 0
	v_mul_f32_e32 v13, v13, v13
	v_mul_f32_e32 v15, v15, v15
	v_fmac_f32_e32 v13, v12, v12
	v_fmac_f32_e32 v15, v14, v14
	v_add_f32_e32 v12, v13, v15
	v_add_f32_e32 v12, v18, v12
	s_waitcnt vmcnt(12)
	v_add_f32_e32 v10, v6, v186
	v_add_f32_e32 v11, v7, v187
	v_add_f32_e32 v8, v4, v184
	v_add_f32_e32 v9, v5, v185
	v_cvt_pk_bf16_f32 v5, v10, v11
	v_cvt_pk_bf16_f32 v4, v8, v9
	global_store_dwordx2 v[22:23], v[4:5], off offset:256
	s_nop 0
	v_mul_f32_e32 v9, v9, v9
	v_mul_f32_e32 v11, v11, v11
	v_fmac_f32_e32 v9, v8, v8
	v_fmac_f32_e32 v11, v10, v10
	v_add_f32_e32 v8, v9, v11
	v_add_f32_e32 v8, v12, v8
	s_waitcnt vmcnt(12)
	v_add_f32_e32 v2, v2, v190
	v_add_f32_e32 v3, v3, v191
	v_add_f32_e32 v4, v0, v188
	v_add_f32_e32 v5, v1, v189
	v_mul_f32_e32 v1, v3, v3
	v_mul_f32_e32 v0, v5, v5
	v_fmac_f32_e32 v0, v4, v4
	v_fmac_f32_e32 v1, v2, v2
	v_add_f32_e32 v0, v0, v1
	v_add_f32_e32 v0, v8, v0
	ds_bpermute_b32 v1, v147, v0
	v_cvt_pk_bf16_f32 v4, v4, v5
	v_cvt_pk_bf16_f32 v5, v2, v3
	global_store_dwordx2 v[22:23], v[4:5], off offset:288
	s_waitcnt lgkmcnt(0)
	v_add_f32_e32 v0, v0, v1
	ds_bpermute_b32 v1, v148, v0
	s_and_saveexec_b64 s[40:41], s[6:7]
	s_cbranch_execz .LBB0_2936
	v_lshlrev_b64 v[2:3], 7, v[16:17]
	v_lshl_add_u64 v[2:3], s[52:53], 0, v[2:3]
	v_lshl_add_u64 v[2:3], s[38:39], 2, v[2:3]
	s_lshl_b32 s14, s3, 2
	v_lshl_add_u64 v[2:3], v[2:3], 0, s[14:15]
	s_waitcnt lgkmcnt(0)
	v_add_f32_e32 v0, v0, v1
	global_store_dword v[2:3], v0, off

.LBB0_2996:
	s_add_u32 s8, s24, s4
	v_add_co_u32_e32 v54, vcc, s11, v12
	s_addc_u32 s9, s25, s5
	v_lshl_add_u64 v[22:23], s[24:25], 0, v[10:11]
	v_addc_co_u32_e32 v55, vcc, -1, v13, vcc
	s_add_u32 s12, s8, 0x4000
	v_add_co_u32_e32 v56, vcc, s10, v22
	s_addc_u32 s13, s9, 0
	global_load_dwordx4 v[18:21], v[0:1], off
	v_addc_co_u32_e32 v57, vcc, 0, v23, vcc
	global_load_dwordx4 v[22:25], v15, s[8:9]
	global_load_dwordx4 v[26:29], v15, s[8:9] offset:64
	global_load_dwordx2 v[58:59], v[56:57], off
	global_load_dwordx4 v[30:33], v14, s[12:13] offset:16
	global_load_dwordx4 v[34:37], v14, s[12:13] offset:32
	global_load_dwordx4 v[38:41], v14, s[12:13] offset:48
	s_add_u32 s8, s8, 0x4040
	s_addc_u32 s9, s9, 0
	global_load_dwordx4 v[42:45], v14, s[8:9] offset:16
	global_load_dwordx4 v[46:49], v14, s[8:9] offset:32
	global_load_dwordx4 v[50:53], v14, s[8:9] offset:48
	s_add_i32 s26, s26, s28
	s_add_u32 s4, s4, s6
	s_addc_u32 s5, s5, s7
	v_lshl_add_u64 v[10:11], v[10:11], 0, s[0:1]
	s_cmpk_gt_i32 s26, 0x3fff
	s_waitcnt vmcnt(8)
	v_mov_b32_e32 v60, v22
	v_mov_b32_e32 v22, v24
	s_waitcnt vmcnt(5)
	v_mov_b32_e32 v61, v30
	v_mov_b32_e32 v30, v23
	v_mov_b32_e32 v23, v32
	v_mov_b32_e32 v32, v25
	s_waitcnt vmcnt(4)
	v_mov_b32_e32 v24, v35
	v_mov_b32_e32 v25, v36
	v_mov_b32_e32 v35, v37
	v_add_f32_e32 v30, v60, v30
	v_add_f32_e32 v31, v61, v31
	v_add_f32_e32 v22, v22, v32
	v_add_f32_e32 v23, v23, v33
	v_add_f32_e32 v24, v24, v34
	v_add_f32_e32 v25, v25, v35
	v_add_f32_e32 v22, v30, v22
	v_add_f32_e32 v23, v31, v23
	v_pk_add_f32 v[24:25], v[24:25], v[24:25] op_sel:[0,1] op_sel_hi:[1,0]
	v_add_f32_e32 v17, 0, v22
	v_mov_b32_e32 v63, v26
	v_mov_b32_e32 v65, v28
	s_waitcnt vmcnt(3)
	v_add_f32_e32 v64, v38, v39
	v_add_f32_e32 v28, v40, v41
	v_mov_b32_e32 v25, v27
	v_add_f32_e32 v62, v17, v23
	v_add_f32_e32 v28, v64, v28
	v_add_f32_e32 v29, v65, v29
	s_waitcnt vmcnt(2)
	v_mov_b32_e32 v30, v43
	v_mov_b32_e32 v31, v44
	v_mov_b32_e32 v43, v45
	v_add_f32_e32 v24, v62, v24
	v_add_f32_e32 v25, v63, v25
	v_add_f32_e32 v26, v30, v42
	v_add_f32_e32 v27, v31, v43
	v_add_f32_e32 v24, v24, v28
	v_add_f32_e32 v25, v25, v29
	v_add_f32_e32 v22, v26, v27
	v_add_f32_e32 v23, v27, v26
	v_pk_add_f32 v[24:25], v[24:25], v[24:25] op_sel:[0,1] op_sel_hi:[1,0]
	s_waitcnt vmcnt(1)
	v_add_f32_e32 v32, v46, v47
	v_add_f32_e32 v34, v48, v49
	s_waitcnt vmcnt(0)
	v_mov_b32_e32 v33, v52
	v_mov_b32_e32 v35, v53
	v_mov_b32_e32 v23, v51
	v_mov_b32_e32 v25, v50
	v_add_f32_e32 v30, v32, v34
	v_add_f32_e32 v31, v33, v35
	v_add_f32_e32 v22, v24, v22
	v_add_f32_e32 v23, v25, v23
	v_lshlrev_b32_e32 v66, 16, v58
	v_add_f32_e32 v22, v22, v30
	v_add_f32_e32 v23, v23, v31
	v_and_b32_e32 v67, 0xffff0000, v58
	v_add_f32_e32 v17, v22, v23
	v_fmamk_f32 v17, v17, 0x3a000000, v16
	v_rsq_f32_e32 v22, v17
	v_lshlrev_b32_e32 v58, 16, v59
	v_and_b32_e32 v59, 0xffff0000, v59
	v_mul_f32_e32 v24, v22, v66
	v_mul_f32_e32 v25, v22, v67
	v_mul_f32_e32 v26, v22, v58
	v_mul_f32_e32 v27, v22, v59
	v_mul_f32_e32 v20, v20, v26
	v_mul_f32_e32 v21, v21, v27
	v_mul_f32_e32 v18, v18, v24
	v_mul_f32_e32 v19, v19, v25
	global_store_dwordx4 v[54:55], v[18:21], off offset:-3072
	global_load_dwordx2 v[24:25], v[56:57], off offset:512
	s_nop 0
	global_load_dwordx4 v[18:21], v[0:1], off offset:1024
	s_waitcnt vmcnt(1)
	v_lshlrev_b32_e32 v26, 16, v24
	v_and_b32_e32 v27, 0xffff0000, v24
	v_lshlrev_b32_e32 v24, 16, v25
	v_and_b32_e32 v25, 0xffff0000, v25
	v_mul_f32_e32 v26, v22, v26
	v_mul_f32_e32 v27, v22, v27
	v_mul_f32_e32 v24, v22, v24
	v_mul_f32_e32 v25, v22, v25
	s_waitcnt vmcnt(0)
	v_mul_f32_e32 v20, v20, v24
	v_mul_f32_e32 v21, v21, v25
	v_mul_f32_e32 v18, v18, v26
	v_mul_f32_e32 v19, v19, v27
	global_store_dwordx4 v[54:55], v[18:21], off offset:-2048
	global_load_dwordx2 v[24:25], v[56:57], off offset:1024
	s_nop 0
	global_load_dwordx4 v[18:21], v[0:1], off offset:2048
	s_waitcnt vmcnt(1)
	v_lshlrev_b32_e32 v26, 16, v24
	v_and_b32_e32 v27, 0xffff0000, v24
	v_lshlrev_b32_e32 v24, 16, v25
	v_and_b32_e32 v25, 0xffff0000, v25
	v_mul_f32_e32 v26, v22, v26
	v_mul_f32_e32 v27, v22, v27
	v_mul_f32_e32 v24, v22, v24
	v_mul_f32_e32 v25, v22, v25
	s_waitcnt vmcnt(0)
	v_mul_f32_e32 v20, v20, v24
	v_mul_f32_e32 v21, v21, v25
	v_mul_f32_e32 v18, v18, v26
	v_mul_f32_e32 v19, v19, v27
	global_store_dwordx4 v[54:55], v[18:21], off offset:-1024
	global_load_dwordx2 v[24:25], v[56:57], off offset:1536
	s_nop 0
	global_load_dwordx4 v[18:21], v[0:1], off offset:3072
	s_waitcnt vmcnt(1)
	v_lshlrev_b32_e32 v26, 16, v24
	v_and_b32_e32 v27, 0xffff0000, v24
	v_lshlrev_b32_e32 v24, 16, v25
	v_and_b32_e32 v25, 0xffff0000, v25
	v_mul_f32_e32 v26, v22, v26
	v_mul_f32_e32 v27, v22, v27
	v_mul_f32_e32 v24, v22, v24
	v_mul_f32_e32 v25, v22, v25
	s_waitcnt vmcnt(0)
	v_mul_f32_e32 v20, v20, v24
	v_mul_f32_e32 v21, v21, v25
	v_mul_f32_e32 v18, v18, v26
	v_mul_f32_e32 v19, v19, v27
	global_store_dwordx4 v[12:13], v[18:21], off offset:-4096
	global_load_dwordx2 v[24:25], v[56:57], off offset:2048
	s_nop 0
	global_load_dwordx4 v[18:21], v[2:3], off
	s_waitcnt vmcnt(1)
	v_lshlrev_b32_e32 v26, 16, v24
	v_and_b32_e32 v27, 0xffff0000, v24
	v_lshlrev_b32_e32 v24, 16, v25
	v_and_b32_e32 v25, 0xffff0000, v25
	v_mul_f32_e32 v26, v22, v26
	v_mul_f32_e32 v27, v22, v27
	v_mul_f32_e32 v24, v22, v24
	v_mul_f32_e32 v25, v22, v25
	s_waitcnt vmcnt(0)
	v_mul_f32_e32 v20, v20, v24
	v_mul_f32_e32 v21, v21, v25
	v_mul_f32_e32 v18, v18, v26
	v_mul_f32_e32 v19, v19, v27
	global_store_dwordx4 v[12:13], v[18:21], off offset:-3072
	global_load_dwordx2 v[24:25], v[56:57], off offset:2560
	s_nop 0
	global_load_dwordx4 v[18:21], v[4:5], off
	s_waitcnt vmcnt(1)
	v_lshlrev_b32_e32 v26, 16, v24
	v_and_b32_e32 v27, 0xffff0000, v24
	v_lshlrev_b32_e32 v24, 16, v25
	v_and_b32_e32 v25, 0xffff0000, v25
	v_mul_f32_e32 v26, v22, v26
	v_mul_f32_e32 v27, v22, v27
	v_mul_f32_e32 v24, v22, v24
	v_mul_f32_e32 v25, v22, v25
	s_waitcnt vmcnt(0)
	v_mul_f32_e32 v20, v20, v24
	v_mul_f32_e32 v21, v21, v25
	v_mul_f32_e32 v18, v18, v26
	v_mul_f32_e32 v19, v19, v27
	global_store_dwordx4 v[12:13], v[18:21], off offset:-2048
	global_load_dwordx2 v[24:25], v[56:57], off offset:3072
	s_nop 0
	global_load_dwordx4 v[18:21], v[6:7], off
	s_waitcnt vmcnt(1)
	v_lshlrev_b32_e32 v26, 16, v24
	v_and_b32_e32 v27, 0xffff0000, v24
	v_lshlrev_b32_e32 v24, 16, v25
	v_and_b32_e32 v25, 0xffff0000, v25
	v_mul_f32_e32 v26, v22, v26
	v_mul_f32_e32 v27, v22, v27
	v_mul_f32_e32 v24, v22, v24
	v_mul_f32_e32 v25, v22, v25
	s_waitcnt vmcnt(0)
	v_mul_f32_e32 v20, v20, v24
	v_mul_f32_e32 v21, v21, v25
	v_mul_f32_e32 v18, v18, v26
	v_mul_f32_e32 v19, v19, v27
	global_store_dwordx4 v[12:13], v[18:21], off offset:-1024
	global_load_dwordx2 v[24:25], v[56:57], off offset:3584
	s_nop 0
	global_load_dwordx4 v[18:21], v[8:9], off
	s_waitcnt vmcnt(1)
	v_lshlrev_b32_e32 v26, 16, v24
	v_and_b32_e32 v27, 0xffff0000, v24
	v_lshlrev_b32_e32 v24, 16, v25
	v_and_b32_e32 v25, 0xffff0000, v25
	v_mul_f32_e32 v26, v22, v26
	v_mul_f32_e32 v27, v22, v27
	v_mul_f32_e32 v23, v22, v25
	v_mul_f32_e32 v22, v22, v24
	s_waitcnt vmcnt(0)
	v_mul_f32_e32 v20, v20, v22
	v_mul_f32_e32 v21, v21, v23
	v_mul_f32_e32 v18, v18, v26
	v_mul_f32_e32 v19, v19, v27
	global_store_dwordx4 v[12:13], v[18:21], off
	v_lshl_add_u64 v[12:13], v[12:13], 0, s[2:3]
	s_cbranch_scc0 .LBB0_2996
